# v60 + the two asm waits before each LOAD barrier merged into one s_waitcnt vmcnt(N) lgkmcnt(0)
# speedup vs baseline: 1.0067x; 1.0067x over previous
.LBB0_297:
	s_add_u32 s47, s38, s46
	s_addc_u32 s66, s39, 0
	s_add_u32 s64, s47, 0x100
	s_addc_u32 s65, s66, 0
	s_and_b64 s[48:49], s[44:45], exec
	s_cselect_b32 s49, s70, s65
	s_cselect_b32 s48, s71, s64
	s_add_u32 s46, s36, s46
	s_addc_u32 s64, s37, 0
	s_add_u32 s46, s46, 0x100
	s_addc_u32 s64, s64, 0
	s_and_b64 s[44:45], s[44:45], exec
	s_cselect_b32 s65, s72, s64
	s_cselect_b32 s64, s73, s46
	s_add_u32 s68, s47, 0x10080
	ds_read_b128 v[150:153], v146
	ds_read_b128 v[154:157], v146 offset:1024
	ds_read_b128 v[158:161], v146 offset:2048
	ds_read_b128 v[162:165], v146 offset:3072
	ds_read_b128 v[166:169], v147
	ds_read_b128 v[170:173], v147 offset:1024
	ds_read_b128 v[174:177], v147 offset:2048
	ds_read_b128 v[178:181], v147 offset:3072
	s_addc_u32 s69, s66, 0
	s_add_i32 s83, s30, s2
	s_add_i32 m0, s16, 0xc000
	s_add_i32 s84, s16, 0xe000
	s_add_i32 s80, s83, 0x2000
	s_add_u32 s66, s64, 0x40000
	s_addc_u32 s67, s65, 0
	s_add_i32 s82, s31, s2
	s_add_i32 s81, s82, 0x2000
	s_add_i32 s79, 0, 0x18000
	s_add_i32 s78, 0, 0x1c000
	s_add_u32 s46, s48, 0x10000
	s_addc_u32 s47, s49, 0
	s_add_i32 s77, s79, s2
	s_add_i32 s75, s77, 0x2000
	s_add_u32 s44, s64, 0x40080
	s_addc_u32 s45, s65, 0
	s_add_i32 s76, s78, s2
	s_add_i32 s74, s76, 0x2000
	v_lshl_add_u64 v[202:203], s[68:69], 0, v[130:131]
	ds_read_b128 v[182:185], v148
	ds_read_b128 v[186:189], v148 offset:1024
	ds_read_b128 v[190:193], v148 offset:2048
	ds_read_b128 v[194:197], v148 offset:3072
	ds_read_b128 v[198:201], v148 offset:4096
	ds_read_b128 v[206:209], v148 offset:5120
	ds_read_b128 v[210:213], v148 offset:6144
	ds_read_b128 v[214:217], v148 offset:7168
	global_load_lds_dwordx4 v[202:203], off
	v_lshl_add_u64 v[202:203], s[68:69], 0, v[132:133]
	s_mov_b32 m0, s84
	s_nop 0
	global_load_lds_dwordx4 v[202:203], off
	s_waitcnt vmcnt(8) lgkmcnt(0)
	s_setprio 1
	s_barrier
	v_mfma_f32_16x16x32_bf16 v[126:129], v[150:153], v[182:185], v[126:129]
	v_mfma_f32_16x16x32_bf16 v[122:125], v[158:161], v[182:185], v[122:125]
	v_mfma_f32_16x16x32_bf16 v[118:121], v[150:153], v[190:193], v[118:121]
	v_mfma_f32_16x16x32_bf16 v[114:117], v[158:161], v[190:193], v[114:117]
	v_mfma_f32_16x16x32_bf16 v[102:105], v[150:153], v[198:201], v[102:105]
	v_mfma_f32_16x16x32_bf16 v[98:101], v[158:161], v[198:201], v[98:101]
	v_mfma_f32_16x16x32_bf16 v[86:89], v[150:153], v[210:213], v[86:89]
	v_mfma_f32_16x16x32_bf16 v[82:85], v[158:161], v[210:213], v[82:85]
	v_mfma_f32_16x16x32_bf16 v[126:129], v[154:157], v[186:189], v[126:129]
	v_mfma_f32_16x16x32_bf16 v[122:125], v[162:165], v[186:189], v[122:125]
	v_mfma_f32_16x16x32_bf16 v[118:121], v[154:157], v[194:197], v[118:121]
	v_mfma_f32_16x16x32_bf16 v[114:117], v[162:165], v[194:197], v[114:117]
	v_mfma_f32_16x16x32_bf16 v[102:105], v[154:157], v[206:209], v[102:105]
	v_mfma_f32_16x16x32_bf16 v[98:101], v[162:165], v[206:209], v[98:101]
	v_mfma_f32_16x16x32_bf16 v[86:89], v[154:157], v[214:217], v[86:89]
	v_mfma_f32_16x16x32_bf16 v[82:85], v[162:165], v[214:217], v[82:85]
	v_mfma_f32_16x16x32_bf16 v[110:113], v[166:169], v[182:185], v[110:113]
	v_mfma_f32_16x16x32_bf16 v[106:109], v[174:177], v[182:185], v[106:109]
	v_mfma_f32_16x16x32_bf16 v[94:97], v[166:169], v[190:193], v[94:97]
	v_mfma_f32_16x16x32_bf16 v[90:93], v[174:177], v[190:193], v[90:93]
	v_mfma_f32_16x16x32_bf16 v[78:81], v[166:169], v[198:201], v[78:81]
	v_mfma_f32_16x16x32_bf16 v[74:77], v[174:177], v[198:201], v[74:77]
	v_mfma_f32_16x16x32_bf16 v[70:73], v[166:169], v[210:213], v[70:73]
	v_mfma_f32_16x16x32_bf16 v[66:69], v[174:177], v[210:213], v[66:69]
	v_mfma_f32_16x16x32_bf16 v[110:113], v[170:173], v[186:189], v[110:113]
	v_mfma_f32_16x16x32_bf16 v[106:109], v[178:181], v[186:189], v[106:109]
	v_mfma_f32_16x16x32_bf16 v[94:97], v[170:173], v[194:197], v[94:97]
	v_mfma_f32_16x16x32_bf16 v[90:93], v[178:181], v[194:197], v[90:93]
	v_mfma_f32_16x16x32_bf16 v[78:81], v[170:173], v[206:209], v[78:81]
	v_mfma_f32_16x16x32_bf16 v[74:77], v[178:181], v[206:209], v[74:77]
	v_mfma_f32_16x16x32_bf16 v[70:73], v[170:173], v[214:217], v[70:73]
	v_mfma_f32_16x16x32_bf16 v[66:69], v[178:181], v[214:217], v[66:69]
	s_setprio 0
	s_barrier
	s_mov_b32 m0, s83
	v_lshl_add_u64 v[202:203], s[64:65], 0, v[136:137]
	ds_read_b128 v[182:185], v148 offset:16384
	ds_read_b128 v[186:189], v148 offset:17408
	ds_read_b128 v[190:193], v148 offset:18432
	ds_read_b128 v[194:197], v148 offset:19456
	ds_read_b128 v[198:201], v148 offset:20480
	ds_read_b128 v[206:209], v148 offset:21504
	ds_read_b128 v[210:213], v148 offset:22528
	ds_read_b128 v[214:217], v148 offset:23552
	global_load_lds_dwordx4 v[202:203], off
	v_lshl_add_u64 v[218:219], s[64:65], 0, v[134:135]
	s_mov_b32 m0, s80
	v_lshl_add_u64 v[220:221], s[66:67], 0, v[136:137]
	global_load_lds_dwordx4 v[218:219], off
	s_mov_b32 m0, s82
	v_lshl_add_u64 v[222:223], s[48:49], 0, v[132:133]
	global_load_lds_dwordx4 v[220:221], off
	v_lshl_add_u64 v[220:221], s[66:67], 0, v[134:135]
	s_mov_b32 m0, s81
	s_nop 0
	global_load_lds_dwordx4 v[220:221], off
	v_lshl_add_u64 v[220:221], s[48:49], 0, v[130:131]
	s_mov_b32 m0, s16
	s_nop 0
	global_load_lds_dwordx4 v[220:221], off
	s_mov_b32 m0, s17
	s_nop 0
	global_load_lds_dwordx4 v[222:223], off
	s_waitcnt vmcnt(8) lgkmcnt(0)
	s_setprio 1
	s_barrier
	v_mfma_f32_16x16x32_bf16 v[62:65], v[150:153], v[182:185], v[62:65]
	v_mfma_f32_16x16x32_bf16 v[58:61], v[158:161], v[182:185], v[58:61]
	v_mfma_f32_16x16x32_bf16 v[54:57], v[150:153], v[190:193], v[54:57]
	v_mfma_f32_16x16x32_bf16 v[50:53], v[158:161], v[190:193], v[50:53]
	v_mfma_f32_16x16x32_bf16 v[38:41], v[150:153], v[198:201], v[38:41]
	v_mfma_f32_16x16x32_bf16 v[34:37], v[158:161], v[198:201], v[34:37]
	v_mfma_f32_16x16x32_bf16 v[22:25], v[150:153], v[210:213], v[22:25]
	v_mfma_f32_16x16x32_bf16 v[18:21], v[158:161], v[210:213], v[18:21]
	v_mfma_f32_16x16x32_bf16 v[62:65], v[154:157], v[186:189], v[62:65]
	v_mfma_f32_16x16x32_bf16 v[58:61], v[162:165], v[186:189], v[58:61]
	v_mfma_f32_16x16x32_bf16 v[54:57], v[154:157], v[194:197], v[54:57]
	v_mfma_f32_16x16x32_bf16 v[50:53], v[162:165], v[194:197], v[50:53]
	v_mfma_f32_16x16x32_bf16 v[38:41], v[154:157], v[206:209], v[38:41]
	v_mfma_f32_16x16x32_bf16 v[34:37], v[162:165], v[206:209], v[34:37]
	v_mfma_f32_16x16x32_bf16 v[22:25], v[154:157], v[214:217], v[22:25]
	v_mfma_f32_16x16x32_bf16 v[18:21], v[162:165], v[214:217], v[18:21]
	v_mfma_f32_16x16x32_bf16 v[46:49], v[166:169], v[182:185], v[46:49]
	v_mfma_f32_16x16x32_bf16 v[42:45], v[174:177], v[182:185], v[42:45]
	v_mfma_f32_16x16x32_bf16 v[30:33], v[166:169], v[190:193], v[30:33]
	v_mfma_f32_16x16x32_bf16 v[26:29], v[174:177], v[190:193], v[26:29]
	v_mfma_f32_16x16x32_bf16 v[14:17], v[166:169], v[198:201], v[14:17]
	v_mfma_f32_16x16x32_bf16 v[10:13], v[174:177], v[198:201], v[10:13]
	v_mfma_f32_16x16x32_bf16 v[6:9], v[166:169], v[210:213], v[6:9]
	v_mfma_f32_16x16x32_bf16 v[2:5], v[174:177], v[210:213], v[2:5]
	v_mfma_f32_16x16x32_bf16 v[46:49], v[170:173], v[186:189], v[46:49]
	v_mfma_f32_16x16x32_bf16 v[42:45], v[178:181], v[186:189], v[42:45]
	v_mfma_f32_16x16x32_bf16 v[30:33], v[170:173], v[194:197], v[30:33]
	v_mfma_f32_16x16x32_bf16 v[26:29], v[178:181], v[194:197], v[26:29]
	v_mfma_f32_16x16x32_bf16 v[14:17], v[170:173], v[206:209], v[14:17]
	v_mfma_f32_16x16x32_bf16 v[10:13], v[178:181], v[206:209], v[10:13]
	v_mfma_f32_16x16x32_bf16 v[6:9], v[170:173], v[214:217], v[6:9]
	v_mfma_f32_16x16x32_bf16 v[2:5], v[178:181], v[214:217], v[2:5]
	s_setprio 0
	s_barrier
	v_add_u32_e32 v149, s79, v145
	ds_read_b128 v[150:153], v149
	ds_read_b128 v[154:157], v149 offset:1024
	ds_read_b128 v[158:161], v149 offset:2048
	ds_read_b128 v[162:165], v149 offset:3072
	v_add_u32_e32 v149, s78, v145
	ds_read_b128 v[166:169], v149
	ds_read_b128 v[170:173], v149 offset:1024
	ds_read_b128 v[174:177], v149 offset:2048
	ds_read_b128 v[178:181], v149 offset:3072
	s_mov_b32 m0, s18
	v_lshl_add_u64 v[224:225], s[46:47], 0, v[130:131]
	ds_read_b128 v[182:185], v148 offset:32768
	ds_read_b128 v[186:189], v148 offset:33792
	ds_read_b128 v[190:193], v148 offset:34816
	ds_read_b128 v[194:197], v148 offset:35840
	ds_read_b128 v[198:201], v148 offset:36864
	ds_read_b128 v[206:209], v148 offset:37888
	ds_read_b128 v[210:213], v148 offset:38912
	ds_read_b128 v[214:217], v148 offset:39936
	global_load_lds_dwordx4 v[224:225], off
	v_lshl_add_u64 v[224:225], s[46:47], 0, v[132:133]
	s_mov_b32 m0, s19
	s_nop 0
	global_load_lds_dwordx4 v[224:225], off
	s_waitcnt vmcnt(8) lgkmcnt(0)
	s_setprio 1
	s_barrier
	v_mfma_f32_16x16x32_bf16 v[126:129], v[150:153], v[182:185], v[126:129]
	v_mfma_f32_16x16x32_bf16 v[122:125], v[158:161], v[182:185], v[122:125]
	v_mfma_f32_16x16x32_bf16 v[118:121], v[150:153], v[190:193], v[118:121]
	v_mfma_f32_16x16x32_bf16 v[114:117], v[158:161], v[190:193], v[114:117]
	v_mfma_f32_16x16x32_bf16 v[102:105], v[150:153], v[198:201], v[102:105]
	v_mfma_f32_16x16x32_bf16 v[98:101], v[158:161], v[198:201], v[98:101]
	v_mfma_f32_16x16x32_bf16 v[86:89], v[150:153], v[210:213], v[86:89]
	v_mfma_f32_16x16x32_bf16 v[82:85], v[158:161], v[210:213], v[82:85]
	v_mfma_f32_16x16x32_bf16 v[126:129], v[154:157], v[186:189], v[126:129]
	v_mfma_f32_16x16x32_bf16 v[122:125], v[162:165], v[186:189], v[122:125]
	v_mfma_f32_16x16x32_bf16 v[118:121], v[154:157], v[194:197], v[118:121]
	v_mfma_f32_16x16x32_bf16 v[114:117], v[162:165], v[194:197], v[114:117]
	v_mfma_f32_16x16x32_bf16 v[102:105], v[154:157], v[206:209], v[102:105]
	v_mfma_f32_16x16x32_bf16 v[98:101], v[162:165], v[206:209], v[98:101]
	v_mfma_f32_16x16x32_bf16 v[86:89], v[154:157], v[214:217], v[86:89]
	v_mfma_f32_16x16x32_bf16 v[82:85], v[162:165], v[214:217], v[82:85]
	v_mfma_f32_16x16x32_bf16 v[110:113], v[166:169], v[182:185], v[110:113]
	v_mfma_f32_16x16x32_bf16 v[106:109], v[174:177], v[182:185], v[106:109]
	v_mfma_f32_16x16x32_bf16 v[94:97], v[166:169], v[190:193], v[94:97]
	v_mfma_f32_16x16x32_bf16 v[90:93], v[174:177], v[190:193], v[90:93]
	v_mfma_f32_16x16x32_bf16 v[78:81], v[166:169], v[198:201], v[78:81]
	v_mfma_f32_16x16x32_bf16 v[74:77], v[174:177], v[198:201], v[74:77]
	v_mfma_f32_16x16x32_bf16 v[70:73], v[166:169], v[210:213], v[70:73]
	v_mfma_f32_16x16x32_bf16 v[66:69], v[174:177], v[210:213], v[66:69]
	v_mfma_f32_16x16x32_bf16 v[110:113], v[170:173], v[186:189], v[110:113]
	v_mfma_f32_16x16x32_bf16 v[106:109], v[178:181], v[186:189], v[106:109]
	v_mfma_f32_16x16x32_bf16 v[94:97], v[170:173], v[194:197], v[94:97]
	v_mfma_f32_16x16x32_bf16 v[90:93], v[178:181], v[194:197], v[90:93]
	v_mfma_f32_16x16x32_bf16 v[78:81], v[170:173], v[206:209], v[78:81]
	v_mfma_f32_16x16x32_bf16 v[74:77], v[178:181], v[206:209], v[74:77]
	v_mfma_f32_16x16x32_bf16 v[70:73], v[170:173], v[214:217], v[70:73]
	v_mfma_f32_16x16x32_bf16 v[66:69], v[178:181], v[214:217], v[66:69]
	s_setprio 0
	s_barrier
	s_mov_b32 m0, s77
	v_lshl_add_u64 v[202:203], v[202:203], 0, s[8:9]
	ds_read_b128 v[182:185], v148 offset:49152
	ds_read_b128 v[186:189], v148 offset:50176
	ds_read_b128 v[190:193], v148 offset:51200
	ds_read_b128 v[194:197], v148 offset:52224
	ds_read_b128 v[198:201], v148 offset:53248
	ds_read_b128 v[206:209], v148 offset:54272
	ds_read_b128 v[210:213], v148 offset:55296
	ds_read_b128 v[214:217], v148 offset:56320
	global_load_lds_dwordx4 v[202:203], off
	v_lshl_add_u64 v[202:203], v[218:219], 0, s[8:9]
	s_mov_b32 m0, s75
	s_nop 0
	global_load_lds_dwordx4 v[202:203], off
	v_lshl_add_u64 v[202:203], s[44:45], 0, v[136:137]
	s_mov_b32 m0, s76
	s_nop 0
	global_load_lds_dwordx4 v[202:203], off
	v_lshl_add_u64 v[202:203], s[44:45], 0, v[134:135]
	s_mov_b32 m0, s74
	s_nop 0
	global_load_lds_dwordx4 v[202:203], off
	v_lshl_add_u64 v[202:203], v[220:221], 0, s[8:9]
	s_mov_b32 m0, s28
	s_nop 0
	global_load_lds_dwordx4 v[202:203], off
	v_lshl_add_u64 v[202:203], v[222:223], 0, s[8:9]
	s_mov_b32 m0, s29
	s_nop 0
	global_load_lds_dwordx4 v[202:203], off
	s_waitcnt vmcnt(8) lgkmcnt(0)
	s_setprio 1
	s_barrier
	v_mfma_f32_16x16x32_bf16 v[62:65], v[150:153], v[182:185], v[62:65]
	v_mfma_f32_16x16x32_bf16 v[58:61], v[158:161], v[182:185], v[58:61]
	v_mfma_f32_16x16x32_bf16 v[54:57], v[150:153], v[190:193], v[54:57]
	v_mfma_f32_16x16x32_bf16 v[50:53], v[158:161], v[190:193], v[50:53]
	v_mfma_f32_16x16x32_bf16 v[38:41], v[150:153], v[198:201], v[38:41]
	v_mfma_f32_16x16x32_bf16 v[34:37], v[158:161], v[198:201], v[34:37]
	v_mfma_f32_16x16x32_bf16 v[22:25], v[150:153], v[210:213], v[22:25]
	v_mfma_f32_16x16x32_bf16 v[18:21], v[158:161], v[210:213], v[18:21]
	v_mfma_f32_16x16x32_bf16 v[62:65], v[154:157], v[186:189], v[62:65]
	v_mfma_f32_16x16x32_bf16 v[58:61], v[162:165], v[186:189], v[58:61]
	v_mfma_f32_16x16x32_bf16 v[54:57], v[154:157], v[194:197], v[54:57]
	v_mfma_f32_16x16x32_bf16 v[50:53], v[162:165], v[194:197], v[50:53]
	v_mfma_f32_16x16x32_bf16 v[38:41], v[154:157], v[206:209], v[38:41]
	v_mfma_f32_16x16x32_bf16 v[34:37], v[162:165], v[206:209], v[34:37]
	v_mfma_f32_16x16x32_bf16 v[22:25], v[154:157], v[214:217], v[22:25]
	v_mfma_f32_16x16x32_bf16 v[18:21], v[162:165], v[214:217], v[18:21]
	v_mfma_f32_16x16x32_bf16 v[46:49], v[166:169], v[182:185], v[46:49]
	v_mfma_f32_16x16x32_bf16 v[42:45], v[174:177], v[182:185], v[42:45]
	v_mfma_f32_16x16x32_bf16 v[30:33], v[166:169], v[190:193], v[30:33]
	v_mfma_f32_16x16x32_bf16 v[26:29], v[174:177], v[190:193], v[26:29]
	v_mfma_f32_16x16x32_bf16 v[14:17], v[166:169], v[198:201], v[14:17]
	v_mfma_f32_16x16x32_bf16 v[10:13], v[174:177], v[198:201], v[10:13]
	v_mfma_f32_16x16x32_bf16 v[6:9], v[166:169], v[210:213], v[6:9]
	v_mfma_f32_16x16x32_bf16 v[2:5], v[174:177], v[210:213], v[2:5]
	v_mfma_f32_16x16x32_bf16 v[46:49], v[170:173], v[186:189], v[46:49]
	v_mfma_f32_16x16x32_bf16 v[42:45], v[178:181], v[186:189], v[42:45]
	v_mfma_f32_16x16x32_bf16 v[30:33], v[170:173], v[194:197], v[30:33]
	v_mfma_f32_16x16x32_bf16 v[26:29], v[178:181], v[194:197], v[26:29]
	v_mfma_f32_16x16x32_bf16 v[14:17], v[170:173], v[206:209], v[14:17]
	v_mfma_f32_16x16x32_bf16 v[10:13], v[178:181], v[206:209], v[10:13]
	v_mfma_f32_16x16x32_bf16 v[6:9], v[170:173], v[214:217], v[6:9]
	v_mfma_f32_16x16x32_bf16 v[2:5], v[178:181], v[214:217], v[2:5]
	s_setprio 0
	s_barrier
	s_movk_i32 s46, 0x100
	s_andn2_b64 vcc, exec, s[42:43]
	s_mov_b64 s[44:45], -1
	s_mov_b64 s[42:43], 0
	s_cbranch_vccz .LBB0_297
	s_and_b64 vcc, exec, s[10:11]
	s_cbranch_vccz .LBB0_300
	s_barrier

.LBB0_313:
	s_add_u32 s49, s38, s48
	s_addc_u32 s68, s39, 0
	s_add_u32 s66, s49, 0x100
	s_addc_u32 s67, s68, 0
	s_and_b64 s[64:65], s[46:47], exec
	s_cselect_b32 s65, s43, s67
	s_cselect_b32 s64, s75, s66
	s_add_u32 s48, s36, s48
	s_addc_u32 s66, s37, 0
	s_add_u32 s48, s48, 0x100
	s_addc_u32 s66, s66, 0
	s_and_b64 s[46:47], s[46:47], exec
	s_cselect_b32 s67, s76, s66
	s_cselect_b32 s66, s77, s48
	s_add_u32 s70, s49, 0x10080
	ds_read_b128 v[144:147], v140
	ds_read_b128 v[148:151], v140 offset:1024
	ds_read_b128 v[152:155], v140 offset:2048
	ds_read_b128 v[156:159], v140 offset:3072
	ds_read_b128 v[160:163], v141
	ds_read_b128 v[164:167], v141 offset:1024
	ds_read_b128 v[168:171], v141 offset:2048
	ds_read_b128 v[172:175], v141 offset:3072
	s_addc_u32 s71, s68, 0
	s_add_i32 s87, s33, s2
	s_add_i32 m0, s16, 0xc000
	s_add_i32 s88, s16, 0xe000
	s_add_i32 s84, s87, 0x2000
	s_add_u32 s68, s66, 0x1000
	s_addc_u32 s69, s67, 0
	s_add_i32 s86, s34, s2
	s_add_i32 s85, s86, 0x2000
	s_add_i32 s83, 0, 0x18000
	s_add_i32 s82, 0, 0x1c000
	s_add_u32 s48, s64, 0x10000
	s_addc_u32 s49, s65, 0
	s_add_i32 s81, s83, s2
	s_add_i32 s79, s81, 0x2000
	s_add_u32 s46, s66, 0x1080
	s_addc_u32 s47, s67, 0
	s_add_i32 s80, s82, s2
	s_add_i32 s78, s80, 0x2000
	v_lshl_add_u64 v[210:211], s[70:71], 0, v[130:131]
	ds_read_b128 v[176:179], v142
	ds_read_b128 v[180:183], v142 offset:1024
	ds_read_b128 v[184:187], v142 offset:2048
	ds_read_b128 v[188:191], v142 offset:3072
	ds_read_b128 v[192:195], v142 offset:4096
	ds_read_b128 v[196:199], v142 offset:5120
	ds_read_b128 v[200:203], v142 offset:6144
	ds_read_b128 v[206:209], v142 offset:7168
	global_load_lds_dwordx4 v[210:211], off
	v_lshl_add_u64 v[210:211], s[70:71], 0, v[132:133]
	s_mov_b32 m0, s88
	s_nop 0
	global_load_lds_dwordx4 v[210:211], off
	s_waitcnt vmcnt(8) lgkmcnt(0)
	s_setprio 1
	s_barrier
	v_mfma_f32_16x16x32_bf16 v[126:129], v[144:147], v[176:179], v[126:129]
	v_mfma_f32_16x16x32_bf16 v[122:125], v[152:155], v[176:179], v[122:125]
	v_mfma_f32_16x16x32_bf16 v[118:121], v[144:147], v[184:187], v[118:121]
	v_mfma_f32_16x16x32_bf16 v[114:117], v[152:155], v[184:187], v[114:117]
	v_mfma_f32_16x16x32_bf16 v[102:105], v[144:147], v[192:195], v[102:105]
	v_mfma_f32_16x16x32_bf16 v[98:101], v[152:155], v[192:195], v[98:101]
	v_mfma_f32_16x16x32_bf16 v[86:89], v[144:147], v[200:203], v[86:89]
	v_mfma_f32_16x16x32_bf16 v[82:85], v[152:155], v[200:203], v[82:85]
	v_mfma_f32_16x16x32_bf16 v[126:129], v[148:151], v[180:183], v[126:129]
	v_mfma_f32_16x16x32_bf16 v[122:125], v[156:159], v[180:183], v[122:125]
	v_mfma_f32_16x16x32_bf16 v[118:121], v[148:151], v[188:191], v[118:121]
	v_mfma_f32_16x16x32_bf16 v[114:117], v[156:159], v[188:191], v[114:117]
	v_mfma_f32_16x16x32_bf16 v[102:105], v[148:151], v[196:199], v[102:105]
	v_mfma_f32_16x16x32_bf16 v[98:101], v[156:159], v[196:199], v[98:101]
	v_mfma_f32_16x16x32_bf16 v[86:89], v[148:151], v[206:209], v[86:89]
	v_mfma_f32_16x16x32_bf16 v[82:85], v[156:159], v[206:209], v[82:85]
	v_mfma_f32_16x16x32_bf16 v[110:113], v[160:163], v[176:179], v[110:113]
	v_mfma_f32_16x16x32_bf16 v[106:109], v[168:171], v[176:179], v[106:109]
	v_mfma_f32_16x16x32_bf16 v[94:97], v[160:163], v[184:187], v[94:97]
	v_mfma_f32_16x16x32_bf16 v[90:93], v[168:171], v[184:187], v[90:93]
	v_mfma_f32_16x16x32_bf16 v[78:81], v[160:163], v[192:195], v[78:81]
	v_mfma_f32_16x16x32_bf16 v[74:77], v[168:171], v[192:195], v[74:77]
	v_mfma_f32_16x16x32_bf16 v[70:73], v[160:163], v[200:203], v[70:73]
	v_mfma_f32_16x16x32_bf16 v[66:69], v[168:171], v[200:203], v[66:69]
	v_mfma_f32_16x16x32_bf16 v[110:113], v[164:167], v[180:183], v[110:113]
	v_mfma_f32_16x16x32_bf16 v[106:109], v[172:175], v[180:183], v[106:109]
	v_mfma_f32_16x16x32_bf16 v[94:97], v[164:167], v[188:191], v[94:97]
	v_mfma_f32_16x16x32_bf16 v[90:93], v[172:175], v[188:191], v[90:93]
	v_mfma_f32_16x16x32_bf16 v[78:81], v[164:167], v[196:199], v[78:81]
	v_mfma_f32_16x16x32_bf16 v[74:77], v[172:175], v[196:199], v[74:77]
	v_mfma_f32_16x16x32_bf16 v[70:73], v[164:167], v[206:209], v[70:73]
	v_mfma_f32_16x16x32_bf16 v[66:69], v[172:175], v[206:209], v[66:69]
	s_setprio 0
	s_barrier
	s_mov_b32 m0, s87
	v_lshl_add_u64 v[210:211], s[66:67], 0, v[136:137]
	ds_read_b128 v[176:179], v142 offset:16384
	ds_read_b128 v[180:183], v142 offset:17408
	ds_read_b128 v[184:187], v142 offset:18432
	ds_read_b128 v[188:191], v142 offset:19456
	ds_read_b128 v[192:195], v142 offset:20480
	ds_read_b128 v[196:199], v142 offset:21504
	ds_read_b128 v[200:203], v142 offset:22528
	ds_read_b128 v[206:209], v142 offset:23552
	global_load_lds_dwordx4 v[210:211], off
	v_lshl_add_u64 v[212:213], s[66:67], 0, v[134:135]
	s_mov_b32 m0, s84
	v_lshl_add_u64 v[214:215], s[68:69], 0, v[136:137]
	global_load_lds_dwordx4 v[212:213], off
	s_mov_b32 m0, s86
	v_lshl_add_u64 v[216:217], s[64:65], 0, v[132:133]
	global_load_lds_dwordx4 v[214:215], off
	v_lshl_add_u64 v[214:215], s[68:69], 0, v[134:135]
	s_mov_b32 m0, s85
	s_nop 0
	global_load_lds_dwordx4 v[214:215], off
	v_lshl_add_u64 v[214:215], s[64:65], 0, v[130:131]
	s_mov_b32 m0, s16
	s_nop 0
	global_load_lds_dwordx4 v[214:215], off
	s_mov_b32 m0, s17
	s_nop 0
	global_load_lds_dwordx4 v[216:217], off
	s_waitcnt vmcnt(8) lgkmcnt(0)
	s_setprio 1
	s_barrier
	v_mfma_f32_16x16x32_bf16 v[62:65], v[144:147], v[176:179], v[62:65]
	v_mfma_f32_16x16x32_bf16 v[58:61], v[152:155], v[176:179], v[58:61]
	v_mfma_f32_16x16x32_bf16 v[54:57], v[144:147], v[184:187], v[54:57]
	v_mfma_f32_16x16x32_bf16 v[50:53], v[152:155], v[184:187], v[50:53]
	v_mfma_f32_16x16x32_bf16 v[38:41], v[144:147], v[192:195], v[38:41]
	v_mfma_f32_16x16x32_bf16 v[34:37], v[152:155], v[192:195], v[34:37]
	v_mfma_f32_16x16x32_bf16 v[22:25], v[144:147], v[200:203], v[22:25]
	v_mfma_f32_16x16x32_bf16 v[18:21], v[152:155], v[200:203], v[18:21]
	v_mfma_f32_16x16x32_bf16 v[62:65], v[148:151], v[180:183], v[62:65]
	v_mfma_f32_16x16x32_bf16 v[58:61], v[156:159], v[180:183], v[58:61]
	v_mfma_f32_16x16x32_bf16 v[54:57], v[148:151], v[188:191], v[54:57]
	v_mfma_f32_16x16x32_bf16 v[50:53], v[156:159], v[188:191], v[50:53]
	v_mfma_f32_16x16x32_bf16 v[38:41], v[148:151], v[196:199], v[38:41]
	v_mfma_f32_16x16x32_bf16 v[34:37], v[156:159], v[196:199], v[34:37]
	v_mfma_f32_16x16x32_bf16 v[22:25], v[148:151], v[206:209], v[22:25]
	v_mfma_f32_16x16x32_bf16 v[18:21], v[156:159], v[206:209], v[18:21]
	v_mfma_f32_16x16x32_bf16 v[46:49], v[160:163], v[176:179], v[46:49]
	v_mfma_f32_16x16x32_bf16 v[42:45], v[168:171], v[176:179], v[42:45]
	v_mfma_f32_16x16x32_bf16 v[30:33], v[160:163], v[184:187], v[30:33]
	v_mfma_f32_16x16x32_bf16 v[26:29], v[168:171], v[184:187], v[26:29]
	v_mfma_f32_16x16x32_bf16 v[14:17], v[160:163], v[192:195], v[14:17]
	v_mfma_f32_16x16x32_bf16 v[10:13], v[168:171], v[192:195], v[10:13]
	v_mfma_f32_16x16x32_bf16 v[6:9], v[160:163], v[200:203], v[6:9]
	v_mfma_f32_16x16x32_bf16 v[2:5], v[168:171], v[200:203], v[2:5]
	v_mfma_f32_16x16x32_bf16 v[46:49], v[164:167], v[180:183], v[46:49]
	v_mfma_f32_16x16x32_bf16 v[42:45], v[172:175], v[180:183], v[42:45]
	v_mfma_f32_16x16x32_bf16 v[30:33], v[164:167], v[188:191], v[30:33]
	v_mfma_f32_16x16x32_bf16 v[26:29], v[172:175], v[188:191], v[26:29]
	v_mfma_f32_16x16x32_bf16 v[14:17], v[164:167], v[196:199], v[14:17]
	v_mfma_f32_16x16x32_bf16 v[10:13], v[172:175], v[196:199], v[10:13]
	v_mfma_f32_16x16x32_bf16 v[6:9], v[164:167], v[206:209], v[6:9]
	v_mfma_f32_16x16x32_bf16 v[2:5], v[172:175], v[206:209], v[2:5]
	s_setprio 0
	s_barrier
	v_add_u32_e32 v143, s83, v139
	ds_read_b128 v[144:147], v143
	ds_read_b128 v[148:151], v143 offset:1024
	ds_read_b128 v[152:155], v143 offset:2048
	ds_read_b128 v[156:159], v143 offset:3072
	v_add_u32_e32 v143, s82, v139
	ds_read_b128 v[160:163], v143
	ds_read_b128 v[164:167], v143 offset:1024
	ds_read_b128 v[168:171], v143 offset:2048
	ds_read_b128 v[172:175], v143 offset:3072
	s_mov_b32 m0, s18
	v_lshl_add_u64 v[218:219], s[48:49], 0, v[130:131]
	ds_read_b128 v[176:179], v142 offset:32768
	ds_read_b128 v[180:183], v142 offset:33792
	ds_read_b128 v[184:187], v142 offset:34816
	ds_read_b128 v[188:191], v142 offset:35840
	ds_read_b128 v[192:195], v142 offset:36864
	ds_read_b128 v[196:199], v142 offset:37888
	ds_read_b128 v[200:203], v142 offset:38912
	ds_read_b128 v[206:209], v142 offset:39936
	global_load_lds_dwordx4 v[218:219], off
	v_lshl_add_u64 v[218:219], s[48:49], 0, v[132:133]
	s_mov_b32 m0, s19
	s_nop 0
	global_load_lds_dwordx4 v[218:219], off
	s_waitcnt vmcnt(8) lgkmcnt(0)
	s_setprio 1
	s_barrier
	v_mfma_f32_16x16x32_bf16 v[126:129], v[144:147], v[176:179], v[126:129]
	v_mfma_f32_16x16x32_bf16 v[122:125], v[152:155], v[176:179], v[122:125]
	v_mfma_f32_16x16x32_bf16 v[118:121], v[144:147], v[184:187], v[118:121]
	v_mfma_f32_16x16x32_bf16 v[114:117], v[152:155], v[184:187], v[114:117]
	v_mfma_f32_16x16x32_bf16 v[102:105], v[144:147], v[192:195], v[102:105]
	v_mfma_f32_16x16x32_bf16 v[98:101], v[152:155], v[192:195], v[98:101]
	v_mfma_f32_16x16x32_bf16 v[86:89], v[144:147], v[200:203], v[86:89]
	v_mfma_f32_16x16x32_bf16 v[82:85], v[152:155], v[200:203], v[82:85]
	v_mfma_f32_16x16x32_bf16 v[126:129], v[148:151], v[180:183], v[126:129]
	v_mfma_f32_16x16x32_bf16 v[122:125], v[156:159], v[180:183], v[122:125]
	v_mfma_f32_16x16x32_bf16 v[118:121], v[148:151], v[188:191], v[118:121]
	v_mfma_f32_16x16x32_bf16 v[114:117], v[156:159], v[188:191], v[114:117]
	v_mfma_f32_16x16x32_bf16 v[102:105], v[148:151], v[196:199], v[102:105]
	v_mfma_f32_16x16x32_bf16 v[98:101], v[156:159], v[196:199], v[98:101]
	v_mfma_f32_16x16x32_bf16 v[86:89], v[148:151], v[206:209], v[86:89]
	v_mfma_f32_16x16x32_bf16 v[82:85], v[156:159], v[206:209], v[82:85]
	v_mfma_f32_16x16x32_bf16 v[110:113], v[160:163], v[176:179], v[110:113]
	v_mfma_f32_16x16x32_bf16 v[106:109], v[168:171], v[176:179], v[106:109]
	v_mfma_f32_16x16x32_bf16 v[94:97], v[160:163], v[184:187], v[94:97]
	v_mfma_f32_16x16x32_bf16 v[90:93], v[168:171], v[184:187], v[90:93]
	v_mfma_f32_16x16x32_bf16 v[78:81], v[160:163], v[192:195], v[78:81]
	v_mfma_f32_16x16x32_bf16 v[74:77], v[168:171], v[192:195], v[74:77]
	v_mfma_f32_16x16x32_bf16 v[70:73], v[160:163], v[200:203], v[70:73]
	v_mfma_f32_16x16x32_bf16 v[66:69], v[168:171], v[200:203], v[66:69]
	v_mfma_f32_16x16x32_bf16 v[110:113], v[164:167], v[180:183], v[110:113]
	v_mfma_f32_16x16x32_bf16 v[106:109], v[172:175], v[180:183], v[106:109]
	v_mfma_f32_16x16x32_bf16 v[94:97], v[164:167], v[188:191], v[94:97]
	v_mfma_f32_16x16x32_bf16 v[90:93], v[172:175], v[188:191], v[90:93]
	v_mfma_f32_16x16x32_bf16 v[78:81], v[164:167], v[196:199], v[78:81]
	v_mfma_f32_16x16x32_bf16 v[74:77], v[172:175], v[196:199], v[74:77]
	v_mfma_f32_16x16x32_bf16 v[70:73], v[164:167], v[206:209], v[70:73]
	v_mfma_f32_16x16x32_bf16 v[66:69], v[172:175], v[206:209], v[66:69]
	s_setprio 0
	s_barrier
	s_mov_b32 m0, s81
	v_lshl_add_u64 v[210:211], v[210:211], 0, s[8:9]
	ds_read_b128 v[176:179], v142 offset:49152
	ds_read_b128 v[180:183], v142 offset:50176
	ds_read_b128 v[184:187], v142 offset:51200
	ds_read_b128 v[188:191], v142 offset:52224
	ds_read_b128 v[192:195], v142 offset:53248
	ds_read_b128 v[196:199], v142 offset:54272
	ds_read_b128 v[200:203], v142 offset:55296
	ds_read_b128 v[206:209], v142 offset:56320
	global_load_lds_dwordx4 v[210:211], off
	v_lshl_add_u64 v[210:211], v[212:213], 0, s[8:9]
	s_mov_b32 m0, s79
	s_nop 0
	global_load_lds_dwordx4 v[210:211], off
	v_lshl_add_u64 v[210:211], s[46:47], 0, v[136:137]
	s_mov_b32 m0, s80
	s_nop 0
	global_load_lds_dwordx4 v[210:211], off
	v_lshl_add_u64 v[210:211], s[46:47], 0, v[134:135]
	s_mov_b32 m0, s78
	s_nop 0
	global_load_lds_dwordx4 v[210:211], off
	v_lshl_add_u64 v[210:211], v[214:215], 0, s[8:9]
	s_mov_b32 m0, s30
	s_nop 0
	global_load_lds_dwordx4 v[210:211], off
	v_lshl_add_u64 v[210:211], v[216:217], 0, s[8:9]
	s_mov_b32 m0, s31
	s_nop 0
	global_load_lds_dwordx4 v[210:211], off
	s_waitcnt vmcnt(8) lgkmcnt(0)
	s_setprio 1
	s_barrier
	v_mfma_f32_16x16x32_bf16 v[62:65], v[144:147], v[176:179], v[62:65]
	v_mfma_f32_16x16x32_bf16 v[58:61], v[152:155], v[176:179], v[58:61]
	v_mfma_f32_16x16x32_bf16 v[54:57], v[144:147], v[184:187], v[54:57]
	v_mfma_f32_16x16x32_bf16 v[50:53], v[152:155], v[184:187], v[50:53]
	v_mfma_f32_16x16x32_bf16 v[38:41], v[144:147], v[192:195], v[38:41]
	v_mfma_f32_16x16x32_bf16 v[34:37], v[152:155], v[192:195], v[34:37]
	v_mfma_f32_16x16x32_bf16 v[22:25], v[144:147], v[200:203], v[22:25]
	v_mfma_f32_16x16x32_bf16 v[18:21], v[152:155], v[200:203], v[18:21]
	v_mfma_f32_16x16x32_bf16 v[62:65], v[148:151], v[180:183], v[62:65]
	v_mfma_f32_16x16x32_bf16 v[58:61], v[156:159], v[180:183], v[58:61]
	v_mfma_f32_16x16x32_bf16 v[54:57], v[148:151], v[188:191], v[54:57]
	v_mfma_f32_16x16x32_bf16 v[50:53], v[156:159], v[188:191], v[50:53]
	v_mfma_f32_16x16x32_bf16 v[38:41], v[148:151], v[196:199], v[38:41]
	v_mfma_f32_16x16x32_bf16 v[34:37], v[156:159], v[196:199], v[34:37]
	v_mfma_f32_16x16x32_bf16 v[22:25], v[148:151], v[206:209], v[22:25]
	v_mfma_f32_16x16x32_bf16 v[18:21], v[156:159], v[206:209], v[18:21]
	v_mfma_f32_16x16x32_bf16 v[46:49], v[160:163], v[176:179], v[46:49]
	v_mfma_f32_16x16x32_bf16 v[42:45], v[168:171], v[176:179], v[42:45]
	v_mfma_f32_16x16x32_bf16 v[30:33], v[160:163], v[184:187], v[30:33]
	v_mfma_f32_16x16x32_bf16 v[26:29], v[168:171], v[184:187], v[26:29]
	v_mfma_f32_16x16x32_bf16 v[14:17], v[160:163], v[192:195], v[14:17]
	v_mfma_f32_16x16x32_bf16 v[10:13], v[168:171], v[192:195], v[10:13]
	v_mfma_f32_16x16x32_bf16 v[6:9], v[160:163], v[200:203], v[6:9]
	v_mfma_f32_16x16x32_bf16 v[2:5], v[168:171], v[200:203], v[2:5]
	v_mfma_f32_16x16x32_bf16 v[46:49], v[164:167], v[180:183], v[46:49]
	v_mfma_f32_16x16x32_bf16 v[42:45], v[172:175], v[180:183], v[42:45]
	v_mfma_f32_16x16x32_bf16 v[30:33], v[164:167], v[188:191], v[30:33]
	v_mfma_f32_16x16x32_bf16 v[26:29], v[172:175], v[188:191], v[26:29]
	v_mfma_f32_16x16x32_bf16 v[14:17], v[164:167], v[196:199], v[14:17]
	v_mfma_f32_16x16x32_bf16 v[10:13], v[172:175], v[196:199], v[10:13]
	v_mfma_f32_16x16x32_bf16 v[6:9], v[164:167], v[206:209], v[6:9]
	v_mfma_f32_16x16x32_bf16 v[2:5], v[172:175], v[206:209], v[2:5]
	s_setprio 0
	s_barrier
	s_movk_i32 s48, 0x100
	s_andn2_b64 vcc, exec, s[44:45]
	s_mov_b64 s[46:47], -1
	s_mov_b64 s[44:45], 0
	s_cbranch_vccz .LBB0_313
	s_and_b64 vcc, exec, s[10:11]
	s_cbranch_vccz .LBB0_316
	s_barrier

.LBB0_383:
	s_add_u32 s26, s0, s22
	s_addc_u32 s27, s1, s23
	s_and_b64 s[44:45], s[36:37], exec
	s_cselect_b32 s15, s27, s43
	s_cselect_b32 s39, s26, s42
	s_add_u32 s66, s42, 0x100
	s_addc_u32 s67, s43, 0
	s_mov_b32 s68, -2
	s_mov_b64 s[42:43], 0
	ds_read_b128 v[152:155], v146
	ds_read_b128 v[156:159], v146 offset:1024
	ds_read_b128 v[160:163], v146 offset:2048
	ds_read_b128 v[164:167], v146 offset:3072
	ds_read_b128 v[168:171], v147
	ds_read_b128 v[172:175], v147 offset:1024
	ds_read_b128 v[176:179], v147 offset:2048
	ds_read_b128 v[180:183], v147 offset:3072
	s_add_u32 s44, s42, 0x100
	s_addc_u32 s45, s43, 0
	s_add_u32 s46, s66, s42
	s_addc_u32 s47, s67, s43
	s_cmp_eq_u32 s68, 4
	s_cselect_b32 s48, 0, s44
	s_cselect_b32 s49, 0, s45
	s_cselect_b32 s46, s39, s46
	s_cselect_b32 s47, s15, s47
	s_add_u32 s48, s6, s48
	s_addc_u32 s49, s7, s49
	s_mov_b32 m0, s29
	v_lshl_add_u64 v[218:219], v[138:139], 0, s[42:43]
	ds_read_b128 v[184:187], v148
	ds_read_b128 v[188:191], v148 offset:1024
	ds_read_b128 v[192:195], v148 offset:2048
	ds_read_b128 v[196:199], v148 offset:3072
	ds_read_b128 v[200:203], v148 offset:4096
	ds_read_b128 v[206:209], v148 offset:5120
	ds_read_b128 v[210:213], v148 offset:6144
	ds_read_b128 v[214:217], v148 offset:7168
	global_load_lds_dwordx4 v[218:219], off
	v_lshl_add_u64 v[218:219], v[140:141], 0, s[42:43]
	s_mov_b32 m0, s30
	s_nop 0
	global_load_lds_dwordx4 v[218:219], off
	s_waitcnt vmcnt(8) lgkmcnt(0)
	s_setprio 1
	s_barrier
	v_mfma_f32_16x16x32_bf16 v[126:129], v[152:155], v[184:187], 0
	v_mfma_f32_16x16x32_bf16 v[122:125], v[160:163], v[184:187], 0
	v_mfma_f32_16x16x32_bf16 v[118:121], v[152:155], v[192:195], 0
	v_mfma_f32_16x16x32_bf16 v[114:117], v[160:163], v[192:195], 0
	v_mfma_f32_16x16x32_bf16 v[102:105], v[152:155], v[200:203], 0
	v_mfma_f32_16x16x32_bf16 v[98:101], v[160:163], v[200:203], 0
	v_mfma_f32_16x16x32_bf16 v[86:89], v[152:155], v[210:213], 0
	v_mfma_f32_16x16x32_bf16 v[82:85], v[160:163], v[210:213], 0
	v_mfma_f32_16x16x32_bf16 v[126:129], v[156:159], v[188:191], v[126:129]
	v_mfma_f32_16x16x32_bf16 v[122:125], v[164:167], v[188:191], v[122:125]
	v_mfma_f32_16x16x32_bf16 v[118:121], v[156:159], v[196:199], v[118:121]
	v_mfma_f32_16x16x32_bf16 v[114:117], v[164:167], v[196:199], v[114:117]
	v_mfma_f32_16x16x32_bf16 v[102:105], v[156:159], v[206:209], v[102:105]
	v_mfma_f32_16x16x32_bf16 v[98:101], v[164:167], v[206:209], v[98:101]
	v_mfma_f32_16x16x32_bf16 v[86:89], v[156:159], v[214:217], v[86:89]
	v_mfma_f32_16x16x32_bf16 v[82:85], v[164:167], v[214:217], v[82:85]
	v_mfma_f32_16x16x32_bf16 v[110:113], v[168:171], v[184:187], 0
	v_mfma_f32_16x16x32_bf16 v[106:109], v[176:179], v[184:187], 0
	v_mfma_f32_16x16x32_bf16 v[94:97], v[168:171], v[192:195], 0
	v_mfma_f32_16x16x32_bf16 v[90:93], v[176:179], v[192:195], 0
	v_mfma_f32_16x16x32_bf16 v[78:81], v[168:171], v[200:203], 0
	v_mfma_f32_16x16x32_bf16 v[74:77], v[176:179], v[200:203], 0
	v_mfma_f32_16x16x32_bf16 v[70:73], v[168:171], v[210:213], 0
	v_mfma_f32_16x16x32_bf16 v[66:69], v[176:179], v[210:213], 0
	v_mfma_f32_16x16x32_bf16 v[110:113], v[172:175], v[188:191], v[110:113]
	v_mfma_f32_16x16x32_bf16 v[106:109], v[180:183], v[188:191], v[106:109]
	v_mfma_f32_16x16x32_bf16 v[94:97], v[172:175], v[196:199], v[94:97]
	v_mfma_f32_16x16x32_bf16 v[90:93], v[180:183], v[196:199], v[90:93]
	v_mfma_f32_16x16x32_bf16 v[78:81], v[172:175], v[206:209], v[78:81]
	v_mfma_f32_16x16x32_bf16 v[74:77], v[180:183], v[206:209], v[74:77]
	v_mfma_f32_16x16x32_bf16 v[70:73], v[172:175], v[214:217], v[70:73]
	v_mfma_f32_16x16x32_bf16 v[66:69], v[180:183], v[214:217], v[66:69]
	s_setprio 0
	s_barrier
	s_mov_b32 m0, s31
	v_lshl_add_u64 v[218:219], s[46:47], 0, v[134:135]
	s_add_u32 s42, s46, 0x20000
	ds_read_b128 v[184:187], v148 offset:16384
	ds_read_b128 v[188:191], v148 offset:17408
	ds_read_b128 v[192:195], v148 offset:18432
	ds_read_b128 v[196:199], v148 offset:19456
	ds_read_b128 v[200:203], v148 offset:20480
	ds_read_b128 v[206:209], v148 offset:21504
	ds_read_b128 v[210:213], v148 offset:22528
	ds_read_b128 v[214:217], v148 offset:23552
	global_load_lds_dwordx4 v[218:219], off
	v_lshl_add_u64 v[220:221], s[46:47], 0, v[130:131]
	s_mov_b32 m0, s33
	s_addc_u32 s43, s47, 0
	global_load_lds_dwordx4 v[220:221], off
	v_lshl_add_u64 v[222:223], s[42:43], 0, v[134:135]
	s_mov_b32 m0, s34
	v_lshl_add_u64 v[224:225], s[48:49], 0, v[132:133]
	global_load_lds_dwordx4 v[222:223], off
	v_lshl_add_u64 v[222:223], s[42:43], 0, v[130:131]
	s_mov_b32 m0, s35
	s_nop 0
	global_load_lds_dwordx4 v[222:223], off
	v_lshl_add_u64 v[222:223], s[48:49], 0, v[136:137]
	s_mov_b32 m0, s2
	s_nop 0
	global_load_lds_dwordx4 v[222:223], off
	s_mov_b32 m0, s3
	s_nop 0
	global_load_lds_dwordx4 v[224:225], off
	s_waitcnt vmcnt(8) lgkmcnt(0)
	s_setprio 1
	s_barrier
	v_mfma_f32_16x16x32_bf16 v[62:65], v[152:155], v[184:187], 0
	v_mfma_f32_16x16x32_bf16 v[58:61], v[160:163], v[184:187], 0
	v_mfma_f32_16x16x32_bf16 v[54:57], v[152:155], v[192:195], 0
	v_mfma_f32_16x16x32_bf16 v[50:53], v[160:163], v[192:195], 0
	v_mfma_f32_16x16x32_bf16 v[38:41], v[152:155], v[200:203], 0
	v_mfma_f32_16x16x32_bf16 v[34:37], v[160:163], v[200:203], 0
	v_mfma_f32_16x16x32_bf16 v[22:25], v[152:155], v[210:213], 0
	v_mfma_f32_16x16x32_bf16 v[18:21], v[160:163], v[210:213], 0
	v_mfma_f32_16x16x32_bf16 v[62:65], v[156:159], v[188:191], v[62:65]
	v_mfma_f32_16x16x32_bf16 v[58:61], v[164:167], v[188:191], v[58:61]
	v_mfma_f32_16x16x32_bf16 v[54:57], v[156:159], v[196:199], v[54:57]
	v_mfma_f32_16x16x32_bf16 v[50:53], v[164:167], v[196:199], v[50:53]
	v_mfma_f32_16x16x32_bf16 v[38:41], v[156:159], v[206:209], v[38:41]
	v_mfma_f32_16x16x32_bf16 v[34:37], v[164:167], v[206:209], v[34:37]
	v_mfma_f32_16x16x32_bf16 v[22:25], v[156:159], v[214:217], v[22:25]
	v_mfma_f32_16x16x32_bf16 v[18:21], v[164:167], v[214:217], v[18:21]
	v_mfma_f32_16x16x32_bf16 v[46:49], v[168:171], v[184:187], 0
	v_mfma_f32_16x16x32_bf16 v[42:45], v[176:179], v[184:187], 0
	v_mfma_f32_16x16x32_bf16 v[30:33], v[168:171], v[192:195], 0
	v_mfma_f32_16x16x32_bf16 v[26:29], v[176:179], v[192:195], 0
	v_mfma_f32_16x16x32_bf16 v[14:17], v[168:171], v[200:203], 0
	v_mfma_f32_16x16x32_bf16 v[10:13], v[176:179], v[200:203], 0
	v_mfma_f32_16x16x32_bf16 v[6:9], v[168:171], v[210:213], 0
	v_mfma_f32_16x16x32_bf16 v[2:5], v[176:179], v[210:213], 0
	v_mfma_f32_16x16x32_bf16 v[46:49], v[172:175], v[188:191], v[46:49]
	v_mfma_f32_16x16x32_bf16 v[42:45], v[180:183], v[188:191], v[42:45]
	v_mfma_f32_16x16x32_bf16 v[30:33], v[172:175], v[196:199], v[30:33]
	v_mfma_f32_16x16x32_bf16 v[26:29], v[180:183], v[196:199], v[26:29]
	v_mfma_f32_16x16x32_bf16 v[14:17], v[172:175], v[206:209], v[14:17]
	v_mfma_f32_16x16x32_bf16 v[10:13], v[180:183], v[206:209], v[10:13]
	v_mfma_f32_16x16x32_bf16 v[6:9], v[172:175], v[214:217], v[6:9]
	v_mfma_f32_16x16x32_bf16 v[2:5], v[180:183], v[214:217], v[2:5]
	s_setprio 0
	s_barrier
	ds_read_b128 v[152:155], v149
	ds_read_b128 v[156:159], v149 offset:1024
	ds_read_b128 v[160:163], v149 offset:2048
	ds_read_b128 v[164:167], v149 offset:3072
	ds_read_b128 v[168:171], v150
	ds_read_b128 v[172:175], v150 offset:1024
	ds_read_b128 v[176:179], v150 offset:2048
	ds_read_b128 v[180:183], v150 offset:3072
	s_add_u32 s42, s48, 0x20000
	s_addc_u32 s43, s49, 0
	s_mov_b32 m0, s16
	v_lshl_add_u64 v[226:227], s[42:43], 0, v[136:137]
	ds_read_b128 v[184:187], v148 offset:32768
	ds_read_b128 v[188:191], v148 offset:33792
	ds_read_b128 v[192:195], v148 offset:34816
	ds_read_b128 v[196:199], v148 offset:35840
	ds_read_b128 v[200:203], v148 offset:36864
	ds_read_b128 v[206:209], v148 offset:37888
	ds_read_b128 v[210:213], v148 offset:38912
	ds_read_b128 v[214:217], v148 offset:39936
	global_load_lds_dwordx4 v[226:227], off
	v_lshl_add_u64 v[226:227], s[42:43], 0, v[132:133]
	s_mov_b32 m0, s17
	s_nop 0
	global_load_lds_dwordx4 v[226:227], off
	s_waitcnt vmcnt(8) lgkmcnt(0)
	s_setprio 1
	s_barrier
	v_mfma_f32_16x16x32_bf16 v[126:129], v[152:155], v[184:187], v[126:129]
	v_mfma_f32_16x16x32_bf16 v[122:125], v[160:163], v[184:187], v[122:125]
	v_mfma_f32_16x16x32_bf16 v[118:121], v[152:155], v[192:195], v[118:121]
	v_mfma_f32_16x16x32_bf16 v[114:117], v[160:163], v[192:195], v[114:117]
	v_mfma_f32_16x16x32_bf16 v[102:105], v[152:155], v[200:203], v[102:105]
	v_mfma_f32_16x16x32_bf16 v[98:101], v[160:163], v[200:203], v[98:101]
	v_mfma_f32_16x16x32_bf16 v[86:89], v[152:155], v[210:213], v[86:89]
	v_mfma_f32_16x16x32_bf16 v[82:85], v[160:163], v[210:213], v[82:85]
	v_mfma_f32_16x16x32_bf16 v[126:129], v[156:159], v[188:191], v[126:129]
	v_mfma_f32_16x16x32_bf16 v[122:125], v[164:167], v[188:191], v[122:125]
	v_mfma_f32_16x16x32_bf16 v[118:121], v[156:159], v[196:199], v[118:121]
	v_mfma_f32_16x16x32_bf16 v[114:117], v[164:167], v[196:199], v[114:117]
	v_mfma_f32_16x16x32_bf16 v[102:105], v[156:159], v[206:209], v[102:105]
	v_mfma_f32_16x16x32_bf16 v[98:101], v[164:167], v[206:209], v[98:101]
	v_mfma_f32_16x16x32_bf16 v[86:89], v[156:159], v[214:217], v[86:89]
	v_mfma_f32_16x16x32_bf16 v[82:85], v[164:167], v[214:217], v[82:85]
	v_mfma_f32_16x16x32_bf16 v[110:113], v[168:171], v[184:187], v[110:113]
	v_mfma_f32_16x16x32_bf16 v[106:109], v[176:179], v[184:187], v[106:109]
	v_mfma_f32_16x16x32_bf16 v[94:97], v[168:171], v[192:195], v[94:97]
	v_mfma_f32_16x16x32_bf16 v[90:93], v[176:179], v[192:195], v[90:93]
	v_mfma_f32_16x16x32_bf16 v[78:81], v[168:171], v[200:203], v[78:81]
	v_mfma_f32_16x16x32_bf16 v[74:77], v[176:179], v[200:203], v[74:77]
	v_mfma_f32_16x16x32_bf16 v[70:73], v[168:171], v[210:213], v[70:73]
	v_mfma_f32_16x16x32_bf16 v[66:69], v[176:179], v[210:213], v[66:69]
	v_mfma_f32_16x16x32_bf16 v[110:113], v[172:175], v[188:191], v[110:113]
	v_mfma_f32_16x16x32_bf16 v[106:109], v[180:183], v[188:191], v[106:109]
	v_mfma_f32_16x16x32_bf16 v[94:97], v[172:175], v[196:199], v[94:97]
	v_mfma_f32_16x16x32_bf16 v[90:93], v[180:183], v[196:199], v[90:93]
	v_mfma_f32_16x16x32_bf16 v[78:81], v[172:175], v[206:209], v[78:81]
	v_mfma_f32_16x16x32_bf16 v[74:77], v[180:183], v[206:209], v[74:77]
	v_mfma_f32_16x16x32_bf16 v[70:73], v[172:175], v[214:217], v[70:73]
	v_mfma_f32_16x16x32_bf16 v[66:69], v[180:183], v[214:217], v[66:69]
	s_setprio 0
	s_barrier
	s_mov_b32 m0, s62
	v_lshl_add_u64 v[218:219], v[218:219], 0, s[10:11]
	s_add_u32 s42, s46, 0x20080
	ds_read_b128 v[184:187], v148 offset:49152
	ds_read_b128 v[188:191], v148 offset:50176
	ds_read_b128 v[192:195], v148 offset:51200
	ds_read_b128 v[196:199], v148 offset:52224
	ds_read_b128 v[200:203], v148 offset:53248
	ds_read_b128 v[206:209], v148 offset:54272
	ds_read_b128 v[210:213], v148 offset:55296
	ds_read_b128 v[214:217], v148 offset:56320
	global_load_lds_dwordx4 v[218:219], off
	v_lshl_add_u64 v[218:219], v[220:221], 0, s[10:11]
	s_mov_b32 m0, s63
	s_addc_u32 s43, s47, 0
	global_load_lds_dwordx4 v[218:219], off
	v_lshl_add_u64 v[218:219], s[42:43], 0, v[134:135]
	s_mov_b32 m0, s64
	s_nop 0
	global_load_lds_dwordx4 v[218:219], off
	v_lshl_add_u64 v[218:219], s[42:43], 0, v[130:131]
	s_mov_b32 m0, s65
	s_nop 0
	global_load_lds_dwordx4 v[218:219], off
	v_lshl_add_u64 v[218:219], v[222:223], 0, s[10:11]
	s_mov_b32 m0, s25
	s_nop 0
	global_load_lds_dwordx4 v[218:219], off
	v_lshl_add_u64 v[218:219], v[224:225], 0, s[10:11]
	s_mov_b32 m0, s28
	s_nop 0
	global_load_lds_dwordx4 v[218:219], off
	s_waitcnt vmcnt(8) lgkmcnt(0)
	s_setprio 1
	s_barrier
	v_mfma_f32_16x16x32_bf16 v[62:65], v[152:155], v[184:187], v[62:65]
	v_mfma_f32_16x16x32_bf16 v[58:61], v[160:163], v[184:187], v[58:61]
	v_mfma_f32_16x16x32_bf16 v[54:57], v[152:155], v[192:195], v[54:57]
	v_mfma_f32_16x16x32_bf16 v[50:53], v[160:163], v[192:195], v[50:53]
	v_mfma_f32_16x16x32_bf16 v[38:41], v[152:155], v[200:203], v[38:41]
	v_mfma_f32_16x16x32_bf16 v[34:37], v[160:163], v[200:203], v[34:37]
	v_mfma_f32_16x16x32_bf16 v[22:25], v[152:155], v[210:213], v[22:25]
	v_mfma_f32_16x16x32_bf16 v[18:21], v[160:163], v[210:213], v[18:21]
	v_mfma_f32_16x16x32_bf16 v[62:65], v[156:159], v[188:191], v[62:65]
	v_mfma_f32_16x16x32_bf16 v[58:61], v[164:167], v[188:191], v[58:61]
	v_mfma_f32_16x16x32_bf16 v[54:57], v[156:159], v[196:199], v[54:57]
	v_mfma_f32_16x16x32_bf16 v[50:53], v[164:167], v[196:199], v[50:53]
	v_mfma_f32_16x16x32_bf16 v[38:41], v[156:159], v[206:209], v[38:41]
	v_mfma_f32_16x16x32_bf16 v[34:37], v[164:167], v[206:209], v[34:37]
	v_mfma_f32_16x16x32_bf16 v[22:25], v[156:159], v[214:217], v[22:25]
	v_mfma_f32_16x16x32_bf16 v[18:21], v[164:167], v[214:217], v[18:21]
	v_mfma_f32_16x16x32_bf16 v[46:49], v[168:171], v[184:187], v[46:49]
	v_mfma_f32_16x16x32_bf16 v[42:45], v[176:179], v[184:187], v[42:45]
	v_mfma_f32_16x16x32_bf16 v[30:33], v[168:171], v[192:195], v[30:33]
	v_mfma_f32_16x16x32_bf16 v[26:29], v[176:179], v[192:195], v[26:29]
	v_mfma_f32_16x16x32_bf16 v[14:17], v[168:171], v[200:203], v[14:17]
	v_mfma_f32_16x16x32_bf16 v[10:13], v[176:179], v[200:203], v[10:13]
	v_mfma_f32_16x16x32_bf16 v[6:9], v[168:171], v[210:213], v[6:9]
	v_mfma_f32_16x16x32_bf16 v[2:5], v[176:179], v[210:213], v[2:5]
	v_mfma_f32_16x16x32_bf16 v[46:49], v[172:175], v[188:191], v[46:49]
	v_mfma_f32_16x16x32_bf16 v[42:45], v[180:183], v[188:191], v[42:45]
	v_mfma_f32_16x16x32_bf16 v[30:33], v[172:175], v[196:199], v[30:33]
	v_mfma_f32_16x16x32_bf16 v[26:29], v[180:183], v[196:199], v[26:29]
	v_mfma_f32_16x16x32_bf16 v[14:17], v[172:175], v[206:209], v[14:17]
	v_mfma_f32_16x16x32_bf16 v[10:13], v[180:183], v[206:209], v[10:13]
	v_mfma_f32_16x16x32_bf16 v[6:9], v[172:175], v[214:217], v[6:9]
	v_mfma_f32_16x16x32_bf16 v[2:5], v[180:183], v[214:217], v[2:5]
	s_setprio 0
	s_barrier
	s_add_i32 s68, s68, 2
	s_cmp_gt_u32 s68, 5
	s_mov_b64 s[42:43], s[44:45]
.LBB0_384:
	ds_read_b128 v[152:155], v146
	ds_read_b128 v[156:159], v146 offset:1024
	ds_read_b128 v[160:163], v146 offset:2048
	ds_read_b128 v[164:167], v146 offset:3072
	ds_read_b128 v[168:171], v147
	ds_read_b128 v[172:175], v147 offset:1024
	ds_read_b128 v[176:179], v147 offset:2048
	ds_read_b128 v[180:183], v147 offset:3072
	s_add_u32 s44, s42, 0x100
	s_addc_u32 s45, s43, 0
	s_add_u32 s46, s66, s42
	s_addc_u32 s47, s67, s43
	s_cmp_eq_u32 s68, 4
	s_cselect_b32 s48, 0, s44
	s_cselect_b32 s49, 0, s45
	s_cselect_b32 s46, s39, s46
	s_cselect_b32 s47, s15, s47
	s_add_u32 s48, s6, s48
	s_addc_u32 s49, s7, s49
	s_mov_b32 m0, s29
	v_lshl_add_u64 v[218:219], v[138:139], 0, s[42:43]
	ds_read_b128 v[184:187], v148
	ds_read_b128 v[188:191], v148 offset:1024
	ds_read_b128 v[192:195], v148 offset:2048
	ds_read_b128 v[196:199], v148 offset:3072
	ds_read_b128 v[200:203], v148 offset:4096
	ds_read_b128 v[206:209], v148 offset:5120
	ds_read_b128 v[210:213], v148 offset:6144
	ds_read_b128 v[214:217], v148 offset:7168
	global_load_lds_dwordx4 v[218:219], off
	v_lshl_add_u64 v[218:219], v[140:141], 0, s[42:43]
	s_mov_b32 m0, s30
	s_nop 0
	global_load_lds_dwordx4 v[218:219], off
	s_waitcnt vmcnt(8) lgkmcnt(0)
	s_setprio 1
	s_barrier
	v_mfma_f32_16x16x32_bf16 v[126:129], v[152:155], v[184:187], v[126:129]
	v_mfma_f32_16x16x32_bf16 v[122:125], v[160:163], v[184:187], v[122:125]
	v_mfma_f32_16x16x32_bf16 v[118:121], v[152:155], v[192:195], v[118:121]
	v_mfma_f32_16x16x32_bf16 v[114:117], v[160:163], v[192:195], v[114:117]
	v_mfma_f32_16x16x32_bf16 v[102:105], v[152:155], v[200:203], v[102:105]
	v_mfma_f32_16x16x32_bf16 v[98:101], v[160:163], v[200:203], v[98:101]
	v_mfma_f32_16x16x32_bf16 v[86:89], v[152:155], v[210:213], v[86:89]
	v_mfma_f32_16x16x32_bf16 v[82:85], v[160:163], v[210:213], v[82:85]
	v_mfma_f32_16x16x32_bf16 v[126:129], v[156:159], v[188:191], v[126:129]
	v_mfma_f32_16x16x32_bf16 v[122:125], v[164:167], v[188:191], v[122:125]
	v_mfma_f32_16x16x32_bf16 v[118:121], v[156:159], v[196:199], v[118:121]
	v_mfma_f32_16x16x32_bf16 v[114:117], v[164:167], v[196:199], v[114:117]
	v_mfma_f32_16x16x32_bf16 v[102:105], v[156:159], v[206:209], v[102:105]
	v_mfma_f32_16x16x32_bf16 v[98:101], v[164:167], v[206:209], v[98:101]
	v_mfma_f32_16x16x32_bf16 v[86:89], v[156:159], v[214:217], v[86:89]
	v_mfma_f32_16x16x32_bf16 v[82:85], v[164:167], v[214:217], v[82:85]
	v_mfma_f32_16x16x32_bf16 v[110:113], v[168:171], v[184:187], v[110:113]
	v_mfma_f32_16x16x32_bf16 v[106:109], v[176:179], v[184:187], v[106:109]
	v_mfma_f32_16x16x32_bf16 v[94:97], v[168:171], v[192:195], v[94:97]
	v_mfma_f32_16x16x32_bf16 v[90:93], v[176:179], v[192:195], v[90:93]
	v_mfma_f32_16x16x32_bf16 v[78:81], v[168:171], v[200:203], v[78:81]
	v_mfma_f32_16x16x32_bf16 v[74:77], v[176:179], v[200:203], v[74:77]
	v_mfma_f32_16x16x32_bf16 v[70:73], v[168:171], v[210:213], v[70:73]
	v_mfma_f32_16x16x32_bf16 v[66:69], v[176:179], v[210:213], v[66:69]
	v_mfma_f32_16x16x32_bf16 v[110:113], v[172:175], v[188:191], v[110:113]
	v_mfma_f32_16x16x32_bf16 v[106:109], v[180:183], v[188:191], v[106:109]
	v_mfma_f32_16x16x32_bf16 v[94:97], v[172:175], v[196:199], v[94:97]
	v_mfma_f32_16x16x32_bf16 v[90:93], v[180:183], v[196:199], v[90:93]
	v_mfma_f32_16x16x32_bf16 v[78:81], v[172:175], v[206:209], v[78:81]
	v_mfma_f32_16x16x32_bf16 v[74:77], v[180:183], v[206:209], v[74:77]
	v_mfma_f32_16x16x32_bf16 v[70:73], v[172:175], v[214:217], v[70:73]
	v_mfma_f32_16x16x32_bf16 v[66:69], v[180:183], v[214:217], v[66:69]
	s_setprio 0
	s_barrier
	s_mov_b32 m0, s31
	v_lshl_add_u64 v[218:219], s[46:47], 0, v[134:135]
	s_add_u32 s42, s46, 0x20000
	ds_read_b128 v[184:187], v148 offset:16384
	ds_read_b128 v[188:191], v148 offset:17408
	ds_read_b128 v[192:195], v148 offset:18432
	ds_read_b128 v[196:199], v148 offset:19456
	ds_read_b128 v[200:203], v148 offset:20480
	ds_read_b128 v[206:209], v148 offset:21504
	ds_read_b128 v[210:213], v148 offset:22528
	ds_read_b128 v[214:217], v148 offset:23552
	global_load_lds_dwordx4 v[218:219], off
	v_lshl_add_u64 v[220:221], s[46:47], 0, v[130:131]
	s_mov_b32 m0, s33
	s_addc_u32 s43, s47, 0
	global_load_lds_dwordx4 v[220:221], off
	v_lshl_add_u64 v[222:223], s[42:43], 0, v[134:135]
	s_mov_b32 m0, s34
	v_lshl_add_u64 v[224:225], s[48:49], 0, v[132:133]
	global_load_lds_dwordx4 v[222:223], off
	v_lshl_add_u64 v[222:223], s[42:43], 0, v[130:131]
	s_mov_b32 m0, s35
	s_nop 0
	global_load_lds_dwordx4 v[222:223], off
	v_lshl_add_u64 v[222:223], s[48:49], 0, v[136:137]
	s_mov_b32 m0, s2
	s_nop 0
	global_load_lds_dwordx4 v[222:223], off
	s_mov_b32 m0, s3
	s_nop 0
	global_load_lds_dwordx4 v[224:225], off
	s_waitcnt vmcnt(8) lgkmcnt(0)
	s_setprio 1
	s_barrier
	v_mfma_f32_16x16x32_bf16 v[62:65], v[152:155], v[184:187], v[62:65]
	v_mfma_f32_16x16x32_bf16 v[58:61], v[160:163], v[184:187], v[58:61]
	v_mfma_f32_16x16x32_bf16 v[54:57], v[152:155], v[192:195], v[54:57]
	v_mfma_f32_16x16x32_bf16 v[50:53], v[160:163], v[192:195], v[50:53]
	v_mfma_f32_16x16x32_bf16 v[38:41], v[152:155], v[200:203], v[38:41]
	v_mfma_f32_16x16x32_bf16 v[34:37], v[160:163], v[200:203], v[34:37]
	v_mfma_f32_16x16x32_bf16 v[22:25], v[152:155], v[210:213], v[22:25]
	v_mfma_f32_16x16x32_bf16 v[18:21], v[160:163], v[210:213], v[18:21]
	v_mfma_f32_16x16x32_bf16 v[62:65], v[156:159], v[188:191], v[62:65]
	v_mfma_f32_16x16x32_bf16 v[58:61], v[164:167], v[188:191], v[58:61]
	v_mfma_f32_16x16x32_bf16 v[54:57], v[156:159], v[196:199], v[54:57]
	v_mfma_f32_16x16x32_bf16 v[50:53], v[164:167], v[196:199], v[50:53]
	v_mfma_f32_16x16x32_bf16 v[38:41], v[156:159], v[206:209], v[38:41]
	v_mfma_f32_16x16x32_bf16 v[34:37], v[164:167], v[206:209], v[34:37]
	v_mfma_f32_16x16x32_bf16 v[22:25], v[156:159], v[214:217], v[22:25]
	v_mfma_f32_16x16x32_bf16 v[18:21], v[164:167], v[214:217], v[18:21]
	v_mfma_f32_16x16x32_bf16 v[46:49], v[168:171], v[184:187], v[46:49]
	v_mfma_f32_16x16x32_bf16 v[42:45], v[176:179], v[184:187], v[42:45]
	v_mfma_f32_16x16x32_bf16 v[30:33], v[168:171], v[192:195], v[30:33]
	v_mfma_f32_16x16x32_bf16 v[26:29], v[176:179], v[192:195], v[26:29]
	v_mfma_f32_16x16x32_bf16 v[14:17], v[168:171], v[200:203], v[14:17]
	v_mfma_f32_16x16x32_bf16 v[10:13], v[176:179], v[200:203], v[10:13]
	v_mfma_f32_16x16x32_bf16 v[6:9], v[168:171], v[210:213], v[6:9]
	v_mfma_f32_16x16x32_bf16 v[2:5], v[176:179], v[210:213], v[2:5]
	v_mfma_f32_16x16x32_bf16 v[46:49], v[172:175], v[188:191], v[46:49]
	v_mfma_f32_16x16x32_bf16 v[42:45], v[180:183], v[188:191], v[42:45]
	v_mfma_f32_16x16x32_bf16 v[30:33], v[172:175], v[196:199], v[30:33]
	v_mfma_f32_16x16x32_bf16 v[26:29], v[180:183], v[196:199], v[26:29]
	v_mfma_f32_16x16x32_bf16 v[14:17], v[172:175], v[206:209], v[14:17]
	v_mfma_f32_16x16x32_bf16 v[10:13], v[180:183], v[206:209], v[10:13]
	v_mfma_f32_16x16x32_bf16 v[6:9], v[172:175], v[214:217], v[6:9]
	v_mfma_f32_16x16x32_bf16 v[2:5], v[180:183], v[214:217], v[2:5]
	s_setprio 0
	s_barrier
	ds_read_b128 v[152:155], v149
	ds_read_b128 v[156:159], v149 offset:1024
	ds_read_b128 v[160:163], v149 offset:2048
	ds_read_b128 v[164:167], v149 offset:3072
	ds_read_b128 v[168:171], v150
	ds_read_b128 v[172:175], v150 offset:1024
	ds_read_b128 v[176:179], v150 offset:2048
	ds_read_b128 v[180:183], v150 offset:3072
	s_add_u32 s42, s48, 0x20000
	s_addc_u32 s43, s49, 0
	s_mov_b32 m0, s16
	v_lshl_add_u64 v[226:227], s[42:43], 0, v[136:137]
	ds_read_b128 v[184:187], v148 offset:32768
	ds_read_b128 v[188:191], v148 offset:33792
	ds_read_b128 v[192:195], v148 offset:34816
	ds_read_b128 v[196:199], v148 offset:35840
	ds_read_b128 v[200:203], v148 offset:36864
	ds_read_b128 v[206:209], v148 offset:37888
	ds_read_b128 v[210:213], v148 offset:38912
	ds_read_b128 v[214:217], v148 offset:39936
	global_load_lds_dwordx4 v[226:227], off
	v_lshl_add_u64 v[226:227], s[42:43], 0, v[132:133]
	s_mov_b32 m0, s17
	s_nop 0
	global_load_lds_dwordx4 v[226:227], off
	s_waitcnt vmcnt(8) lgkmcnt(0)
	s_setprio 1
	s_barrier
	v_mfma_f32_16x16x32_bf16 v[126:129], v[152:155], v[184:187], v[126:129]
	v_mfma_f32_16x16x32_bf16 v[122:125], v[160:163], v[184:187], v[122:125]
	v_mfma_f32_16x16x32_bf16 v[118:121], v[152:155], v[192:195], v[118:121]
	v_mfma_f32_16x16x32_bf16 v[114:117], v[160:163], v[192:195], v[114:117]
	v_mfma_f32_16x16x32_bf16 v[102:105], v[152:155], v[200:203], v[102:105]
	v_mfma_f32_16x16x32_bf16 v[98:101], v[160:163], v[200:203], v[98:101]
	v_mfma_f32_16x16x32_bf16 v[86:89], v[152:155], v[210:213], v[86:89]
	v_mfma_f32_16x16x32_bf16 v[82:85], v[160:163], v[210:213], v[82:85]
	v_mfma_f32_16x16x32_bf16 v[126:129], v[156:159], v[188:191], v[126:129]
	v_mfma_f32_16x16x32_bf16 v[122:125], v[164:167], v[188:191], v[122:125]
	v_mfma_f32_16x16x32_bf16 v[118:121], v[156:159], v[196:199], v[118:121]
	v_mfma_f32_16x16x32_bf16 v[114:117], v[164:167], v[196:199], v[114:117]
	v_mfma_f32_16x16x32_bf16 v[102:105], v[156:159], v[206:209], v[102:105]
	v_mfma_f32_16x16x32_bf16 v[98:101], v[164:167], v[206:209], v[98:101]
	v_mfma_f32_16x16x32_bf16 v[86:89], v[156:159], v[214:217], v[86:89]
	v_mfma_f32_16x16x32_bf16 v[82:85], v[164:167], v[214:217], v[82:85]
	v_mfma_f32_16x16x32_bf16 v[110:113], v[168:171], v[184:187], v[110:113]
	v_mfma_f32_16x16x32_bf16 v[106:109], v[176:179], v[184:187], v[106:109]
	v_mfma_f32_16x16x32_bf16 v[94:97], v[168:171], v[192:195], v[94:97]
	v_mfma_f32_16x16x32_bf16 v[90:93], v[176:179], v[192:195], v[90:93]
	v_mfma_f32_16x16x32_bf16 v[78:81], v[168:171], v[200:203], v[78:81]
	v_mfma_f32_16x16x32_bf16 v[74:77], v[176:179], v[200:203], v[74:77]
	v_mfma_f32_16x16x32_bf16 v[70:73], v[168:171], v[210:213], v[70:73]
	v_mfma_f32_16x16x32_bf16 v[66:69], v[176:179], v[210:213], v[66:69]
	v_mfma_f32_16x16x32_bf16 v[110:113], v[172:175], v[188:191], v[110:113]
	v_mfma_f32_16x16x32_bf16 v[106:109], v[180:183], v[188:191], v[106:109]
	v_mfma_f32_16x16x32_bf16 v[94:97], v[172:175], v[196:199], v[94:97]
	v_mfma_f32_16x16x32_bf16 v[90:93], v[180:183], v[196:199], v[90:93]
	v_mfma_f32_16x16x32_bf16 v[78:81], v[172:175], v[206:209], v[78:81]
	v_mfma_f32_16x16x32_bf16 v[74:77], v[180:183], v[206:209], v[74:77]
	v_mfma_f32_16x16x32_bf16 v[70:73], v[172:175], v[214:217], v[70:73]
	v_mfma_f32_16x16x32_bf16 v[66:69], v[180:183], v[214:217], v[66:69]
	s_setprio 0
	s_barrier
	s_mov_b32 m0, s62
	v_lshl_add_u64 v[218:219], v[218:219], 0, s[10:11]
	s_add_u32 s42, s46, 0x20080
	ds_read_b128 v[184:187], v148 offset:49152
	ds_read_b128 v[188:191], v148 offset:50176
	ds_read_b128 v[192:195], v148 offset:51200
	ds_read_b128 v[196:199], v148 offset:52224
	ds_read_b128 v[200:203], v148 offset:53248
	ds_read_b128 v[206:209], v148 offset:54272
	ds_read_b128 v[210:213], v148 offset:55296
	ds_read_b128 v[214:217], v148 offset:56320
	global_load_lds_dwordx4 v[218:219], off
	v_lshl_add_u64 v[218:219], v[220:221], 0, s[10:11]
	s_mov_b32 m0, s63
	s_addc_u32 s43, s47, 0
	global_load_lds_dwordx4 v[218:219], off
	v_lshl_add_u64 v[218:219], s[42:43], 0, v[134:135]
	s_mov_b32 m0, s64
	s_nop 0
	global_load_lds_dwordx4 v[218:219], off
	v_lshl_add_u64 v[218:219], s[42:43], 0, v[130:131]
	s_mov_b32 m0, s65
	s_nop 0
	global_load_lds_dwordx4 v[218:219], off
	v_lshl_add_u64 v[218:219], v[222:223], 0, s[10:11]
	s_mov_b32 m0, s25
	s_nop 0
	global_load_lds_dwordx4 v[218:219], off
	v_lshl_add_u64 v[218:219], v[224:225], 0, s[10:11]
	s_mov_b32 m0, s28
	s_nop 0
	global_load_lds_dwordx4 v[218:219], off
	s_waitcnt vmcnt(8) lgkmcnt(0)
	s_setprio 1
	s_barrier
	v_mfma_f32_16x16x32_bf16 v[62:65], v[152:155], v[184:187], v[62:65]
	v_mfma_f32_16x16x32_bf16 v[58:61], v[160:163], v[184:187], v[58:61]
	v_mfma_f32_16x16x32_bf16 v[54:57], v[152:155], v[192:195], v[54:57]
	v_mfma_f32_16x16x32_bf16 v[50:53], v[160:163], v[192:195], v[50:53]
	v_mfma_f32_16x16x32_bf16 v[38:41], v[152:155], v[200:203], v[38:41]
	v_mfma_f32_16x16x32_bf16 v[34:37], v[160:163], v[200:203], v[34:37]
	v_mfma_f32_16x16x32_bf16 v[22:25], v[152:155], v[210:213], v[22:25]
	v_mfma_f32_16x16x32_bf16 v[18:21], v[160:163], v[210:213], v[18:21]
	v_mfma_f32_16x16x32_bf16 v[62:65], v[156:159], v[188:191], v[62:65]
	v_mfma_f32_16x16x32_bf16 v[58:61], v[164:167], v[188:191], v[58:61]
	v_mfma_f32_16x16x32_bf16 v[54:57], v[156:159], v[196:199], v[54:57]
	v_mfma_f32_16x16x32_bf16 v[50:53], v[164:167], v[196:199], v[50:53]
	v_mfma_f32_16x16x32_bf16 v[38:41], v[156:159], v[206:209], v[38:41]
	v_mfma_f32_16x16x32_bf16 v[34:37], v[164:167], v[206:209], v[34:37]
	v_mfma_f32_16x16x32_bf16 v[22:25], v[156:159], v[214:217], v[22:25]
	v_mfma_f32_16x16x32_bf16 v[18:21], v[164:167], v[214:217], v[18:21]
	v_mfma_f32_16x16x32_bf16 v[46:49], v[168:171], v[184:187], v[46:49]
	v_mfma_f32_16x16x32_bf16 v[42:45], v[176:179], v[184:187], v[42:45]
	v_mfma_f32_16x16x32_bf16 v[30:33], v[168:171], v[192:195], v[30:33]
	v_mfma_f32_16x16x32_bf16 v[26:29], v[176:179], v[192:195], v[26:29]
	v_mfma_f32_16x16x32_bf16 v[14:17], v[168:171], v[200:203], v[14:17]
	v_mfma_f32_16x16x32_bf16 v[10:13], v[176:179], v[200:203], v[10:13]
	v_mfma_f32_16x16x32_bf16 v[6:9], v[168:171], v[210:213], v[6:9]
	v_mfma_f32_16x16x32_bf16 v[2:5], v[176:179], v[210:213], v[2:5]
	v_mfma_f32_16x16x32_bf16 v[46:49], v[172:175], v[188:191], v[46:49]
	v_mfma_f32_16x16x32_bf16 v[42:45], v[180:183], v[188:191], v[42:45]
	v_mfma_f32_16x16x32_bf16 v[30:33], v[172:175], v[196:199], v[30:33]
	v_mfma_f32_16x16x32_bf16 v[26:29], v[180:183], v[196:199], v[26:29]
	v_mfma_f32_16x16x32_bf16 v[14:17], v[172:175], v[206:209], v[14:17]
	v_mfma_f32_16x16x32_bf16 v[10:13], v[180:183], v[206:209], v[10:13]
	v_mfma_f32_16x16x32_bf16 v[6:9], v[172:175], v[214:217], v[6:9]
	v_mfma_f32_16x16x32_bf16 v[2:5], v[180:183], v[214:217], v[2:5]
	s_setprio 0
	s_barrier
	s_add_i32 s68, s68, 2
	s_cmp_gt_u32 s68, 5
	s_mov_b64 s[42:43], s[44:45]
	s_cbranch_scc0 .LBB0_384
	s_and_b64 vcc, exec, s[12:13]
	s_cbranch_vccz .LBB0_387
	s_barrier

.LBB0_406:
	s_lshl_b32 s74, s12, 7
	s_add_i32 s12, s12, 2
	v_cndmask_b32_e64 v138, 0, 1, s[66:67]
	s_lshl_b64 s[66:67], s[12:13], 7
	s_and_b64 s[68:69], s[64:65], exec
	s_cselect_b32 s66, 0, s66
	s_cselect_b32 s67, 0, s67
	s_add_u32 s70, s8, s66
	s_addc_u32 s71, s9, s67
	s_lshl_b64 s[66:67], s[12:13], 12
	s_add_u32 s12, s48, s66
	s_addc_u32 s66, s49, s67
	s_and_b64 s[64:65], s[64:65], exec
	s_cselect_b32 s73, s14, s66
	s_cselect_b32 s72, s15, s12
	s_add_u32 s76, s10, s74
	s_addc_u32 s77, s11, 0
	s_add_i32 s91, s62, s16
	s_add_i32 m0, s17, 0xc000
	s_add_i32 s92, s17, 0xe000
	s_add_i32 s88, s91, 0x2000
	s_add_u32 s74, s72, 0x10000
	ds_read_b128 v[146:149], v141
	ds_read_b128 v[150:153], v141 offset:1024
	ds_read_b128 v[154:157], v141 offset:2048
	ds_read_b128 v[158:161], v141 offset:3072
	ds_read_b128 v[162:165], v143
	ds_read_b128 v[166:169], v143 offset:1024
	ds_read_b128 v[170:173], v143 offset:2048
	ds_read_b128 v[174:177], v143 offset:3072
	s_addc_u32 s75, s73, 0
	s_add_i32 s90, s63, s16
	s_add_i32 s89, s90, 0x2000
	s_add_i32 s87, 0, 0x18000
	s_add_i32 s86, 0, 0x1c000
	s_add_u32 s68, s70, 0x10000
	s_addc_u32 s69, s71, 0
	s_add_u32 s64, s72, 0x1000
	s_addc_u32 s65, s73, 0
	s_add_i32 s85, s87, s16
	s_add_i32 s83, s85, 0x2000
	s_add_u32 s66, s72, 0x11000
	s_addc_u32 s67, s73, 0
	s_add_i32 s84, s86, s16
	s_add_i32 s12, s84, 0x2000
	v_cmp_ne_u32_e32 vcc, 1, v138
	v_lshl_add_u64 v[202:203], s[76:77], 0, v[136:137]
	v_lshl_add_u64 v[202:203], v[202:203], 0, s[36:37]
	ds_read_b128 v[178:181], v144
	ds_read_b128 v[182:185], v144 offset:1024
	ds_read_b128 v[186:189], v144 offset:2048
	ds_read_b128 v[190:193], v144 offset:3072
	ds_read_b128 v[194:197], v144 offset:4096
	ds_read_b128 v[198:201], v144 offset:5120
	ds_read_b128 v[206:209], v144 offset:6144
	ds_read_b128 v[210:213], v144 offset:7168
	global_load_lds_dwordx4 v[202:203], off
	v_lshl_add_u64 v[202:203], s[76:77], 0, v[132:133]
	v_lshl_add_u64 v[202:203], v[202:203], 0, s[36:37]
	s_mov_b32 m0, s92
	s_nop 0
	global_load_lds_dwordx4 v[202:203], off
	s_waitcnt vmcnt(8) lgkmcnt(0)
	s_setprio 1
	s_barrier
	v_mfma_f32_16x16x32_bf16 v[126:129], v[146:149], v[178:181], v[126:129]
	v_mfma_f32_16x16x32_bf16 v[122:125], v[154:157], v[178:181], v[122:125]
	v_mfma_f32_16x16x32_bf16 v[118:121], v[146:149], v[186:189], v[118:121]
	v_mfma_f32_16x16x32_bf16 v[110:113], v[154:157], v[186:189], v[110:113]
	v_mfma_f32_16x16x32_bf16 v[102:105], v[146:149], v[194:197], v[102:105]
	v_mfma_f32_16x16x32_bf16 v[98:101], v[154:157], v[194:197], v[98:101]
	v_mfma_f32_16x16x32_bf16 v[86:89], v[146:149], v[206:209], v[86:89]
	v_mfma_f32_16x16x32_bf16 v[82:85], v[154:157], v[206:209], v[82:85]
	v_mfma_f32_16x16x32_bf16 v[126:129], v[150:153], v[182:185], v[126:129]
	v_mfma_f32_16x16x32_bf16 v[122:125], v[158:161], v[182:185], v[122:125]
	v_mfma_f32_16x16x32_bf16 v[118:121], v[150:153], v[190:193], v[118:121]
	v_mfma_f32_16x16x32_bf16 v[110:113], v[158:161], v[190:193], v[110:113]
	v_mfma_f32_16x16x32_bf16 v[102:105], v[150:153], v[198:201], v[102:105]
	v_mfma_f32_16x16x32_bf16 v[98:101], v[158:161], v[198:201], v[98:101]
	v_mfma_f32_16x16x32_bf16 v[86:89], v[150:153], v[210:213], v[86:89]
	v_mfma_f32_16x16x32_bf16 v[82:85], v[158:161], v[210:213], v[82:85]
	v_mfma_f32_16x16x32_bf16 v[114:117], v[162:165], v[178:181], v[114:117]
	v_mfma_f32_16x16x32_bf16 v[106:109], v[170:173], v[178:181], v[106:109]
	v_mfma_f32_16x16x32_bf16 v[94:97], v[162:165], v[186:189], v[94:97]
	v_mfma_f32_16x16x32_bf16 v[90:93], v[170:173], v[186:189], v[90:93]
	v_mfma_f32_16x16x32_bf16 v[78:81], v[162:165], v[194:197], v[78:81]
	v_mfma_f32_16x16x32_bf16 v[74:77], v[170:173], v[194:197], v[74:77]
	v_mfma_f32_16x16x32_bf16 v[70:73], v[162:165], v[206:209], v[70:73]
	v_mfma_f32_16x16x32_bf16 v[66:69], v[170:173], v[206:209], v[66:69]
	v_mfma_f32_16x16x32_bf16 v[114:117], v[166:169], v[182:185], v[114:117]
	v_mfma_f32_16x16x32_bf16 v[106:109], v[174:177], v[182:185], v[106:109]
	v_mfma_f32_16x16x32_bf16 v[94:97], v[166:169], v[190:193], v[94:97]
	v_mfma_f32_16x16x32_bf16 v[90:93], v[174:177], v[190:193], v[90:93]
	v_mfma_f32_16x16x32_bf16 v[78:81], v[166:169], v[198:201], v[78:81]
	v_mfma_f32_16x16x32_bf16 v[74:77], v[174:177], v[198:201], v[74:77]
	v_mfma_f32_16x16x32_bf16 v[70:73], v[166:169], v[210:213], v[70:73]
	v_mfma_f32_16x16x32_bf16 v[66:69], v[174:177], v[210:213], v[66:69]
	s_setprio 0
	s_barrier
	s_mov_b32 m0, s91
	v_lshl_add_u64 v[202:203], s[72:73], 0, v[134:135]
	ds_read_b128 v[178:181], v144 offset:16384
	ds_read_b128 v[182:185], v144 offset:17408
	ds_read_b128 v[186:189], v144 offset:18432
	ds_read_b128 v[190:193], v144 offset:19456
	ds_read_b128 v[194:197], v144 offset:20480
	ds_read_b128 v[198:201], v144 offset:21504
	ds_read_b128 v[206:209], v144 offset:22528
	ds_read_b128 v[210:213], v144 offset:23552
	global_load_lds_dwordx4 v[202:203], off
	v_lshl_add_u64 v[202:203], s[72:73], 0, v[130:131]
	s_mov_b32 m0, s88
	v_lshl_add_u64 v[214:215], s[70:71], 0, v[132:133]
	global_load_lds_dwordx4 v[202:203], off
	v_lshl_add_u64 v[202:203], s[74:75], 0, v[134:135]
	s_mov_b32 m0, s90
	s_nop 0
	global_load_lds_dwordx4 v[202:203], off
	v_lshl_add_u64 v[202:203], s[74:75], 0, v[130:131]
	s_mov_b32 m0, s89
	s_nop 0
	global_load_lds_dwordx4 v[202:203], off
	v_lshl_add_u64 v[202:203], s[70:71], 0, v[136:137]
	s_mov_b32 m0, s17
	s_nop 0
	global_load_lds_dwordx4 v[202:203], off
	s_mov_b32 m0, s18
	s_nop 0
	global_load_lds_dwordx4 v[214:215], off
	s_waitcnt vmcnt(8) lgkmcnt(0)
	s_setprio 1
	s_barrier
	v_mfma_f32_16x16x32_bf16 v[62:65], v[146:149], v[178:181], v[62:65]
	v_mfma_f32_16x16x32_bf16 v[58:61], v[154:157], v[178:181], v[58:61]
	v_mfma_f32_16x16x32_bf16 v[54:57], v[146:149], v[186:189], v[54:57]
	v_mfma_f32_16x16x32_bf16 v[50:53], v[154:157], v[186:189], v[50:53]
	v_mfma_f32_16x16x32_bf16 v[38:41], v[146:149], v[194:197], v[38:41]
	v_mfma_f32_16x16x32_bf16 v[34:37], v[154:157], v[194:197], v[34:37]
	v_mfma_f32_16x16x32_bf16 v[22:25], v[146:149], v[206:209], v[22:25]
	v_mfma_f32_16x16x32_bf16 v[18:21], v[154:157], v[206:209], v[18:21]
	v_mfma_f32_16x16x32_bf16 v[62:65], v[150:153], v[182:185], v[62:65]
	v_mfma_f32_16x16x32_bf16 v[58:61], v[158:161], v[182:185], v[58:61]
	v_mfma_f32_16x16x32_bf16 v[54:57], v[150:153], v[190:193], v[54:57]
	v_mfma_f32_16x16x32_bf16 v[50:53], v[158:161], v[190:193], v[50:53]
	v_mfma_f32_16x16x32_bf16 v[38:41], v[150:153], v[198:201], v[38:41]
	v_mfma_f32_16x16x32_bf16 v[34:37], v[158:161], v[198:201], v[34:37]
	v_mfma_f32_16x16x32_bf16 v[22:25], v[150:153], v[210:213], v[22:25]
	v_mfma_f32_16x16x32_bf16 v[18:21], v[158:161], v[210:213], v[18:21]
	v_mfma_f32_16x16x32_bf16 v[46:49], v[162:165], v[178:181], v[46:49]
	v_mfma_f32_16x16x32_bf16 v[42:45], v[170:173], v[178:181], v[42:45]
	v_mfma_f32_16x16x32_bf16 v[30:33], v[162:165], v[186:189], v[30:33]
	v_mfma_f32_16x16x32_bf16 v[26:29], v[170:173], v[186:189], v[26:29]
	v_mfma_f32_16x16x32_bf16 v[14:17], v[162:165], v[194:197], v[14:17]
	v_mfma_f32_16x16x32_bf16 v[10:13], v[170:173], v[194:197], v[10:13]
	v_mfma_f32_16x16x32_bf16 v[6:9], v[162:165], v[206:209], v[6:9]
	v_mfma_f32_16x16x32_bf16 v[2:5], v[170:173], v[206:209], v[2:5]
	v_mfma_f32_16x16x32_bf16 v[46:49], v[166:169], v[182:185], v[46:49]
	v_mfma_f32_16x16x32_bf16 v[42:45], v[174:177], v[182:185], v[42:45]
	v_mfma_f32_16x16x32_bf16 v[30:33], v[166:169], v[190:193], v[30:33]
	v_mfma_f32_16x16x32_bf16 v[26:29], v[174:177], v[190:193], v[26:29]
	v_mfma_f32_16x16x32_bf16 v[14:17], v[166:169], v[198:201], v[14:17]
	v_mfma_f32_16x16x32_bf16 v[10:13], v[174:177], v[198:201], v[10:13]
	v_mfma_f32_16x16x32_bf16 v[6:9], v[166:169], v[210:213], v[6:9]
	v_mfma_f32_16x16x32_bf16 v[2:5], v[174:177], v[210:213], v[2:5]
	s_setprio 0
	s_barrier
	v_add_u32_e32 v138, s87, v140
	ds_read_b128 v[146:149], v138
	ds_read_b128 v[150:153], v138 offset:1024
	ds_read_b128 v[154:157], v138 offset:2048
	ds_read_b128 v[158:161], v138 offset:3072
	v_add_u32_e32 v138, s86, v140
	ds_read_b128 v[162:165], v138
	ds_read_b128 v[166:169], v138 offset:1024
	ds_read_b128 v[170:173], v138 offset:2048
	ds_read_b128 v[174:177], v138 offset:3072
	s_mov_b32 m0, s19
	v_lshl_add_u64 v[216:217], s[68:69], 0, v[136:137]
	ds_read_b128 v[178:181], v144 offset:32768
	ds_read_b128 v[182:185], v144 offset:33792
	ds_read_b128 v[186:189], v144 offset:34816
	ds_read_b128 v[190:193], v144 offset:35840
	ds_read_b128 v[194:197], v144 offset:36864
	ds_read_b128 v[198:201], v144 offset:37888
	ds_read_b128 v[206:209], v144 offset:38912
	ds_read_b128 v[210:213], v144 offset:39936
	global_load_lds_dwordx4 v[216:217], off
	v_lshl_add_u64 v[216:217], s[68:69], 0, v[132:133]
	s_mov_b32 m0, s24
	s_nop 0
	global_load_lds_dwordx4 v[216:217], off
	s_waitcnt vmcnt(8) lgkmcnt(0)
	s_setprio 1
	s_barrier
	v_mfma_f32_16x16x32_bf16 v[126:129], v[146:149], v[178:181], v[126:129]
	v_mfma_f32_16x16x32_bf16 v[122:125], v[154:157], v[178:181], v[122:125]
	v_mfma_f32_16x16x32_bf16 v[118:121], v[146:149], v[186:189], v[118:121]
	v_mfma_f32_16x16x32_bf16 v[110:113], v[154:157], v[186:189], v[110:113]
	v_mfma_f32_16x16x32_bf16 v[102:105], v[146:149], v[194:197], v[102:105]
	v_mfma_f32_16x16x32_bf16 v[98:101], v[154:157], v[194:197], v[98:101]
	v_mfma_f32_16x16x32_bf16 v[86:89], v[146:149], v[206:209], v[86:89]
	v_mfma_f32_16x16x32_bf16 v[82:85], v[154:157], v[206:209], v[82:85]
	v_mfma_f32_16x16x32_bf16 v[126:129], v[150:153], v[182:185], v[126:129]
	v_mfma_f32_16x16x32_bf16 v[122:125], v[158:161], v[182:185], v[122:125]
	v_mfma_f32_16x16x32_bf16 v[118:121], v[150:153], v[190:193], v[118:121]
	v_mfma_f32_16x16x32_bf16 v[110:113], v[158:161], v[190:193], v[110:113]
	v_mfma_f32_16x16x32_bf16 v[102:105], v[150:153], v[198:201], v[102:105]
	v_mfma_f32_16x16x32_bf16 v[98:101], v[158:161], v[198:201], v[98:101]
	v_mfma_f32_16x16x32_bf16 v[86:89], v[150:153], v[210:213], v[86:89]
	v_mfma_f32_16x16x32_bf16 v[82:85], v[158:161], v[210:213], v[82:85]
	v_mfma_f32_16x16x32_bf16 v[114:117], v[162:165], v[178:181], v[114:117]
	v_mfma_f32_16x16x32_bf16 v[106:109], v[170:173], v[178:181], v[106:109]
	v_mfma_f32_16x16x32_bf16 v[94:97], v[162:165], v[186:189], v[94:97]
	v_mfma_f32_16x16x32_bf16 v[90:93], v[170:173], v[186:189], v[90:93]
	v_mfma_f32_16x16x32_bf16 v[78:81], v[162:165], v[194:197], v[78:81]
	v_mfma_f32_16x16x32_bf16 v[74:77], v[170:173], v[194:197], v[74:77]
	v_mfma_f32_16x16x32_bf16 v[70:73], v[162:165], v[206:209], v[70:73]
	v_mfma_f32_16x16x32_bf16 v[66:69], v[170:173], v[206:209], v[66:69]
	v_mfma_f32_16x16x32_bf16 v[114:117], v[166:169], v[182:185], v[114:117]
	v_mfma_f32_16x16x32_bf16 v[106:109], v[174:177], v[182:185], v[106:109]
	v_mfma_f32_16x16x32_bf16 v[94:97], v[166:169], v[190:193], v[94:97]
	v_mfma_f32_16x16x32_bf16 v[90:93], v[174:177], v[190:193], v[90:93]
	v_mfma_f32_16x16x32_bf16 v[78:81], v[166:169], v[198:201], v[78:81]
	v_mfma_f32_16x16x32_bf16 v[74:77], v[174:177], v[198:201], v[74:77]
	v_mfma_f32_16x16x32_bf16 v[70:73], v[166:169], v[210:213], v[70:73]
	v_mfma_f32_16x16x32_bf16 v[66:69], v[174:177], v[210:213], v[66:69]
	s_setprio 0
	s_barrier
	s_mov_b32 m0, s85
	v_lshl_add_u64 v[216:217], s[64:65], 0, v[134:135]
	ds_read_b128 v[178:181], v144 offset:49152
	ds_read_b128 v[182:185], v144 offset:50176
	ds_read_b128 v[186:189], v144 offset:51200
	ds_read_b128 v[190:193], v144 offset:52224
	ds_read_b128 v[194:197], v144 offset:53248
	ds_read_b128 v[198:201], v144 offset:54272
	ds_read_b128 v[206:209], v144 offset:55296
	ds_read_b128 v[210:213], v144 offset:56320
	global_load_lds_dwordx4 v[216:217], off
	v_lshl_add_u64 v[216:217], s[64:65], 0, v[130:131]
	s_mov_b32 m0, s83
	v_lshl_add_u64 v[202:203], v[202:203], 0, s[36:37]
	global_load_lds_dwordx4 v[216:217], off
	v_lshl_add_u64 v[216:217], s[66:67], 0, v[134:135]
	s_mov_b32 m0, s84
	s_nop 0
	global_load_lds_dwordx4 v[216:217], off
	v_lshl_add_u64 v[216:217], s[66:67], 0, v[130:131]
	s_mov_b32 m0, s12
	s_nop 0
	global_load_lds_dwordx4 v[216:217], off
	s_mov_b32 m0, s31
	s_nop 0
	global_load_lds_dwordx4 v[202:203], off
	v_lshl_add_u64 v[202:203], v[214:215], 0, s[36:37]
	s_mov_b32 m0, s33
	s_nop 0
	global_load_lds_dwordx4 v[202:203], off
	s_waitcnt vmcnt(8) lgkmcnt(0)
	s_setprio 1
	s_barrier
	v_mfma_f32_16x16x32_bf16 v[62:65], v[146:149], v[178:181], v[62:65]
	v_mfma_f32_16x16x32_bf16 v[58:61], v[154:157], v[178:181], v[58:61]
	v_mfma_f32_16x16x32_bf16 v[54:57], v[146:149], v[186:189], v[54:57]
	v_mfma_f32_16x16x32_bf16 v[50:53], v[154:157], v[186:189], v[50:53]
	v_mfma_f32_16x16x32_bf16 v[38:41], v[146:149], v[194:197], v[38:41]
	v_mfma_f32_16x16x32_bf16 v[34:37], v[154:157], v[194:197], v[34:37]
	v_mfma_f32_16x16x32_bf16 v[22:25], v[146:149], v[206:209], v[22:25]
	v_mfma_f32_16x16x32_bf16 v[18:21], v[154:157], v[206:209], v[18:21]
	v_mfma_f32_16x16x32_bf16 v[62:65], v[150:153], v[182:185], v[62:65]
	v_mfma_f32_16x16x32_bf16 v[58:61], v[158:161], v[182:185], v[58:61]
	v_mfma_f32_16x16x32_bf16 v[54:57], v[150:153], v[190:193], v[54:57]
	v_mfma_f32_16x16x32_bf16 v[50:53], v[158:161], v[190:193], v[50:53]
	v_mfma_f32_16x16x32_bf16 v[38:41], v[150:153], v[198:201], v[38:41]
	v_mfma_f32_16x16x32_bf16 v[34:37], v[158:161], v[198:201], v[34:37]
	v_mfma_f32_16x16x32_bf16 v[22:25], v[150:153], v[210:213], v[22:25]
	v_mfma_f32_16x16x32_bf16 v[18:21], v[158:161], v[210:213], v[18:21]
	v_mfma_f32_16x16x32_bf16 v[46:49], v[162:165], v[178:181], v[46:49]
	v_mfma_f32_16x16x32_bf16 v[42:45], v[170:173], v[178:181], v[42:45]
	v_mfma_f32_16x16x32_bf16 v[30:33], v[162:165], v[186:189], v[30:33]
	v_mfma_f32_16x16x32_bf16 v[26:29], v[170:173], v[186:189], v[26:29]
	v_mfma_f32_16x16x32_bf16 v[14:17], v[162:165], v[194:197], v[14:17]
	v_mfma_f32_16x16x32_bf16 v[10:13], v[170:173], v[194:197], v[10:13]
	v_mfma_f32_16x16x32_bf16 v[6:9], v[162:165], v[206:209], v[6:9]
	v_mfma_f32_16x16x32_bf16 v[2:5], v[170:173], v[206:209], v[2:5]
	v_mfma_f32_16x16x32_bf16 v[46:49], v[166:169], v[182:185], v[46:49]
	v_mfma_f32_16x16x32_bf16 v[42:45], v[174:177], v[182:185], v[42:45]
	v_mfma_f32_16x16x32_bf16 v[30:33], v[166:169], v[190:193], v[30:33]
	v_mfma_f32_16x16x32_bf16 v[26:29], v[174:177], v[190:193], v[26:29]
	v_mfma_f32_16x16x32_bf16 v[14:17], v[166:169], v[198:201], v[14:17]
	v_mfma_f32_16x16x32_bf16 v[10:13], v[174:177], v[198:201], v[10:13]
	v_mfma_f32_16x16x32_bf16 v[6:9], v[166:169], v[210:213], v[6:9]
	v_mfma_f32_16x16x32_bf16 v[2:5], v[174:177], v[210:213], v[2:5]
	s_setprio 0
	s_barrier
	s_mov_b64 s[66:67], 0
	s_mov_b64 s[64:65], -1
	s_mov_b32 s12, 2
	s_cbranch_vccz .LBB0_406
	s_and_b64 vcc, exec, s[22:23]
	s_cbranch_vccz .LBB0_409
	s_barrier

.LBB0_476:
	s_add_u32 s22, s2, s49
	s_addc_u32 s23, s3, s29
	s_and_b64 s[26:27], s[20:21], exec
	s_cselect_b32 s63, s23, s37
	s_cselect_b32 s64, s22, s36
	s_add_u32 s26, s16, s12
	s_addc_u32 s27, s17, s13
	s_and_b64 s[42:43], s[20:21], exec
	s_cselect_b32 s65, s27, s39
	s_cselect_b32 s66, s26, s38
	s_add_u32 s36, s36, 0x20080
	s_addc_u32 s37, s37, 0
	s_add_u32 s67, s38, 0x100
	s_addc_u32 s68, s39, 0
	s_mov_b32 s69, -2
	ds_read_b128 v[148:151], v144
	ds_read_b128 v[152:155], v144 offset:1024
	ds_read_b128 v[156:159], v144 offset:2048
	ds_read_b128 v[160:163], v144 offset:3072
	ds_read_b128 v[164:167], v145
	ds_read_b128 v[168:171], v145 offset:1024
	ds_read_b128 v[172:175], v145 offset:2048
	ds_read_b128 v[176:179], v145 offset:3072
	s_add_u32 s38, s36, 0xfffe0080
	s_addc_u32 s39, s37, -1
	s_cmp_eq_u32 s69, 4
	s_cselect_b32 s43, s63, s39
	s_cselect_b32 s42, s64, s38
	s_cselect_b32 s39, s65, s68
	s_cselect_b32 s38, s66, s67
	v_lshl_add_u64 v[214:215], s[36:37], 0, v[138:139]
	s_add_i32 m0, s19, 0xc000
	ds_read_b128 v[180:183], v146
	ds_read_b128 v[184:187], v146 offset:1024
	ds_read_b128 v[188:191], v146 offset:2048
	ds_read_b128 v[192:195], v146 offset:3072
	ds_read_b128 v[196:199], v146 offset:4096
	ds_read_b128 v[200:203], v146 offset:5120
	ds_read_b128 v[206:209], v146 offset:6144
	ds_read_b128 v[210:213], v146 offset:7168
	global_load_lds_dwordx4 v[214:215], off
	v_lshl_add_u64 v[214:215], s[36:37], 0, v[140:141]
	s_add_i32 m0, s19, 0xe000
	s_nop 0
	global_load_lds_dwordx4 v[214:215], off
	s_waitcnt vmcnt(8) lgkmcnt(0)
	s_setprio 1
	s_barrier
	v_mfma_f32_16x16x32_bf16 v[126:129], v[148:151], v[180:183], 0
	v_mfma_f32_16x16x32_bf16 v[122:125], v[156:159], v[180:183], 0
	v_mfma_f32_16x16x32_bf16 v[118:121], v[148:151], v[188:191], 0
	v_mfma_f32_16x16x32_bf16 v[114:117], v[156:159], v[188:191], 0
	v_mfma_f32_16x16x32_bf16 v[102:105], v[148:151], v[196:199], 0
	v_mfma_f32_16x16x32_bf16 v[98:101], v[156:159], v[196:199], 0
	v_mfma_f32_16x16x32_bf16 v[86:89], v[148:151], v[206:209], 0
	v_mfma_f32_16x16x32_bf16 v[82:85], v[156:159], v[206:209], 0
	v_mfma_f32_16x16x32_bf16 v[126:129], v[152:155], v[184:187], v[126:129]
	v_mfma_f32_16x16x32_bf16 v[122:125], v[160:163], v[184:187], v[122:125]
	v_mfma_f32_16x16x32_bf16 v[118:121], v[152:155], v[192:195], v[118:121]
	v_mfma_f32_16x16x32_bf16 v[114:117], v[160:163], v[192:195], v[114:117]
	v_mfma_f32_16x16x32_bf16 v[102:105], v[152:155], v[200:203], v[102:105]
	v_mfma_f32_16x16x32_bf16 v[98:101], v[160:163], v[200:203], v[98:101]
	v_mfma_f32_16x16x32_bf16 v[86:89], v[152:155], v[210:213], v[86:89]
	v_mfma_f32_16x16x32_bf16 v[82:85], v[160:163], v[210:213], v[82:85]
	v_mfma_f32_16x16x32_bf16 v[110:113], v[164:167], v[180:183], 0
	v_mfma_f32_16x16x32_bf16 v[106:109], v[172:175], v[180:183], 0
	v_mfma_f32_16x16x32_bf16 v[94:97], v[164:167], v[188:191], 0
	v_mfma_f32_16x16x32_bf16 v[90:93], v[172:175], v[188:191], 0
	v_mfma_f32_16x16x32_bf16 v[78:81], v[164:167], v[196:199], 0
	v_mfma_f32_16x16x32_bf16 v[74:77], v[172:175], v[196:199], 0
	v_mfma_f32_16x16x32_bf16 v[70:73], v[164:167], v[206:209], 0
	v_mfma_f32_16x16x32_bf16 v[66:69], v[172:175], v[206:209], 0
	v_mfma_f32_16x16x32_bf16 v[110:113], v[168:171], v[184:187], v[110:113]
	v_mfma_f32_16x16x32_bf16 v[106:109], v[176:179], v[184:187], v[106:109]
	v_mfma_f32_16x16x32_bf16 v[94:97], v[168:171], v[192:195], v[94:97]
	v_mfma_f32_16x16x32_bf16 v[90:93], v[176:179], v[192:195], v[90:93]
	v_mfma_f32_16x16x32_bf16 v[78:81], v[168:171], v[200:203], v[78:81]
	v_mfma_f32_16x16x32_bf16 v[74:77], v[176:179], v[200:203], v[74:77]
	v_mfma_f32_16x16x32_bf16 v[70:73], v[168:171], v[210:213], v[70:73]
	v_mfma_f32_16x16x32_bf16 v[66:69], v[176:179], v[210:213], v[66:69]
	s_setprio 0
	s_barrier
	s_add_i32 s70, s35, s18
	v_lshl_add_u64 v[214:215], s[38:39], 0, v[134:135]
	s_mov_b32 m0, s70
	ds_read_b128 v[180:183], v146 offset:16384
	ds_read_b128 v[184:187], v146 offset:17408
	ds_read_b128 v[188:191], v146 offset:18432
	ds_read_b128 v[192:195], v146 offset:19456
	ds_read_b128 v[196:199], v146 offset:20480
	ds_read_b128 v[200:203], v146 offset:21504
	ds_read_b128 v[206:209], v146 offset:22528
	ds_read_b128 v[210:213], v146 offset:23552
	global_load_lds_dwordx4 v[214:215], off
	s_add_i32 m0, s70, 0x2000
	s_add_u32 s70, s38, 0x200000
	v_lshl_add_u64 v[216:217], s[38:39], 0, v[130:131]
	s_addc_u32 s71, s39, 0
	s_add_i32 s72, s44, s18
	global_load_lds_dwordx4 v[216:217], off
	v_lshl_add_u64 v[218:219], s[70:71], 0, v[134:135]
	s_mov_b32 m0, s72
	v_lshl_add_u64 v[220:221], s[42:43], 0, v[132:133]
	global_load_lds_dwordx4 v[218:219], off
	v_lshl_add_u64 v[218:219], s[70:71], 0, v[130:131]
	s_add_i32 m0, s72, 0x2000
	s_nop 0
	global_load_lds_dwordx4 v[218:219], off
	v_lshl_add_u64 v[218:219], s[42:43], 0, v[136:137]
	s_mov_b32 m0, s19
	s_nop 0
	global_load_lds_dwordx4 v[218:219], off
	s_mov_b32 m0, s24
	s_nop 0
	global_load_lds_dwordx4 v[220:221], off
	s_waitcnt vmcnt(8) lgkmcnt(0)
	s_setprio 1
	s_barrier
	v_mfma_f32_16x16x32_bf16 v[62:65], v[148:151], v[180:183], 0
	v_mfma_f32_16x16x32_bf16 v[58:61], v[156:159], v[180:183], 0
	v_mfma_f32_16x16x32_bf16 v[54:57], v[148:151], v[188:191], 0
	v_mfma_f32_16x16x32_bf16 v[50:53], v[156:159], v[188:191], 0
	v_mfma_f32_16x16x32_bf16 v[38:41], v[148:151], v[196:199], 0
	v_mfma_f32_16x16x32_bf16 v[34:37], v[156:159], v[196:199], 0
	v_mfma_f32_16x16x32_bf16 v[22:25], v[148:151], v[206:209], 0
	v_mfma_f32_16x16x32_bf16 v[18:21], v[156:159], v[206:209], 0
	v_mfma_f32_16x16x32_bf16 v[62:65], v[152:155], v[184:187], v[62:65]
	v_mfma_f32_16x16x32_bf16 v[58:61], v[160:163], v[184:187], v[58:61]
	v_mfma_f32_16x16x32_bf16 v[54:57], v[152:155], v[192:195], v[54:57]
	v_mfma_f32_16x16x32_bf16 v[50:53], v[160:163], v[192:195], v[50:53]
	v_mfma_f32_16x16x32_bf16 v[38:41], v[152:155], v[200:203], v[38:41]
	v_mfma_f32_16x16x32_bf16 v[34:37], v[160:163], v[200:203], v[34:37]
	v_mfma_f32_16x16x32_bf16 v[22:25], v[152:155], v[210:213], v[22:25]
	v_mfma_f32_16x16x32_bf16 v[18:21], v[160:163], v[210:213], v[18:21]
	v_mfma_f32_16x16x32_bf16 v[46:49], v[164:167], v[180:183], 0
	v_mfma_f32_16x16x32_bf16 v[42:45], v[172:175], v[180:183], 0
	v_mfma_f32_16x16x32_bf16 v[30:33], v[164:167], v[188:191], 0
	v_mfma_f32_16x16x32_bf16 v[26:29], v[172:175], v[188:191], 0
	v_mfma_f32_16x16x32_bf16 v[14:17], v[164:167], v[196:199], 0
	v_mfma_f32_16x16x32_bf16 v[10:13], v[172:175], v[196:199], 0
	v_mfma_f32_16x16x32_bf16 v[6:9], v[164:167], v[206:209], 0
	v_mfma_f32_16x16x32_bf16 v[2:5], v[172:175], v[206:209], 0
	v_mfma_f32_16x16x32_bf16 v[46:49], v[168:171], v[184:187], v[46:49]
	v_mfma_f32_16x16x32_bf16 v[42:45], v[176:179], v[184:187], v[42:45]
	v_mfma_f32_16x16x32_bf16 v[30:33], v[168:171], v[192:195], v[30:33]
	v_mfma_f32_16x16x32_bf16 v[26:29], v[176:179], v[192:195], v[26:29]
	v_mfma_f32_16x16x32_bf16 v[14:17], v[168:171], v[200:203], v[14:17]
	v_mfma_f32_16x16x32_bf16 v[10:13], v[176:179], v[200:203], v[10:13]
	v_mfma_f32_16x16x32_bf16 v[6:9], v[168:171], v[210:213], v[6:9]
	v_mfma_f32_16x16x32_bf16 v[2:5], v[176:179], v[210:213], v[2:5]
	s_setprio 0
	s_barrier
	s_add_i32 s70, 0, 0x18000
	v_add_u32_e32 v147, s70, v143
	s_add_i32 s71, 0, 0x1c000
	ds_read_b128 v[148:151], v147
	ds_read_b128 v[152:155], v147 offset:1024
	ds_read_b128 v[156:159], v147 offset:2048
	ds_read_b128 v[160:163], v147 offset:3072
	v_add_u32_e32 v147, s71, v143
	ds_read_b128 v[164:167], v147
	ds_read_b128 v[168:171], v147 offset:1024
	ds_read_b128 v[172:175], v147 offset:2048
	ds_read_b128 v[176:179], v147 offset:3072
	s_add_u32 s42, s42, 0x20000
	s_addc_u32 s43, s43, 0
	s_mov_b32 m0, s25
	v_lshl_add_u64 v[222:223], s[42:43], 0, v[136:137]
	ds_read_b128 v[180:183], v146 offset:32768
	ds_read_b128 v[184:187], v146 offset:33792
	ds_read_b128 v[188:191], v146 offset:34816
	ds_read_b128 v[192:195], v146 offset:35840
	ds_read_b128 v[196:199], v146 offset:36864
	ds_read_b128 v[200:203], v146 offset:37888
	ds_read_b128 v[206:209], v146 offset:38912
	ds_read_b128 v[210:213], v146 offset:39936
	global_load_lds_dwordx4 v[222:223], off
	v_lshl_add_u64 v[222:223], s[42:43], 0, v[132:133]
	s_mov_b32 m0, s28
	s_nop 0
	global_load_lds_dwordx4 v[222:223], off
	s_waitcnt vmcnt(8) lgkmcnt(0)
	s_setprio 1
	s_barrier
	v_mfma_f32_16x16x32_bf16 v[126:129], v[148:151], v[180:183], v[126:129]
	v_mfma_f32_16x16x32_bf16 v[122:125], v[156:159], v[180:183], v[122:125]
	v_mfma_f32_16x16x32_bf16 v[118:121], v[148:151], v[188:191], v[118:121]
	v_mfma_f32_16x16x32_bf16 v[114:117], v[156:159], v[188:191], v[114:117]
	v_mfma_f32_16x16x32_bf16 v[102:105], v[148:151], v[196:199], v[102:105]
	v_mfma_f32_16x16x32_bf16 v[98:101], v[156:159], v[196:199], v[98:101]
	v_mfma_f32_16x16x32_bf16 v[86:89], v[148:151], v[206:209], v[86:89]
	v_mfma_f32_16x16x32_bf16 v[82:85], v[156:159], v[206:209], v[82:85]
	v_mfma_f32_16x16x32_bf16 v[126:129], v[152:155], v[184:187], v[126:129]
	v_mfma_f32_16x16x32_bf16 v[122:125], v[160:163], v[184:187], v[122:125]
	v_mfma_f32_16x16x32_bf16 v[118:121], v[152:155], v[192:195], v[118:121]
	v_mfma_f32_16x16x32_bf16 v[114:117], v[160:163], v[192:195], v[114:117]
	v_mfma_f32_16x16x32_bf16 v[102:105], v[152:155], v[200:203], v[102:105]
	v_mfma_f32_16x16x32_bf16 v[98:101], v[160:163], v[200:203], v[98:101]
	v_mfma_f32_16x16x32_bf16 v[86:89], v[152:155], v[210:213], v[86:89]
	v_mfma_f32_16x16x32_bf16 v[82:85], v[160:163], v[210:213], v[82:85]
	v_mfma_f32_16x16x32_bf16 v[110:113], v[164:167], v[180:183], v[110:113]
	v_mfma_f32_16x16x32_bf16 v[106:109], v[172:175], v[180:183], v[106:109]
	v_mfma_f32_16x16x32_bf16 v[94:97], v[164:167], v[188:191], v[94:97]
	v_mfma_f32_16x16x32_bf16 v[90:93], v[172:175], v[188:191], v[90:93]
	v_mfma_f32_16x16x32_bf16 v[78:81], v[164:167], v[196:199], v[78:81]
	v_mfma_f32_16x16x32_bf16 v[74:77], v[172:175], v[196:199], v[74:77]
	v_mfma_f32_16x16x32_bf16 v[70:73], v[164:167], v[206:209], v[70:73]
	v_mfma_f32_16x16x32_bf16 v[66:69], v[172:175], v[206:209], v[66:69]
	v_mfma_f32_16x16x32_bf16 v[110:113], v[168:171], v[184:187], v[110:113]
	v_mfma_f32_16x16x32_bf16 v[106:109], v[176:179], v[184:187], v[106:109]
	v_mfma_f32_16x16x32_bf16 v[94:97], v[168:171], v[192:195], v[94:97]
	v_mfma_f32_16x16x32_bf16 v[90:93], v[176:179], v[192:195], v[90:93]
	v_mfma_f32_16x16x32_bf16 v[78:81], v[168:171], v[200:203], v[78:81]
	v_mfma_f32_16x16x32_bf16 v[74:77], v[176:179], v[200:203], v[74:77]
	v_mfma_f32_16x16x32_bf16 v[70:73], v[168:171], v[210:213], v[70:73]
	v_mfma_f32_16x16x32_bf16 v[66:69], v[176:179], v[210:213], v[66:69]
	s_setprio 0
	s_barrier
	s_add_i32 s42, s70, s18
	v_lshl_add_u64 v[214:215], v[214:215], 0, s[8:9]
	s_mov_b32 m0, s42
	ds_read_b128 v[180:183], v146 offset:49152
	ds_read_b128 v[184:187], v146 offset:50176
	ds_read_b128 v[188:191], v146 offset:51200
	ds_read_b128 v[192:195], v146 offset:52224
	ds_read_b128 v[196:199], v146 offset:53248
	ds_read_b128 v[200:203], v146 offset:54272
	ds_read_b128 v[206:209], v146 offset:55296
	ds_read_b128 v[210:213], v146 offset:56320
	global_load_lds_dwordx4 v[214:215], off
	s_add_i32 m0, s42, 0x2000
	s_add_u32 s38, s38, 0x200080
	v_lshl_add_u64 v[214:215], v[216:217], 0, s[8:9]
	s_addc_u32 s39, s39, 0
	s_add_i32 s42, s71, s18
	global_load_lds_dwordx4 v[214:215], off
	v_lshl_add_u64 v[214:215], s[38:39], 0, v[134:135]
	s_mov_b32 m0, s42
	s_nop 0
	global_load_lds_dwordx4 v[214:215], off
	v_lshl_add_u64 v[214:215], s[38:39], 0, v[130:131]
	s_add_i32 m0, s42, 0x2000
	s_nop 0
	global_load_lds_dwordx4 v[214:215], off
	v_lshl_add_u64 v[214:215], v[218:219], 0, s[8:9]
	s_mov_b32 m0, s33
	s_nop 0
	global_load_lds_dwordx4 v[214:215], off
	v_lshl_add_u64 v[214:215], v[220:221], 0, s[8:9]
	s_mov_b32 m0, s34
	s_nop 0
	global_load_lds_dwordx4 v[214:215], off
	s_waitcnt vmcnt(8) lgkmcnt(0)
	s_setprio 1
	s_barrier
	v_mfma_f32_16x16x32_bf16 v[62:65], v[148:151], v[180:183], v[62:65]
	v_mfma_f32_16x16x32_bf16 v[58:61], v[156:159], v[180:183], v[58:61]
	v_mfma_f32_16x16x32_bf16 v[54:57], v[148:151], v[188:191], v[54:57]
	v_mfma_f32_16x16x32_bf16 v[50:53], v[156:159], v[188:191], v[50:53]
	v_mfma_f32_16x16x32_bf16 v[38:41], v[148:151], v[196:199], v[38:41]
	v_mfma_f32_16x16x32_bf16 v[34:37], v[156:159], v[196:199], v[34:37]
	v_mfma_f32_16x16x32_bf16 v[22:25], v[148:151], v[206:209], v[22:25]
	v_mfma_f32_16x16x32_bf16 v[18:21], v[156:159], v[206:209], v[18:21]
	v_mfma_f32_16x16x32_bf16 v[62:65], v[152:155], v[184:187], v[62:65]
	v_mfma_f32_16x16x32_bf16 v[58:61], v[160:163], v[184:187], v[58:61]
	v_mfma_f32_16x16x32_bf16 v[54:57], v[152:155], v[192:195], v[54:57]
	v_mfma_f32_16x16x32_bf16 v[50:53], v[160:163], v[192:195], v[50:53]
	v_mfma_f32_16x16x32_bf16 v[38:41], v[152:155], v[200:203], v[38:41]
	v_mfma_f32_16x16x32_bf16 v[34:37], v[160:163], v[200:203], v[34:37]
	v_mfma_f32_16x16x32_bf16 v[22:25], v[152:155], v[210:213], v[22:25]
	v_mfma_f32_16x16x32_bf16 v[18:21], v[160:163], v[210:213], v[18:21]
	v_mfma_f32_16x16x32_bf16 v[46:49], v[164:167], v[180:183], v[46:49]
	v_mfma_f32_16x16x32_bf16 v[42:45], v[172:175], v[180:183], v[42:45]
	v_mfma_f32_16x16x32_bf16 v[30:33], v[164:167], v[188:191], v[30:33]
	v_mfma_f32_16x16x32_bf16 v[26:29], v[172:175], v[188:191], v[26:29]
	v_mfma_f32_16x16x32_bf16 v[14:17], v[164:167], v[196:199], v[14:17]
	v_mfma_f32_16x16x32_bf16 v[10:13], v[172:175], v[196:199], v[10:13]
	v_mfma_f32_16x16x32_bf16 v[6:9], v[164:167], v[206:209], v[6:9]
	v_mfma_f32_16x16x32_bf16 v[2:5], v[172:175], v[206:209], v[2:5]
	v_mfma_f32_16x16x32_bf16 v[46:49], v[168:171], v[184:187], v[46:49]
	v_mfma_f32_16x16x32_bf16 v[42:45], v[176:179], v[184:187], v[42:45]
	v_mfma_f32_16x16x32_bf16 v[30:33], v[168:171], v[192:195], v[30:33]
	v_mfma_f32_16x16x32_bf16 v[26:29], v[176:179], v[192:195], v[26:29]
	v_mfma_f32_16x16x32_bf16 v[14:17], v[168:171], v[200:203], v[14:17]
	v_mfma_f32_16x16x32_bf16 v[10:13], v[176:179], v[200:203], v[10:13]
	v_mfma_f32_16x16x32_bf16 v[6:9], v[168:171], v[210:213], v[6:9]
	v_mfma_f32_16x16x32_bf16 v[2:5], v[176:179], v[210:213], v[2:5]
	s_setprio 0
	s_barrier
	s_add_i32 s69, s69, 2
	s_add_u32 s36, s36, 0x100
	s_addc_u32 s37, s37, 0
	s_add_u32 s67, s67, 0x100
	s_addc_u32 s68, s68, 0
	s_cmp_gt_u32 s69, 5
.LBB0_477:
	ds_read_b128 v[148:151], v144
	ds_read_b128 v[152:155], v144 offset:1024
	ds_read_b128 v[156:159], v144 offset:2048
	ds_read_b128 v[160:163], v144 offset:3072
	ds_read_b128 v[164:167], v145
	ds_read_b128 v[168:171], v145 offset:1024
	ds_read_b128 v[172:175], v145 offset:2048
	ds_read_b128 v[176:179], v145 offset:3072
	s_add_u32 s38, s36, 0xfffe0080
	s_addc_u32 s39, s37, -1
	s_cmp_eq_u32 s69, 4
	s_cselect_b32 s43, s63, s39
	s_cselect_b32 s42, s64, s38
	s_cselect_b32 s39, s65, s68
	s_cselect_b32 s38, s66, s67
	v_lshl_add_u64 v[214:215], s[36:37], 0, v[138:139]
	s_add_i32 m0, s19, 0xc000
	ds_read_b128 v[180:183], v146
	ds_read_b128 v[184:187], v146 offset:1024
	ds_read_b128 v[188:191], v146 offset:2048
	ds_read_b128 v[192:195], v146 offset:3072
	ds_read_b128 v[196:199], v146 offset:4096
	ds_read_b128 v[200:203], v146 offset:5120
	ds_read_b128 v[206:209], v146 offset:6144
	ds_read_b128 v[210:213], v146 offset:7168
	global_load_lds_dwordx4 v[214:215], off
	v_lshl_add_u64 v[214:215], s[36:37], 0, v[140:141]
	s_add_i32 m0, s19, 0xe000
	s_nop 0
	global_load_lds_dwordx4 v[214:215], off
	s_waitcnt vmcnt(8) lgkmcnt(0)
	s_setprio 1
	s_barrier
	v_mfma_f32_16x16x32_bf16 v[126:129], v[148:151], v[180:183], v[126:129]
	v_mfma_f32_16x16x32_bf16 v[122:125], v[156:159], v[180:183], v[122:125]
	v_mfma_f32_16x16x32_bf16 v[118:121], v[148:151], v[188:191], v[118:121]
	v_mfma_f32_16x16x32_bf16 v[114:117], v[156:159], v[188:191], v[114:117]
	v_mfma_f32_16x16x32_bf16 v[102:105], v[148:151], v[196:199], v[102:105]
	v_mfma_f32_16x16x32_bf16 v[98:101], v[156:159], v[196:199], v[98:101]
	v_mfma_f32_16x16x32_bf16 v[86:89], v[148:151], v[206:209], v[86:89]
	v_mfma_f32_16x16x32_bf16 v[82:85], v[156:159], v[206:209], v[82:85]
	v_mfma_f32_16x16x32_bf16 v[126:129], v[152:155], v[184:187], v[126:129]
	v_mfma_f32_16x16x32_bf16 v[122:125], v[160:163], v[184:187], v[122:125]
	v_mfma_f32_16x16x32_bf16 v[118:121], v[152:155], v[192:195], v[118:121]
	v_mfma_f32_16x16x32_bf16 v[114:117], v[160:163], v[192:195], v[114:117]
	v_mfma_f32_16x16x32_bf16 v[102:105], v[152:155], v[200:203], v[102:105]
	v_mfma_f32_16x16x32_bf16 v[98:101], v[160:163], v[200:203], v[98:101]
	v_mfma_f32_16x16x32_bf16 v[86:89], v[152:155], v[210:213], v[86:89]
	v_mfma_f32_16x16x32_bf16 v[82:85], v[160:163], v[210:213], v[82:85]
	v_mfma_f32_16x16x32_bf16 v[110:113], v[164:167], v[180:183], v[110:113]
	v_mfma_f32_16x16x32_bf16 v[106:109], v[172:175], v[180:183], v[106:109]
	v_mfma_f32_16x16x32_bf16 v[94:97], v[164:167], v[188:191], v[94:97]
	v_mfma_f32_16x16x32_bf16 v[90:93], v[172:175], v[188:191], v[90:93]
	v_mfma_f32_16x16x32_bf16 v[78:81], v[164:167], v[196:199], v[78:81]
	v_mfma_f32_16x16x32_bf16 v[74:77], v[172:175], v[196:199], v[74:77]
	v_mfma_f32_16x16x32_bf16 v[70:73], v[164:167], v[206:209], v[70:73]
	v_mfma_f32_16x16x32_bf16 v[66:69], v[172:175], v[206:209], v[66:69]
	v_mfma_f32_16x16x32_bf16 v[110:113], v[168:171], v[184:187], v[110:113]
	v_mfma_f32_16x16x32_bf16 v[106:109], v[176:179], v[184:187], v[106:109]
	v_mfma_f32_16x16x32_bf16 v[94:97], v[168:171], v[192:195], v[94:97]
	v_mfma_f32_16x16x32_bf16 v[90:93], v[176:179], v[192:195], v[90:93]
	v_mfma_f32_16x16x32_bf16 v[78:81], v[168:171], v[200:203], v[78:81]
	v_mfma_f32_16x16x32_bf16 v[74:77], v[176:179], v[200:203], v[74:77]
	v_mfma_f32_16x16x32_bf16 v[70:73], v[168:171], v[210:213], v[70:73]
	v_mfma_f32_16x16x32_bf16 v[66:69], v[176:179], v[210:213], v[66:69]
	s_setprio 0
	s_barrier
	s_add_i32 s70, s35, s18
	v_lshl_add_u64 v[214:215], s[38:39], 0, v[134:135]
	s_mov_b32 m0, s70
	ds_read_b128 v[180:183], v146 offset:16384
	ds_read_b128 v[184:187], v146 offset:17408
	ds_read_b128 v[188:191], v146 offset:18432
	ds_read_b128 v[192:195], v146 offset:19456
	ds_read_b128 v[196:199], v146 offset:20480
	ds_read_b128 v[200:203], v146 offset:21504
	ds_read_b128 v[206:209], v146 offset:22528
	ds_read_b128 v[210:213], v146 offset:23552
	global_load_lds_dwordx4 v[214:215], off
	s_add_i32 m0, s70, 0x2000
	s_add_u32 s70, s38, 0x200000
	v_lshl_add_u64 v[216:217], s[38:39], 0, v[130:131]
	s_addc_u32 s71, s39, 0
	s_add_i32 s72, s44, s18
	global_load_lds_dwordx4 v[216:217], off
	v_lshl_add_u64 v[218:219], s[70:71], 0, v[134:135]
	s_mov_b32 m0, s72
	v_lshl_add_u64 v[220:221], s[42:43], 0, v[132:133]
	global_load_lds_dwordx4 v[218:219], off
	v_lshl_add_u64 v[218:219], s[70:71], 0, v[130:131]
	s_add_i32 m0, s72, 0x2000
	s_nop 0
	global_load_lds_dwordx4 v[218:219], off
	v_lshl_add_u64 v[218:219], s[42:43], 0, v[136:137]
	s_mov_b32 m0, s19
	s_nop 0
	global_load_lds_dwordx4 v[218:219], off
	s_mov_b32 m0, s24
	s_nop 0
	global_load_lds_dwordx4 v[220:221], off
	s_waitcnt vmcnt(8) lgkmcnt(0)
	s_setprio 1
	s_barrier
	v_mfma_f32_16x16x32_bf16 v[62:65], v[148:151], v[180:183], v[62:65]
	v_mfma_f32_16x16x32_bf16 v[58:61], v[156:159], v[180:183], v[58:61]
	v_mfma_f32_16x16x32_bf16 v[54:57], v[148:151], v[188:191], v[54:57]
	v_mfma_f32_16x16x32_bf16 v[50:53], v[156:159], v[188:191], v[50:53]
	v_mfma_f32_16x16x32_bf16 v[38:41], v[148:151], v[196:199], v[38:41]
	v_mfma_f32_16x16x32_bf16 v[34:37], v[156:159], v[196:199], v[34:37]
	v_mfma_f32_16x16x32_bf16 v[22:25], v[148:151], v[206:209], v[22:25]
	v_mfma_f32_16x16x32_bf16 v[18:21], v[156:159], v[206:209], v[18:21]
	v_mfma_f32_16x16x32_bf16 v[62:65], v[152:155], v[184:187], v[62:65]
	v_mfma_f32_16x16x32_bf16 v[58:61], v[160:163], v[184:187], v[58:61]
	v_mfma_f32_16x16x32_bf16 v[54:57], v[152:155], v[192:195], v[54:57]
	v_mfma_f32_16x16x32_bf16 v[50:53], v[160:163], v[192:195], v[50:53]
	v_mfma_f32_16x16x32_bf16 v[38:41], v[152:155], v[200:203], v[38:41]
	v_mfma_f32_16x16x32_bf16 v[34:37], v[160:163], v[200:203], v[34:37]
	v_mfma_f32_16x16x32_bf16 v[22:25], v[152:155], v[210:213], v[22:25]
	v_mfma_f32_16x16x32_bf16 v[18:21], v[160:163], v[210:213], v[18:21]
	v_mfma_f32_16x16x32_bf16 v[46:49], v[164:167], v[180:183], v[46:49]
	v_mfma_f32_16x16x32_bf16 v[42:45], v[172:175], v[180:183], v[42:45]
	v_mfma_f32_16x16x32_bf16 v[30:33], v[164:167], v[188:191], v[30:33]
	v_mfma_f32_16x16x32_bf16 v[26:29], v[172:175], v[188:191], v[26:29]
	v_mfma_f32_16x16x32_bf16 v[14:17], v[164:167], v[196:199], v[14:17]
	v_mfma_f32_16x16x32_bf16 v[10:13], v[172:175], v[196:199], v[10:13]
	v_mfma_f32_16x16x32_bf16 v[6:9], v[164:167], v[206:209], v[6:9]
	v_mfma_f32_16x16x32_bf16 v[2:5], v[172:175], v[206:209], v[2:5]
	v_mfma_f32_16x16x32_bf16 v[46:49], v[168:171], v[184:187], v[46:49]
	v_mfma_f32_16x16x32_bf16 v[42:45], v[176:179], v[184:187], v[42:45]
	v_mfma_f32_16x16x32_bf16 v[30:33], v[168:171], v[192:195], v[30:33]
	v_mfma_f32_16x16x32_bf16 v[26:29], v[176:179], v[192:195], v[26:29]
	v_mfma_f32_16x16x32_bf16 v[14:17], v[168:171], v[200:203], v[14:17]
	v_mfma_f32_16x16x32_bf16 v[10:13], v[176:179], v[200:203], v[10:13]
	v_mfma_f32_16x16x32_bf16 v[6:9], v[168:171], v[210:213], v[6:9]
	v_mfma_f32_16x16x32_bf16 v[2:5], v[176:179], v[210:213], v[2:5]
	s_setprio 0
	s_barrier
	s_add_i32 s70, 0, 0x18000
	v_add_u32_e32 v147, s70, v143
	s_add_i32 s71, 0, 0x1c000
	ds_read_b128 v[148:151], v147
	ds_read_b128 v[152:155], v147 offset:1024
	ds_read_b128 v[156:159], v147 offset:2048
	ds_read_b128 v[160:163], v147 offset:3072
	v_add_u32_e32 v147, s71, v143
	ds_read_b128 v[164:167], v147
	ds_read_b128 v[168:171], v147 offset:1024
	ds_read_b128 v[172:175], v147 offset:2048
	ds_read_b128 v[176:179], v147 offset:3072
	s_add_u32 s42, s42, 0x20000
	s_addc_u32 s43, s43, 0
	s_mov_b32 m0, s25
	v_lshl_add_u64 v[222:223], s[42:43], 0, v[136:137]
	ds_read_b128 v[180:183], v146 offset:32768
	ds_read_b128 v[184:187], v146 offset:33792
	ds_read_b128 v[188:191], v146 offset:34816
	ds_read_b128 v[192:195], v146 offset:35840
	ds_read_b128 v[196:199], v146 offset:36864
	ds_read_b128 v[200:203], v146 offset:37888
	ds_read_b128 v[206:209], v146 offset:38912
	ds_read_b128 v[210:213], v146 offset:39936
	global_load_lds_dwordx4 v[222:223], off
	v_lshl_add_u64 v[222:223], s[42:43], 0, v[132:133]
	s_mov_b32 m0, s28
	s_nop 0
	global_load_lds_dwordx4 v[222:223], off
	s_waitcnt vmcnt(8) lgkmcnt(0)
	s_setprio 1
	s_barrier
	v_mfma_f32_16x16x32_bf16 v[126:129], v[148:151], v[180:183], v[126:129]
	v_mfma_f32_16x16x32_bf16 v[122:125], v[156:159], v[180:183], v[122:125]
	v_mfma_f32_16x16x32_bf16 v[118:121], v[148:151], v[188:191], v[118:121]
	v_mfma_f32_16x16x32_bf16 v[114:117], v[156:159], v[188:191], v[114:117]
	v_mfma_f32_16x16x32_bf16 v[102:105], v[148:151], v[196:199], v[102:105]
	v_mfma_f32_16x16x32_bf16 v[98:101], v[156:159], v[196:199], v[98:101]
	v_mfma_f32_16x16x32_bf16 v[86:89], v[148:151], v[206:209], v[86:89]
	v_mfma_f32_16x16x32_bf16 v[82:85], v[156:159], v[206:209], v[82:85]
	v_mfma_f32_16x16x32_bf16 v[126:129], v[152:155], v[184:187], v[126:129]
	v_mfma_f32_16x16x32_bf16 v[122:125], v[160:163], v[184:187], v[122:125]
	v_mfma_f32_16x16x32_bf16 v[118:121], v[152:155], v[192:195], v[118:121]
	v_mfma_f32_16x16x32_bf16 v[114:117], v[160:163], v[192:195], v[114:117]
	v_mfma_f32_16x16x32_bf16 v[102:105], v[152:155], v[200:203], v[102:105]
	v_mfma_f32_16x16x32_bf16 v[98:101], v[160:163], v[200:203], v[98:101]
	v_mfma_f32_16x16x32_bf16 v[86:89], v[152:155], v[210:213], v[86:89]
	v_mfma_f32_16x16x32_bf16 v[82:85], v[160:163], v[210:213], v[82:85]
	v_mfma_f32_16x16x32_bf16 v[110:113], v[164:167], v[180:183], v[110:113]
	v_mfma_f32_16x16x32_bf16 v[106:109], v[172:175], v[180:183], v[106:109]
	v_mfma_f32_16x16x32_bf16 v[94:97], v[164:167], v[188:191], v[94:97]
	v_mfma_f32_16x16x32_bf16 v[90:93], v[172:175], v[188:191], v[90:93]
	v_mfma_f32_16x16x32_bf16 v[78:81], v[164:167], v[196:199], v[78:81]
	v_mfma_f32_16x16x32_bf16 v[74:77], v[172:175], v[196:199], v[74:77]
	v_mfma_f32_16x16x32_bf16 v[70:73], v[164:167], v[206:209], v[70:73]
	v_mfma_f32_16x16x32_bf16 v[66:69], v[172:175], v[206:209], v[66:69]
	v_mfma_f32_16x16x32_bf16 v[110:113], v[168:171], v[184:187], v[110:113]
	v_mfma_f32_16x16x32_bf16 v[106:109], v[176:179], v[184:187], v[106:109]
	v_mfma_f32_16x16x32_bf16 v[94:97], v[168:171], v[192:195], v[94:97]
	v_mfma_f32_16x16x32_bf16 v[90:93], v[176:179], v[192:195], v[90:93]
	v_mfma_f32_16x16x32_bf16 v[78:81], v[168:171], v[200:203], v[78:81]
	v_mfma_f32_16x16x32_bf16 v[74:77], v[176:179], v[200:203], v[74:77]
	v_mfma_f32_16x16x32_bf16 v[70:73], v[168:171], v[210:213], v[70:73]
	v_mfma_f32_16x16x32_bf16 v[66:69], v[176:179], v[210:213], v[66:69]
	s_setprio 0
	s_barrier
	s_add_i32 s42, s70, s18
	v_lshl_add_u64 v[214:215], v[214:215], 0, s[8:9]
	s_mov_b32 m0, s42
	ds_read_b128 v[180:183], v146 offset:49152
	ds_read_b128 v[184:187], v146 offset:50176
	ds_read_b128 v[188:191], v146 offset:51200
	ds_read_b128 v[192:195], v146 offset:52224
	ds_read_b128 v[196:199], v146 offset:53248
	ds_read_b128 v[200:203], v146 offset:54272
	ds_read_b128 v[206:209], v146 offset:55296
	ds_read_b128 v[210:213], v146 offset:56320
	global_load_lds_dwordx4 v[214:215], off
	s_add_i32 m0, s42, 0x2000
	s_add_u32 s38, s38, 0x200080
	v_lshl_add_u64 v[214:215], v[216:217], 0, s[8:9]
	s_addc_u32 s39, s39, 0
	s_add_i32 s42, s71, s18
	global_load_lds_dwordx4 v[214:215], off
	v_lshl_add_u64 v[214:215], s[38:39], 0, v[134:135]
	s_mov_b32 m0, s42
	s_nop 0
	global_load_lds_dwordx4 v[214:215], off
	v_lshl_add_u64 v[214:215], s[38:39], 0, v[130:131]
	s_add_i32 m0, s42, 0x2000
	s_nop 0
	global_load_lds_dwordx4 v[214:215], off
	v_lshl_add_u64 v[214:215], v[218:219], 0, s[8:9]
	s_mov_b32 m0, s33
	s_nop 0
	global_load_lds_dwordx4 v[214:215], off
	v_lshl_add_u64 v[214:215], v[220:221], 0, s[8:9]
	s_mov_b32 m0, s34
	s_nop 0
	global_load_lds_dwordx4 v[214:215], off
	s_waitcnt vmcnt(8) lgkmcnt(0)
	s_setprio 1
	s_barrier
	v_mfma_f32_16x16x32_bf16 v[62:65], v[148:151], v[180:183], v[62:65]
	v_mfma_f32_16x16x32_bf16 v[58:61], v[156:159], v[180:183], v[58:61]
	v_mfma_f32_16x16x32_bf16 v[54:57], v[148:151], v[188:191], v[54:57]
	v_mfma_f32_16x16x32_bf16 v[50:53], v[156:159], v[188:191], v[50:53]
	v_mfma_f32_16x16x32_bf16 v[38:41], v[148:151], v[196:199], v[38:41]
	v_mfma_f32_16x16x32_bf16 v[34:37], v[156:159], v[196:199], v[34:37]
	v_mfma_f32_16x16x32_bf16 v[22:25], v[148:151], v[206:209], v[22:25]
	v_mfma_f32_16x16x32_bf16 v[18:21], v[156:159], v[206:209], v[18:21]
	v_mfma_f32_16x16x32_bf16 v[62:65], v[152:155], v[184:187], v[62:65]
	v_mfma_f32_16x16x32_bf16 v[58:61], v[160:163], v[184:187], v[58:61]
	v_mfma_f32_16x16x32_bf16 v[54:57], v[152:155], v[192:195], v[54:57]
	v_mfma_f32_16x16x32_bf16 v[50:53], v[160:163], v[192:195], v[50:53]
	v_mfma_f32_16x16x32_bf16 v[38:41], v[152:155], v[200:203], v[38:41]
	v_mfma_f32_16x16x32_bf16 v[34:37], v[160:163], v[200:203], v[34:37]
	v_mfma_f32_16x16x32_bf16 v[22:25], v[152:155], v[210:213], v[22:25]
	v_mfma_f32_16x16x32_bf16 v[18:21], v[160:163], v[210:213], v[18:21]
	v_mfma_f32_16x16x32_bf16 v[46:49], v[164:167], v[180:183], v[46:49]
	v_mfma_f32_16x16x32_bf16 v[42:45], v[172:175], v[180:183], v[42:45]
	v_mfma_f32_16x16x32_bf16 v[30:33], v[164:167], v[188:191], v[30:33]
	v_mfma_f32_16x16x32_bf16 v[26:29], v[172:175], v[188:191], v[26:29]
	v_mfma_f32_16x16x32_bf16 v[14:17], v[164:167], v[196:199], v[14:17]
	v_mfma_f32_16x16x32_bf16 v[10:13], v[172:175], v[196:199], v[10:13]
	v_mfma_f32_16x16x32_bf16 v[6:9], v[164:167], v[206:209], v[6:9]
	v_mfma_f32_16x16x32_bf16 v[2:5], v[172:175], v[206:209], v[2:5]
	v_mfma_f32_16x16x32_bf16 v[46:49], v[168:171], v[184:187], v[46:49]
	v_mfma_f32_16x16x32_bf16 v[42:45], v[176:179], v[184:187], v[42:45]
	v_mfma_f32_16x16x32_bf16 v[30:33], v[168:171], v[192:195], v[30:33]
	v_mfma_f32_16x16x32_bf16 v[26:29], v[176:179], v[192:195], v[26:29]
	v_mfma_f32_16x16x32_bf16 v[14:17], v[168:171], v[200:203], v[14:17]
	v_mfma_f32_16x16x32_bf16 v[10:13], v[176:179], v[200:203], v[10:13]
	v_mfma_f32_16x16x32_bf16 v[6:9], v[168:171], v[210:213], v[6:9]
	v_mfma_f32_16x16x32_bf16 v[2:5], v[176:179], v[210:213], v[2:5]
	s_setprio 0
	s_barrier
	s_add_i32 s69, s69, 2
	s_add_u32 s36, s36, 0x100
	s_addc_u32 s37, s37, 0
	s_add_u32 s67, s67, 0x100
	s_addc_u32 s68, s68, 0
	s_cmp_gt_u32 s69, 5
	s_cbranch_scc0 .LBB0_477
	s_and_b64 vcc, exec, s[10:11]
	s_cbranch_vccz .LBB0_480
	s_barrier

.LBB0_565:
	v_readlane_b32 s62, v249, 27
	v_readlane_b32 s63, v249, 28
	s_add_u32 s72, s62, s68
	s_addc_u32 s73, s63, s69
	s_and_b64 s[62:63], s[70:71], exec
	s_cselect_b32 s31, s73, s77
	s_cselect_b32 s33, s72, s76
	s_add_u32 s74, s35, s66
	s_addc_u32 s75, s85, s67
	s_and_b64 s[62:63], s[70:71], exec
	s_cselect_b32 s34, s75, s79
	s_cselect_b32 s39, s74, s78
	s_add_i32 s45, s7, -2
	s_add_u32 s76, s76, 0x40080
	s_addc_u32 s77, s77, 0
	s_add_u32 s47, s78, 0x100
	s_addc_u32 s62, s79, 0
	s_mov_b32 s63, 0
	s_waitcnt vmcnt(0)
	ds_read_b128 v[114:117], v190
	ds_read_b128 v[118:121], v190 offset:1024
	ds_read_b128 v[122:125], v190 offset:2048
	ds_read_b128 v[126:129], v190 offset:3072
	ds_read_b128 v[146:149], v191
	ds_read_b128 v[150:153], v191 offset:1024
	ds_read_b128 v[154:157], v191 offset:2048
	ds_read_b128 v[158:161], v191 offset:3072
	s_add_i32 s82, s63, 2
	s_add_u32 s78, s76, 0xfffc0080
	s_addc_u32 s79, s77, -1
	s_cmp_eq_u32 s45, s63
	s_cselect_b32 s81, s31, s79
	s_cselect_b32 s80, s33, s78
	s_cselect_b32 s79, s34, s62
	s_cselect_b32 s78, s39, s47
	v_lshl_add_u64 v[186:187], s[76:77], 0, v[180:181]
	s_add_i32 m0, s87, 0xc000
	ds_read_b128 v[162:165], v192
	ds_read_b128 v[166:169], v192 offset:1024
	ds_read_b128 v[194:197], v192 offset:2048
	ds_read_b128 v[198:201], v192 offset:3072
	ds_read_b128 v[206:209], v192 offset:4096
	ds_read_b128 v[210:213], v192 offset:5120
	ds_read_b128 v[214:217], v192 offset:6144
	ds_read_b128 v[218:221], v192 offset:7168
	global_load_lds_dwordx4 v[186:187], off
	v_lshl_add_u64 v[186:187], s[76:77], 0, v[182:183]
	s_add_i32 m0, s87, 0xe000
	s_nop 0
	global_load_lds_dwordx4 v[186:187], off
	s_waitcnt vmcnt(8)
	s_waitcnt lgkmcnt(0)
	s_setprio 1
	s_barrier
	v_mfma_f32_16x16x32_bf16 v[142:145], v[114:117], v[162:165], 0
	v_mfma_f32_16x16x32_bf16 v[138:141], v[122:125], v[162:165], 0
	v_mfma_f32_16x16x32_bf16 v[110:113], v[114:117], v[194:197], 0
	v_mfma_f32_16x16x32_bf16 v[106:109], v[122:125], v[194:197], 0
	v_mfma_f32_16x16x32_bf16 v[98:101], v[114:117], v[206:209], 0
	v_mfma_f32_16x16x32_bf16 v[90:93], v[122:125], v[206:209], 0
	v_mfma_f32_16x16x32_bf16 v[82:85], v[114:117], v[214:217], 0
	v_mfma_f32_16x16x32_bf16 v[74:77], v[122:125], v[214:217], 0
	v_mfma_f32_16x16x32_bf16 v[142:145], v[118:121], v[166:169], v[142:145]
	v_mfma_f32_16x16x32_bf16 v[138:141], v[126:129], v[166:169], v[138:141]
	v_mfma_f32_16x16x32_bf16 v[110:113], v[118:121], v[198:201], v[110:113]
	v_mfma_f32_16x16x32_bf16 v[106:109], v[126:129], v[198:201], v[106:109]
	v_mfma_f32_16x16x32_bf16 v[98:101], v[118:121], v[210:213], v[98:101]
	v_mfma_f32_16x16x32_bf16 v[90:93], v[126:129], v[210:213], v[90:93]
	v_mfma_f32_16x16x32_bf16 v[82:85], v[118:121], v[218:221], v[82:85]
	v_mfma_f32_16x16x32_bf16 v[74:77], v[126:129], v[218:221], v[74:77]
	v_mfma_f32_16x16x32_bf16 v[134:137], v[146:149], v[162:165], 0
	v_mfma_f32_16x16x32_bf16 v[130:133], v[154:157], v[162:165], 0
	v_mfma_f32_16x16x32_bf16 v[102:105], v[146:149], v[194:197], 0
	v_mfma_f32_16x16x32_bf16 v[94:97], v[154:157], v[194:197], 0
	v_mfma_f32_16x16x32_bf16 v[86:89], v[146:149], v[206:209], 0
	v_mfma_f32_16x16x32_bf16 v[78:81], v[154:157], v[206:209], 0
	v_mfma_f32_16x16x32_bf16 v[70:73], v[146:149], v[214:217], 0
	v_mfma_f32_16x16x32_bf16 v[66:69], v[154:157], v[214:217], 0
	v_mfma_f32_16x16x32_bf16 v[134:137], v[150:153], v[166:169], v[134:137]
	v_mfma_f32_16x16x32_bf16 v[130:133], v[158:161], v[166:169], v[130:133]
	v_mfma_f32_16x16x32_bf16 v[102:105], v[150:153], v[198:201], v[102:105]
	v_mfma_f32_16x16x32_bf16 v[94:97], v[158:161], v[198:201], v[94:97]
	v_mfma_f32_16x16x32_bf16 v[86:89], v[150:153], v[210:213], v[86:89]
	v_mfma_f32_16x16x32_bf16 v[78:81], v[158:161], v[210:213], v[78:81]
	v_mfma_f32_16x16x32_bf16 v[70:73], v[150:153], v[218:221], v[70:73]
	v_mfma_f32_16x16x32_bf16 v[66:69], v[158:161], v[218:221], v[66:69]
	s_setprio 0
	s_barrier
	s_add_i32 s63, s24, s86
	v_lshl_add_u64 v[186:187], s[78:79], 0, v[172:173]
	s_mov_b32 m0, s63
	ds_read_b128 v[162:165], v192 offset:16384
	ds_read_b128 v[166:169], v192 offset:17408
	ds_read_b128 v[194:197], v192 offset:18432
	ds_read_b128 v[198:201], v192 offset:19456
	ds_read_b128 v[206:209], v192 offset:20480
	ds_read_b128 v[210:213], v192 offset:21504
	ds_read_b128 v[214:217], v192 offset:22528
	ds_read_b128 v[218:221], v192 offset:23552
	global_load_lds_dwordx4 v[186:187], off
	s_add_i32 m0, s63, 0x2000
	s_add_u32 vcc_lo, s78, 0x40000
	v_lshl_add_u64 v[202:203], s[78:79], 0, v[176:177]
	s_addc_u32 vcc_hi, s79, 0
	s_add_i32 s63, s25, s86
	global_load_lds_dwordx4 v[202:203], off
	v_lshl_add_u64 v[222:223], vcc, 0, v[172:173]
	s_mov_b32 m0, s63
	v_lshl_add_u64 v[224:225], s[80:81], 0, v[174:175]
	global_load_lds_dwordx4 v[222:223], off
	v_lshl_add_u64 v[222:223], vcc, 0, v[176:177]
	s_add_i32 m0, s63, 0x2000
	s_nop 0
	global_load_lds_dwordx4 v[222:223], off
	v_lshl_add_u64 v[222:223], s[80:81], 0, v[170:171]
	s_mov_b32 m0, s87
	s_nop 0
	global_load_lds_dwordx4 v[222:223], off
	s_mov_b32 m0, s88
	s_nop 0
	global_load_lds_dwordx4 v[224:225], off
	s_waitcnt vmcnt(8) lgkmcnt(0)
	s_setprio 1
	s_barrier
	v_mfma_f32_16x16x32_bf16 v[62:65], v[114:117], v[162:165], 0
	v_mfma_f32_16x16x32_bf16 v[58:61], v[122:125], v[162:165], 0
	v_mfma_f32_16x16x32_bf16 v[50:53], v[114:117], v[194:197], 0
	v_mfma_f32_16x16x32_bf16 v[42:45], v[122:125], v[194:197], 0
	v_mfma_f32_16x16x32_bf16 v[34:37], v[114:117], v[206:209], 0
	v_mfma_f32_16x16x32_bf16 v[26:29], v[122:125], v[206:209], 0
	v_mfma_f32_16x16x32_bf16 v[18:21], v[114:117], v[214:217], 0
	v_mfma_f32_16x16x32_bf16 v[10:13], v[122:125], v[214:217], 0
	v_mfma_f32_16x16x32_bf16 v[62:65], v[118:121], v[166:169], v[62:65]
	v_mfma_f32_16x16x32_bf16 v[58:61], v[126:129], v[166:169], v[58:61]
	v_mfma_f32_16x16x32_bf16 v[50:53], v[118:121], v[198:201], v[50:53]
	v_mfma_f32_16x16x32_bf16 v[42:45], v[126:129], v[198:201], v[42:45]
	v_mfma_f32_16x16x32_bf16 v[34:37], v[118:121], v[210:213], v[34:37]
	v_mfma_f32_16x16x32_bf16 v[26:29], v[126:129], v[210:213], v[26:29]
	v_mfma_f32_16x16x32_bf16 v[18:21], v[118:121], v[218:221], v[18:21]
	v_mfma_f32_16x16x32_bf16 v[10:13], v[126:129], v[218:221], v[10:13]
	v_mfma_f32_16x16x32_bf16 v[54:57], v[146:149], v[162:165], 0
	v_mfma_f32_16x16x32_bf16 v[46:49], v[154:157], v[162:165], 0
	v_mfma_f32_16x16x32_bf16 v[38:41], v[146:149], v[194:197], 0
	v_mfma_f32_16x16x32_bf16 v[30:33], v[154:157], v[194:197], 0
	v_mfma_f32_16x16x32_bf16 v[22:25], v[146:149], v[206:209], 0
	v_mfma_f32_16x16x32_bf16 v[14:17], v[154:157], v[206:209], 0
	v_mfma_f32_16x16x32_bf16 v[6:9], v[146:149], v[214:217], 0
	v_mfma_f32_16x16x32_bf16 v[2:5], v[154:157], v[214:217], 0
	v_mfma_f32_16x16x32_bf16 v[54:57], v[150:153], v[166:169], v[54:57]
	v_mfma_f32_16x16x32_bf16 v[46:49], v[158:161], v[166:169], v[46:49]
	v_mfma_f32_16x16x32_bf16 v[38:41], v[150:153], v[198:201], v[38:41]
	v_mfma_f32_16x16x32_bf16 v[30:33], v[158:161], v[198:201], v[30:33]
	v_mfma_f32_16x16x32_bf16 v[22:25], v[150:153], v[210:213], v[22:25]
	v_mfma_f32_16x16x32_bf16 v[14:17], v[158:161], v[210:213], v[14:17]
	v_mfma_f32_16x16x32_bf16 v[6:9], v[150:153], v[218:221], v[6:9]
	v_mfma_f32_16x16x32_bf16 v[2:5], v[158:161], v[218:221], v[2:5]
	s_setprio 0
	s_barrier
	s_add_i32 s63, 0, 0x18000
	s_add_i32 s83, 0, 0x1c000
	v_add_u32_e32 v126, s63, v189
	v_add_u32_e32 v158, s83, v189
	ds_read_b128 v[114:117], v126
	ds_read_b128 v[118:121], v126 offset:1024
	ds_read_b128 v[122:125], v126 offset:2048
	ds_read_b128 v[126:129], v126 offset:3072
	ds_read_b128 v[146:149], v158
	ds_read_b128 v[150:153], v158 offset:1024
	ds_read_b128 v[154:157], v158 offset:2048
	ds_read_b128 v[158:161], v158 offset:3072
	s_add_u32 s80, s80, 0x40000
	s_addc_u32 s81, s81, 0
	s_mov_b32 m0, s89
	v_lshl_add_u64 v[226:227], s[80:81], 0, v[170:171]
	ds_read_b128 v[162:165], v192 offset:32768
	ds_read_b128 v[166:169], v192 offset:33792
	ds_read_b128 v[194:197], v192 offset:34816
	ds_read_b128 v[198:201], v192 offset:35840
	ds_read_b128 v[206:209], v192 offset:36864
	ds_read_b128 v[210:213], v192 offset:37888
	ds_read_b128 v[214:217], v192 offset:38912
	ds_read_b128 v[218:221], v192 offset:39936
	global_load_lds_dwordx4 v[226:227], off
	v_lshl_add_u64 v[226:227], s[80:81], 0, v[174:175]
	s_mov_b32 m0, s90
	s_nop 0
	global_load_lds_dwordx4 v[226:227], off
	s_waitcnt vmcnt(8) lgkmcnt(0)
	s_setprio 1
	s_barrier
	v_mfma_f32_16x16x32_bf16 v[142:145], v[114:117], v[162:165], v[142:145]
	v_mfma_f32_16x16x32_bf16 v[138:141], v[122:125], v[162:165], v[138:141]
	v_mfma_f32_16x16x32_bf16 v[110:113], v[114:117], v[194:197], v[110:113]
	v_mfma_f32_16x16x32_bf16 v[106:109], v[122:125], v[194:197], v[106:109]
	v_mfma_f32_16x16x32_bf16 v[98:101], v[114:117], v[206:209], v[98:101]
	v_mfma_f32_16x16x32_bf16 v[90:93], v[122:125], v[206:209], v[90:93]
	v_mfma_f32_16x16x32_bf16 v[82:85], v[114:117], v[214:217], v[82:85]
	v_mfma_f32_16x16x32_bf16 v[74:77], v[122:125], v[214:217], v[74:77]
	v_mfma_f32_16x16x32_bf16 v[142:145], v[118:121], v[166:169], v[142:145]
	v_mfma_f32_16x16x32_bf16 v[138:141], v[126:129], v[166:169], v[138:141]
	v_mfma_f32_16x16x32_bf16 v[110:113], v[118:121], v[198:201], v[110:113]
	v_mfma_f32_16x16x32_bf16 v[106:109], v[126:129], v[198:201], v[106:109]
	v_mfma_f32_16x16x32_bf16 v[98:101], v[118:121], v[210:213], v[98:101]
	v_mfma_f32_16x16x32_bf16 v[90:93], v[126:129], v[210:213], v[90:93]
	v_mfma_f32_16x16x32_bf16 v[82:85], v[118:121], v[218:221], v[82:85]
	v_mfma_f32_16x16x32_bf16 v[74:77], v[126:129], v[218:221], v[74:77]
	v_mfma_f32_16x16x32_bf16 v[134:137], v[146:149], v[162:165], v[134:137]
	v_mfma_f32_16x16x32_bf16 v[130:133], v[154:157], v[162:165], v[130:133]
	v_mfma_f32_16x16x32_bf16 v[102:105], v[146:149], v[194:197], v[102:105]
	v_mfma_f32_16x16x32_bf16 v[94:97], v[154:157], v[194:197], v[94:97]
	v_mfma_f32_16x16x32_bf16 v[86:89], v[146:149], v[206:209], v[86:89]
	v_mfma_f32_16x16x32_bf16 v[78:81], v[154:157], v[206:209], v[78:81]
	v_mfma_f32_16x16x32_bf16 v[70:73], v[146:149], v[214:217], v[70:73]
	v_mfma_f32_16x16x32_bf16 v[66:69], v[154:157], v[214:217], v[66:69]
	v_mfma_f32_16x16x32_bf16 v[134:137], v[150:153], v[166:169], v[134:137]
	v_mfma_f32_16x16x32_bf16 v[130:133], v[158:161], v[166:169], v[130:133]
	v_mfma_f32_16x16x32_bf16 v[102:105], v[150:153], v[198:201], v[102:105]
	v_mfma_f32_16x16x32_bf16 v[94:97], v[158:161], v[198:201], v[94:97]
	v_mfma_f32_16x16x32_bf16 v[86:89], v[150:153], v[210:213], v[86:89]
	v_mfma_f32_16x16x32_bf16 v[78:81], v[158:161], v[210:213], v[78:81]
	v_mfma_f32_16x16x32_bf16 v[70:73], v[150:153], v[218:221], v[70:73]
	v_mfma_f32_16x16x32_bf16 v[66:69], v[158:161], v[218:221], v[66:69]
	s_setprio 0
	s_barrier
	s_add_i32 s63, s63, s86
	v_lshl_add_u64 v[186:187], v[186:187], 0, s[22:23]
	s_mov_b32 m0, s63
	ds_read_b128 v[162:165], v192 offset:49152
	ds_read_b128 v[166:169], v192 offset:50176
	ds_read_b128 v[194:197], v192 offset:51200
	ds_read_b128 v[198:201], v192 offset:52224
	ds_read_b128 v[206:209], v192 offset:53248
	ds_read_b128 v[210:213], v192 offset:54272
	ds_read_b128 v[214:217], v192 offset:55296
	ds_read_b128 v[218:221], v192 offset:56320
	global_load_lds_dwordx4 v[186:187], off
	s_add_i32 m0, s63, 0x2000
	s_add_u32 s78, s78, 0x40080
	v_lshl_add_u64 v[186:187], v[202:203], 0, s[22:23]
	s_addc_u32 s79, s79, 0
	s_add_i32 s63, s83, s86
	global_load_lds_dwordx4 v[186:187], off
	v_lshl_add_u64 v[186:187], s[78:79], 0, v[172:173]
	s_mov_b32 m0, s63
	s_nop 0
	global_load_lds_dwordx4 v[186:187], off
	v_lshl_add_u64 v[186:187], s[78:79], 0, v[176:177]
	s_add_i32 m0, s63, 0x2000
	s_nop 0
	global_load_lds_dwordx4 v[186:187], off
	v_lshl_add_u64 v[186:187], v[222:223], 0, s[22:23]
	s_mov_b32 m0, s95
	s_nop 0
	global_load_lds_dwordx4 v[186:187], off
	v_lshl_add_u64 v[186:187], v[224:225], 0, s[22:23]
	s_mov_b32 m0, s96
	s_nop 0
	global_load_lds_dwordx4 v[186:187], off
	s_waitcnt vmcnt(8) lgkmcnt(0)
	s_setprio 1
	s_barrier
	v_mfma_f32_16x16x32_bf16 v[62:65], v[114:117], v[162:165], v[62:65]
	v_mfma_f32_16x16x32_bf16 v[58:61], v[122:125], v[162:165], v[58:61]
	v_mfma_f32_16x16x32_bf16 v[50:53], v[114:117], v[194:197], v[50:53]
	v_mfma_f32_16x16x32_bf16 v[42:45], v[122:125], v[194:197], v[42:45]
	v_mfma_f32_16x16x32_bf16 v[34:37], v[114:117], v[206:209], v[34:37]
	v_mfma_f32_16x16x32_bf16 v[26:29], v[122:125], v[206:209], v[26:29]
	v_mfma_f32_16x16x32_bf16 v[18:21], v[114:117], v[214:217], v[18:21]
	v_mfma_f32_16x16x32_bf16 v[10:13], v[122:125], v[214:217], v[10:13]
	v_mfma_f32_16x16x32_bf16 v[62:65], v[118:121], v[166:169], v[62:65]
	v_mfma_f32_16x16x32_bf16 v[58:61], v[126:129], v[166:169], v[58:61]
	v_mfma_f32_16x16x32_bf16 v[50:53], v[118:121], v[198:201], v[50:53]
	v_mfma_f32_16x16x32_bf16 v[42:45], v[126:129], v[198:201], v[42:45]
	v_mfma_f32_16x16x32_bf16 v[34:37], v[118:121], v[210:213], v[34:37]
	v_mfma_f32_16x16x32_bf16 v[26:29], v[126:129], v[210:213], v[26:29]
	v_mfma_f32_16x16x32_bf16 v[18:21], v[118:121], v[218:221], v[18:21]
	v_mfma_f32_16x16x32_bf16 v[10:13], v[126:129], v[218:221], v[10:13]
	v_mfma_f32_16x16x32_bf16 v[54:57], v[146:149], v[162:165], v[54:57]
	v_mfma_f32_16x16x32_bf16 v[46:49], v[154:157], v[162:165], v[46:49]
	v_mfma_f32_16x16x32_bf16 v[38:41], v[146:149], v[194:197], v[38:41]
	v_mfma_f32_16x16x32_bf16 v[30:33], v[154:157], v[194:197], v[30:33]
	v_mfma_f32_16x16x32_bf16 v[22:25], v[146:149], v[206:209], v[22:25]
	v_mfma_f32_16x16x32_bf16 v[14:17], v[154:157], v[206:209], v[14:17]
	v_mfma_f32_16x16x32_bf16 v[6:9], v[146:149], v[214:217], v[6:9]
	v_mfma_f32_16x16x32_bf16 v[2:5], v[154:157], v[214:217], v[2:5]
	v_mfma_f32_16x16x32_bf16 v[54:57], v[150:153], v[166:169], v[54:57]
	v_mfma_f32_16x16x32_bf16 v[46:49], v[158:161], v[166:169], v[46:49]
	v_mfma_f32_16x16x32_bf16 v[38:41], v[150:153], v[198:201], v[38:41]
	v_mfma_f32_16x16x32_bf16 v[30:33], v[158:161], v[198:201], v[30:33]
	v_mfma_f32_16x16x32_bf16 v[22:25], v[150:153], v[210:213], v[22:25]
	v_mfma_f32_16x16x32_bf16 v[14:17], v[158:161], v[210:213], v[14:17]
	v_mfma_f32_16x16x32_bf16 v[6:9], v[150:153], v[218:221], v[6:9]
	v_mfma_f32_16x16x32_bf16 v[2:5], v[158:161], v[218:221], v[2:5]
	s_setprio 0
	s_barrier
	s_add_u32 s76, s76, 0x100
	s_addc_u32 s77, s77, 0
	s_add_u32 s47, s47, 0x100
	s_addc_u32 s62, s62, 0
	s_cmp_ge_i32 s82, s7
	s_mov_b32 s63, s82
.LBB0_566:
	s_waitcnt vmcnt(0)
	ds_read_b128 v[114:117], v190
	ds_read_b128 v[118:121], v190 offset:1024
	ds_read_b128 v[122:125], v190 offset:2048
	ds_read_b128 v[126:129], v190 offset:3072
	ds_read_b128 v[146:149], v191
	ds_read_b128 v[150:153], v191 offset:1024
	ds_read_b128 v[154:157], v191 offset:2048
	ds_read_b128 v[158:161], v191 offset:3072
	s_add_i32 s82, s63, 2
	s_add_u32 s78, s76, 0xfffc0080
	s_addc_u32 s79, s77, -1
	s_cmp_eq_u32 s45, s63
	s_cselect_b32 s81, s31, s79
	s_cselect_b32 s80, s33, s78
	s_cselect_b32 s79, s34, s62
	s_cselect_b32 s78, s39, s47
	v_lshl_add_u64 v[186:187], s[76:77], 0, v[180:181]
	s_add_i32 m0, s87, 0xc000
	ds_read_b128 v[162:165], v192
	ds_read_b128 v[166:169], v192 offset:1024
	ds_read_b128 v[194:197], v192 offset:2048
	ds_read_b128 v[198:201], v192 offset:3072
	ds_read_b128 v[206:209], v192 offset:4096
	ds_read_b128 v[210:213], v192 offset:5120
	ds_read_b128 v[214:217], v192 offset:6144
	ds_read_b128 v[218:221], v192 offset:7168
	global_load_lds_dwordx4 v[186:187], off
	v_lshl_add_u64 v[186:187], s[76:77], 0, v[182:183]
	s_add_i32 m0, s87, 0xe000
	s_nop 0
	global_load_lds_dwordx4 v[186:187], off
	s_waitcnt vmcnt(8)
	s_waitcnt lgkmcnt(0)
	s_setprio 1
	s_barrier
	v_mfma_f32_16x16x32_bf16 v[142:145], v[114:117], v[162:165], v[142:145]
	v_mfma_f32_16x16x32_bf16 v[138:141], v[122:125], v[162:165], v[138:141]
	v_mfma_f32_16x16x32_bf16 v[110:113], v[114:117], v[194:197], v[110:113]
	v_mfma_f32_16x16x32_bf16 v[106:109], v[122:125], v[194:197], v[106:109]
	v_mfma_f32_16x16x32_bf16 v[98:101], v[114:117], v[206:209], v[98:101]
	v_mfma_f32_16x16x32_bf16 v[90:93], v[122:125], v[206:209], v[90:93]
	v_mfma_f32_16x16x32_bf16 v[82:85], v[114:117], v[214:217], v[82:85]
	v_mfma_f32_16x16x32_bf16 v[74:77], v[122:125], v[214:217], v[74:77]
	v_mfma_f32_16x16x32_bf16 v[142:145], v[118:121], v[166:169], v[142:145]
	v_mfma_f32_16x16x32_bf16 v[138:141], v[126:129], v[166:169], v[138:141]
	v_mfma_f32_16x16x32_bf16 v[110:113], v[118:121], v[198:201], v[110:113]
	v_mfma_f32_16x16x32_bf16 v[106:109], v[126:129], v[198:201], v[106:109]
	v_mfma_f32_16x16x32_bf16 v[98:101], v[118:121], v[210:213], v[98:101]
	v_mfma_f32_16x16x32_bf16 v[90:93], v[126:129], v[210:213], v[90:93]
	v_mfma_f32_16x16x32_bf16 v[82:85], v[118:121], v[218:221], v[82:85]
	v_mfma_f32_16x16x32_bf16 v[74:77], v[126:129], v[218:221], v[74:77]
	v_mfma_f32_16x16x32_bf16 v[134:137], v[146:149], v[162:165], v[134:137]
	v_mfma_f32_16x16x32_bf16 v[130:133], v[154:157], v[162:165], v[130:133]
	v_mfma_f32_16x16x32_bf16 v[102:105], v[146:149], v[194:197], v[102:105]
	v_mfma_f32_16x16x32_bf16 v[94:97], v[154:157], v[194:197], v[94:97]
	v_mfma_f32_16x16x32_bf16 v[86:89], v[146:149], v[206:209], v[86:89]
	v_mfma_f32_16x16x32_bf16 v[78:81], v[154:157], v[206:209], v[78:81]
	v_mfma_f32_16x16x32_bf16 v[70:73], v[146:149], v[214:217], v[70:73]
	v_mfma_f32_16x16x32_bf16 v[66:69], v[154:157], v[214:217], v[66:69]
	v_mfma_f32_16x16x32_bf16 v[134:137], v[150:153], v[166:169], v[134:137]
	v_mfma_f32_16x16x32_bf16 v[130:133], v[158:161], v[166:169], v[130:133]
	v_mfma_f32_16x16x32_bf16 v[102:105], v[150:153], v[198:201], v[102:105]
	v_mfma_f32_16x16x32_bf16 v[94:97], v[158:161], v[198:201], v[94:97]
	v_mfma_f32_16x16x32_bf16 v[86:89], v[150:153], v[210:213], v[86:89]
	v_mfma_f32_16x16x32_bf16 v[78:81], v[158:161], v[210:213], v[78:81]
	v_mfma_f32_16x16x32_bf16 v[70:73], v[150:153], v[218:221], v[70:73]
	v_mfma_f32_16x16x32_bf16 v[66:69], v[158:161], v[218:221], v[66:69]
	s_setprio 0
	s_barrier
	s_add_i32 s63, s24, s86
	v_lshl_add_u64 v[186:187], s[78:79], 0, v[172:173]
	s_mov_b32 m0, s63
	ds_read_b128 v[162:165], v192 offset:16384
	ds_read_b128 v[166:169], v192 offset:17408
	ds_read_b128 v[194:197], v192 offset:18432
	ds_read_b128 v[198:201], v192 offset:19456
	ds_read_b128 v[206:209], v192 offset:20480
	ds_read_b128 v[210:213], v192 offset:21504
	ds_read_b128 v[214:217], v192 offset:22528
	ds_read_b128 v[218:221], v192 offset:23552
	global_load_lds_dwordx4 v[186:187], off
	s_add_i32 m0, s63, 0x2000
	s_add_u32 vcc_lo, s78, 0x40000
	v_lshl_add_u64 v[202:203], s[78:79], 0, v[176:177]
	s_addc_u32 vcc_hi, s79, 0
	s_add_i32 s63, s25, s86
	global_load_lds_dwordx4 v[202:203], off
	v_lshl_add_u64 v[222:223], vcc, 0, v[172:173]
	s_mov_b32 m0, s63
	v_lshl_add_u64 v[224:225], s[80:81], 0, v[174:175]
	global_load_lds_dwordx4 v[222:223], off
	v_lshl_add_u64 v[222:223], vcc, 0, v[176:177]
	s_add_i32 m0, s63, 0x2000
	s_nop 0
	global_load_lds_dwordx4 v[222:223], off
	v_lshl_add_u64 v[222:223], s[80:81], 0, v[170:171]
	s_mov_b32 m0, s87
	s_nop 0
	global_load_lds_dwordx4 v[222:223], off
	s_mov_b32 m0, s88
	s_nop 0
	global_load_lds_dwordx4 v[224:225], off
	s_waitcnt vmcnt(8) lgkmcnt(0)
	s_setprio 1
	s_barrier
	v_mfma_f32_16x16x32_bf16 v[62:65], v[114:117], v[162:165], v[62:65]
	v_mfma_f32_16x16x32_bf16 v[58:61], v[122:125], v[162:165], v[58:61]
	v_mfma_f32_16x16x32_bf16 v[50:53], v[114:117], v[194:197], v[50:53]
	v_mfma_f32_16x16x32_bf16 v[42:45], v[122:125], v[194:197], v[42:45]
	v_mfma_f32_16x16x32_bf16 v[34:37], v[114:117], v[206:209], v[34:37]
	v_mfma_f32_16x16x32_bf16 v[26:29], v[122:125], v[206:209], v[26:29]
	v_mfma_f32_16x16x32_bf16 v[18:21], v[114:117], v[214:217], v[18:21]
	v_mfma_f32_16x16x32_bf16 v[10:13], v[122:125], v[214:217], v[10:13]
	v_mfma_f32_16x16x32_bf16 v[62:65], v[118:121], v[166:169], v[62:65]
	v_mfma_f32_16x16x32_bf16 v[58:61], v[126:129], v[166:169], v[58:61]
	v_mfma_f32_16x16x32_bf16 v[50:53], v[118:121], v[198:201], v[50:53]
	v_mfma_f32_16x16x32_bf16 v[42:45], v[126:129], v[198:201], v[42:45]
	v_mfma_f32_16x16x32_bf16 v[34:37], v[118:121], v[210:213], v[34:37]
	v_mfma_f32_16x16x32_bf16 v[26:29], v[126:129], v[210:213], v[26:29]
	v_mfma_f32_16x16x32_bf16 v[18:21], v[118:121], v[218:221], v[18:21]
	v_mfma_f32_16x16x32_bf16 v[10:13], v[126:129], v[218:221], v[10:13]
	v_mfma_f32_16x16x32_bf16 v[54:57], v[146:149], v[162:165], v[54:57]
	v_mfma_f32_16x16x32_bf16 v[46:49], v[154:157], v[162:165], v[46:49]
	v_mfma_f32_16x16x32_bf16 v[38:41], v[146:149], v[194:197], v[38:41]
	v_mfma_f32_16x16x32_bf16 v[30:33], v[154:157], v[194:197], v[30:33]
	v_mfma_f32_16x16x32_bf16 v[22:25], v[146:149], v[206:209], v[22:25]
	v_mfma_f32_16x16x32_bf16 v[14:17], v[154:157], v[206:209], v[14:17]
	v_mfma_f32_16x16x32_bf16 v[6:9], v[146:149], v[214:217], v[6:9]
	v_mfma_f32_16x16x32_bf16 v[2:5], v[154:157], v[214:217], v[2:5]
	v_mfma_f32_16x16x32_bf16 v[54:57], v[150:153], v[166:169], v[54:57]
	v_mfma_f32_16x16x32_bf16 v[46:49], v[158:161], v[166:169], v[46:49]
	v_mfma_f32_16x16x32_bf16 v[38:41], v[150:153], v[198:201], v[38:41]
	v_mfma_f32_16x16x32_bf16 v[30:33], v[158:161], v[198:201], v[30:33]
	v_mfma_f32_16x16x32_bf16 v[22:25], v[150:153], v[210:213], v[22:25]
	v_mfma_f32_16x16x32_bf16 v[14:17], v[158:161], v[210:213], v[14:17]
	v_mfma_f32_16x16x32_bf16 v[6:9], v[150:153], v[218:221], v[6:9]
	v_mfma_f32_16x16x32_bf16 v[2:5], v[158:161], v[218:221], v[2:5]
	s_setprio 0
	s_barrier
	s_add_i32 s63, 0, 0x18000
	s_add_i32 s83, 0, 0x1c000
	v_add_u32_e32 v126, s63, v189
	v_add_u32_e32 v158, s83, v189
	ds_read_b128 v[114:117], v126
	ds_read_b128 v[118:121], v126 offset:1024
	ds_read_b128 v[122:125], v126 offset:2048
	ds_read_b128 v[126:129], v126 offset:3072
	ds_read_b128 v[146:149], v158
	ds_read_b128 v[150:153], v158 offset:1024
	ds_read_b128 v[154:157], v158 offset:2048
	ds_read_b128 v[158:161], v158 offset:3072
	s_add_u32 s80, s80, 0x40000
	s_addc_u32 s81, s81, 0
	s_mov_b32 m0, s89
	v_lshl_add_u64 v[226:227], s[80:81], 0, v[170:171]
	ds_read_b128 v[162:165], v192 offset:32768
	ds_read_b128 v[166:169], v192 offset:33792
	ds_read_b128 v[194:197], v192 offset:34816
	ds_read_b128 v[198:201], v192 offset:35840
	ds_read_b128 v[206:209], v192 offset:36864
	ds_read_b128 v[210:213], v192 offset:37888
	ds_read_b128 v[214:217], v192 offset:38912
	ds_read_b128 v[218:221], v192 offset:39936
	global_load_lds_dwordx4 v[226:227], off
	v_lshl_add_u64 v[226:227], s[80:81], 0, v[174:175]
	s_mov_b32 m0, s90
	s_nop 0
	global_load_lds_dwordx4 v[226:227], off
	s_waitcnt vmcnt(8) lgkmcnt(0)
	s_setprio 1
	s_barrier
	v_mfma_f32_16x16x32_bf16 v[142:145], v[114:117], v[162:165], v[142:145]
	v_mfma_f32_16x16x32_bf16 v[138:141], v[122:125], v[162:165], v[138:141]
	v_mfma_f32_16x16x32_bf16 v[110:113], v[114:117], v[194:197], v[110:113]
	v_mfma_f32_16x16x32_bf16 v[106:109], v[122:125], v[194:197], v[106:109]
	v_mfma_f32_16x16x32_bf16 v[98:101], v[114:117], v[206:209], v[98:101]
	v_mfma_f32_16x16x32_bf16 v[90:93], v[122:125], v[206:209], v[90:93]
	v_mfma_f32_16x16x32_bf16 v[82:85], v[114:117], v[214:217], v[82:85]
	v_mfma_f32_16x16x32_bf16 v[74:77], v[122:125], v[214:217], v[74:77]
	v_mfma_f32_16x16x32_bf16 v[142:145], v[118:121], v[166:169], v[142:145]
	v_mfma_f32_16x16x32_bf16 v[138:141], v[126:129], v[166:169], v[138:141]
	v_mfma_f32_16x16x32_bf16 v[110:113], v[118:121], v[198:201], v[110:113]
	v_mfma_f32_16x16x32_bf16 v[106:109], v[126:129], v[198:201], v[106:109]
	v_mfma_f32_16x16x32_bf16 v[98:101], v[118:121], v[210:213], v[98:101]
	v_mfma_f32_16x16x32_bf16 v[90:93], v[126:129], v[210:213], v[90:93]
	v_mfma_f32_16x16x32_bf16 v[82:85], v[118:121], v[218:221], v[82:85]
	v_mfma_f32_16x16x32_bf16 v[74:77], v[126:129], v[218:221], v[74:77]
	v_mfma_f32_16x16x32_bf16 v[134:137], v[146:149], v[162:165], v[134:137]
	v_mfma_f32_16x16x32_bf16 v[130:133], v[154:157], v[162:165], v[130:133]
	v_mfma_f32_16x16x32_bf16 v[102:105], v[146:149], v[194:197], v[102:105]
	v_mfma_f32_16x16x32_bf16 v[94:97], v[154:157], v[194:197], v[94:97]
	v_mfma_f32_16x16x32_bf16 v[86:89], v[146:149], v[206:209], v[86:89]
	v_mfma_f32_16x16x32_bf16 v[78:81], v[154:157], v[206:209], v[78:81]
	v_mfma_f32_16x16x32_bf16 v[70:73], v[146:149], v[214:217], v[70:73]
	v_mfma_f32_16x16x32_bf16 v[66:69], v[154:157], v[214:217], v[66:69]
	v_mfma_f32_16x16x32_bf16 v[134:137], v[150:153], v[166:169], v[134:137]
	v_mfma_f32_16x16x32_bf16 v[130:133], v[158:161], v[166:169], v[130:133]
	v_mfma_f32_16x16x32_bf16 v[102:105], v[150:153], v[198:201], v[102:105]
	v_mfma_f32_16x16x32_bf16 v[94:97], v[158:161], v[198:201], v[94:97]
	v_mfma_f32_16x16x32_bf16 v[86:89], v[150:153], v[210:213], v[86:89]
	v_mfma_f32_16x16x32_bf16 v[78:81], v[158:161], v[210:213], v[78:81]
	v_mfma_f32_16x16x32_bf16 v[70:73], v[150:153], v[218:221], v[70:73]
	v_mfma_f32_16x16x32_bf16 v[66:69], v[158:161], v[218:221], v[66:69]
	s_setprio 0
	s_barrier
	s_add_i32 s63, s63, s86
	v_lshl_add_u64 v[186:187], v[186:187], 0, s[22:23]
	s_mov_b32 m0, s63
	ds_read_b128 v[162:165], v192 offset:49152
	ds_read_b128 v[166:169], v192 offset:50176
	ds_read_b128 v[194:197], v192 offset:51200
	ds_read_b128 v[198:201], v192 offset:52224
	ds_read_b128 v[206:209], v192 offset:53248
	ds_read_b128 v[210:213], v192 offset:54272
	ds_read_b128 v[214:217], v192 offset:55296
	ds_read_b128 v[218:221], v192 offset:56320
	global_load_lds_dwordx4 v[186:187], off
	s_add_i32 m0, s63, 0x2000
	s_add_u32 s78, s78, 0x40080
	v_lshl_add_u64 v[186:187], v[202:203], 0, s[22:23]
	s_addc_u32 s79, s79, 0
	s_add_i32 s63, s83, s86
	global_load_lds_dwordx4 v[186:187], off
	v_lshl_add_u64 v[186:187], s[78:79], 0, v[172:173]
	s_mov_b32 m0, s63
	s_nop 0
	global_load_lds_dwordx4 v[186:187], off
	v_lshl_add_u64 v[186:187], s[78:79], 0, v[176:177]
	s_add_i32 m0, s63, 0x2000
	s_nop 0
	global_load_lds_dwordx4 v[186:187], off
	v_lshl_add_u64 v[186:187], v[222:223], 0, s[22:23]
	s_mov_b32 m0, s95
	s_nop 0
	global_load_lds_dwordx4 v[186:187], off
	v_lshl_add_u64 v[186:187], v[224:225], 0, s[22:23]
	s_mov_b32 m0, s96
	s_nop 0
	global_load_lds_dwordx4 v[186:187], off
	s_waitcnt vmcnt(8) lgkmcnt(0)
	s_setprio 1
	s_barrier
	v_mfma_f32_16x16x32_bf16 v[62:65], v[114:117], v[162:165], v[62:65]
	v_mfma_f32_16x16x32_bf16 v[58:61], v[122:125], v[162:165], v[58:61]
	v_mfma_f32_16x16x32_bf16 v[50:53], v[114:117], v[194:197], v[50:53]
	v_mfma_f32_16x16x32_bf16 v[42:45], v[122:125], v[194:197], v[42:45]
	v_mfma_f32_16x16x32_bf16 v[34:37], v[114:117], v[206:209], v[34:37]
	v_mfma_f32_16x16x32_bf16 v[26:29], v[122:125], v[206:209], v[26:29]
	v_mfma_f32_16x16x32_bf16 v[18:21], v[114:117], v[214:217], v[18:21]
	v_mfma_f32_16x16x32_bf16 v[10:13], v[122:125], v[214:217], v[10:13]
	v_mfma_f32_16x16x32_bf16 v[62:65], v[118:121], v[166:169], v[62:65]
	v_mfma_f32_16x16x32_bf16 v[58:61], v[126:129], v[166:169], v[58:61]
	v_mfma_f32_16x16x32_bf16 v[50:53], v[118:121], v[198:201], v[50:53]
	v_mfma_f32_16x16x32_bf16 v[42:45], v[126:129], v[198:201], v[42:45]
	v_mfma_f32_16x16x32_bf16 v[34:37], v[118:121], v[210:213], v[34:37]
	v_mfma_f32_16x16x32_bf16 v[26:29], v[126:129], v[210:213], v[26:29]
	v_mfma_f32_16x16x32_bf16 v[18:21], v[118:121], v[218:221], v[18:21]
	v_mfma_f32_16x16x32_bf16 v[10:13], v[126:129], v[218:221], v[10:13]
	v_mfma_f32_16x16x32_bf16 v[54:57], v[146:149], v[162:165], v[54:57]
	v_mfma_f32_16x16x32_bf16 v[46:49], v[154:157], v[162:165], v[46:49]
	v_mfma_f32_16x16x32_bf16 v[38:41], v[146:149], v[194:197], v[38:41]
	v_mfma_f32_16x16x32_bf16 v[30:33], v[154:157], v[194:197], v[30:33]
	v_mfma_f32_16x16x32_bf16 v[22:25], v[146:149], v[206:209], v[22:25]
	v_mfma_f32_16x16x32_bf16 v[14:17], v[154:157], v[206:209], v[14:17]
	v_mfma_f32_16x16x32_bf16 v[6:9], v[146:149], v[214:217], v[6:9]
	v_mfma_f32_16x16x32_bf16 v[2:5], v[154:157], v[214:217], v[2:5]
	v_mfma_f32_16x16x32_bf16 v[54:57], v[150:153], v[166:169], v[54:57]
	v_mfma_f32_16x16x32_bf16 v[46:49], v[158:161], v[166:169], v[46:49]
	v_mfma_f32_16x16x32_bf16 v[38:41], v[150:153], v[198:201], v[38:41]
	v_mfma_f32_16x16x32_bf16 v[30:33], v[158:161], v[198:201], v[30:33]
	v_mfma_f32_16x16x32_bf16 v[22:25], v[150:153], v[210:213], v[22:25]
	v_mfma_f32_16x16x32_bf16 v[14:17], v[158:161], v[210:213], v[14:17]
	v_mfma_f32_16x16x32_bf16 v[6:9], v[150:153], v[218:221], v[6:9]
	v_mfma_f32_16x16x32_bf16 v[2:5], v[158:161], v[218:221], v[2:5]
	s_setprio 0
	s_barrier
	s_add_u32 s76, s76, 0x100
	s_addc_u32 s77, s77, 0
	s_add_u32 s47, s47, 0x100
	s_addc_u32 s62, s62, 0
	s_cmp_ge_i32 s82, s7
	s_mov_b32 s63, s82
	s_cbranch_scc0 .LBB0_566
	s_and_b64 vcc, exec, s[26:27]
	s_cbranch_vccz .LBB0_569
	s_barrier

.LBB0_744:
	s_add_u32 s36, s96, s22
	s_addc_u32 s37, s97, s23
	s_and_b64 s[14:15], s[4:5], exec
	s_cselect_b32 s14, s37, s43
	s_cselect_b32 s15, s36, s42
	s_add_u32 s38, s2, s26
	s_addc_u32 s39, s3, s27
	s_and_b64 s[46:47], s[4:5], exec
	s_cselect_b32 s21, s39, s45
	s_cselect_b32 s65, s38, s44
	s_add_u32 s42, s42, 0x40080
	s_addc_u32 s43, s43, 0
	s_add_u32 s66, s44, 0x100
	s_addc_u32 s67, s45, 0
	s_mov_b32 s68, -2
	ds_read_b128 v[154:157], v150
	ds_read_b128 v[158:161], v150 offset:1024
	ds_read_b128 v[162:165], v150 offset:2048
	ds_read_b128 v[166:169], v150 offset:3072
	ds_read_b128 v[170:173], v151
	ds_read_b128 v[174:177], v151 offset:1024
	ds_read_b128 v[178:181], v151 offset:2048
	ds_read_b128 v[182:185], v151 offset:3072
	s_add_u32 s44, s42, 0xfffc0080
	s_addc_u32 s45, s43, -1
	s_cmp_eq_u32 s68, 12
	s_cselect_b32 s47, s14, s45
	s_cselect_b32 s46, s15, s44
	s_cselect_b32 s45, s21, s67
	s_cselect_b32 s44, s65, s66
	v_lshl_add_u64 v[146:147], s[42:43], 0, v[138:139]
	s_add_i32 m0, s19, 0xc000
	ds_read_b128 v[186:189], v152
	ds_read_b128 v[190:193], v152 offset:1024
	ds_read_b128 v[194:197], v152 offset:2048
	ds_read_b128 v[198:201], v152 offset:3072
	ds_read_b128 v[206:209], v152 offset:4096
	ds_read_b128 v[210:213], v152 offset:5120
	ds_read_b128 v[214:217], v152 offset:6144
	ds_read_b128 v[218:221], v152 offset:7168
	global_load_lds_dwordx4 v[146:147], off
	v_lshl_add_u64 v[146:147], s[42:43], 0, v[140:141]
	s_add_i32 m0, s19, 0xe000
	s_nop 0
	global_load_lds_dwordx4 v[146:147], off
	s_waitcnt vmcnt(8) lgkmcnt(0)
	s_setprio 1
	s_barrier
	v_mfma_f32_16x16x32_bf16 v[126:129], v[154:157], v[186:189], 0
	v_mfma_f32_16x16x32_bf16 v[122:125], v[162:165], v[186:189], 0
	v_mfma_f32_16x16x32_bf16 v[110:113], v[154:157], v[194:197], 0
	v_mfma_f32_16x16x32_bf16 v[106:109], v[162:165], v[194:197], 0
	v_mfma_f32_16x16x32_bf16 v[94:97], v[154:157], v[206:209], 0
	v_mfma_f32_16x16x32_bf16 v[90:93], v[162:165], v[206:209], 0
	v_mfma_f32_16x16x32_bf16 v[78:81], v[154:157], v[214:217], 0
	v_mfma_f32_16x16x32_bf16 v[74:77], v[162:165], v[214:217], 0
	v_mfma_f32_16x16x32_bf16 v[126:129], v[158:161], v[190:193], v[126:129]
	v_mfma_f32_16x16x32_bf16 v[122:125], v[166:169], v[190:193], v[122:125]
	v_mfma_f32_16x16x32_bf16 v[110:113], v[158:161], v[198:201], v[110:113]
	v_mfma_f32_16x16x32_bf16 v[106:109], v[166:169], v[198:201], v[106:109]
	v_mfma_f32_16x16x32_bf16 v[94:97], v[158:161], v[210:213], v[94:97]
	v_mfma_f32_16x16x32_bf16 v[90:93], v[166:169], v[210:213], v[90:93]
	v_mfma_f32_16x16x32_bf16 v[78:81], v[158:161], v[218:221], v[78:81]
	v_mfma_f32_16x16x32_bf16 v[74:77], v[166:169], v[218:221], v[74:77]
	v_mfma_f32_16x16x32_bf16 v[118:121], v[170:173], v[186:189], 0
	v_mfma_f32_16x16x32_bf16 v[114:117], v[178:181], v[186:189], 0
	v_mfma_f32_16x16x32_bf16 v[102:105], v[170:173], v[194:197], 0
	v_mfma_f32_16x16x32_bf16 v[98:101], v[178:181], v[194:197], 0
	v_mfma_f32_16x16x32_bf16 v[86:89], v[170:173], v[206:209], 0
	v_mfma_f32_16x16x32_bf16 v[82:85], v[178:181], v[206:209], 0
	v_mfma_f32_16x16x32_bf16 v[70:73], v[170:173], v[214:217], 0
	v_mfma_f32_16x16x32_bf16 v[66:69], v[178:181], v[214:217], 0
	v_mfma_f32_16x16x32_bf16 v[118:121], v[174:177], v[190:193], v[118:121]
	v_mfma_f32_16x16x32_bf16 v[114:117], v[182:185], v[190:193], v[114:117]
	v_mfma_f32_16x16x32_bf16 v[102:105], v[174:177], v[198:201], v[102:105]
	v_mfma_f32_16x16x32_bf16 v[98:101], v[182:185], v[198:201], v[98:101]
	v_mfma_f32_16x16x32_bf16 v[86:89], v[174:177], v[210:213], v[86:89]
	v_mfma_f32_16x16x32_bf16 v[82:85], v[182:185], v[210:213], v[82:85]
	v_mfma_f32_16x16x32_bf16 v[70:73], v[174:177], v[218:221], v[70:73]
	v_mfma_f32_16x16x32_bf16 v[66:69], v[182:185], v[218:221], v[66:69]
	s_setprio 0
	s_barrier
	s_add_i32 s69, s49, s16
	v_lshl_add_u64 v[146:147], s[44:45], 0, v[134:135]
	s_mov_b32 m0, s69
	ds_read_b128 v[186:189], v152 offset:16384
	ds_read_b128 v[190:193], v152 offset:17408
	ds_read_b128 v[194:197], v152 offset:18432
	ds_read_b128 v[198:201], v152 offset:19456
	ds_read_b128 v[206:209], v152 offset:20480
	ds_read_b128 v[210:213], v152 offset:21504
	ds_read_b128 v[214:217], v152 offset:22528
	ds_read_b128 v[218:221], v152 offset:23552
	global_load_lds_dwordx4 v[146:147], off
	s_add_i32 m0, s69, 0x2000
	s_add_u32 s70, s44, 0x40000
	v_lshl_add_u64 v[202:203], s[44:45], 0, v[130:131]
	s_addc_u32 s71, s45, 0
	s_add_i32 s69, s62, s16
	global_load_lds_dwordx4 v[202:203], off
	v_lshl_add_u64 v[222:223], s[70:71], 0, v[134:135]
	s_mov_b32 m0, s69
	v_lshl_add_u64 v[224:225], s[46:47], 0, v[132:133]
	global_load_lds_dwordx4 v[222:223], off
	v_lshl_add_u64 v[222:223], s[70:71], 0, v[130:131]
	s_add_i32 m0, s69, 0x2000
	s_nop 0
	global_load_lds_dwordx4 v[222:223], off
	v_lshl_add_u64 v[222:223], s[46:47], 0, v[136:137]
	s_mov_b32 m0, s19
	s_nop 0
	global_load_lds_dwordx4 v[222:223], off
	s_mov_b32 m0, s24
	s_nop 0
	global_load_lds_dwordx4 v[224:225], off
	s_waitcnt vmcnt(8) lgkmcnt(0)
	s_setprio 1
	s_barrier
	v_mfma_f32_16x16x32_bf16 v[62:65], v[154:157], v[186:189], 0
	v_mfma_f32_16x16x32_bf16 v[58:61], v[162:165], v[186:189], 0
	v_mfma_f32_16x16x32_bf16 v[46:49], v[154:157], v[194:197], 0
	v_mfma_f32_16x16x32_bf16 v[42:45], v[162:165], v[194:197], 0
	v_mfma_f32_16x16x32_bf16 v[30:33], v[154:157], v[206:209], 0
	v_mfma_f32_16x16x32_bf16 v[26:29], v[162:165], v[206:209], 0
	v_mfma_f32_16x16x32_bf16 v[14:17], v[154:157], v[214:217], 0
	v_mfma_f32_16x16x32_bf16 v[10:13], v[162:165], v[214:217], 0
	v_mfma_f32_16x16x32_bf16 v[62:65], v[158:161], v[190:193], v[62:65]
	v_mfma_f32_16x16x32_bf16 v[58:61], v[166:169], v[190:193], v[58:61]
	v_mfma_f32_16x16x32_bf16 v[46:49], v[158:161], v[198:201], v[46:49]
	v_mfma_f32_16x16x32_bf16 v[42:45], v[166:169], v[198:201], v[42:45]
	v_mfma_f32_16x16x32_bf16 v[30:33], v[158:161], v[210:213], v[30:33]
	v_mfma_f32_16x16x32_bf16 v[26:29], v[166:169], v[210:213], v[26:29]
	v_mfma_f32_16x16x32_bf16 v[14:17], v[158:161], v[218:221], v[14:17]
	v_mfma_f32_16x16x32_bf16 v[10:13], v[166:169], v[218:221], v[10:13]
	v_mfma_f32_16x16x32_bf16 v[54:57], v[170:173], v[186:189], 0
	v_mfma_f32_16x16x32_bf16 v[50:53], v[178:181], v[186:189], 0
	v_mfma_f32_16x16x32_bf16 v[38:41], v[170:173], v[194:197], 0
	v_mfma_f32_16x16x32_bf16 v[34:37], v[178:181], v[194:197], 0
	v_mfma_f32_16x16x32_bf16 v[22:25], v[170:173], v[206:209], 0
	v_mfma_f32_16x16x32_bf16 v[18:21], v[178:181], v[206:209], 0
	v_mfma_f32_16x16x32_bf16 v[6:9], v[170:173], v[214:217], 0
	v_mfma_f32_16x16x32_bf16 v[2:5], v[178:181], v[214:217], 0
	v_mfma_f32_16x16x32_bf16 v[54:57], v[174:177], v[190:193], v[54:57]
	v_mfma_f32_16x16x32_bf16 v[50:53], v[182:185], v[190:193], v[50:53]
	v_mfma_f32_16x16x32_bf16 v[38:41], v[174:177], v[198:201], v[38:41]
	v_mfma_f32_16x16x32_bf16 v[34:37], v[182:185], v[198:201], v[34:37]
	v_mfma_f32_16x16x32_bf16 v[22:25], v[174:177], v[210:213], v[22:25]
	v_mfma_f32_16x16x32_bf16 v[18:21], v[182:185], v[210:213], v[18:21]
	v_mfma_f32_16x16x32_bf16 v[6:9], v[174:177], v[218:221], v[6:9]
	v_mfma_f32_16x16x32_bf16 v[2:5], v[182:185], v[218:221], v[2:5]
	s_setprio 0
	s_barrier
	s_add_i32 s69, 0, 0x18000
	v_add_u32_e32 v153, s69, v149
	s_add_i32 s70, 0, 0x1c000
	ds_read_b128 v[154:157], v153
	ds_read_b128 v[158:161], v153 offset:1024
	ds_read_b128 v[162:165], v153 offset:2048
	ds_read_b128 v[166:169], v153 offset:3072
	v_add_u32_e32 v153, s70, v149
	ds_read_b128 v[170:173], v153
	ds_read_b128 v[174:177], v153 offset:1024
	ds_read_b128 v[178:181], v153 offset:2048
	ds_read_b128 v[182:185], v153 offset:3072
	s_add_u32 s46, s46, 0x40000
	s_addc_u32 s47, s47, 0
	s_mov_b32 m0, s25
	v_lshl_add_u64 v[226:227], s[46:47], 0, v[136:137]
	ds_read_b128 v[186:189], v152 offset:32768
	ds_read_b128 v[190:193], v152 offset:33792
	ds_read_b128 v[194:197], v152 offset:34816
	ds_read_b128 v[198:201], v152 offset:35840
	ds_read_b128 v[206:209], v152 offset:36864
	ds_read_b128 v[210:213], v152 offset:37888
	ds_read_b128 v[214:217], v152 offset:38912
	ds_read_b128 v[218:221], v152 offset:39936
	global_load_lds_dwordx4 v[226:227], off
	v_lshl_add_u64 v[226:227], s[46:47], 0, v[132:133]
	s_mov_b32 m0, s28
	s_nop 0
	global_load_lds_dwordx4 v[226:227], off
	s_waitcnt vmcnt(8) lgkmcnt(0)
	s_setprio 1
	s_barrier
	v_mfma_f32_16x16x32_bf16 v[126:129], v[154:157], v[186:189], v[126:129]
	v_mfma_f32_16x16x32_bf16 v[122:125], v[162:165], v[186:189], v[122:125]
	v_mfma_f32_16x16x32_bf16 v[110:113], v[154:157], v[194:197], v[110:113]
	v_mfma_f32_16x16x32_bf16 v[106:109], v[162:165], v[194:197], v[106:109]
	v_mfma_f32_16x16x32_bf16 v[94:97], v[154:157], v[206:209], v[94:97]
	v_mfma_f32_16x16x32_bf16 v[90:93], v[162:165], v[206:209], v[90:93]
	v_mfma_f32_16x16x32_bf16 v[78:81], v[154:157], v[214:217], v[78:81]
	v_mfma_f32_16x16x32_bf16 v[74:77], v[162:165], v[214:217], v[74:77]
	v_mfma_f32_16x16x32_bf16 v[126:129], v[158:161], v[190:193], v[126:129]
	v_mfma_f32_16x16x32_bf16 v[122:125], v[166:169], v[190:193], v[122:125]
	v_mfma_f32_16x16x32_bf16 v[110:113], v[158:161], v[198:201], v[110:113]
	v_mfma_f32_16x16x32_bf16 v[106:109], v[166:169], v[198:201], v[106:109]
	v_mfma_f32_16x16x32_bf16 v[94:97], v[158:161], v[210:213], v[94:97]
	v_mfma_f32_16x16x32_bf16 v[90:93], v[166:169], v[210:213], v[90:93]
	v_mfma_f32_16x16x32_bf16 v[78:81], v[158:161], v[218:221], v[78:81]
	v_mfma_f32_16x16x32_bf16 v[74:77], v[166:169], v[218:221], v[74:77]
	v_mfma_f32_16x16x32_bf16 v[118:121], v[170:173], v[186:189], v[118:121]
	v_mfma_f32_16x16x32_bf16 v[114:117], v[178:181], v[186:189], v[114:117]
	v_mfma_f32_16x16x32_bf16 v[102:105], v[170:173], v[194:197], v[102:105]
	v_mfma_f32_16x16x32_bf16 v[98:101], v[178:181], v[194:197], v[98:101]
	v_mfma_f32_16x16x32_bf16 v[86:89], v[170:173], v[206:209], v[86:89]
	v_mfma_f32_16x16x32_bf16 v[82:85], v[178:181], v[206:209], v[82:85]
	v_mfma_f32_16x16x32_bf16 v[70:73], v[170:173], v[214:217], v[70:73]
	v_mfma_f32_16x16x32_bf16 v[66:69], v[178:181], v[214:217], v[66:69]
	v_mfma_f32_16x16x32_bf16 v[118:121], v[174:177], v[190:193], v[118:121]
	v_mfma_f32_16x16x32_bf16 v[114:117], v[182:185], v[190:193], v[114:117]
	v_mfma_f32_16x16x32_bf16 v[102:105], v[174:177], v[198:201], v[102:105]
	v_mfma_f32_16x16x32_bf16 v[98:101], v[182:185], v[198:201], v[98:101]
	v_mfma_f32_16x16x32_bf16 v[86:89], v[174:177], v[210:213], v[86:89]
	v_mfma_f32_16x16x32_bf16 v[82:85], v[182:185], v[210:213], v[82:85]
	v_mfma_f32_16x16x32_bf16 v[70:73], v[174:177], v[218:221], v[70:73]
	v_mfma_f32_16x16x32_bf16 v[66:69], v[182:185], v[218:221], v[66:69]
	s_setprio 0
	s_barrier
	s_add_i32 s46, s69, s16
	v_lshl_add_u64 v[146:147], v[146:147], 0, s[10:11]
	s_mov_b32 m0, s46
	ds_read_b128 v[186:189], v152 offset:49152
	ds_read_b128 v[190:193], v152 offset:50176
	ds_read_b128 v[194:197], v152 offset:51200
	ds_read_b128 v[198:201], v152 offset:52224
	ds_read_b128 v[206:209], v152 offset:53248
	ds_read_b128 v[210:213], v152 offset:54272
	ds_read_b128 v[214:217], v152 offset:55296
	ds_read_b128 v[218:221], v152 offset:56320
	global_load_lds_dwordx4 v[146:147], off
	s_add_i32 m0, s46, 0x2000
	s_add_u32 s44, s44, 0x40080
	v_lshl_add_u64 v[146:147], v[202:203], 0, s[10:11]
	s_addc_u32 s45, s45, 0
	s_add_i32 s46, s70, s16
	global_load_lds_dwordx4 v[146:147], off
	v_lshl_add_u64 v[146:147], s[44:45], 0, v[134:135]
	s_mov_b32 m0, s46
	s_nop 0
	global_load_lds_dwordx4 v[146:147], off
	v_lshl_add_u64 v[146:147], s[44:45], 0, v[130:131]
	s_add_i32 m0, s46, 0x2000
	s_nop 0
	global_load_lds_dwordx4 v[146:147], off
	v_lshl_add_u64 v[146:147], v[222:223], 0, s[10:11]
	s_mov_b32 m0, s33
	s_nop 0
	global_load_lds_dwordx4 v[146:147], off
	v_lshl_add_u64 v[146:147], v[224:225], 0, s[10:11]
	s_mov_b32 m0, s35
	s_nop 0
	global_load_lds_dwordx4 v[146:147], off
	s_waitcnt vmcnt(8) lgkmcnt(0)
	s_setprio 1
	s_barrier
	v_mfma_f32_16x16x32_bf16 v[62:65], v[154:157], v[186:189], v[62:65]
	v_mfma_f32_16x16x32_bf16 v[58:61], v[162:165], v[186:189], v[58:61]
	v_mfma_f32_16x16x32_bf16 v[46:49], v[154:157], v[194:197], v[46:49]
	v_mfma_f32_16x16x32_bf16 v[42:45], v[162:165], v[194:197], v[42:45]
	v_mfma_f32_16x16x32_bf16 v[30:33], v[154:157], v[206:209], v[30:33]
	v_mfma_f32_16x16x32_bf16 v[26:29], v[162:165], v[206:209], v[26:29]
	v_mfma_f32_16x16x32_bf16 v[14:17], v[154:157], v[214:217], v[14:17]
	v_mfma_f32_16x16x32_bf16 v[10:13], v[162:165], v[214:217], v[10:13]
	v_mfma_f32_16x16x32_bf16 v[62:65], v[158:161], v[190:193], v[62:65]
	v_mfma_f32_16x16x32_bf16 v[58:61], v[166:169], v[190:193], v[58:61]
	v_mfma_f32_16x16x32_bf16 v[46:49], v[158:161], v[198:201], v[46:49]
	v_mfma_f32_16x16x32_bf16 v[42:45], v[166:169], v[198:201], v[42:45]
	v_mfma_f32_16x16x32_bf16 v[30:33], v[158:161], v[210:213], v[30:33]
	v_mfma_f32_16x16x32_bf16 v[26:29], v[166:169], v[210:213], v[26:29]
	v_mfma_f32_16x16x32_bf16 v[14:17], v[158:161], v[218:221], v[14:17]
	v_mfma_f32_16x16x32_bf16 v[10:13], v[166:169], v[218:221], v[10:13]
	v_mfma_f32_16x16x32_bf16 v[54:57], v[170:173], v[186:189], v[54:57]
	v_mfma_f32_16x16x32_bf16 v[50:53], v[178:181], v[186:189], v[50:53]
	v_mfma_f32_16x16x32_bf16 v[38:41], v[170:173], v[194:197], v[38:41]
	v_mfma_f32_16x16x32_bf16 v[34:37], v[178:181], v[194:197], v[34:37]
	v_mfma_f32_16x16x32_bf16 v[22:25], v[170:173], v[206:209], v[22:25]
	v_mfma_f32_16x16x32_bf16 v[18:21], v[178:181], v[206:209], v[18:21]
	v_mfma_f32_16x16x32_bf16 v[6:9], v[170:173], v[214:217], v[6:9]
	v_mfma_f32_16x16x32_bf16 v[2:5], v[178:181], v[214:217], v[2:5]
	v_mfma_f32_16x16x32_bf16 v[54:57], v[174:177], v[190:193], v[54:57]
	v_mfma_f32_16x16x32_bf16 v[50:53], v[182:185], v[190:193], v[50:53]
	v_mfma_f32_16x16x32_bf16 v[38:41], v[174:177], v[198:201], v[38:41]
	v_mfma_f32_16x16x32_bf16 v[34:37], v[182:185], v[198:201], v[34:37]
	v_mfma_f32_16x16x32_bf16 v[22:25], v[174:177], v[210:213], v[22:25]
	v_mfma_f32_16x16x32_bf16 v[18:21], v[182:185], v[210:213], v[18:21]
	v_mfma_f32_16x16x32_bf16 v[6:9], v[174:177], v[218:221], v[6:9]
	v_mfma_f32_16x16x32_bf16 v[2:5], v[182:185], v[218:221], v[2:5]
	s_setprio 0
	s_barrier
	s_add_i32 s68, s68, 2
	s_add_u32 s42, s42, 0x100
	s_addc_u32 s43, s43, 0
	s_add_u32 s66, s66, 0x100
	s_addc_u32 s67, s67, 0
	s_cmp_gt_u32 s68, 13
.LBB0_745:
	ds_read_b128 v[154:157], v150
	ds_read_b128 v[158:161], v150 offset:1024
	ds_read_b128 v[162:165], v150 offset:2048
	ds_read_b128 v[166:169], v150 offset:3072
	ds_read_b128 v[170:173], v151
	ds_read_b128 v[174:177], v151 offset:1024
	ds_read_b128 v[178:181], v151 offset:2048
	ds_read_b128 v[182:185], v151 offset:3072
	s_add_u32 s44, s42, 0xfffc0080
	s_addc_u32 s45, s43, -1
	s_cmp_eq_u32 s68, 12
	s_cselect_b32 s47, s14, s45
	s_cselect_b32 s46, s15, s44
	s_cselect_b32 s45, s21, s67
	s_cselect_b32 s44, s65, s66
	v_lshl_add_u64 v[146:147], s[42:43], 0, v[138:139]
	s_add_i32 m0, s19, 0xc000
	ds_read_b128 v[186:189], v152
	ds_read_b128 v[190:193], v152 offset:1024
	ds_read_b128 v[194:197], v152 offset:2048
	ds_read_b128 v[198:201], v152 offset:3072
	ds_read_b128 v[206:209], v152 offset:4096
	ds_read_b128 v[210:213], v152 offset:5120
	ds_read_b128 v[214:217], v152 offset:6144
	ds_read_b128 v[218:221], v152 offset:7168
	global_load_lds_dwordx4 v[146:147], off
	v_lshl_add_u64 v[146:147], s[42:43], 0, v[140:141]
	s_add_i32 m0, s19, 0xe000
	s_nop 0
	global_load_lds_dwordx4 v[146:147], off
	s_waitcnt vmcnt(8) lgkmcnt(0)
	s_setprio 1
	s_barrier
	v_mfma_f32_16x16x32_bf16 v[126:129], v[154:157], v[186:189], v[126:129]
	v_mfma_f32_16x16x32_bf16 v[122:125], v[162:165], v[186:189], v[122:125]
	v_mfma_f32_16x16x32_bf16 v[110:113], v[154:157], v[194:197], v[110:113]
	v_mfma_f32_16x16x32_bf16 v[106:109], v[162:165], v[194:197], v[106:109]
	v_mfma_f32_16x16x32_bf16 v[94:97], v[154:157], v[206:209], v[94:97]
	v_mfma_f32_16x16x32_bf16 v[90:93], v[162:165], v[206:209], v[90:93]
	v_mfma_f32_16x16x32_bf16 v[78:81], v[154:157], v[214:217], v[78:81]
	v_mfma_f32_16x16x32_bf16 v[74:77], v[162:165], v[214:217], v[74:77]
	v_mfma_f32_16x16x32_bf16 v[126:129], v[158:161], v[190:193], v[126:129]
	v_mfma_f32_16x16x32_bf16 v[122:125], v[166:169], v[190:193], v[122:125]
	v_mfma_f32_16x16x32_bf16 v[110:113], v[158:161], v[198:201], v[110:113]
	v_mfma_f32_16x16x32_bf16 v[106:109], v[166:169], v[198:201], v[106:109]
	v_mfma_f32_16x16x32_bf16 v[94:97], v[158:161], v[210:213], v[94:97]
	v_mfma_f32_16x16x32_bf16 v[90:93], v[166:169], v[210:213], v[90:93]
	v_mfma_f32_16x16x32_bf16 v[78:81], v[158:161], v[218:221], v[78:81]
	v_mfma_f32_16x16x32_bf16 v[74:77], v[166:169], v[218:221], v[74:77]
	v_mfma_f32_16x16x32_bf16 v[118:121], v[170:173], v[186:189], v[118:121]
	v_mfma_f32_16x16x32_bf16 v[114:117], v[178:181], v[186:189], v[114:117]
	v_mfma_f32_16x16x32_bf16 v[102:105], v[170:173], v[194:197], v[102:105]
	v_mfma_f32_16x16x32_bf16 v[98:101], v[178:181], v[194:197], v[98:101]
	v_mfma_f32_16x16x32_bf16 v[86:89], v[170:173], v[206:209], v[86:89]
	v_mfma_f32_16x16x32_bf16 v[82:85], v[178:181], v[206:209], v[82:85]
	v_mfma_f32_16x16x32_bf16 v[70:73], v[170:173], v[214:217], v[70:73]
	v_mfma_f32_16x16x32_bf16 v[66:69], v[178:181], v[214:217], v[66:69]
	v_mfma_f32_16x16x32_bf16 v[118:121], v[174:177], v[190:193], v[118:121]
	v_mfma_f32_16x16x32_bf16 v[114:117], v[182:185], v[190:193], v[114:117]
	v_mfma_f32_16x16x32_bf16 v[102:105], v[174:177], v[198:201], v[102:105]
	v_mfma_f32_16x16x32_bf16 v[98:101], v[182:185], v[198:201], v[98:101]
	v_mfma_f32_16x16x32_bf16 v[86:89], v[174:177], v[210:213], v[86:89]
	v_mfma_f32_16x16x32_bf16 v[82:85], v[182:185], v[210:213], v[82:85]
	v_mfma_f32_16x16x32_bf16 v[70:73], v[174:177], v[218:221], v[70:73]
	v_mfma_f32_16x16x32_bf16 v[66:69], v[182:185], v[218:221], v[66:69]
	s_setprio 0
	s_barrier
	s_add_i32 s69, s49, s16
	v_lshl_add_u64 v[146:147], s[44:45], 0, v[134:135]
	s_mov_b32 m0, s69
	ds_read_b128 v[186:189], v152 offset:16384
	ds_read_b128 v[190:193], v152 offset:17408
	ds_read_b128 v[194:197], v152 offset:18432
	ds_read_b128 v[198:201], v152 offset:19456
	ds_read_b128 v[206:209], v152 offset:20480
	ds_read_b128 v[210:213], v152 offset:21504
	ds_read_b128 v[214:217], v152 offset:22528
	ds_read_b128 v[218:221], v152 offset:23552
	global_load_lds_dwordx4 v[146:147], off
	s_add_i32 m0, s69, 0x2000
	s_add_u32 s70, s44, 0x40000
	v_lshl_add_u64 v[202:203], s[44:45], 0, v[130:131]
	s_addc_u32 s71, s45, 0
	s_add_i32 s69, s62, s16
	global_load_lds_dwordx4 v[202:203], off
	v_lshl_add_u64 v[222:223], s[70:71], 0, v[134:135]
	s_mov_b32 m0, s69
	v_lshl_add_u64 v[224:225], s[46:47], 0, v[132:133]
	global_load_lds_dwordx4 v[222:223], off
	v_lshl_add_u64 v[222:223], s[70:71], 0, v[130:131]
	s_add_i32 m0, s69, 0x2000
	s_nop 0
	global_load_lds_dwordx4 v[222:223], off
	v_lshl_add_u64 v[222:223], s[46:47], 0, v[136:137]
	s_mov_b32 m0, s19
	s_nop 0
	global_load_lds_dwordx4 v[222:223], off
	s_mov_b32 m0, s24
	s_nop 0
	global_load_lds_dwordx4 v[224:225], off
	s_waitcnt vmcnt(8) lgkmcnt(0)
	s_setprio 1
	s_barrier
	v_mfma_f32_16x16x32_bf16 v[62:65], v[154:157], v[186:189], v[62:65]
	v_mfma_f32_16x16x32_bf16 v[58:61], v[162:165], v[186:189], v[58:61]
	v_mfma_f32_16x16x32_bf16 v[46:49], v[154:157], v[194:197], v[46:49]
	v_mfma_f32_16x16x32_bf16 v[42:45], v[162:165], v[194:197], v[42:45]
	v_mfma_f32_16x16x32_bf16 v[30:33], v[154:157], v[206:209], v[30:33]
	v_mfma_f32_16x16x32_bf16 v[26:29], v[162:165], v[206:209], v[26:29]
	v_mfma_f32_16x16x32_bf16 v[14:17], v[154:157], v[214:217], v[14:17]
	v_mfma_f32_16x16x32_bf16 v[10:13], v[162:165], v[214:217], v[10:13]
	v_mfma_f32_16x16x32_bf16 v[62:65], v[158:161], v[190:193], v[62:65]
	v_mfma_f32_16x16x32_bf16 v[58:61], v[166:169], v[190:193], v[58:61]
	v_mfma_f32_16x16x32_bf16 v[46:49], v[158:161], v[198:201], v[46:49]
	v_mfma_f32_16x16x32_bf16 v[42:45], v[166:169], v[198:201], v[42:45]
	v_mfma_f32_16x16x32_bf16 v[30:33], v[158:161], v[210:213], v[30:33]
	v_mfma_f32_16x16x32_bf16 v[26:29], v[166:169], v[210:213], v[26:29]
	v_mfma_f32_16x16x32_bf16 v[14:17], v[158:161], v[218:221], v[14:17]
	v_mfma_f32_16x16x32_bf16 v[10:13], v[166:169], v[218:221], v[10:13]
	v_mfma_f32_16x16x32_bf16 v[54:57], v[170:173], v[186:189], v[54:57]
	v_mfma_f32_16x16x32_bf16 v[50:53], v[178:181], v[186:189], v[50:53]
	v_mfma_f32_16x16x32_bf16 v[38:41], v[170:173], v[194:197], v[38:41]
	v_mfma_f32_16x16x32_bf16 v[34:37], v[178:181], v[194:197], v[34:37]
	v_mfma_f32_16x16x32_bf16 v[22:25], v[170:173], v[206:209], v[22:25]
	v_mfma_f32_16x16x32_bf16 v[18:21], v[178:181], v[206:209], v[18:21]
	v_mfma_f32_16x16x32_bf16 v[6:9], v[170:173], v[214:217], v[6:9]
	v_mfma_f32_16x16x32_bf16 v[2:5], v[178:181], v[214:217], v[2:5]
	v_mfma_f32_16x16x32_bf16 v[54:57], v[174:177], v[190:193], v[54:57]
	v_mfma_f32_16x16x32_bf16 v[50:53], v[182:185], v[190:193], v[50:53]
	v_mfma_f32_16x16x32_bf16 v[38:41], v[174:177], v[198:201], v[38:41]
	v_mfma_f32_16x16x32_bf16 v[34:37], v[182:185], v[198:201], v[34:37]
	v_mfma_f32_16x16x32_bf16 v[22:25], v[174:177], v[210:213], v[22:25]
	v_mfma_f32_16x16x32_bf16 v[18:21], v[182:185], v[210:213], v[18:21]
	v_mfma_f32_16x16x32_bf16 v[6:9], v[174:177], v[218:221], v[6:9]
	v_mfma_f32_16x16x32_bf16 v[2:5], v[182:185], v[218:221], v[2:5]
	s_setprio 0
	s_barrier
	s_add_i32 s69, 0, 0x18000
	v_add_u32_e32 v153, s69, v149
	s_add_i32 s70, 0, 0x1c000
	ds_read_b128 v[154:157], v153
	ds_read_b128 v[158:161], v153 offset:1024
	ds_read_b128 v[162:165], v153 offset:2048
	ds_read_b128 v[166:169], v153 offset:3072
	v_add_u32_e32 v153, s70, v149
	ds_read_b128 v[170:173], v153
	ds_read_b128 v[174:177], v153 offset:1024
	ds_read_b128 v[178:181], v153 offset:2048
	ds_read_b128 v[182:185], v153 offset:3072
	s_add_u32 s46, s46, 0x40000
	s_addc_u32 s47, s47, 0
	s_mov_b32 m0, s25
	v_lshl_add_u64 v[226:227], s[46:47], 0, v[136:137]
	ds_read_b128 v[186:189], v152 offset:32768
	ds_read_b128 v[190:193], v152 offset:33792
	ds_read_b128 v[194:197], v152 offset:34816
	ds_read_b128 v[198:201], v152 offset:35840
	ds_read_b128 v[206:209], v152 offset:36864
	ds_read_b128 v[210:213], v152 offset:37888
	ds_read_b128 v[214:217], v152 offset:38912
	ds_read_b128 v[218:221], v152 offset:39936
	global_load_lds_dwordx4 v[226:227], off
	v_lshl_add_u64 v[226:227], s[46:47], 0, v[132:133]
	s_mov_b32 m0, s28
	s_nop 0
	global_load_lds_dwordx4 v[226:227], off
	s_waitcnt vmcnt(8) lgkmcnt(0)
	s_setprio 1
	s_barrier
	v_mfma_f32_16x16x32_bf16 v[126:129], v[154:157], v[186:189], v[126:129]
	v_mfma_f32_16x16x32_bf16 v[122:125], v[162:165], v[186:189], v[122:125]
	v_mfma_f32_16x16x32_bf16 v[110:113], v[154:157], v[194:197], v[110:113]
	v_mfma_f32_16x16x32_bf16 v[106:109], v[162:165], v[194:197], v[106:109]
	v_mfma_f32_16x16x32_bf16 v[94:97], v[154:157], v[206:209], v[94:97]
	v_mfma_f32_16x16x32_bf16 v[90:93], v[162:165], v[206:209], v[90:93]
	v_mfma_f32_16x16x32_bf16 v[78:81], v[154:157], v[214:217], v[78:81]
	v_mfma_f32_16x16x32_bf16 v[74:77], v[162:165], v[214:217], v[74:77]
	v_mfma_f32_16x16x32_bf16 v[126:129], v[158:161], v[190:193], v[126:129]
	v_mfma_f32_16x16x32_bf16 v[122:125], v[166:169], v[190:193], v[122:125]
	v_mfma_f32_16x16x32_bf16 v[110:113], v[158:161], v[198:201], v[110:113]
	v_mfma_f32_16x16x32_bf16 v[106:109], v[166:169], v[198:201], v[106:109]
	v_mfma_f32_16x16x32_bf16 v[94:97], v[158:161], v[210:213], v[94:97]
	v_mfma_f32_16x16x32_bf16 v[90:93], v[166:169], v[210:213], v[90:93]
	v_mfma_f32_16x16x32_bf16 v[78:81], v[158:161], v[218:221], v[78:81]
	v_mfma_f32_16x16x32_bf16 v[74:77], v[166:169], v[218:221], v[74:77]
	v_mfma_f32_16x16x32_bf16 v[118:121], v[170:173], v[186:189], v[118:121]
	v_mfma_f32_16x16x32_bf16 v[114:117], v[178:181], v[186:189], v[114:117]
	v_mfma_f32_16x16x32_bf16 v[102:105], v[170:173], v[194:197], v[102:105]
	v_mfma_f32_16x16x32_bf16 v[98:101], v[178:181], v[194:197], v[98:101]
	v_mfma_f32_16x16x32_bf16 v[86:89], v[170:173], v[206:209], v[86:89]
	v_mfma_f32_16x16x32_bf16 v[82:85], v[178:181], v[206:209], v[82:85]
	v_mfma_f32_16x16x32_bf16 v[70:73], v[170:173], v[214:217], v[70:73]
	v_mfma_f32_16x16x32_bf16 v[66:69], v[178:181], v[214:217], v[66:69]
	v_mfma_f32_16x16x32_bf16 v[118:121], v[174:177], v[190:193], v[118:121]
	v_mfma_f32_16x16x32_bf16 v[114:117], v[182:185], v[190:193], v[114:117]
	v_mfma_f32_16x16x32_bf16 v[102:105], v[174:177], v[198:201], v[102:105]
	v_mfma_f32_16x16x32_bf16 v[98:101], v[182:185], v[198:201], v[98:101]
	v_mfma_f32_16x16x32_bf16 v[86:89], v[174:177], v[210:213], v[86:89]
	v_mfma_f32_16x16x32_bf16 v[82:85], v[182:185], v[210:213], v[82:85]
	v_mfma_f32_16x16x32_bf16 v[70:73], v[174:177], v[218:221], v[70:73]
	v_mfma_f32_16x16x32_bf16 v[66:69], v[182:185], v[218:221], v[66:69]
	s_setprio 0
	s_barrier
	s_add_i32 s46, s69, s16
	v_lshl_add_u64 v[146:147], v[146:147], 0, s[10:11]
	s_mov_b32 m0, s46
	ds_read_b128 v[186:189], v152 offset:49152
	ds_read_b128 v[190:193], v152 offset:50176
	ds_read_b128 v[194:197], v152 offset:51200
	ds_read_b128 v[198:201], v152 offset:52224
	ds_read_b128 v[206:209], v152 offset:53248
	ds_read_b128 v[210:213], v152 offset:54272
	ds_read_b128 v[214:217], v152 offset:55296
	ds_read_b128 v[218:221], v152 offset:56320
	global_load_lds_dwordx4 v[146:147], off
	s_add_i32 m0, s46, 0x2000
	s_add_u32 s44, s44, 0x40080
	v_lshl_add_u64 v[146:147], v[202:203], 0, s[10:11]
	s_addc_u32 s45, s45, 0
	s_add_i32 s46, s70, s16
	global_load_lds_dwordx4 v[146:147], off
	v_lshl_add_u64 v[146:147], s[44:45], 0, v[134:135]
	s_mov_b32 m0, s46
	s_nop 0
	global_load_lds_dwordx4 v[146:147], off
	v_lshl_add_u64 v[146:147], s[44:45], 0, v[130:131]
	s_add_i32 m0, s46, 0x2000
	s_nop 0
	global_load_lds_dwordx4 v[146:147], off
	v_lshl_add_u64 v[146:147], v[222:223], 0, s[10:11]
	s_mov_b32 m0, s33
	s_nop 0
	global_load_lds_dwordx4 v[146:147], off
	v_lshl_add_u64 v[146:147], v[224:225], 0, s[10:11]
	s_mov_b32 m0, s35
	s_nop 0
	global_load_lds_dwordx4 v[146:147], off
	s_waitcnt vmcnt(8) lgkmcnt(0)
	s_setprio 1
	s_barrier
	v_mfma_f32_16x16x32_bf16 v[62:65], v[154:157], v[186:189], v[62:65]
	v_mfma_f32_16x16x32_bf16 v[58:61], v[162:165], v[186:189], v[58:61]
	v_mfma_f32_16x16x32_bf16 v[46:49], v[154:157], v[194:197], v[46:49]
	v_mfma_f32_16x16x32_bf16 v[42:45], v[162:165], v[194:197], v[42:45]
	v_mfma_f32_16x16x32_bf16 v[30:33], v[154:157], v[206:209], v[30:33]
	v_mfma_f32_16x16x32_bf16 v[26:29], v[162:165], v[206:209], v[26:29]
	v_mfma_f32_16x16x32_bf16 v[14:17], v[154:157], v[214:217], v[14:17]
	v_mfma_f32_16x16x32_bf16 v[10:13], v[162:165], v[214:217], v[10:13]
	v_mfma_f32_16x16x32_bf16 v[62:65], v[158:161], v[190:193], v[62:65]
	v_mfma_f32_16x16x32_bf16 v[58:61], v[166:169], v[190:193], v[58:61]
	v_mfma_f32_16x16x32_bf16 v[46:49], v[158:161], v[198:201], v[46:49]
	v_mfma_f32_16x16x32_bf16 v[42:45], v[166:169], v[198:201], v[42:45]
	v_mfma_f32_16x16x32_bf16 v[30:33], v[158:161], v[210:213], v[30:33]
	v_mfma_f32_16x16x32_bf16 v[26:29], v[166:169], v[210:213], v[26:29]
	v_mfma_f32_16x16x32_bf16 v[14:17], v[158:161], v[218:221], v[14:17]
	v_mfma_f32_16x16x32_bf16 v[10:13], v[166:169], v[218:221], v[10:13]
	v_mfma_f32_16x16x32_bf16 v[54:57], v[170:173], v[186:189], v[54:57]
	v_mfma_f32_16x16x32_bf16 v[50:53], v[178:181], v[186:189], v[50:53]
	v_mfma_f32_16x16x32_bf16 v[38:41], v[170:173], v[194:197], v[38:41]
	v_mfma_f32_16x16x32_bf16 v[34:37], v[178:181], v[194:197], v[34:37]
	v_mfma_f32_16x16x32_bf16 v[22:25], v[170:173], v[206:209], v[22:25]
	v_mfma_f32_16x16x32_bf16 v[18:21], v[178:181], v[206:209], v[18:21]
	v_mfma_f32_16x16x32_bf16 v[6:9], v[170:173], v[214:217], v[6:9]
	v_mfma_f32_16x16x32_bf16 v[2:5], v[178:181], v[214:217], v[2:5]
	v_mfma_f32_16x16x32_bf16 v[54:57], v[174:177], v[190:193], v[54:57]
	v_mfma_f32_16x16x32_bf16 v[50:53], v[182:185], v[190:193], v[50:53]
	v_mfma_f32_16x16x32_bf16 v[38:41], v[174:177], v[198:201], v[38:41]
	v_mfma_f32_16x16x32_bf16 v[34:37], v[182:185], v[198:201], v[34:37]
	v_mfma_f32_16x16x32_bf16 v[22:25], v[174:177], v[210:213], v[22:25]
	v_mfma_f32_16x16x32_bf16 v[18:21], v[182:185], v[210:213], v[18:21]
	v_mfma_f32_16x16x32_bf16 v[6:9], v[174:177], v[218:221], v[6:9]
	v_mfma_f32_16x16x32_bf16 v[2:5], v[182:185], v[218:221], v[2:5]
	s_setprio 0
	s_barrier
	s_add_i32 s68, s68, 2
	s_add_u32 s42, s42, 0x100
	s_addc_u32 s43, s43, 0
	s_add_u32 s66, s66, 0x100
	s_addc_u32 s67, s67, 0
	s_cmp_gt_u32 s68, 13
	s_cbranch_scc0 .LBB0_745
	s_and_b64 vcc, exec, s[12:13]
	s_cbranch_vccz .LBB0_748
	s_barrier

.LBB0_833:
	s_add_u32 s72, s0, s68
	s_addc_u32 s73, s1, s69
	s_and_b64 s[62:63], s[70:71], exec
	s_cselect_b32 s15, s73, s77
	s_cselect_b32 s33, s72, s76
	s_add_u32 s74, s35, s66
	s_addc_u32 s75, s85, s67
	s_and_b64 s[62:63], s[70:71], exec
	s_cselect_b32 s34, s75, s79
	s_cselect_b32 s39, s74, s78
	s_add_i32 s45, s7, -2
	s_add_u32 s76, s76, 0x100080
	s_addc_u32 s77, s77, 0
	s_add_u32 s47, s78, 0x100
	s_addc_u32 s62, s79, 0
	s_mov_b32 s63, 0
	s_waitcnt vmcnt(0)
	ds_read_b128 v[114:117], v190
	ds_read_b128 v[118:121], v190 offset:1024
	ds_read_b128 v[122:125], v190 offset:2048
	ds_read_b128 v[126:129], v190 offset:3072
	ds_read_b128 v[146:149], v191
	ds_read_b128 v[150:153], v191 offset:1024
	ds_read_b128 v[154:157], v191 offset:2048
	ds_read_b128 v[158:161], v191 offset:3072
	s_add_i32 s82, s63, 2
	s_add_u32 s78, s76, 0xfff00080
	s_addc_u32 s79, s77, -1
	s_cmp_eq_u32 s45, s63
	s_cselect_b32 s81, s15, s79
	s_cselect_b32 s80, s33, s78
	s_cselect_b32 s79, s34, s62
	s_cselect_b32 s78, s39, s47
	v_lshl_add_u64 v[186:187], s[76:77], 0, v[180:181]
	s_add_i32 m0, s87, 0xc000
	ds_read_b128 v[162:165], v192
	ds_read_b128 v[166:169], v192 offset:1024
	ds_read_b128 v[194:197], v192 offset:2048
	ds_read_b128 v[198:201], v192 offset:3072
	ds_read_b128 v[206:209], v192 offset:4096
	ds_read_b128 v[210:213], v192 offset:5120
	ds_read_b128 v[214:217], v192 offset:6144
	ds_read_b128 v[218:221], v192 offset:7168
	global_load_lds_dwordx4 v[186:187], off
	v_lshl_add_u64 v[186:187], s[76:77], 0, v[182:183]
	s_add_i32 m0, s87, 0xe000
	s_nop 0
	global_load_lds_dwordx4 v[186:187], off
	s_waitcnt vmcnt(8) lgkmcnt(0)
	s_setprio 1
	s_barrier
	v_mfma_f32_16x16x32_bf16 v[142:145], v[114:117], v[162:165], 0
	v_mfma_f32_16x16x32_bf16 v[138:141], v[122:125], v[162:165], 0
	v_mfma_f32_16x16x32_bf16 v[110:113], v[114:117], v[194:197], 0
	v_mfma_f32_16x16x32_bf16 v[106:109], v[122:125], v[194:197], 0
	v_mfma_f32_16x16x32_bf16 v[98:101], v[114:117], v[206:209], 0
	v_mfma_f32_16x16x32_bf16 v[90:93], v[122:125], v[206:209], 0
	v_mfma_f32_16x16x32_bf16 v[82:85], v[114:117], v[214:217], 0
	v_mfma_f32_16x16x32_bf16 v[74:77], v[122:125], v[214:217], 0
	v_mfma_f32_16x16x32_bf16 v[142:145], v[118:121], v[166:169], v[142:145]
	v_mfma_f32_16x16x32_bf16 v[138:141], v[126:129], v[166:169], v[138:141]
	v_mfma_f32_16x16x32_bf16 v[110:113], v[118:121], v[198:201], v[110:113]
	v_mfma_f32_16x16x32_bf16 v[106:109], v[126:129], v[198:201], v[106:109]
	v_mfma_f32_16x16x32_bf16 v[98:101], v[118:121], v[210:213], v[98:101]
	v_mfma_f32_16x16x32_bf16 v[90:93], v[126:129], v[210:213], v[90:93]
	v_mfma_f32_16x16x32_bf16 v[82:85], v[118:121], v[218:221], v[82:85]
	v_mfma_f32_16x16x32_bf16 v[74:77], v[126:129], v[218:221], v[74:77]
	v_mfma_f32_16x16x32_bf16 v[134:137], v[146:149], v[162:165], 0
	v_mfma_f32_16x16x32_bf16 v[130:133], v[154:157], v[162:165], 0
	v_mfma_f32_16x16x32_bf16 v[102:105], v[146:149], v[194:197], 0
	v_mfma_f32_16x16x32_bf16 v[94:97], v[154:157], v[194:197], 0
	v_mfma_f32_16x16x32_bf16 v[86:89], v[146:149], v[206:209], 0
	v_mfma_f32_16x16x32_bf16 v[78:81], v[154:157], v[206:209], 0
	v_mfma_f32_16x16x32_bf16 v[70:73], v[146:149], v[214:217], 0
	v_mfma_f32_16x16x32_bf16 v[66:69], v[154:157], v[214:217], 0
	v_mfma_f32_16x16x32_bf16 v[134:137], v[150:153], v[166:169], v[134:137]
	v_mfma_f32_16x16x32_bf16 v[130:133], v[158:161], v[166:169], v[130:133]
	v_mfma_f32_16x16x32_bf16 v[102:105], v[150:153], v[198:201], v[102:105]
	v_mfma_f32_16x16x32_bf16 v[94:97], v[158:161], v[198:201], v[94:97]
	v_mfma_f32_16x16x32_bf16 v[86:89], v[150:153], v[210:213], v[86:89]
	v_mfma_f32_16x16x32_bf16 v[78:81], v[158:161], v[210:213], v[78:81]
	v_mfma_f32_16x16x32_bf16 v[70:73], v[150:153], v[218:221], v[70:73]
	v_mfma_f32_16x16x32_bf16 v[66:69], v[158:161], v[218:221], v[66:69]
	s_setprio 0
	s_barrier
	s_add_i32 s63, s24, s86
	v_lshl_add_u64 v[186:187], s[78:79], 0, v[172:173]
	s_mov_b32 m0, s63
	ds_read_b128 v[162:165], v192 offset:16384
	ds_read_b128 v[166:169], v192 offset:17408
	ds_read_b128 v[194:197], v192 offset:18432
	ds_read_b128 v[198:201], v192 offset:19456
	ds_read_b128 v[206:209], v192 offset:20480
	ds_read_b128 v[210:213], v192 offset:21504
	ds_read_b128 v[214:217], v192 offset:22528
	ds_read_b128 v[218:221], v192 offset:23552
	global_load_lds_dwordx4 v[186:187], off
	s_add_i32 m0, s63, 0x2000
	s_add_u32 vcc_lo, s78, 0x100000
	v_lshl_add_u64 v[202:203], s[78:79], 0, v[176:177]
	s_addc_u32 vcc_hi, s79, 0
	s_add_i32 s63, s25, s86
	global_load_lds_dwordx4 v[202:203], off
	v_lshl_add_u64 v[222:223], vcc, 0, v[172:173]
	s_mov_b32 m0, s63
	v_lshl_add_u64 v[224:225], s[80:81], 0, v[174:175]
	global_load_lds_dwordx4 v[222:223], off
	v_lshl_add_u64 v[222:223], vcc, 0, v[176:177]
	s_add_i32 m0, s63, 0x2000
	s_nop 0
	global_load_lds_dwordx4 v[222:223], off
	v_lshl_add_u64 v[222:223], s[80:81], 0, v[170:171]
	s_mov_b32 m0, s87
	s_nop 0
	global_load_lds_dwordx4 v[222:223], off
	s_mov_b32 m0, s88
	s_nop 0
	global_load_lds_dwordx4 v[224:225], off
	s_waitcnt vmcnt(8) lgkmcnt(0)
	s_setprio 1
	s_barrier
	v_mfma_f32_16x16x32_bf16 v[62:65], v[114:117], v[162:165], 0
	v_mfma_f32_16x16x32_bf16 v[58:61], v[122:125], v[162:165], 0
	v_mfma_f32_16x16x32_bf16 v[50:53], v[114:117], v[194:197], 0
	v_mfma_f32_16x16x32_bf16 v[42:45], v[122:125], v[194:197], 0
	v_mfma_f32_16x16x32_bf16 v[34:37], v[114:117], v[206:209], 0
	v_mfma_f32_16x16x32_bf16 v[26:29], v[122:125], v[206:209], 0
	v_mfma_f32_16x16x32_bf16 v[18:21], v[114:117], v[214:217], 0
	v_mfma_f32_16x16x32_bf16 v[10:13], v[122:125], v[214:217], 0
	v_mfma_f32_16x16x32_bf16 v[62:65], v[118:121], v[166:169], v[62:65]
	v_mfma_f32_16x16x32_bf16 v[58:61], v[126:129], v[166:169], v[58:61]
	v_mfma_f32_16x16x32_bf16 v[50:53], v[118:121], v[198:201], v[50:53]
	v_mfma_f32_16x16x32_bf16 v[42:45], v[126:129], v[198:201], v[42:45]
	v_mfma_f32_16x16x32_bf16 v[34:37], v[118:121], v[210:213], v[34:37]
	v_mfma_f32_16x16x32_bf16 v[26:29], v[126:129], v[210:213], v[26:29]
	v_mfma_f32_16x16x32_bf16 v[18:21], v[118:121], v[218:221], v[18:21]
	v_mfma_f32_16x16x32_bf16 v[10:13], v[126:129], v[218:221], v[10:13]
	v_mfma_f32_16x16x32_bf16 v[54:57], v[146:149], v[162:165], 0
	v_mfma_f32_16x16x32_bf16 v[46:49], v[154:157], v[162:165], 0
	v_mfma_f32_16x16x32_bf16 v[38:41], v[146:149], v[194:197], 0
	v_mfma_f32_16x16x32_bf16 v[30:33], v[154:157], v[194:197], 0
	v_mfma_f32_16x16x32_bf16 v[22:25], v[146:149], v[206:209], 0
	v_mfma_f32_16x16x32_bf16 v[14:17], v[154:157], v[206:209], 0
	v_mfma_f32_16x16x32_bf16 v[6:9], v[146:149], v[214:217], 0
	v_mfma_f32_16x16x32_bf16 v[2:5], v[154:157], v[214:217], 0
	v_mfma_f32_16x16x32_bf16 v[54:57], v[150:153], v[166:169], v[54:57]
	v_mfma_f32_16x16x32_bf16 v[46:49], v[158:161], v[166:169], v[46:49]
	v_mfma_f32_16x16x32_bf16 v[38:41], v[150:153], v[198:201], v[38:41]
	v_mfma_f32_16x16x32_bf16 v[30:33], v[158:161], v[198:201], v[30:33]
	v_mfma_f32_16x16x32_bf16 v[22:25], v[150:153], v[210:213], v[22:25]
	v_mfma_f32_16x16x32_bf16 v[14:17], v[158:161], v[210:213], v[14:17]
	v_mfma_f32_16x16x32_bf16 v[6:9], v[150:153], v[218:221], v[6:9]
	v_mfma_f32_16x16x32_bf16 v[2:5], v[158:161], v[218:221], v[2:5]
	s_setprio 0
	s_barrier
	s_add_i32 s63, 0, 0x18000
	s_add_i32 s83, 0, 0x1c000
	v_add_u32_e32 v126, s63, v189
	v_add_u32_e32 v158, s83, v189
	ds_read_b128 v[114:117], v126
	ds_read_b128 v[118:121], v126 offset:1024
	ds_read_b128 v[122:125], v126 offset:2048
	ds_read_b128 v[126:129], v126 offset:3072
	ds_read_b128 v[146:149], v158
	ds_read_b128 v[150:153], v158 offset:1024
	ds_read_b128 v[154:157], v158 offset:2048
	ds_read_b128 v[158:161], v158 offset:3072
	s_add_u32 s80, s80, 0x100000
	s_addc_u32 s81, s81, 0
	s_mov_b32 m0, s89
	v_lshl_add_u64 v[226:227], s[80:81], 0, v[170:171]
	ds_read_b128 v[162:165], v192 offset:32768
	ds_read_b128 v[166:169], v192 offset:33792
	ds_read_b128 v[194:197], v192 offset:34816
	ds_read_b128 v[198:201], v192 offset:35840
	ds_read_b128 v[206:209], v192 offset:36864
	ds_read_b128 v[210:213], v192 offset:37888
	ds_read_b128 v[214:217], v192 offset:38912
	ds_read_b128 v[218:221], v192 offset:39936
	global_load_lds_dwordx4 v[226:227], off
	v_lshl_add_u64 v[226:227], s[80:81], 0, v[174:175]
	s_mov_b32 m0, s90
	s_nop 0
	global_load_lds_dwordx4 v[226:227], off
	s_waitcnt vmcnt(8) lgkmcnt(0)
	s_setprio 1
	s_barrier
	v_mfma_f32_16x16x32_bf16 v[142:145], v[114:117], v[162:165], v[142:145]
	v_mfma_f32_16x16x32_bf16 v[138:141], v[122:125], v[162:165], v[138:141]
	v_mfma_f32_16x16x32_bf16 v[110:113], v[114:117], v[194:197], v[110:113]
	v_mfma_f32_16x16x32_bf16 v[106:109], v[122:125], v[194:197], v[106:109]
	v_mfma_f32_16x16x32_bf16 v[98:101], v[114:117], v[206:209], v[98:101]
	v_mfma_f32_16x16x32_bf16 v[90:93], v[122:125], v[206:209], v[90:93]
	v_mfma_f32_16x16x32_bf16 v[82:85], v[114:117], v[214:217], v[82:85]
	v_mfma_f32_16x16x32_bf16 v[74:77], v[122:125], v[214:217], v[74:77]
	v_mfma_f32_16x16x32_bf16 v[142:145], v[118:121], v[166:169], v[142:145]
	v_mfma_f32_16x16x32_bf16 v[138:141], v[126:129], v[166:169], v[138:141]
	v_mfma_f32_16x16x32_bf16 v[110:113], v[118:121], v[198:201], v[110:113]
	v_mfma_f32_16x16x32_bf16 v[106:109], v[126:129], v[198:201], v[106:109]
	v_mfma_f32_16x16x32_bf16 v[98:101], v[118:121], v[210:213], v[98:101]
	v_mfma_f32_16x16x32_bf16 v[90:93], v[126:129], v[210:213], v[90:93]
	v_mfma_f32_16x16x32_bf16 v[82:85], v[118:121], v[218:221], v[82:85]
	v_mfma_f32_16x16x32_bf16 v[74:77], v[126:129], v[218:221], v[74:77]
	v_mfma_f32_16x16x32_bf16 v[134:137], v[146:149], v[162:165], v[134:137]
	v_mfma_f32_16x16x32_bf16 v[130:133], v[154:157], v[162:165], v[130:133]
	v_mfma_f32_16x16x32_bf16 v[102:105], v[146:149], v[194:197], v[102:105]
	v_mfma_f32_16x16x32_bf16 v[94:97], v[154:157], v[194:197], v[94:97]
	v_mfma_f32_16x16x32_bf16 v[86:89], v[146:149], v[206:209], v[86:89]
	v_mfma_f32_16x16x32_bf16 v[78:81], v[154:157], v[206:209], v[78:81]
	v_mfma_f32_16x16x32_bf16 v[70:73], v[146:149], v[214:217], v[70:73]
	v_mfma_f32_16x16x32_bf16 v[66:69], v[154:157], v[214:217], v[66:69]
	v_mfma_f32_16x16x32_bf16 v[134:137], v[150:153], v[166:169], v[134:137]
	v_mfma_f32_16x16x32_bf16 v[130:133], v[158:161], v[166:169], v[130:133]
	v_mfma_f32_16x16x32_bf16 v[102:105], v[150:153], v[198:201], v[102:105]
	v_mfma_f32_16x16x32_bf16 v[94:97], v[158:161], v[198:201], v[94:97]
	v_mfma_f32_16x16x32_bf16 v[86:89], v[150:153], v[210:213], v[86:89]
	v_mfma_f32_16x16x32_bf16 v[78:81], v[158:161], v[210:213], v[78:81]
	v_mfma_f32_16x16x32_bf16 v[70:73], v[150:153], v[218:221], v[70:73]
	v_mfma_f32_16x16x32_bf16 v[66:69], v[158:161], v[218:221], v[66:69]
	s_setprio 0
	s_barrier
	s_add_i32 s63, s63, s86
	v_lshl_add_u64 v[186:187], v[186:187], 0, s[22:23]
	s_mov_b32 m0, s63
	ds_read_b128 v[162:165], v192 offset:49152
	ds_read_b128 v[166:169], v192 offset:50176
	ds_read_b128 v[194:197], v192 offset:51200
	ds_read_b128 v[198:201], v192 offset:52224
	ds_read_b128 v[206:209], v192 offset:53248
	ds_read_b128 v[210:213], v192 offset:54272
	ds_read_b128 v[214:217], v192 offset:55296
	ds_read_b128 v[218:221], v192 offset:56320
	global_load_lds_dwordx4 v[186:187], off
	s_add_i32 m0, s63, 0x2000
	s_add_u32 s78, s78, 0x100080
	v_lshl_add_u64 v[186:187], v[202:203], 0, s[22:23]
	s_addc_u32 s79, s79, 0
	s_add_i32 s63, s83, s86
	global_load_lds_dwordx4 v[186:187], off
	v_lshl_add_u64 v[186:187], s[78:79], 0, v[172:173]
	s_mov_b32 m0, s63
	s_nop 0
	global_load_lds_dwordx4 v[186:187], off
	v_lshl_add_u64 v[186:187], s[78:79], 0, v[176:177]
	s_add_i32 m0, s63, 0x2000
	s_nop 0
	global_load_lds_dwordx4 v[186:187], off
	v_lshl_add_u64 v[186:187], v[222:223], 0, s[22:23]
	s_mov_b32 m0, s95
	s_nop 0
	global_load_lds_dwordx4 v[186:187], off
	v_lshl_add_u64 v[186:187], v[224:225], 0, s[22:23]
	s_mov_b32 m0, s96
	s_nop 0
	global_load_lds_dwordx4 v[186:187], off
	s_waitcnt vmcnt(8) lgkmcnt(0)
	s_setprio 1
	s_barrier
	v_mfma_f32_16x16x32_bf16 v[62:65], v[114:117], v[162:165], v[62:65]
	v_mfma_f32_16x16x32_bf16 v[58:61], v[122:125], v[162:165], v[58:61]
	v_mfma_f32_16x16x32_bf16 v[50:53], v[114:117], v[194:197], v[50:53]
	v_mfma_f32_16x16x32_bf16 v[42:45], v[122:125], v[194:197], v[42:45]
	v_mfma_f32_16x16x32_bf16 v[34:37], v[114:117], v[206:209], v[34:37]
	v_mfma_f32_16x16x32_bf16 v[26:29], v[122:125], v[206:209], v[26:29]
	v_mfma_f32_16x16x32_bf16 v[18:21], v[114:117], v[214:217], v[18:21]
	v_mfma_f32_16x16x32_bf16 v[10:13], v[122:125], v[214:217], v[10:13]
	v_mfma_f32_16x16x32_bf16 v[62:65], v[118:121], v[166:169], v[62:65]
	v_mfma_f32_16x16x32_bf16 v[58:61], v[126:129], v[166:169], v[58:61]
	v_mfma_f32_16x16x32_bf16 v[50:53], v[118:121], v[198:201], v[50:53]
	v_mfma_f32_16x16x32_bf16 v[42:45], v[126:129], v[198:201], v[42:45]
	v_mfma_f32_16x16x32_bf16 v[34:37], v[118:121], v[210:213], v[34:37]
	v_mfma_f32_16x16x32_bf16 v[26:29], v[126:129], v[210:213], v[26:29]
	v_mfma_f32_16x16x32_bf16 v[18:21], v[118:121], v[218:221], v[18:21]
	v_mfma_f32_16x16x32_bf16 v[10:13], v[126:129], v[218:221], v[10:13]
	v_mfma_f32_16x16x32_bf16 v[54:57], v[146:149], v[162:165], v[54:57]
	v_mfma_f32_16x16x32_bf16 v[46:49], v[154:157], v[162:165], v[46:49]
	v_mfma_f32_16x16x32_bf16 v[38:41], v[146:149], v[194:197], v[38:41]
	v_mfma_f32_16x16x32_bf16 v[30:33], v[154:157], v[194:197], v[30:33]
	v_mfma_f32_16x16x32_bf16 v[22:25], v[146:149], v[206:209], v[22:25]
	v_mfma_f32_16x16x32_bf16 v[14:17], v[154:157], v[206:209], v[14:17]
	v_mfma_f32_16x16x32_bf16 v[6:9], v[146:149], v[214:217], v[6:9]
	v_mfma_f32_16x16x32_bf16 v[2:5], v[154:157], v[214:217], v[2:5]
	v_mfma_f32_16x16x32_bf16 v[54:57], v[150:153], v[166:169], v[54:57]
	v_mfma_f32_16x16x32_bf16 v[46:49], v[158:161], v[166:169], v[46:49]
	v_mfma_f32_16x16x32_bf16 v[38:41], v[150:153], v[198:201], v[38:41]
	v_mfma_f32_16x16x32_bf16 v[30:33], v[158:161], v[198:201], v[30:33]
	v_mfma_f32_16x16x32_bf16 v[22:25], v[150:153], v[210:213], v[22:25]
	v_mfma_f32_16x16x32_bf16 v[14:17], v[158:161], v[210:213], v[14:17]
	v_mfma_f32_16x16x32_bf16 v[6:9], v[150:153], v[218:221], v[6:9]
	v_mfma_f32_16x16x32_bf16 v[2:5], v[158:161], v[218:221], v[2:5]
	s_setprio 0
	s_barrier
	s_add_u32 s76, s76, 0x100
	s_addc_u32 s77, s77, 0
	s_add_u32 s47, s47, 0x100
	s_addc_u32 s62, s62, 0
	s_cmp_ge_i32 s82, s7
	s_mov_b32 s63, s82
.LBB0_834:
	ds_read_b128 v[114:117], v190
	ds_read_b128 v[118:121], v190 offset:1024
	ds_read_b128 v[122:125], v190 offset:2048
	ds_read_b128 v[126:129], v190 offset:3072
	ds_read_b128 v[146:149], v191
	ds_read_b128 v[150:153], v191 offset:1024
	ds_read_b128 v[154:157], v191 offset:2048
	ds_read_b128 v[158:161], v191 offset:3072
	s_add_i32 s82, s63, 2
	s_add_u32 s78, s76, 0xfff00080
	s_addc_u32 s79, s77, -1
	s_cmp_eq_u32 s45, s63
	s_cselect_b32 s81, s15, s79
	s_cselect_b32 s80, s33, s78
	s_cselect_b32 s79, s34, s62
	s_cselect_b32 s78, s39, s47
	v_lshl_add_u64 v[186:187], s[76:77], 0, v[180:181]
	s_add_i32 m0, s87, 0xc000
	ds_read_b128 v[162:165], v192
	ds_read_b128 v[166:169], v192 offset:1024
	ds_read_b128 v[194:197], v192 offset:2048
	ds_read_b128 v[198:201], v192 offset:3072
	ds_read_b128 v[206:209], v192 offset:4096
	ds_read_b128 v[210:213], v192 offset:5120
	ds_read_b128 v[214:217], v192 offset:6144
	ds_read_b128 v[218:221], v192 offset:7168
	global_load_lds_dwordx4 v[186:187], off
	v_lshl_add_u64 v[186:187], s[76:77], 0, v[182:183]
	s_add_i32 m0, s87, 0xe000
	s_nop 0
	global_load_lds_dwordx4 v[186:187], off
	s_waitcnt vmcnt(8) lgkmcnt(0)
	s_setprio 1
	s_barrier
	v_mfma_f32_16x16x32_bf16 v[142:145], v[114:117], v[162:165], v[142:145]
	v_mfma_f32_16x16x32_bf16 v[138:141], v[122:125], v[162:165], v[138:141]
	v_mfma_f32_16x16x32_bf16 v[110:113], v[114:117], v[194:197], v[110:113]
	v_mfma_f32_16x16x32_bf16 v[106:109], v[122:125], v[194:197], v[106:109]
	v_mfma_f32_16x16x32_bf16 v[98:101], v[114:117], v[206:209], v[98:101]
	v_mfma_f32_16x16x32_bf16 v[90:93], v[122:125], v[206:209], v[90:93]
	v_mfma_f32_16x16x32_bf16 v[82:85], v[114:117], v[214:217], v[82:85]
	v_mfma_f32_16x16x32_bf16 v[74:77], v[122:125], v[214:217], v[74:77]
	v_mfma_f32_16x16x32_bf16 v[142:145], v[118:121], v[166:169], v[142:145]
	v_mfma_f32_16x16x32_bf16 v[138:141], v[126:129], v[166:169], v[138:141]
	v_mfma_f32_16x16x32_bf16 v[110:113], v[118:121], v[198:201], v[110:113]
	v_mfma_f32_16x16x32_bf16 v[106:109], v[126:129], v[198:201], v[106:109]
	v_mfma_f32_16x16x32_bf16 v[98:101], v[118:121], v[210:213], v[98:101]
	v_mfma_f32_16x16x32_bf16 v[90:93], v[126:129], v[210:213], v[90:93]
	v_mfma_f32_16x16x32_bf16 v[82:85], v[118:121], v[218:221], v[82:85]
	v_mfma_f32_16x16x32_bf16 v[74:77], v[126:129], v[218:221], v[74:77]
	v_mfma_f32_16x16x32_bf16 v[134:137], v[146:149], v[162:165], v[134:137]
	v_mfma_f32_16x16x32_bf16 v[130:133], v[154:157], v[162:165], v[130:133]
	v_mfma_f32_16x16x32_bf16 v[102:105], v[146:149], v[194:197], v[102:105]
	v_mfma_f32_16x16x32_bf16 v[94:97], v[154:157], v[194:197], v[94:97]
	v_mfma_f32_16x16x32_bf16 v[86:89], v[146:149], v[206:209], v[86:89]
	v_mfma_f32_16x16x32_bf16 v[78:81], v[154:157], v[206:209], v[78:81]
	v_mfma_f32_16x16x32_bf16 v[70:73], v[146:149], v[214:217], v[70:73]
	v_mfma_f32_16x16x32_bf16 v[66:69], v[154:157], v[214:217], v[66:69]
	v_mfma_f32_16x16x32_bf16 v[134:137], v[150:153], v[166:169], v[134:137]
	v_mfma_f32_16x16x32_bf16 v[130:133], v[158:161], v[166:169], v[130:133]
	v_mfma_f32_16x16x32_bf16 v[102:105], v[150:153], v[198:201], v[102:105]
	v_mfma_f32_16x16x32_bf16 v[94:97], v[158:161], v[198:201], v[94:97]
	v_mfma_f32_16x16x32_bf16 v[86:89], v[150:153], v[210:213], v[86:89]
	v_mfma_f32_16x16x32_bf16 v[78:81], v[158:161], v[210:213], v[78:81]
	v_mfma_f32_16x16x32_bf16 v[70:73], v[150:153], v[218:221], v[70:73]
	v_mfma_f32_16x16x32_bf16 v[66:69], v[158:161], v[218:221], v[66:69]
	s_setprio 0
	s_barrier
	s_add_i32 s63, s24, s86
	v_lshl_add_u64 v[186:187], s[78:79], 0, v[172:173]
	s_mov_b32 m0, s63
	ds_read_b128 v[162:165], v192 offset:16384
	ds_read_b128 v[166:169], v192 offset:17408
	ds_read_b128 v[194:197], v192 offset:18432
	ds_read_b128 v[198:201], v192 offset:19456
	ds_read_b128 v[206:209], v192 offset:20480
	ds_read_b128 v[210:213], v192 offset:21504
	ds_read_b128 v[214:217], v192 offset:22528
	ds_read_b128 v[218:221], v192 offset:23552
	global_load_lds_dwordx4 v[186:187], off
	s_add_i32 m0, s63, 0x2000
	s_add_u32 vcc_lo, s78, 0x100000
	v_lshl_add_u64 v[202:203], s[78:79], 0, v[176:177]
	s_addc_u32 vcc_hi, s79, 0
	s_add_i32 s63, s25, s86
	global_load_lds_dwordx4 v[202:203], off
	v_lshl_add_u64 v[222:223], vcc, 0, v[172:173]
	s_mov_b32 m0, s63
	v_lshl_add_u64 v[224:225], s[80:81], 0, v[174:175]
	global_load_lds_dwordx4 v[222:223], off
	v_lshl_add_u64 v[222:223], vcc, 0, v[176:177]
	s_add_i32 m0, s63, 0x2000
	s_nop 0
	global_load_lds_dwordx4 v[222:223], off
	v_lshl_add_u64 v[222:223], s[80:81], 0, v[170:171]
	s_mov_b32 m0, s87
	s_nop 0
	global_load_lds_dwordx4 v[222:223], off
	s_mov_b32 m0, s88
	s_nop 0
	global_load_lds_dwordx4 v[224:225], off
	s_waitcnt vmcnt(8) lgkmcnt(0)
	s_setprio 1
	s_barrier
	v_mfma_f32_16x16x32_bf16 v[62:65], v[114:117], v[162:165], v[62:65]
	v_mfma_f32_16x16x32_bf16 v[58:61], v[122:125], v[162:165], v[58:61]
	v_mfma_f32_16x16x32_bf16 v[50:53], v[114:117], v[194:197], v[50:53]
	v_mfma_f32_16x16x32_bf16 v[42:45], v[122:125], v[194:197], v[42:45]
	v_mfma_f32_16x16x32_bf16 v[34:37], v[114:117], v[206:209], v[34:37]
	v_mfma_f32_16x16x32_bf16 v[26:29], v[122:125], v[206:209], v[26:29]
	v_mfma_f32_16x16x32_bf16 v[18:21], v[114:117], v[214:217], v[18:21]
	v_mfma_f32_16x16x32_bf16 v[10:13], v[122:125], v[214:217], v[10:13]
	v_mfma_f32_16x16x32_bf16 v[62:65], v[118:121], v[166:169], v[62:65]
	v_mfma_f32_16x16x32_bf16 v[58:61], v[126:129], v[166:169], v[58:61]
	v_mfma_f32_16x16x32_bf16 v[50:53], v[118:121], v[198:201], v[50:53]
	v_mfma_f32_16x16x32_bf16 v[42:45], v[126:129], v[198:201], v[42:45]
	v_mfma_f32_16x16x32_bf16 v[34:37], v[118:121], v[210:213], v[34:37]
	v_mfma_f32_16x16x32_bf16 v[26:29], v[126:129], v[210:213], v[26:29]
	v_mfma_f32_16x16x32_bf16 v[18:21], v[118:121], v[218:221], v[18:21]
	v_mfma_f32_16x16x32_bf16 v[10:13], v[126:129], v[218:221], v[10:13]
	v_mfma_f32_16x16x32_bf16 v[54:57], v[146:149], v[162:165], v[54:57]
	v_mfma_f32_16x16x32_bf16 v[46:49], v[154:157], v[162:165], v[46:49]
	v_mfma_f32_16x16x32_bf16 v[38:41], v[146:149], v[194:197], v[38:41]
	v_mfma_f32_16x16x32_bf16 v[30:33], v[154:157], v[194:197], v[30:33]
	v_mfma_f32_16x16x32_bf16 v[22:25], v[146:149], v[206:209], v[22:25]
	v_mfma_f32_16x16x32_bf16 v[14:17], v[154:157], v[206:209], v[14:17]
	v_mfma_f32_16x16x32_bf16 v[6:9], v[146:149], v[214:217], v[6:9]
	v_mfma_f32_16x16x32_bf16 v[2:5], v[154:157], v[214:217], v[2:5]
	v_mfma_f32_16x16x32_bf16 v[54:57], v[150:153], v[166:169], v[54:57]
	v_mfma_f32_16x16x32_bf16 v[46:49], v[158:161], v[166:169], v[46:49]
	v_mfma_f32_16x16x32_bf16 v[38:41], v[150:153], v[198:201], v[38:41]
	v_mfma_f32_16x16x32_bf16 v[30:33], v[158:161], v[198:201], v[30:33]
	v_mfma_f32_16x16x32_bf16 v[22:25], v[150:153], v[210:213], v[22:25]
	v_mfma_f32_16x16x32_bf16 v[14:17], v[158:161], v[210:213], v[14:17]
	v_mfma_f32_16x16x32_bf16 v[6:9], v[150:153], v[218:221], v[6:9]
	v_mfma_f32_16x16x32_bf16 v[2:5], v[158:161], v[218:221], v[2:5]
	s_setprio 0
	s_barrier
	s_add_i32 s63, 0, 0x18000
	s_add_i32 s83, 0, 0x1c000
	v_add_u32_e32 v126, s63, v189
	v_add_u32_e32 v158, s83, v189
	ds_read_b128 v[114:117], v126
	ds_read_b128 v[118:121], v126 offset:1024
	ds_read_b128 v[122:125], v126 offset:2048
	ds_read_b128 v[126:129], v126 offset:3072
	ds_read_b128 v[146:149], v158
	ds_read_b128 v[150:153], v158 offset:1024
	ds_read_b128 v[154:157], v158 offset:2048
	ds_read_b128 v[158:161], v158 offset:3072
	s_add_u32 s80, s80, 0x100000
	s_addc_u32 s81, s81, 0
	s_mov_b32 m0, s89
	v_lshl_add_u64 v[226:227], s[80:81], 0, v[170:171]
	ds_read_b128 v[162:165], v192 offset:32768
	ds_read_b128 v[166:169], v192 offset:33792
	ds_read_b128 v[194:197], v192 offset:34816
	ds_read_b128 v[198:201], v192 offset:35840
	ds_read_b128 v[206:209], v192 offset:36864
	ds_read_b128 v[210:213], v192 offset:37888
	ds_read_b128 v[214:217], v192 offset:38912
	ds_read_b128 v[218:221], v192 offset:39936
	global_load_lds_dwordx4 v[226:227], off
	v_lshl_add_u64 v[226:227], s[80:81], 0, v[174:175]
	s_mov_b32 m0, s90
	s_nop 0
	global_load_lds_dwordx4 v[226:227], off
	s_waitcnt vmcnt(8) lgkmcnt(0)
	s_setprio 1
	s_barrier
	v_mfma_f32_16x16x32_bf16 v[142:145], v[114:117], v[162:165], v[142:145]
	v_mfma_f32_16x16x32_bf16 v[138:141], v[122:125], v[162:165], v[138:141]
	v_mfma_f32_16x16x32_bf16 v[110:113], v[114:117], v[194:197], v[110:113]
	v_mfma_f32_16x16x32_bf16 v[106:109], v[122:125], v[194:197], v[106:109]
	v_mfma_f32_16x16x32_bf16 v[98:101], v[114:117], v[206:209], v[98:101]
	v_mfma_f32_16x16x32_bf16 v[90:93], v[122:125], v[206:209], v[90:93]
	v_mfma_f32_16x16x32_bf16 v[82:85], v[114:117], v[214:217], v[82:85]
	v_mfma_f32_16x16x32_bf16 v[74:77], v[122:125], v[214:217], v[74:77]
	v_mfma_f32_16x16x32_bf16 v[142:145], v[118:121], v[166:169], v[142:145]
	v_mfma_f32_16x16x32_bf16 v[138:141], v[126:129], v[166:169], v[138:141]
	v_mfma_f32_16x16x32_bf16 v[110:113], v[118:121], v[198:201], v[110:113]
	v_mfma_f32_16x16x32_bf16 v[106:109], v[126:129], v[198:201], v[106:109]
	v_mfma_f32_16x16x32_bf16 v[98:101], v[118:121], v[210:213], v[98:101]
	v_mfma_f32_16x16x32_bf16 v[90:93], v[126:129], v[210:213], v[90:93]
	v_mfma_f32_16x16x32_bf16 v[82:85], v[118:121], v[218:221], v[82:85]
	v_mfma_f32_16x16x32_bf16 v[74:77], v[126:129], v[218:221], v[74:77]
	v_mfma_f32_16x16x32_bf16 v[134:137], v[146:149], v[162:165], v[134:137]
	v_mfma_f32_16x16x32_bf16 v[130:133], v[154:157], v[162:165], v[130:133]
	v_mfma_f32_16x16x32_bf16 v[102:105], v[146:149], v[194:197], v[102:105]
	v_mfma_f32_16x16x32_bf16 v[94:97], v[154:157], v[194:197], v[94:97]
	v_mfma_f32_16x16x32_bf16 v[86:89], v[146:149], v[206:209], v[86:89]
	v_mfma_f32_16x16x32_bf16 v[78:81], v[154:157], v[206:209], v[78:81]
	v_mfma_f32_16x16x32_bf16 v[70:73], v[146:149], v[214:217], v[70:73]
	v_mfma_f32_16x16x32_bf16 v[66:69], v[154:157], v[214:217], v[66:69]
	v_mfma_f32_16x16x32_bf16 v[134:137], v[150:153], v[166:169], v[134:137]
	v_mfma_f32_16x16x32_bf16 v[130:133], v[158:161], v[166:169], v[130:133]
	v_mfma_f32_16x16x32_bf16 v[102:105], v[150:153], v[198:201], v[102:105]
	v_mfma_f32_16x16x32_bf16 v[94:97], v[158:161], v[198:201], v[94:97]
	v_mfma_f32_16x16x32_bf16 v[86:89], v[150:153], v[210:213], v[86:89]
	v_mfma_f32_16x16x32_bf16 v[78:81], v[158:161], v[210:213], v[78:81]
	v_mfma_f32_16x16x32_bf16 v[70:73], v[150:153], v[218:221], v[70:73]
	v_mfma_f32_16x16x32_bf16 v[66:69], v[158:161], v[218:221], v[66:69]
	s_setprio 0
	s_barrier
	s_add_i32 s63, s63, s86
	v_lshl_add_u64 v[186:187], v[186:187], 0, s[22:23]
	s_mov_b32 m0, s63
	ds_read_b128 v[162:165], v192 offset:49152
	ds_read_b128 v[166:169], v192 offset:50176
	ds_read_b128 v[194:197], v192 offset:51200
	ds_read_b128 v[198:201], v192 offset:52224
	ds_read_b128 v[206:209], v192 offset:53248
	ds_read_b128 v[210:213], v192 offset:54272
	ds_read_b128 v[214:217], v192 offset:55296
	ds_read_b128 v[218:221], v192 offset:56320
	global_load_lds_dwordx4 v[186:187], off
	s_add_i32 m0, s63, 0x2000
	s_add_u32 s78, s78, 0x100080
	v_lshl_add_u64 v[186:187], v[202:203], 0, s[22:23]
	s_addc_u32 s79, s79, 0
	s_add_i32 s63, s83, s86
	global_load_lds_dwordx4 v[186:187], off
	v_lshl_add_u64 v[186:187], s[78:79], 0, v[172:173]
	s_mov_b32 m0, s63
	s_nop 0
	global_load_lds_dwordx4 v[186:187], off
	v_lshl_add_u64 v[186:187], s[78:79], 0, v[176:177]
	s_add_i32 m0, s63, 0x2000
	s_nop 0
	global_load_lds_dwordx4 v[186:187], off
	v_lshl_add_u64 v[186:187], v[222:223], 0, s[22:23]
	s_mov_b32 m0, s95
	s_nop 0
	global_load_lds_dwordx4 v[186:187], off
	v_lshl_add_u64 v[186:187], v[224:225], 0, s[22:23]
	s_mov_b32 m0, s96
	s_nop 0
	global_load_lds_dwordx4 v[186:187], off
	s_waitcnt vmcnt(8) lgkmcnt(0)
	s_setprio 1
	s_barrier
	v_mfma_f32_16x16x32_bf16 v[62:65], v[114:117], v[162:165], v[62:65]
	v_mfma_f32_16x16x32_bf16 v[58:61], v[122:125], v[162:165], v[58:61]
	v_mfma_f32_16x16x32_bf16 v[50:53], v[114:117], v[194:197], v[50:53]
	v_mfma_f32_16x16x32_bf16 v[42:45], v[122:125], v[194:197], v[42:45]
	v_mfma_f32_16x16x32_bf16 v[34:37], v[114:117], v[206:209], v[34:37]
	v_mfma_f32_16x16x32_bf16 v[26:29], v[122:125], v[206:209], v[26:29]
	v_mfma_f32_16x16x32_bf16 v[18:21], v[114:117], v[214:217], v[18:21]
	v_mfma_f32_16x16x32_bf16 v[10:13], v[122:125], v[214:217], v[10:13]
	v_mfma_f32_16x16x32_bf16 v[62:65], v[118:121], v[166:169], v[62:65]
	v_mfma_f32_16x16x32_bf16 v[58:61], v[126:129], v[166:169], v[58:61]
	v_mfma_f32_16x16x32_bf16 v[50:53], v[118:121], v[198:201], v[50:53]
	v_mfma_f32_16x16x32_bf16 v[42:45], v[126:129], v[198:201], v[42:45]
	v_mfma_f32_16x16x32_bf16 v[34:37], v[118:121], v[210:213], v[34:37]
	v_mfma_f32_16x16x32_bf16 v[26:29], v[126:129], v[210:213], v[26:29]
	v_mfma_f32_16x16x32_bf16 v[18:21], v[118:121], v[218:221], v[18:21]
	v_mfma_f32_16x16x32_bf16 v[10:13], v[126:129], v[218:221], v[10:13]
	v_mfma_f32_16x16x32_bf16 v[54:57], v[146:149], v[162:165], v[54:57]
	v_mfma_f32_16x16x32_bf16 v[46:49], v[154:157], v[162:165], v[46:49]
	v_mfma_f32_16x16x32_bf16 v[38:41], v[146:149], v[194:197], v[38:41]
	v_mfma_f32_16x16x32_bf16 v[30:33], v[154:157], v[194:197], v[30:33]
	v_mfma_f32_16x16x32_bf16 v[22:25], v[146:149], v[206:209], v[22:25]
	v_mfma_f32_16x16x32_bf16 v[14:17], v[154:157], v[206:209], v[14:17]
	v_mfma_f32_16x16x32_bf16 v[6:9], v[146:149], v[214:217], v[6:9]
	v_mfma_f32_16x16x32_bf16 v[2:5], v[154:157], v[214:217], v[2:5]
	v_mfma_f32_16x16x32_bf16 v[54:57], v[150:153], v[166:169], v[54:57]
	v_mfma_f32_16x16x32_bf16 v[46:49], v[158:161], v[166:169], v[46:49]
	v_mfma_f32_16x16x32_bf16 v[38:41], v[150:153], v[198:201], v[38:41]
	v_mfma_f32_16x16x32_bf16 v[30:33], v[158:161], v[198:201], v[30:33]
	v_mfma_f32_16x16x32_bf16 v[22:25], v[150:153], v[210:213], v[22:25]
	v_mfma_f32_16x16x32_bf16 v[14:17], v[158:161], v[210:213], v[14:17]
	v_mfma_f32_16x16x32_bf16 v[6:9], v[150:153], v[218:221], v[6:9]
	v_mfma_f32_16x16x32_bf16 v[2:5], v[158:161], v[218:221], v[2:5]
	s_setprio 0
	s_barrier
	s_add_u32 s76, s76, 0x100
	s_addc_u32 s77, s77, 0
	s_add_u32 s47, s47, 0x100
	s_addc_u32 s62, s62, 0
	s_cmp_ge_i32 s82, s7
	s_mov_b32 s63, s82
	s_cbranch_scc0 .LBB0_834
	s_and_b64 vcc, exec, s[26:27]
	s_cbranch_vccz .LBB0_837
	s_barrier

.LBB0_1012:
	s_add_u32 s48, s96, s44
	s_addc_u32 s49, s97, s45
	s_and_b64 s[14:15], s[4:5], exec
	s_cselect_b32 s6, s49, s65
	s_cselect_b32 s14, s48, s64
	s_add_u32 s50, s3, s46
	s_addc_u32 s51, s35, s47
	s_and_b64 s[18:19], s[4:5], exec
	s_cselect_b32 s15, s51, s67
	s_cselect_b32 s17, s50, s66
	s_add_u32 s64, s64, 0x40080
	s_addc_u32 s65, s65, 0
	s_add_u32 s18, s66, 0x100
	s_addc_u32 s19, s67, 0
	s_mov_b32 s24, -2
	s_waitcnt vmcnt(0)
	ds_read_b128 v[130:133], v172
	ds_read_b128 v[134:137], v172 offset:1024
	ds_read_b128 v[138:141], v172 offset:2048
	ds_read_b128 v[142:145], v172 offset:3072
	ds_read_b128 v[164:167], v173
	ds_read_b128 v[176:179], v173 offset:1024
	ds_read_b128 v[180:183], v173 offset:2048
	ds_read_b128 v[184:187], v173 offset:3072
	s_add_u32 s25, s64, 0xfffc0080
	s_addc_u32 s28, s65, -1
	s_cmp_eq_u32 s24, 12
	s_cselect_b32 s69, s6, s28
	s_cselect_b32 s68, s14, s25
	s_cselect_b32 s67, s15, s19
	s_cselect_b32 s66, s17, s18
	v_lshl_add_u64 v[168:169], s[64:65], 0, v[156:157]
	s_add_i32 m0, s73, 0xc000
	ds_read_b128 v[188:191], v174
	ds_read_b128 v[192:195], v174 offset:1024
	ds_read_b128 v[196:199], v174 offset:2048
	ds_read_b128 v[200:203], v174 offset:3072
	ds_read_b128 v[206:209], v174 offset:4096
	ds_read_b128 v[210:213], v174 offset:5120
	ds_read_b128 v[214:217], v174 offset:6144
	ds_read_b128 v[218:221], v174 offset:7168
	global_load_lds_dwordx4 v[168:169], off
	v_lshl_add_u64 v[168:169], s[64:65], 0, v[158:159]
	s_add_i32 m0, s73, 0xe000
	s_nop 0
	global_load_lds_dwordx4 v[168:169], off
	s_waitcnt vmcnt(8) lgkmcnt(0)
	s_setprio 1
	s_barrier
	v_mfma_f32_16x16x32_bf16 v[126:129], v[130:133], v[188:191], 0
	v_mfma_f32_16x16x32_bf16 v[122:125], v[138:141], v[188:191], 0
	v_mfma_f32_16x16x32_bf16 v[110:113], v[130:133], v[196:199], 0
	v_mfma_f32_16x16x32_bf16 v[106:109], v[138:141], v[196:199], 0
	v_mfma_f32_16x16x32_bf16 v[94:97], v[130:133], v[206:209], 0
	v_mfma_f32_16x16x32_bf16 v[90:93], v[138:141], v[206:209], 0
	v_mfma_f32_16x16x32_bf16 v[78:81], v[130:133], v[214:217], 0
	v_mfma_f32_16x16x32_bf16 v[74:77], v[138:141], v[214:217], 0
	v_mfma_f32_16x16x32_bf16 v[126:129], v[134:137], v[192:195], v[126:129]
	v_mfma_f32_16x16x32_bf16 v[122:125], v[142:145], v[192:195], v[122:125]
	v_mfma_f32_16x16x32_bf16 v[110:113], v[134:137], v[200:203], v[110:113]
	v_mfma_f32_16x16x32_bf16 v[106:109], v[142:145], v[200:203], v[106:109]
	v_mfma_f32_16x16x32_bf16 v[94:97], v[134:137], v[210:213], v[94:97]
	v_mfma_f32_16x16x32_bf16 v[90:93], v[142:145], v[210:213], v[90:93]
	v_mfma_f32_16x16x32_bf16 v[78:81], v[134:137], v[218:221], v[78:81]
	v_mfma_f32_16x16x32_bf16 v[74:77], v[142:145], v[218:221], v[74:77]
	v_mfma_f32_16x16x32_bf16 v[118:121], v[164:167], v[188:191], 0
	v_mfma_f32_16x16x32_bf16 v[114:117], v[180:183], v[188:191], 0
	v_mfma_f32_16x16x32_bf16 v[102:105], v[164:167], v[196:199], 0
	v_mfma_f32_16x16x32_bf16 v[98:101], v[180:183], v[196:199], 0
	v_mfma_f32_16x16x32_bf16 v[86:89], v[164:167], v[206:209], 0
	v_mfma_f32_16x16x32_bf16 v[82:85], v[180:183], v[206:209], 0
	v_mfma_f32_16x16x32_bf16 v[70:73], v[164:167], v[214:217], 0
	v_mfma_f32_16x16x32_bf16 v[66:69], v[180:183], v[214:217], 0
	v_mfma_f32_16x16x32_bf16 v[118:121], v[176:179], v[192:195], v[118:121]
	v_mfma_f32_16x16x32_bf16 v[114:117], v[184:187], v[192:195], v[114:117]
	v_mfma_f32_16x16x32_bf16 v[102:105], v[176:179], v[200:203], v[102:105]
	v_mfma_f32_16x16x32_bf16 v[98:101], v[184:187], v[200:203], v[98:101]
	v_mfma_f32_16x16x32_bf16 v[86:89], v[176:179], v[210:213], v[86:89]
	v_mfma_f32_16x16x32_bf16 v[82:85], v[184:187], v[210:213], v[82:85]
	v_mfma_f32_16x16x32_bf16 v[70:73], v[176:179], v[218:221], v[70:73]
	v_mfma_f32_16x16x32_bf16 v[66:69], v[184:187], v[218:221], v[66:69]
	s_setprio 0
	s_barrier
	s_add_i32 s25, s82, s70
	v_lshl_add_u64 v[168:169], s[66:67], 0, v[150:151]
	s_mov_b32 m0, s25
	ds_read_b128 v[188:191], v174 offset:16384
	ds_read_b128 v[192:195], v174 offset:17408
	ds_read_b128 v[196:199], v174 offset:18432
	ds_read_b128 v[200:203], v174 offset:19456
	ds_read_b128 v[206:209], v174 offset:20480
	ds_read_b128 v[210:213], v174 offset:21504
	ds_read_b128 v[214:217], v174 offset:22528
	ds_read_b128 v[218:221], v174 offset:23552
	global_load_lds_dwordx4 v[168:169], off
	s_add_i32 m0, s25, 0x2000
	s_add_u32 s28, s66, 0x40000
	v_lshl_add_u64 v[222:223], s[66:67], 0, v[146:147]
	s_addc_u32 s29, s67, 0
	s_add_i32 s25, s83, s70
	global_load_lds_dwordx4 v[222:223], off
	v_lshl_add_u64 v[224:225], s[28:29], 0, v[150:151]
	s_mov_b32 m0, s25
	v_lshl_add_u64 v[226:227], s[68:69], 0, v[148:149]
	global_load_lds_dwordx4 v[224:225], off
	v_lshl_add_u64 v[224:225], s[28:29], 0, v[146:147]
	s_add_i32 m0, s25, 0x2000
	s_nop 0
	global_load_lds_dwordx4 v[224:225], off
	v_lshl_add_u64 v[224:225], s[68:69], 0, v[152:153]
	s_mov_b32 m0, s73
	s_nop 0
	global_load_lds_dwordx4 v[224:225], off
	s_mov_b32 m0, s74
	s_nop 0
	global_load_lds_dwordx4 v[226:227], off
	s_waitcnt vmcnt(8) lgkmcnt(0)
	s_setprio 1
	s_barrier
	v_mfma_f32_16x16x32_bf16 v[62:65], v[130:133], v[188:191], 0
	v_mfma_f32_16x16x32_bf16 v[58:61], v[138:141], v[188:191], 0
	v_mfma_f32_16x16x32_bf16 v[46:49], v[130:133], v[196:199], 0
	v_mfma_f32_16x16x32_bf16 v[42:45], v[138:141], v[196:199], 0
	v_mfma_f32_16x16x32_bf16 v[30:33], v[130:133], v[206:209], 0
	v_mfma_f32_16x16x32_bf16 v[26:29], v[138:141], v[206:209], 0
	v_mfma_f32_16x16x32_bf16 v[14:17], v[130:133], v[214:217], 0
	v_mfma_f32_16x16x32_bf16 v[10:13], v[138:141], v[214:217], 0
	v_mfma_f32_16x16x32_bf16 v[62:65], v[134:137], v[192:195], v[62:65]
	v_mfma_f32_16x16x32_bf16 v[58:61], v[142:145], v[192:195], v[58:61]
	v_mfma_f32_16x16x32_bf16 v[46:49], v[134:137], v[200:203], v[46:49]
	v_mfma_f32_16x16x32_bf16 v[42:45], v[142:145], v[200:203], v[42:45]
	v_mfma_f32_16x16x32_bf16 v[30:33], v[134:137], v[210:213], v[30:33]
	v_mfma_f32_16x16x32_bf16 v[26:29], v[142:145], v[210:213], v[26:29]
	v_mfma_f32_16x16x32_bf16 v[14:17], v[134:137], v[218:221], v[14:17]
	v_mfma_f32_16x16x32_bf16 v[10:13], v[142:145], v[218:221], v[10:13]
	v_mfma_f32_16x16x32_bf16 v[54:57], v[164:167], v[188:191], 0
	v_mfma_f32_16x16x32_bf16 v[50:53], v[180:183], v[188:191], 0
	v_mfma_f32_16x16x32_bf16 v[38:41], v[164:167], v[196:199], 0
	v_mfma_f32_16x16x32_bf16 v[34:37], v[180:183], v[196:199], 0
	v_mfma_f32_16x16x32_bf16 v[22:25], v[164:167], v[206:209], 0
	v_mfma_f32_16x16x32_bf16 v[18:21], v[180:183], v[206:209], 0
	v_mfma_f32_16x16x32_bf16 v[6:9], v[164:167], v[214:217], 0
	v_mfma_f32_16x16x32_bf16 v[2:5], v[180:183], v[214:217], 0
	v_mfma_f32_16x16x32_bf16 v[54:57], v[176:179], v[192:195], v[54:57]
	v_mfma_f32_16x16x32_bf16 v[50:53], v[184:187], v[192:195], v[50:53]
	v_mfma_f32_16x16x32_bf16 v[38:41], v[176:179], v[200:203], v[38:41]
	v_mfma_f32_16x16x32_bf16 v[34:37], v[184:187], v[200:203], v[34:37]
	v_mfma_f32_16x16x32_bf16 v[22:25], v[176:179], v[210:213], v[22:25]
	v_mfma_f32_16x16x32_bf16 v[18:21], v[184:187], v[210:213], v[18:21]
	v_mfma_f32_16x16x32_bf16 v[6:9], v[176:179], v[218:221], v[6:9]
	v_mfma_f32_16x16x32_bf16 v[2:5], v[184:187], v[218:221], v[2:5]
	s_setprio 0
	s_barrier
	s_add_i32 s25, 0, 0x18000
	s_add_i32 s30, 0, 0x1c000
	v_add_u32_e32 v142, s25, v171
	v_add_u32_e32 v175, s30, v171
	ds_read_b128 v[130:133], v142
	ds_read_b128 v[134:137], v142 offset:1024
	ds_read_b128 v[138:141], v142 offset:2048
	ds_read_b128 v[142:145], v142 offset:3072
	ds_read_b128 v[164:167], v175
	ds_read_b128 v[176:179], v175 offset:1024
	ds_read_b128 v[180:183], v175 offset:2048
	ds_read_b128 v[184:187], v175 offset:3072
	s_add_u32 s28, s68, 0x40000
	s_addc_u32 s29, s69, 0
	s_mov_b32 m0, s75
	v_lshl_add_u64 v[228:229], s[28:29], 0, v[152:153]
	ds_read_b128 v[188:191], v174 offset:32768
	ds_read_b128 v[192:195], v174 offset:33792
	ds_read_b128 v[196:199], v174 offset:34816
	ds_read_b128 v[200:203], v174 offset:35840
	ds_read_b128 v[206:209], v174 offset:36864
	ds_read_b128 v[210:213], v174 offset:37888
	ds_read_b128 v[214:217], v174 offset:38912
	ds_read_b128 v[218:221], v174 offset:39936
	global_load_lds_dwordx4 v[228:229], off
	v_lshl_add_u64 v[228:229], s[28:29], 0, v[148:149]
	s_mov_b32 m0, s76
	s_nop 0
	global_load_lds_dwordx4 v[228:229], off
	s_waitcnt vmcnt(8) lgkmcnt(0)
	s_setprio 1
	s_barrier
	v_mfma_f32_16x16x32_bf16 v[126:129], v[130:133], v[188:191], v[126:129]
	v_mfma_f32_16x16x32_bf16 v[122:125], v[138:141], v[188:191], v[122:125]
	v_mfma_f32_16x16x32_bf16 v[110:113], v[130:133], v[196:199], v[110:113]
	v_mfma_f32_16x16x32_bf16 v[106:109], v[138:141], v[196:199], v[106:109]
	v_mfma_f32_16x16x32_bf16 v[94:97], v[130:133], v[206:209], v[94:97]
	v_mfma_f32_16x16x32_bf16 v[90:93], v[138:141], v[206:209], v[90:93]
	v_mfma_f32_16x16x32_bf16 v[78:81], v[130:133], v[214:217], v[78:81]
	v_mfma_f32_16x16x32_bf16 v[74:77], v[138:141], v[214:217], v[74:77]
	v_mfma_f32_16x16x32_bf16 v[126:129], v[134:137], v[192:195], v[126:129]
	v_mfma_f32_16x16x32_bf16 v[122:125], v[142:145], v[192:195], v[122:125]
	v_mfma_f32_16x16x32_bf16 v[110:113], v[134:137], v[200:203], v[110:113]
	v_mfma_f32_16x16x32_bf16 v[106:109], v[142:145], v[200:203], v[106:109]
	v_mfma_f32_16x16x32_bf16 v[94:97], v[134:137], v[210:213], v[94:97]
	v_mfma_f32_16x16x32_bf16 v[90:93], v[142:145], v[210:213], v[90:93]
	v_mfma_f32_16x16x32_bf16 v[78:81], v[134:137], v[218:221], v[78:81]
	v_mfma_f32_16x16x32_bf16 v[74:77], v[142:145], v[218:221], v[74:77]
	v_mfma_f32_16x16x32_bf16 v[118:121], v[164:167], v[188:191], v[118:121]
	v_mfma_f32_16x16x32_bf16 v[114:117], v[180:183], v[188:191], v[114:117]
	v_mfma_f32_16x16x32_bf16 v[102:105], v[164:167], v[196:199], v[102:105]
	v_mfma_f32_16x16x32_bf16 v[98:101], v[180:183], v[196:199], v[98:101]
	v_mfma_f32_16x16x32_bf16 v[86:89], v[164:167], v[206:209], v[86:89]
	v_mfma_f32_16x16x32_bf16 v[82:85], v[180:183], v[206:209], v[82:85]
	v_mfma_f32_16x16x32_bf16 v[70:73], v[164:167], v[214:217], v[70:73]
	v_mfma_f32_16x16x32_bf16 v[66:69], v[180:183], v[214:217], v[66:69]
	v_mfma_f32_16x16x32_bf16 v[118:121], v[176:179], v[192:195], v[118:121]
	v_mfma_f32_16x16x32_bf16 v[114:117], v[184:187], v[192:195], v[114:117]
	v_mfma_f32_16x16x32_bf16 v[102:105], v[176:179], v[200:203], v[102:105]
	v_mfma_f32_16x16x32_bf16 v[98:101], v[184:187], v[200:203], v[98:101]
	v_mfma_f32_16x16x32_bf16 v[86:89], v[176:179], v[210:213], v[86:89]
	v_mfma_f32_16x16x32_bf16 v[82:85], v[184:187], v[210:213], v[82:85]
	v_mfma_f32_16x16x32_bf16 v[70:73], v[176:179], v[218:221], v[70:73]
	v_mfma_f32_16x16x32_bf16 v[66:69], v[184:187], v[218:221], v[66:69]
	s_setprio 0
	s_barrier
	s_add_i32 s25, s25, s70
	v_lshl_add_u64 v[168:169], v[168:169], 0, s[36:37]
	s_mov_b32 m0, s25
	ds_read_b128 v[188:191], v174 offset:49152
	ds_read_b128 v[192:195], v174 offset:50176
	ds_read_b128 v[196:199], v174 offset:51200
	ds_read_b128 v[200:203], v174 offset:52224
	ds_read_b128 v[206:209], v174 offset:53248
	ds_read_b128 v[210:213], v174 offset:54272
	ds_read_b128 v[214:217], v174 offset:55296
	ds_read_b128 v[218:221], v174 offset:56320
	global_load_lds_dwordx4 v[168:169], off
	s_add_i32 m0, s25, 0x2000
	s_add_u32 s28, s66, 0x40080
	v_lshl_add_u64 v[168:169], v[222:223], 0, s[36:37]
	s_addc_u32 s29, s67, 0
	s_add_i32 s25, s30, s70
	global_load_lds_dwordx4 v[168:169], off
	v_lshl_add_u64 v[168:169], s[28:29], 0, v[150:151]
	s_mov_b32 m0, s25
	s_nop 0
	global_load_lds_dwordx4 v[168:169], off
	v_lshl_add_u64 v[168:169], s[28:29], 0, v[146:147]
	s_add_i32 m0, s25, 0x2000
	s_nop 0
	global_load_lds_dwordx4 v[168:169], off
	v_lshl_add_u64 v[168:169], v[224:225], 0, s[36:37]
	s_mov_b32 m0, s79
	s_nop 0
	global_load_lds_dwordx4 v[168:169], off
	v_lshl_add_u64 v[168:169], v[226:227], 0, s[36:37]
	s_mov_b32 m0, s80
	s_nop 0
	global_load_lds_dwordx4 v[168:169], off
	s_waitcnt vmcnt(8) lgkmcnt(0)
	s_setprio 1
	s_barrier
	v_mfma_f32_16x16x32_bf16 v[62:65], v[130:133], v[188:191], v[62:65]
	v_mfma_f32_16x16x32_bf16 v[58:61], v[138:141], v[188:191], v[58:61]
	v_mfma_f32_16x16x32_bf16 v[46:49], v[130:133], v[196:199], v[46:49]
	v_mfma_f32_16x16x32_bf16 v[42:45], v[138:141], v[196:199], v[42:45]
	v_mfma_f32_16x16x32_bf16 v[30:33], v[130:133], v[206:209], v[30:33]
	v_mfma_f32_16x16x32_bf16 v[26:29], v[138:141], v[206:209], v[26:29]
	v_mfma_f32_16x16x32_bf16 v[14:17], v[130:133], v[214:217], v[14:17]
	v_mfma_f32_16x16x32_bf16 v[10:13], v[138:141], v[214:217], v[10:13]
	v_mfma_f32_16x16x32_bf16 v[62:65], v[134:137], v[192:195], v[62:65]
	v_mfma_f32_16x16x32_bf16 v[58:61], v[142:145], v[192:195], v[58:61]
	v_mfma_f32_16x16x32_bf16 v[46:49], v[134:137], v[200:203], v[46:49]
	v_mfma_f32_16x16x32_bf16 v[42:45], v[142:145], v[200:203], v[42:45]
	v_mfma_f32_16x16x32_bf16 v[30:33], v[134:137], v[210:213], v[30:33]
	v_mfma_f32_16x16x32_bf16 v[26:29], v[142:145], v[210:213], v[26:29]
	v_mfma_f32_16x16x32_bf16 v[14:17], v[134:137], v[218:221], v[14:17]
	v_mfma_f32_16x16x32_bf16 v[10:13], v[142:145], v[218:221], v[10:13]
	v_mfma_f32_16x16x32_bf16 v[54:57], v[164:167], v[188:191], v[54:57]
	v_mfma_f32_16x16x32_bf16 v[50:53], v[180:183], v[188:191], v[50:53]
	v_mfma_f32_16x16x32_bf16 v[38:41], v[164:167], v[196:199], v[38:41]
	v_mfma_f32_16x16x32_bf16 v[34:37], v[180:183], v[196:199], v[34:37]
	v_mfma_f32_16x16x32_bf16 v[22:25], v[164:167], v[206:209], v[22:25]
	v_mfma_f32_16x16x32_bf16 v[18:21], v[180:183], v[206:209], v[18:21]
	v_mfma_f32_16x16x32_bf16 v[6:9], v[164:167], v[214:217], v[6:9]
	v_mfma_f32_16x16x32_bf16 v[2:5], v[180:183], v[214:217], v[2:5]
	v_mfma_f32_16x16x32_bf16 v[54:57], v[176:179], v[192:195], v[54:57]
	v_mfma_f32_16x16x32_bf16 v[50:53], v[184:187], v[192:195], v[50:53]
	v_mfma_f32_16x16x32_bf16 v[38:41], v[176:179], v[200:203], v[38:41]
	v_mfma_f32_16x16x32_bf16 v[34:37], v[184:187], v[200:203], v[34:37]
	v_mfma_f32_16x16x32_bf16 v[22:25], v[176:179], v[210:213], v[22:25]
	v_mfma_f32_16x16x32_bf16 v[18:21], v[184:187], v[210:213], v[18:21]
	v_mfma_f32_16x16x32_bf16 v[6:9], v[176:179], v[218:221], v[6:9]
	v_mfma_f32_16x16x32_bf16 v[2:5], v[184:187], v[218:221], v[2:5]
	s_setprio 0
	s_barrier
	s_add_i32 s24, s24, 2
	s_add_u32 s64, s64, 0x100
	s_addc_u32 s65, s65, 0
	s_add_u32 s18, s18, 0x100
	s_addc_u32 s19, s19, 0
	s_cmp_gt_u32 s24, 13
.LBB0_1013:
	ds_read_b128 v[130:133], v172
	ds_read_b128 v[134:137], v172 offset:1024
	ds_read_b128 v[138:141], v172 offset:2048
	ds_read_b128 v[142:145], v172 offset:3072
	ds_read_b128 v[164:167], v173
	ds_read_b128 v[176:179], v173 offset:1024
	ds_read_b128 v[180:183], v173 offset:2048
	ds_read_b128 v[184:187], v173 offset:3072
	s_add_u32 s25, s64, 0xfffc0080
	s_addc_u32 s28, s65, -1
	s_cmp_eq_u32 s24, 12
	s_cselect_b32 s69, s6, s28
	s_cselect_b32 s68, s14, s25
	s_cselect_b32 s67, s15, s19
	s_cselect_b32 s66, s17, s18
	v_lshl_add_u64 v[168:169], s[64:65], 0, v[156:157]
	s_add_i32 m0, s73, 0xc000
	ds_read_b128 v[188:191], v174
	ds_read_b128 v[192:195], v174 offset:1024
	ds_read_b128 v[196:199], v174 offset:2048
	ds_read_b128 v[200:203], v174 offset:3072
	ds_read_b128 v[206:209], v174 offset:4096
	ds_read_b128 v[210:213], v174 offset:5120
	ds_read_b128 v[214:217], v174 offset:6144
	ds_read_b128 v[218:221], v174 offset:7168
	global_load_lds_dwordx4 v[168:169], off
	v_lshl_add_u64 v[168:169], s[64:65], 0, v[158:159]
	s_add_i32 m0, s73, 0xe000
	s_nop 0
	global_load_lds_dwordx4 v[168:169], off
	s_waitcnt vmcnt(8) lgkmcnt(0)
	s_setprio 1
	s_barrier
	v_mfma_f32_16x16x32_bf16 v[126:129], v[130:133], v[188:191], v[126:129]
	v_mfma_f32_16x16x32_bf16 v[122:125], v[138:141], v[188:191], v[122:125]
	v_mfma_f32_16x16x32_bf16 v[110:113], v[130:133], v[196:199], v[110:113]
	v_mfma_f32_16x16x32_bf16 v[106:109], v[138:141], v[196:199], v[106:109]
	v_mfma_f32_16x16x32_bf16 v[94:97], v[130:133], v[206:209], v[94:97]
	v_mfma_f32_16x16x32_bf16 v[90:93], v[138:141], v[206:209], v[90:93]
	v_mfma_f32_16x16x32_bf16 v[78:81], v[130:133], v[214:217], v[78:81]
	v_mfma_f32_16x16x32_bf16 v[74:77], v[138:141], v[214:217], v[74:77]
	v_mfma_f32_16x16x32_bf16 v[126:129], v[134:137], v[192:195], v[126:129]
	v_mfma_f32_16x16x32_bf16 v[122:125], v[142:145], v[192:195], v[122:125]
	v_mfma_f32_16x16x32_bf16 v[110:113], v[134:137], v[200:203], v[110:113]
	v_mfma_f32_16x16x32_bf16 v[106:109], v[142:145], v[200:203], v[106:109]
	v_mfma_f32_16x16x32_bf16 v[94:97], v[134:137], v[210:213], v[94:97]
	v_mfma_f32_16x16x32_bf16 v[90:93], v[142:145], v[210:213], v[90:93]
	v_mfma_f32_16x16x32_bf16 v[78:81], v[134:137], v[218:221], v[78:81]
	v_mfma_f32_16x16x32_bf16 v[74:77], v[142:145], v[218:221], v[74:77]
	v_mfma_f32_16x16x32_bf16 v[118:121], v[164:167], v[188:191], v[118:121]
	v_mfma_f32_16x16x32_bf16 v[114:117], v[180:183], v[188:191], v[114:117]
	v_mfma_f32_16x16x32_bf16 v[102:105], v[164:167], v[196:199], v[102:105]
	v_mfma_f32_16x16x32_bf16 v[98:101], v[180:183], v[196:199], v[98:101]
	v_mfma_f32_16x16x32_bf16 v[86:89], v[164:167], v[206:209], v[86:89]
	v_mfma_f32_16x16x32_bf16 v[82:85], v[180:183], v[206:209], v[82:85]
	v_mfma_f32_16x16x32_bf16 v[70:73], v[164:167], v[214:217], v[70:73]
	v_mfma_f32_16x16x32_bf16 v[66:69], v[180:183], v[214:217], v[66:69]
	v_mfma_f32_16x16x32_bf16 v[118:121], v[176:179], v[192:195], v[118:121]
	v_mfma_f32_16x16x32_bf16 v[114:117], v[184:187], v[192:195], v[114:117]
	v_mfma_f32_16x16x32_bf16 v[102:105], v[176:179], v[200:203], v[102:105]
	v_mfma_f32_16x16x32_bf16 v[98:101], v[184:187], v[200:203], v[98:101]
	v_mfma_f32_16x16x32_bf16 v[86:89], v[176:179], v[210:213], v[86:89]
	v_mfma_f32_16x16x32_bf16 v[82:85], v[184:187], v[210:213], v[82:85]
	v_mfma_f32_16x16x32_bf16 v[70:73], v[176:179], v[218:221], v[70:73]
	v_mfma_f32_16x16x32_bf16 v[66:69], v[184:187], v[218:221], v[66:69]
	s_setprio 0
	s_barrier
	s_add_i32 s25, s82, s70
	v_lshl_add_u64 v[168:169], s[66:67], 0, v[150:151]
	s_mov_b32 m0, s25
	ds_read_b128 v[188:191], v174 offset:16384
	ds_read_b128 v[192:195], v174 offset:17408
	ds_read_b128 v[196:199], v174 offset:18432
	ds_read_b128 v[200:203], v174 offset:19456
	ds_read_b128 v[206:209], v174 offset:20480
	ds_read_b128 v[210:213], v174 offset:21504
	ds_read_b128 v[214:217], v174 offset:22528
	ds_read_b128 v[218:221], v174 offset:23552
	global_load_lds_dwordx4 v[168:169], off
	s_add_i32 m0, s25, 0x2000
	s_add_u32 s28, s66, 0x40000
	v_lshl_add_u64 v[222:223], s[66:67], 0, v[146:147]
	s_addc_u32 s29, s67, 0
	s_add_i32 s25, s83, s70
	global_load_lds_dwordx4 v[222:223], off
	v_lshl_add_u64 v[224:225], s[28:29], 0, v[150:151]
	s_mov_b32 m0, s25
	v_lshl_add_u64 v[226:227], s[68:69], 0, v[148:149]
	global_load_lds_dwordx4 v[224:225], off
	v_lshl_add_u64 v[224:225], s[28:29], 0, v[146:147]
	s_add_i32 m0, s25, 0x2000
	s_nop 0
	global_load_lds_dwordx4 v[224:225], off
	v_lshl_add_u64 v[224:225], s[68:69], 0, v[152:153]
	s_mov_b32 m0, s73
	s_nop 0
	global_load_lds_dwordx4 v[224:225], off
	s_mov_b32 m0, s74
	s_nop 0
	global_load_lds_dwordx4 v[226:227], off
	s_waitcnt vmcnt(8) lgkmcnt(0)
	s_setprio 1
	s_barrier
	v_mfma_f32_16x16x32_bf16 v[62:65], v[130:133], v[188:191], v[62:65]
	v_mfma_f32_16x16x32_bf16 v[58:61], v[138:141], v[188:191], v[58:61]
	v_mfma_f32_16x16x32_bf16 v[46:49], v[130:133], v[196:199], v[46:49]
	v_mfma_f32_16x16x32_bf16 v[42:45], v[138:141], v[196:199], v[42:45]
	v_mfma_f32_16x16x32_bf16 v[30:33], v[130:133], v[206:209], v[30:33]
	v_mfma_f32_16x16x32_bf16 v[26:29], v[138:141], v[206:209], v[26:29]
	v_mfma_f32_16x16x32_bf16 v[14:17], v[130:133], v[214:217], v[14:17]
	v_mfma_f32_16x16x32_bf16 v[10:13], v[138:141], v[214:217], v[10:13]
	v_mfma_f32_16x16x32_bf16 v[62:65], v[134:137], v[192:195], v[62:65]
	v_mfma_f32_16x16x32_bf16 v[58:61], v[142:145], v[192:195], v[58:61]
	v_mfma_f32_16x16x32_bf16 v[46:49], v[134:137], v[200:203], v[46:49]
	v_mfma_f32_16x16x32_bf16 v[42:45], v[142:145], v[200:203], v[42:45]
	v_mfma_f32_16x16x32_bf16 v[30:33], v[134:137], v[210:213], v[30:33]
	v_mfma_f32_16x16x32_bf16 v[26:29], v[142:145], v[210:213], v[26:29]
	v_mfma_f32_16x16x32_bf16 v[14:17], v[134:137], v[218:221], v[14:17]
	v_mfma_f32_16x16x32_bf16 v[10:13], v[142:145], v[218:221], v[10:13]
	v_mfma_f32_16x16x32_bf16 v[54:57], v[164:167], v[188:191], v[54:57]
	v_mfma_f32_16x16x32_bf16 v[50:53], v[180:183], v[188:191], v[50:53]
	v_mfma_f32_16x16x32_bf16 v[38:41], v[164:167], v[196:199], v[38:41]
	v_mfma_f32_16x16x32_bf16 v[34:37], v[180:183], v[196:199], v[34:37]
	v_mfma_f32_16x16x32_bf16 v[22:25], v[164:167], v[206:209], v[22:25]
	v_mfma_f32_16x16x32_bf16 v[18:21], v[180:183], v[206:209], v[18:21]
	v_mfma_f32_16x16x32_bf16 v[6:9], v[164:167], v[214:217], v[6:9]
	v_mfma_f32_16x16x32_bf16 v[2:5], v[180:183], v[214:217], v[2:5]
	v_mfma_f32_16x16x32_bf16 v[54:57], v[176:179], v[192:195], v[54:57]
	v_mfma_f32_16x16x32_bf16 v[50:53], v[184:187], v[192:195], v[50:53]
	v_mfma_f32_16x16x32_bf16 v[38:41], v[176:179], v[200:203], v[38:41]
	v_mfma_f32_16x16x32_bf16 v[34:37], v[184:187], v[200:203], v[34:37]
	v_mfma_f32_16x16x32_bf16 v[22:25], v[176:179], v[210:213], v[22:25]
	v_mfma_f32_16x16x32_bf16 v[18:21], v[184:187], v[210:213], v[18:21]
	v_mfma_f32_16x16x32_bf16 v[6:9], v[176:179], v[218:221], v[6:9]
	v_mfma_f32_16x16x32_bf16 v[2:5], v[184:187], v[218:221], v[2:5]
	s_setprio 0
	s_barrier
	s_add_i32 s25, 0, 0x18000
	s_add_i32 s30, 0, 0x1c000
	v_add_u32_e32 v142, s25, v171
	v_add_u32_e32 v175, s30, v171
	ds_read_b128 v[130:133], v142
	ds_read_b128 v[134:137], v142 offset:1024
	ds_read_b128 v[138:141], v142 offset:2048
	ds_read_b128 v[142:145], v142 offset:3072
	ds_read_b128 v[164:167], v175
	ds_read_b128 v[176:179], v175 offset:1024
	ds_read_b128 v[180:183], v175 offset:2048
	ds_read_b128 v[184:187], v175 offset:3072
	s_add_u32 s28, s68, 0x40000
	s_addc_u32 s29, s69, 0
	s_mov_b32 m0, s75
	v_lshl_add_u64 v[228:229], s[28:29], 0, v[152:153]
	ds_read_b128 v[188:191], v174 offset:32768
	ds_read_b128 v[192:195], v174 offset:33792
	ds_read_b128 v[196:199], v174 offset:34816
	ds_read_b128 v[200:203], v174 offset:35840
	ds_read_b128 v[206:209], v174 offset:36864
	ds_read_b128 v[210:213], v174 offset:37888
	ds_read_b128 v[214:217], v174 offset:38912
	ds_read_b128 v[218:221], v174 offset:39936
	global_load_lds_dwordx4 v[228:229], off
	v_lshl_add_u64 v[228:229], s[28:29], 0, v[148:149]
	s_mov_b32 m0, s76
	s_nop 0
	global_load_lds_dwordx4 v[228:229], off
	s_waitcnt vmcnt(8) lgkmcnt(0)
	s_setprio 1
	s_barrier
	v_mfma_f32_16x16x32_bf16 v[126:129], v[130:133], v[188:191], v[126:129]
	v_mfma_f32_16x16x32_bf16 v[122:125], v[138:141], v[188:191], v[122:125]
	v_mfma_f32_16x16x32_bf16 v[110:113], v[130:133], v[196:199], v[110:113]
	v_mfma_f32_16x16x32_bf16 v[106:109], v[138:141], v[196:199], v[106:109]
	v_mfma_f32_16x16x32_bf16 v[94:97], v[130:133], v[206:209], v[94:97]
	v_mfma_f32_16x16x32_bf16 v[90:93], v[138:141], v[206:209], v[90:93]
	v_mfma_f32_16x16x32_bf16 v[78:81], v[130:133], v[214:217], v[78:81]
	v_mfma_f32_16x16x32_bf16 v[74:77], v[138:141], v[214:217], v[74:77]
	v_mfma_f32_16x16x32_bf16 v[126:129], v[134:137], v[192:195], v[126:129]
	v_mfma_f32_16x16x32_bf16 v[122:125], v[142:145], v[192:195], v[122:125]
	v_mfma_f32_16x16x32_bf16 v[110:113], v[134:137], v[200:203], v[110:113]
	v_mfma_f32_16x16x32_bf16 v[106:109], v[142:145], v[200:203], v[106:109]
	v_mfma_f32_16x16x32_bf16 v[94:97], v[134:137], v[210:213], v[94:97]
	v_mfma_f32_16x16x32_bf16 v[90:93], v[142:145], v[210:213], v[90:93]
	v_mfma_f32_16x16x32_bf16 v[78:81], v[134:137], v[218:221], v[78:81]
	v_mfma_f32_16x16x32_bf16 v[74:77], v[142:145], v[218:221], v[74:77]
	v_mfma_f32_16x16x32_bf16 v[118:121], v[164:167], v[188:191], v[118:121]
	v_mfma_f32_16x16x32_bf16 v[114:117], v[180:183], v[188:191], v[114:117]
	v_mfma_f32_16x16x32_bf16 v[102:105], v[164:167], v[196:199], v[102:105]
	v_mfma_f32_16x16x32_bf16 v[98:101], v[180:183], v[196:199], v[98:101]
	v_mfma_f32_16x16x32_bf16 v[86:89], v[164:167], v[206:209], v[86:89]
	v_mfma_f32_16x16x32_bf16 v[82:85], v[180:183], v[206:209], v[82:85]
	v_mfma_f32_16x16x32_bf16 v[70:73], v[164:167], v[214:217], v[70:73]
	v_mfma_f32_16x16x32_bf16 v[66:69], v[180:183], v[214:217], v[66:69]
	v_mfma_f32_16x16x32_bf16 v[118:121], v[176:179], v[192:195], v[118:121]
	v_mfma_f32_16x16x32_bf16 v[114:117], v[184:187], v[192:195], v[114:117]
	v_mfma_f32_16x16x32_bf16 v[102:105], v[176:179], v[200:203], v[102:105]
	v_mfma_f32_16x16x32_bf16 v[98:101], v[184:187], v[200:203], v[98:101]
	v_mfma_f32_16x16x32_bf16 v[86:89], v[176:179], v[210:213], v[86:89]
	v_mfma_f32_16x16x32_bf16 v[82:85], v[184:187], v[210:213], v[82:85]
	v_mfma_f32_16x16x32_bf16 v[70:73], v[176:179], v[218:221], v[70:73]
	v_mfma_f32_16x16x32_bf16 v[66:69], v[184:187], v[218:221], v[66:69]
	s_setprio 0
	s_barrier
	s_add_i32 s25, s25, s70
	v_lshl_add_u64 v[168:169], v[168:169], 0, s[36:37]
	s_mov_b32 m0, s25
	ds_read_b128 v[188:191], v174 offset:49152
	ds_read_b128 v[192:195], v174 offset:50176
	ds_read_b128 v[196:199], v174 offset:51200
	ds_read_b128 v[200:203], v174 offset:52224
	ds_read_b128 v[206:209], v174 offset:53248
	ds_read_b128 v[210:213], v174 offset:54272
	ds_read_b128 v[214:217], v174 offset:55296
	ds_read_b128 v[218:221], v174 offset:56320
	global_load_lds_dwordx4 v[168:169], off
	s_add_i32 m0, s25, 0x2000
	s_add_u32 s28, s66, 0x40080
	v_lshl_add_u64 v[168:169], v[222:223], 0, s[36:37]
	s_addc_u32 s29, s67, 0
	s_add_i32 s25, s30, s70
	global_load_lds_dwordx4 v[168:169], off
	v_lshl_add_u64 v[168:169], s[28:29], 0, v[150:151]
	s_mov_b32 m0, s25
	s_nop 0
	global_load_lds_dwordx4 v[168:169], off
	v_lshl_add_u64 v[168:169], s[28:29], 0, v[146:147]
	s_add_i32 m0, s25, 0x2000
	s_nop 0
	global_load_lds_dwordx4 v[168:169], off
	v_lshl_add_u64 v[168:169], v[224:225], 0, s[36:37]
	s_mov_b32 m0, s79
	s_nop 0
	global_load_lds_dwordx4 v[168:169], off
	v_lshl_add_u64 v[168:169], v[226:227], 0, s[36:37]
	s_mov_b32 m0, s80
	s_nop 0
	global_load_lds_dwordx4 v[168:169], off
	s_waitcnt vmcnt(8) lgkmcnt(0)
	s_setprio 1
	s_barrier
	v_mfma_f32_16x16x32_bf16 v[62:65], v[130:133], v[188:191], v[62:65]
	v_mfma_f32_16x16x32_bf16 v[58:61], v[138:141], v[188:191], v[58:61]
	v_mfma_f32_16x16x32_bf16 v[46:49], v[130:133], v[196:199], v[46:49]
	v_mfma_f32_16x16x32_bf16 v[42:45], v[138:141], v[196:199], v[42:45]
	v_mfma_f32_16x16x32_bf16 v[30:33], v[130:133], v[206:209], v[30:33]
	v_mfma_f32_16x16x32_bf16 v[26:29], v[138:141], v[206:209], v[26:29]
	v_mfma_f32_16x16x32_bf16 v[14:17], v[130:133], v[214:217], v[14:17]
	v_mfma_f32_16x16x32_bf16 v[10:13], v[138:141], v[214:217], v[10:13]
	v_mfma_f32_16x16x32_bf16 v[62:65], v[134:137], v[192:195], v[62:65]
	v_mfma_f32_16x16x32_bf16 v[58:61], v[142:145], v[192:195], v[58:61]
	v_mfma_f32_16x16x32_bf16 v[46:49], v[134:137], v[200:203], v[46:49]
	v_mfma_f32_16x16x32_bf16 v[42:45], v[142:145], v[200:203], v[42:45]
	v_mfma_f32_16x16x32_bf16 v[30:33], v[134:137], v[210:213], v[30:33]
	v_mfma_f32_16x16x32_bf16 v[26:29], v[142:145], v[210:213], v[26:29]
	v_mfma_f32_16x16x32_bf16 v[14:17], v[134:137], v[218:221], v[14:17]
	v_mfma_f32_16x16x32_bf16 v[10:13], v[142:145], v[218:221], v[10:13]
	v_mfma_f32_16x16x32_bf16 v[54:57], v[164:167], v[188:191], v[54:57]
	v_mfma_f32_16x16x32_bf16 v[50:53], v[180:183], v[188:191], v[50:53]
	v_mfma_f32_16x16x32_bf16 v[38:41], v[164:167], v[196:199], v[38:41]
	v_mfma_f32_16x16x32_bf16 v[34:37], v[180:183], v[196:199], v[34:37]
	v_mfma_f32_16x16x32_bf16 v[22:25], v[164:167], v[206:209], v[22:25]
	v_mfma_f32_16x16x32_bf16 v[18:21], v[180:183], v[206:209], v[18:21]
	v_mfma_f32_16x16x32_bf16 v[6:9], v[164:167], v[214:217], v[6:9]
	v_mfma_f32_16x16x32_bf16 v[2:5], v[180:183], v[214:217], v[2:5]
	v_mfma_f32_16x16x32_bf16 v[54:57], v[176:179], v[192:195], v[54:57]
	v_mfma_f32_16x16x32_bf16 v[50:53], v[184:187], v[192:195], v[50:53]
	v_mfma_f32_16x16x32_bf16 v[38:41], v[176:179], v[200:203], v[38:41]
	v_mfma_f32_16x16x32_bf16 v[34:37], v[184:187], v[200:203], v[34:37]
	v_mfma_f32_16x16x32_bf16 v[22:25], v[176:179], v[210:213], v[22:25]
	v_mfma_f32_16x16x32_bf16 v[18:21], v[184:187], v[210:213], v[18:21]
	v_mfma_f32_16x16x32_bf16 v[6:9], v[176:179], v[218:221], v[6:9]
	v_mfma_f32_16x16x32_bf16 v[2:5], v[184:187], v[218:221], v[2:5]
	s_setprio 0
	s_barrier
	s_add_i32 s24, s24, 2
	s_add_u32 s64, s64, 0x100
	s_addc_u32 s65, s65, 0
	s_add_u32 s18, s18, 0x100
	s_addc_u32 s19, s19, 0
	s_cmp_gt_u32 s24, 13
	s_cbranch_scc0 .LBB0_1013
	s_and_b64 vcc, exec, s[38:39]
	s_cbranch_vccz .LBB0_1016
	s_barrier

.LBB0_1427:
	s_add_u32 s90, s35, s86
	s_addc_u32 s91, s64, s87
	s_and_b64 s[14:15], s[88:89], exec
	s_cselect_b32 s14, s91, s11
	s_cselect_b32 s15, s90, s10
	s_add_u32 s92, s65, s74
	s_addc_u32 s93, s68, s75
	s_and_b64 s[66:67], s[88:89], exec
	s_cselect_b32 s51, s93, s95
	s_cselect_b32 s84, s92, s94
	s_add_i32 s85, s18, -2
	s_add_u32 s10, s10, 0x40080
	s_addc_u32 s11, s11, 0
	s_add_u32 vcc_lo, s94, 0x100
	s_addc_u32 vcc_hi, s95, 0
	s_mov_b32 s94, 0
	s_waitcnt vmcnt(0)
	s_add_i32 s66, s94, 2
	s_add_u32 s67, s10, 0xfffc0080
	s_addc_u32 s72, s11, -1
	s_cmp_eq_u32 s85, s94
	s_cselect_b32 s97, s14, s72
	s_cselect_b32 s96, s15, s67
	s_cselect_b32 s95, s51, vcc_hi
	s_cselect_b32 s94, s84, vcc_lo
	s_add_i32 s67, 0, 0x10000
	s_add_i32 s62, 0, 0x14000
	v_add_u32_e32 v126, s67, v199
	v_add_u32_e32 v158, s62, v199
	ds_read_b128 v[114:117], v126
	ds_read_b128 v[118:121], v126 offset:1024
	ds_read_b128 v[122:125], v126 offset:2048
	ds_read_b128 v[126:129], v126 offset:3072
	ds_read_b128 v[146:149], v158
	ds_read_b128 v[150:153], v158 offset:1024
	ds_read_b128 v[154:157], v158 offset:2048
	ds_read_b128 v[158:161], v158 offset:3072
	v_lshl_add_u64 v[202:203], s[10:11], 0, v[196:197]
	s_add_i32 m0, s28, 0xc000
	ds_read_b128 v[162:165], v214
	ds_read_b128 v[166:169], v214 offset:1024
	ds_read_b128 v[216:219], v214 offset:2048
	ds_read_b128 v[220:223], v214 offset:3072
	ds_read_b128 v[224:227], v214 offset:4096
	ds_read_b128 v[228:231], v214 offset:5120
	ds_read_b128 v[232:235], v214 offset:6144
	ds_read_b128 v[236:239], v214 offset:7168
	global_load_lds_dwordx4 v[202:203], off
	v_lshl_add_u64 v[202:203], s[10:11], 0, v[176:177]
	s_add_i32 m0, s28, 0xe000
	s_nop 0
	global_load_lds_dwordx4 v[202:203], off
	s_waitcnt vmcnt(8) lgkmcnt(0)
	s_setprio 1
	s_barrier
	v_mfma_f32_16x16x32_bf16 v[142:145], v[114:117], v[162:165], 0
	v_mfma_f32_16x16x32_bf16 v[138:141], v[122:125], v[162:165], 0
	v_mfma_f32_16x16x32_bf16 v[110:113], v[114:117], v[216:219], 0
	v_mfma_f32_16x16x32_bf16 v[106:109], v[122:125], v[216:219], 0
	v_mfma_f32_16x16x32_bf16 v[98:101], v[114:117], v[224:227], 0
	v_mfma_f32_16x16x32_bf16 v[90:93], v[122:125], v[224:227], 0
	v_mfma_f32_16x16x32_bf16 v[82:85], v[114:117], v[232:235], 0
	v_mfma_f32_16x16x32_bf16 v[74:77], v[122:125], v[232:235], 0
	v_mfma_f32_16x16x32_bf16 v[142:145], v[118:121], v[166:169], v[142:145]
	v_mfma_f32_16x16x32_bf16 v[138:141], v[126:129], v[166:169], v[138:141]
	v_mfma_f32_16x16x32_bf16 v[110:113], v[118:121], v[220:223], v[110:113]
	v_mfma_f32_16x16x32_bf16 v[106:109], v[126:129], v[220:223], v[106:109]
	v_mfma_f32_16x16x32_bf16 v[98:101], v[118:121], v[228:231], v[98:101]
	v_mfma_f32_16x16x32_bf16 v[90:93], v[126:129], v[228:231], v[90:93]
	v_mfma_f32_16x16x32_bf16 v[82:85], v[118:121], v[236:239], v[82:85]
	v_mfma_f32_16x16x32_bf16 v[74:77], v[126:129], v[236:239], v[74:77]
	v_mfma_f32_16x16x32_bf16 v[134:137], v[146:149], v[162:165], 0
	v_mfma_f32_16x16x32_bf16 v[130:133], v[154:157], v[162:165], 0
	v_mfma_f32_16x16x32_bf16 v[102:105], v[146:149], v[216:219], 0
	v_mfma_f32_16x16x32_bf16 v[94:97], v[154:157], v[216:219], 0
	v_mfma_f32_16x16x32_bf16 v[86:89], v[146:149], v[224:227], 0
	v_mfma_f32_16x16x32_bf16 v[78:81], v[154:157], v[224:227], 0
	v_mfma_f32_16x16x32_bf16 v[70:73], v[146:149], v[232:235], 0
	v_mfma_f32_16x16x32_bf16 v[66:69], v[154:157], v[232:235], 0
	v_mfma_f32_16x16x32_bf16 v[134:137], v[150:153], v[166:169], v[134:137]
	v_mfma_f32_16x16x32_bf16 v[130:133], v[158:161], v[166:169], v[130:133]
	v_mfma_f32_16x16x32_bf16 v[102:105], v[150:153], v[220:223], v[102:105]
	v_mfma_f32_16x16x32_bf16 v[94:97], v[158:161], v[220:223], v[94:97]
	v_mfma_f32_16x16x32_bf16 v[86:89], v[150:153], v[228:231], v[86:89]
	v_mfma_f32_16x16x32_bf16 v[78:81], v[158:161], v[228:231], v[78:81]
	v_mfma_f32_16x16x32_bf16 v[70:73], v[150:153], v[236:239], v[70:73]
	v_mfma_f32_16x16x32_bf16 v[66:69], v[158:161], v[236:239], v[66:69]
	s_setprio 0
	s_barrier
	s_add_i32 s63, s67, s17
	v_lshl_add_u64 v[202:203], s[94:95], 0, v[174:175]
	s_mov_b32 m0, s63
	ds_read_b128 v[162:165], v214 offset:16384
	ds_read_b128 v[166:169], v214 offset:17408
	ds_read_b128 v[216:219], v214 offset:18432
	ds_read_b128 v[220:223], v214 offset:19456
	ds_read_b128 v[224:227], v214 offset:20480
	ds_read_b128 v[228:231], v214 offset:21504
	ds_read_b128 v[232:235], v214 offset:22528
	ds_read_b128 v[236:239], v214 offset:23552
	global_load_lds_dwordx4 v[202:203], off
	s_add_i32 m0, s63, 0x2000
	s_add_u32 s72, s94, 0x40000
	v_lshl_add_u64 v[240:241], s[94:95], 0, v[178:179]
	s_addc_u32 s73, s95, 0
	s_add_i32 s62, s62, s17
	global_load_lds_dwordx4 v[240:241], off
	v_lshl_add_u64 v[242:243], s[72:73], 0, v[174:175]
	s_mov_b32 m0, s62
	v_lshl_add_u64 v[244:245], s[96:97], 0, v[176:177]
	global_load_lds_dwordx4 v[242:243], off
	v_lshl_add_u64 v[242:243], s[72:73], 0, v[178:179]
	s_add_i32 m0, s62, 0x2000
	s_nop 0
	global_load_lds_dwordx4 v[242:243], off
	v_lshl_add_u64 v[242:243], s[96:97], 0, v[172:173]
	s_mov_b32 m0, s28
	s_nop 0
	global_load_lds_dwordx4 v[242:243], off
	s_mov_b32 m0, s29
	s_nop 0
	global_load_lds_dwordx4 v[244:245], off
	s_waitcnt vmcnt(8) lgkmcnt(0)
	s_setprio 1
	s_barrier
	v_mfma_f32_16x16x32_bf16 v[62:65], v[114:117], v[162:165], 0
	v_mfma_f32_16x16x32_bf16 v[58:61], v[122:125], v[162:165], 0
	v_mfma_f32_16x16x32_bf16 v[50:53], v[114:117], v[216:219], 0
	v_mfma_f32_16x16x32_bf16 v[42:45], v[122:125], v[216:219], 0
	v_mfma_f32_16x16x32_bf16 v[34:37], v[114:117], v[224:227], 0
	v_mfma_f32_16x16x32_bf16 v[26:29], v[122:125], v[224:227], 0
	v_mfma_f32_16x16x32_bf16 v[18:21], v[114:117], v[232:235], 0
	v_mfma_f32_16x16x32_bf16 v[10:13], v[122:125], v[232:235], 0
	v_mfma_f32_16x16x32_bf16 v[62:65], v[118:121], v[166:169], v[62:65]
	v_mfma_f32_16x16x32_bf16 v[58:61], v[126:129], v[166:169], v[58:61]
	v_mfma_f32_16x16x32_bf16 v[50:53], v[118:121], v[220:223], v[50:53]
	v_mfma_f32_16x16x32_bf16 v[42:45], v[126:129], v[220:223], v[42:45]
	v_mfma_f32_16x16x32_bf16 v[34:37], v[118:121], v[228:231], v[34:37]
	v_mfma_f32_16x16x32_bf16 v[26:29], v[126:129], v[228:231], v[26:29]
	v_mfma_f32_16x16x32_bf16 v[18:21], v[118:121], v[236:239], v[18:21]
	v_mfma_f32_16x16x32_bf16 v[10:13], v[126:129], v[236:239], v[10:13]
	v_mfma_f32_16x16x32_bf16 v[54:57], v[146:149], v[162:165], 0
	v_mfma_f32_16x16x32_bf16 v[46:49], v[154:157], v[162:165], 0
	v_mfma_f32_16x16x32_bf16 v[38:41], v[146:149], v[216:219], 0
	v_mfma_f32_16x16x32_bf16 v[30:33], v[154:157], v[216:219], 0
	v_mfma_f32_16x16x32_bf16 v[22:25], v[146:149], v[224:227], 0
	v_mfma_f32_16x16x32_bf16 v[14:17], v[154:157], v[224:227], 0
	v_mfma_f32_16x16x32_bf16 v[6:9], v[146:149], v[232:235], 0
	v_mfma_f32_16x16x32_bf16 v[2:5], v[154:157], v[232:235], 0
	v_mfma_f32_16x16x32_bf16 v[54:57], v[150:153], v[166:169], v[54:57]
	v_mfma_f32_16x16x32_bf16 v[46:49], v[158:161], v[166:169], v[46:49]
	v_mfma_f32_16x16x32_bf16 v[38:41], v[150:153], v[220:223], v[38:41]
	v_mfma_f32_16x16x32_bf16 v[30:33], v[158:161], v[220:223], v[30:33]
	v_mfma_f32_16x16x32_bf16 v[22:25], v[150:153], v[228:231], v[22:25]
	v_mfma_f32_16x16x32_bf16 v[14:17], v[158:161], v[228:231], v[14:17]
	v_mfma_f32_16x16x32_bf16 v[6:9], v[150:153], v[236:239], v[6:9]
	v_mfma_f32_16x16x32_bf16 v[2:5], v[158:161], v[236:239], v[2:5]
	s_setprio 0
	s_barrier
	s_add_i32 s62, 0, 0x18000
	s_add_i32 s63, 0, 0x1c000
	v_add_u32_e32 v126, s62, v199
	v_add_u32_e32 v158, s63, v199
	ds_read_b128 v[114:117], v126
	ds_read_b128 v[118:121], v126 offset:1024
	ds_read_b128 v[122:125], v126 offset:2048
	ds_read_b128 v[126:129], v126 offset:3072
	ds_read_b128 v[146:149], v158
	ds_read_b128 v[150:153], v158 offset:1024
	ds_read_b128 v[154:157], v158 offset:2048
	ds_read_b128 v[158:161], v158 offset:3072
	s_add_u32 s72, s96, 0x40000
	s_addc_u32 s73, s97, 0
	s_mov_b32 m0, s30
	v_lshl_add_u64 v[246:247], s[72:73], 0, v[172:173]
	ds_read_b128 v[162:165], v214 offset:32768
	ds_read_b128 v[166:169], v214 offset:33792
	ds_read_b128 v[216:219], v214 offset:34816
	ds_read_b128 v[220:223], v214 offset:35840
	ds_read_b128 v[224:227], v214 offset:36864
	ds_read_b128 v[228:231], v214 offset:37888
	ds_read_b128 v[232:235], v214 offset:38912
	ds_read_b128 v[236:239], v214 offset:39936
	global_load_lds_dwordx4 v[246:247], off
	v_lshl_add_u64 v[246:247], s[72:73], 0, v[176:177]
	s_mov_b32 m0, s31
	s_nop 0
	global_load_lds_dwordx4 v[246:247], off
	s_waitcnt vmcnt(8) lgkmcnt(0)
	s_setprio 1
	s_barrier
	v_mfma_f32_16x16x32_bf16 v[142:145], v[114:117], v[162:165], v[142:145]
	v_mfma_f32_16x16x32_bf16 v[138:141], v[122:125], v[162:165], v[138:141]
	v_mfma_f32_16x16x32_bf16 v[110:113], v[114:117], v[216:219], v[110:113]
	v_mfma_f32_16x16x32_bf16 v[106:109], v[122:125], v[216:219], v[106:109]
	v_mfma_f32_16x16x32_bf16 v[98:101], v[114:117], v[224:227], v[98:101]
	v_mfma_f32_16x16x32_bf16 v[90:93], v[122:125], v[224:227], v[90:93]
	v_mfma_f32_16x16x32_bf16 v[82:85], v[114:117], v[232:235], v[82:85]
	v_mfma_f32_16x16x32_bf16 v[74:77], v[122:125], v[232:235], v[74:77]
	v_mfma_f32_16x16x32_bf16 v[142:145], v[118:121], v[166:169], v[142:145]
	v_mfma_f32_16x16x32_bf16 v[138:141], v[126:129], v[166:169], v[138:141]
	v_mfma_f32_16x16x32_bf16 v[110:113], v[118:121], v[220:223], v[110:113]
	v_mfma_f32_16x16x32_bf16 v[106:109], v[126:129], v[220:223], v[106:109]
	v_mfma_f32_16x16x32_bf16 v[98:101], v[118:121], v[228:231], v[98:101]
	v_mfma_f32_16x16x32_bf16 v[90:93], v[126:129], v[228:231], v[90:93]
	v_mfma_f32_16x16x32_bf16 v[82:85], v[118:121], v[236:239], v[82:85]
	v_mfma_f32_16x16x32_bf16 v[74:77], v[126:129], v[236:239], v[74:77]
	v_mfma_f32_16x16x32_bf16 v[134:137], v[146:149], v[162:165], v[134:137]
	v_mfma_f32_16x16x32_bf16 v[130:133], v[154:157], v[162:165], v[130:133]
	v_mfma_f32_16x16x32_bf16 v[102:105], v[146:149], v[216:219], v[102:105]
	v_mfma_f32_16x16x32_bf16 v[94:97], v[154:157], v[216:219], v[94:97]
	v_mfma_f32_16x16x32_bf16 v[86:89], v[146:149], v[224:227], v[86:89]
	v_mfma_f32_16x16x32_bf16 v[78:81], v[154:157], v[224:227], v[78:81]
	v_mfma_f32_16x16x32_bf16 v[70:73], v[146:149], v[232:235], v[70:73]
	v_mfma_f32_16x16x32_bf16 v[66:69], v[154:157], v[232:235], v[66:69]
	v_mfma_f32_16x16x32_bf16 v[134:137], v[150:153], v[166:169], v[134:137]
	v_mfma_f32_16x16x32_bf16 v[130:133], v[158:161], v[166:169], v[130:133]
	v_mfma_f32_16x16x32_bf16 v[102:105], v[150:153], v[220:223], v[102:105]
	v_mfma_f32_16x16x32_bf16 v[94:97], v[158:161], v[220:223], v[94:97]
	v_mfma_f32_16x16x32_bf16 v[86:89], v[150:153], v[228:231], v[86:89]
	v_mfma_f32_16x16x32_bf16 v[78:81], v[158:161], v[228:231], v[78:81]
	v_mfma_f32_16x16x32_bf16 v[70:73], v[150:153], v[236:239], v[70:73]
	v_mfma_f32_16x16x32_bf16 v[66:69], v[158:161], v[236:239], v[66:69]
	s_setprio 0
	s_barrier
	s_add_i32 s62, s62, s17
	v_lshl_add_u64 v[202:203], v[202:203], 0, s[76:77]
	s_mov_b32 m0, s62
	ds_read_b128 v[162:165], v214 offset:49152
	ds_read_b128 v[166:169], v214 offset:50176
	ds_read_b128 v[216:219], v214 offset:51200
	ds_read_b128 v[220:223], v214 offset:52224
	ds_read_b128 v[224:227], v214 offset:53248
	ds_read_b128 v[228:231], v214 offset:54272
	ds_read_b128 v[232:235], v214 offset:55296
	ds_read_b128 v[236:239], v214 offset:56320
	global_load_lds_dwordx4 v[202:203], off
	s_add_i32 m0, s62, 0x2000
	s_add_u32 s72, s94, 0x40080
	v_lshl_add_u64 v[202:203], v[240:241], 0, s[76:77]
	s_addc_u32 s73, s95, 0
	s_add_i32 s62, s63, s17
	global_load_lds_dwordx4 v[202:203], off
	v_lshl_add_u64 v[202:203], s[72:73], 0, v[174:175]
	s_mov_b32 m0, s62
	s_nop 0
	global_load_lds_dwordx4 v[202:203], off
	v_lshl_add_u64 v[202:203], s[72:73], 0, v[178:179]
	s_add_i32 m0, s62, 0x2000
	s_nop 0
	global_load_lds_dwordx4 v[202:203], off
	v_lshl_add_u64 v[202:203], v[242:243], 0, s[76:77]
	s_mov_b32 m0, s44
	s_nop 0
	global_load_lds_dwordx4 v[202:203], off
	v_lshl_add_u64 v[202:203], v[244:245], 0, s[76:77]
	s_mov_b32 m0, s36
	s_nop 0
	global_load_lds_dwordx4 v[202:203], off
	s_waitcnt vmcnt(8) lgkmcnt(0)
	s_setprio 1
	s_barrier
	v_mfma_f32_16x16x32_bf16 v[62:65], v[114:117], v[162:165], v[62:65]
	v_mfma_f32_16x16x32_bf16 v[58:61], v[122:125], v[162:165], v[58:61]
	v_mfma_f32_16x16x32_bf16 v[50:53], v[114:117], v[216:219], v[50:53]
	v_mfma_f32_16x16x32_bf16 v[42:45], v[122:125], v[216:219], v[42:45]
	v_mfma_f32_16x16x32_bf16 v[34:37], v[114:117], v[224:227], v[34:37]
	v_mfma_f32_16x16x32_bf16 v[26:29], v[122:125], v[224:227], v[26:29]
	v_mfma_f32_16x16x32_bf16 v[18:21], v[114:117], v[232:235], v[18:21]
	v_mfma_f32_16x16x32_bf16 v[10:13], v[122:125], v[232:235], v[10:13]
	v_mfma_f32_16x16x32_bf16 v[62:65], v[118:121], v[166:169], v[62:65]
	v_mfma_f32_16x16x32_bf16 v[58:61], v[126:129], v[166:169], v[58:61]
	v_mfma_f32_16x16x32_bf16 v[50:53], v[118:121], v[220:223], v[50:53]
	v_mfma_f32_16x16x32_bf16 v[42:45], v[126:129], v[220:223], v[42:45]
	v_mfma_f32_16x16x32_bf16 v[34:37], v[118:121], v[228:231], v[34:37]
	v_mfma_f32_16x16x32_bf16 v[26:29], v[126:129], v[228:231], v[26:29]
	v_mfma_f32_16x16x32_bf16 v[18:21], v[118:121], v[236:239], v[18:21]
	v_mfma_f32_16x16x32_bf16 v[10:13], v[126:129], v[236:239], v[10:13]
	v_mfma_f32_16x16x32_bf16 v[54:57], v[146:149], v[162:165], v[54:57]
	v_mfma_f32_16x16x32_bf16 v[46:49], v[154:157], v[162:165], v[46:49]
	v_mfma_f32_16x16x32_bf16 v[38:41], v[146:149], v[216:219], v[38:41]
	v_mfma_f32_16x16x32_bf16 v[30:33], v[154:157], v[216:219], v[30:33]
	v_mfma_f32_16x16x32_bf16 v[22:25], v[146:149], v[224:227], v[22:25]
	v_mfma_f32_16x16x32_bf16 v[14:17], v[154:157], v[224:227], v[14:17]
	v_mfma_f32_16x16x32_bf16 v[6:9], v[146:149], v[232:235], v[6:9]
	v_mfma_f32_16x16x32_bf16 v[2:5], v[154:157], v[232:235], v[2:5]
	v_mfma_f32_16x16x32_bf16 v[54:57], v[150:153], v[166:169], v[54:57]
	v_mfma_f32_16x16x32_bf16 v[46:49], v[158:161], v[166:169], v[46:49]
	v_mfma_f32_16x16x32_bf16 v[38:41], v[150:153], v[220:223], v[38:41]
	v_mfma_f32_16x16x32_bf16 v[30:33], v[158:161], v[220:223], v[30:33]
	v_mfma_f32_16x16x32_bf16 v[22:25], v[150:153], v[228:231], v[22:25]
	v_mfma_f32_16x16x32_bf16 v[14:17], v[158:161], v[228:231], v[14:17]
	v_mfma_f32_16x16x32_bf16 v[6:9], v[150:153], v[236:239], v[6:9]
	v_mfma_f32_16x16x32_bf16 v[2:5], v[158:161], v[236:239], v[2:5]
	s_setprio 0
	s_barrier
	s_add_u32 s10, s10, 0x100
	s_addc_u32 s11, s11, 0
	s_add_u32 vcc_lo, vcc_lo, 0x100
	s_addc_u32 vcc_hi, vcc_hi, 0
	s_cmp_ge_i32 s66, s18
	s_mov_b32 s94, s66
.LBB0_1428:
	s_add_i32 s66, s94, 2
	s_add_u32 s67, s10, 0xfffc0080
	s_addc_u32 s72, s11, -1
	s_cmp_eq_u32 s85, s94
	s_cselect_b32 s97, s14, s72
	s_cselect_b32 s96, s15, s67
	s_cselect_b32 s95, s51, vcc_hi
	s_cselect_b32 s94, s84, vcc_lo
	s_add_i32 s67, 0, 0x10000
	s_add_i32 s62, 0, 0x14000
	v_add_u32_e32 v126, s67, v199
	v_add_u32_e32 v158, s62, v199
	ds_read_b128 v[114:117], v126
	ds_read_b128 v[118:121], v126 offset:1024
	ds_read_b128 v[122:125], v126 offset:2048
	ds_read_b128 v[126:129], v126 offset:3072
	ds_read_b128 v[146:149], v158
	ds_read_b128 v[150:153], v158 offset:1024
	ds_read_b128 v[154:157], v158 offset:2048
	ds_read_b128 v[158:161], v158 offset:3072
	v_lshl_add_u64 v[202:203], s[10:11], 0, v[196:197]
	s_add_i32 m0, s28, 0xc000
	ds_read_b128 v[162:165], v214
	ds_read_b128 v[166:169], v214 offset:1024
	ds_read_b128 v[216:219], v214 offset:2048
	ds_read_b128 v[220:223], v214 offset:3072
	ds_read_b128 v[224:227], v214 offset:4096
	ds_read_b128 v[228:231], v214 offset:5120
	ds_read_b128 v[232:235], v214 offset:6144
	ds_read_b128 v[236:239], v214 offset:7168
	global_load_lds_dwordx4 v[202:203], off
	v_lshl_add_u64 v[202:203], s[10:11], 0, v[176:177]
	s_add_i32 m0, s28, 0xe000
	s_nop 0
	global_load_lds_dwordx4 v[202:203], off
	s_waitcnt vmcnt(8) lgkmcnt(0)
	s_setprio 1
	s_barrier
	v_mfma_f32_16x16x32_bf16 v[142:145], v[114:117], v[162:165], v[142:145]
	v_mfma_f32_16x16x32_bf16 v[138:141], v[122:125], v[162:165], v[138:141]
	v_mfma_f32_16x16x32_bf16 v[110:113], v[114:117], v[216:219], v[110:113]
	v_mfma_f32_16x16x32_bf16 v[106:109], v[122:125], v[216:219], v[106:109]
	v_mfma_f32_16x16x32_bf16 v[98:101], v[114:117], v[224:227], v[98:101]
	v_mfma_f32_16x16x32_bf16 v[90:93], v[122:125], v[224:227], v[90:93]
	v_mfma_f32_16x16x32_bf16 v[82:85], v[114:117], v[232:235], v[82:85]
	v_mfma_f32_16x16x32_bf16 v[74:77], v[122:125], v[232:235], v[74:77]
	v_mfma_f32_16x16x32_bf16 v[142:145], v[118:121], v[166:169], v[142:145]
	v_mfma_f32_16x16x32_bf16 v[138:141], v[126:129], v[166:169], v[138:141]
	v_mfma_f32_16x16x32_bf16 v[110:113], v[118:121], v[220:223], v[110:113]
	v_mfma_f32_16x16x32_bf16 v[106:109], v[126:129], v[220:223], v[106:109]
	v_mfma_f32_16x16x32_bf16 v[98:101], v[118:121], v[228:231], v[98:101]
	v_mfma_f32_16x16x32_bf16 v[90:93], v[126:129], v[228:231], v[90:93]
	v_mfma_f32_16x16x32_bf16 v[82:85], v[118:121], v[236:239], v[82:85]
	v_mfma_f32_16x16x32_bf16 v[74:77], v[126:129], v[236:239], v[74:77]
	v_mfma_f32_16x16x32_bf16 v[134:137], v[146:149], v[162:165], v[134:137]
	v_mfma_f32_16x16x32_bf16 v[130:133], v[154:157], v[162:165], v[130:133]
	v_mfma_f32_16x16x32_bf16 v[102:105], v[146:149], v[216:219], v[102:105]
	v_mfma_f32_16x16x32_bf16 v[94:97], v[154:157], v[216:219], v[94:97]
	v_mfma_f32_16x16x32_bf16 v[86:89], v[146:149], v[224:227], v[86:89]
	v_mfma_f32_16x16x32_bf16 v[78:81], v[154:157], v[224:227], v[78:81]
	v_mfma_f32_16x16x32_bf16 v[70:73], v[146:149], v[232:235], v[70:73]
	v_mfma_f32_16x16x32_bf16 v[66:69], v[154:157], v[232:235], v[66:69]
	v_mfma_f32_16x16x32_bf16 v[134:137], v[150:153], v[166:169], v[134:137]
	v_mfma_f32_16x16x32_bf16 v[130:133], v[158:161], v[166:169], v[130:133]
	v_mfma_f32_16x16x32_bf16 v[102:105], v[150:153], v[220:223], v[102:105]
	v_mfma_f32_16x16x32_bf16 v[94:97], v[158:161], v[220:223], v[94:97]
	v_mfma_f32_16x16x32_bf16 v[86:89], v[150:153], v[228:231], v[86:89]
	v_mfma_f32_16x16x32_bf16 v[78:81], v[158:161], v[228:231], v[78:81]
	v_mfma_f32_16x16x32_bf16 v[70:73], v[150:153], v[236:239], v[70:73]
	v_mfma_f32_16x16x32_bf16 v[66:69], v[158:161], v[236:239], v[66:69]
	s_setprio 0
	s_barrier
	s_add_i32 s63, s67, s17
	v_lshl_add_u64 v[202:203], s[94:95], 0, v[174:175]
	s_mov_b32 m0, s63
	ds_read_b128 v[162:165], v214 offset:16384
	ds_read_b128 v[166:169], v214 offset:17408
	ds_read_b128 v[216:219], v214 offset:18432
	ds_read_b128 v[220:223], v214 offset:19456
	ds_read_b128 v[224:227], v214 offset:20480
	ds_read_b128 v[228:231], v214 offset:21504
	ds_read_b128 v[232:235], v214 offset:22528
	ds_read_b128 v[236:239], v214 offset:23552
	global_load_lds_dwordx4 v[202:203], off
	s_add_i32 m0, s63, 0x2000
	s_add_u32 s72, s94, 0x40000
	v_lshl_add_u64 v[240:241], s[94:95], 0, v[178:179]
	s_addc_u32 s73, s95, 0
	s_add_i32 s62, s62, s17
	global_load_lds_dwordx4 v[240:241], off
	v_lshl_add_u64 v[242:243], s[72:73], 0, v[174:175]
	s_mov_b32 m0, s62
	v_lshl_add_u64 v[244:245], s[96:97], 0, v[176:177]
	global_load_lds_dwordx4 v[242:243], off
	v_lshl_add_u64 v[242:243], s[72:73], 0, v[178:179]
	s_add_i32 m0, s62, 0x2000
	s_nop 0
	global_load_lds_dwordx4 v[242:243], off
	v_lshl_add_u64 v[242:243], s[96:97], 0, v[172:173]
	s_mov_b32 m0, s28
	s_nop 0
	global_load_lds_dwordx4 v[242:243], off
	s_mov_b32 m0, s29
	s_nop 0
	global_load_lds_dwordx4 v[244:245], off
	s_waitcnt vmcnt(8) lgkmcnt(0)
	s_setprio 1
	s_barrier
	v_mfma_f32_16x16x32_bf16 v[62:65], v[114:117], v[162:165], v[62:65]
	v_mfma_f32_16x16x32_bf16 v[58:61], v[122:125], v[162:165], v[58:61]
	v_mfma_f32_16x16x32_bf16 v[50:53], v[114:117], v[216:219], v[50:53]
	v_mfma_f32_16x16x32_bf16 v[42:45], v[122:125], v[216:219], v[42:45]
	v_mfma_f32_16x16x32_bf16 v[34:37], v[114:117], v[224:227], v[34:37]
	v_mfma_f32_16x16x32_bf16 v[26:29], v[122:125], v[224:227], v[26:29]
	v_mfma_f32_16x16x32_bf16 v[18:21], v[114:117], v[232:235], v[18:21]
	v_mfma_f32_16x16x32_bf16 v[10:13], v[122:125], v[232:235], v[10:13]
	v_mfma_f32_16x16x32_bf16 v[62:65], v[118:121], v[166:169], v[62:65]
	v_mfma_f32_16x16x32_bf16 v[58:61], v[126:129], v[166:169], v[58:61]
	v_mfma_f32_16x16x32_bf16 v[50:53], v[118:121], v[220:223], v[50:53]
	v_mfma_f32_16x16x32_bf16 v[42:45], v[126:129], v[220:223], v[42:45]
	v_mfma_f32_16x16x32_bf16 v[34:37], v[118:121], v[228:231], v[34:37]
	v_mfma_f32_16x16x32_bf16 v[26:29], v[126:129], v[228:231], v[26:29]
	v_mfma_f32_16x16x32_bf16 v[18:21], v[118:121], v[236:239], v[18:21]
	v_mfma_f32_16x16x32_bf16 v[10:13], v[126:129], v[236:239], v[10:13]
	v_mfma_f32_16x16x32_bf16 v[54:57], v[146:149], v[162:165], v[54:57]
	v_mfma_f32_16x16x32_bf16 v[46:49], v[154:157], v[162:165], v[46:49]
	v_mfma_f32_16x16x32_bf16 v[38:41], v[146:149], v[216:219], v[38:41]
	v_mfma_f32_16x16x32_bf16 v[30:33], v[154:157], v[216:219], v[30:33]
	v_mfma_f32_16x16x32_bf16 v[22:25], v[146:149], v[224:227], v[22:25]
	v_mfma_f32_16x16x32_bf16 v[14:17], v[154:157], v[224:227], v[14:17]
	v_mfma_f32_16x16x32_bf16 v[6:9], v[146:149], v[232:235], v[6:9]
	v_mfma_f32_16x16x32_bf16 v[2:5], v[154:157], v[232:235], v[2:5]
	v_mfma_f32_16x16x32_bf16 v[54:57], v[150:153], v[166:169], v[54:57]
	v_mfma_f32_16x16x32_bf16 v[46:49], v[158:161], v[166:169], v[46:49]
	v_mfma_f32_16x16x32_bf16 v[38:41], v[150:153], v[220:223], v[38:41]
	v_mfma_f32_16x16x32_bf16 v[30:33], v[158:161], v[220:223], v[30:33]
	v_mfma_f32_16x16x32_bf16 v[22:25], v[150:153], v[228:231], v[22:25]
	v_mfma_f32_16x16x32_bf16 v[14:17], v[158:161], v[228:231], v[14:17]
	v_mfma_f32_16x16x32_bf16 v[6:9], v[150:153], v[236:239], v[6:9]
	v_mfma_f32_16x16x32_bf16 v[2:5], v[158:161], v[236:239], v[2:5]
	s_setprio 0
	s_barrier
	s_add_i32 s62, 0, 0x18000
	s_add_i32 s63, 0, 0x1c000
	v_add_u32_e32 v126, s62, v199
	v_add_u32_e32 v158, s63, v199
	ds_read_b128 v[114:117], v126
	ds_read_b128 v[118:121], v126 offset:1024
	ds_read_b128 v[122:125], v126 offset:2048
	ds_read_b128 v[126:129], v126 offset:3072
	ds_read_b128 v[146:149], v158
	ds_read_b128 v[150:153], v158 offset:1024
	ds_read_b128 v[154:157], v158 offset:2048
	ds_read_b128 v[158:161], v158 offset:3072
	s_add_u32 s72, s96, 0x40000
	s_addc_u32 s73, s97, 0
	s_mov_b32 m0, s30
	v_lshl_add_u64 v[246:247], s[72:73], 0, v[172:173]
	ds_read_b128 v[162:165], v214 offset:32768
	ds_read_b128 v[166:169], v214 offset:33792
	ds_read_b128 v[216:219], v214 offset:34816
	ds_read_b128 v[220:223], v214 offset:35840
	ds_read_b128 v[224:227], v214 offset:36864
	ds_read_b128 v[228:231], v214 offset:37888
	ds_read_b128 v[232:235], v214 offset:38912
	ds_read_b128 v[236:239], v214 offset:39936
	global_load_lds_dwordx4 v[246:247], off
	v_lshl_add_u64 v[246:247], s[72:73], 0, v[176:177]
	s_mov_b32 m0, s31
	s_nop 0
	global_load_lds_dwordx4 v[246:247], off
	s_waitcnt vmcnt(8) lgkmcnt(0)
	s_setprio 1
	s_barrier
	v_mfma_f32_16x16x32_bf16 v[142:145], v[114:117], v[162:165], v[142:145]
	v_mfma_f32_16x16x32_bf16 v[138:141], v[122:125], v[162:165], v[138:141]
	v_mfma_f32_16x16x32_bf16 v[110:113], v[114:117], v[216:219], v[110:113]
	v_mfma_f32_16x16x32_bf16 v[106:109], v[122:125], v[216:219], v[106:109]
	v_mfma_f32_16x16x32_bf16 v[98:101], v[114:117], v[224:227], v[98:101]
	v_mfma_f32_16x16x32_bf16 v[90:93], v[122:125], v[224:227], v[90:93]
	v_mfma_f32_16x16x32_bf16 v[82:85], v[114:117], v[232:235], v[82:85]
	v_mfma_f32_16x16x32_bf16 v[74:77], v[122:125], v[232:235], v[74:77]
	v_mfma_f32_16x16x32_bf16 v[142:145], v[118:121], v[166:169], v[142:145]
	v_mfma_f32_16x16x32_bf16 v[138:141], v[126:129], v[166:169], v[138:141]
	v_mfma_f32_16x16x32_bf16 v[110:113], v[118:121], v[220:223], v[110:113]
	v_mfma_f32_16x16x32_bf16 v[106:109], v[126:129], v[220:223], v[106:109]
	v_mfma_f32_16x16x32_bf16 v[98:101], v[118:121], v[228:231], v[98:101]
	v_mfma_f32_16x16x32_bf16 v[90:93], v[126:129], v[228:231], v[90:93]
	v_mfma_f32_16x16x32_bf16 v[82:85], v[118:121], v[236:239], v[82:85]
	v_mfma_f32_16x16x32_bf16 v[74:77], v[126:129], v[236:239], v[74:77]
	v_mfma_f32_16x16x32_bf16 v[134:137], v[146:149], v[162:165], v[134:137]
	v_mfma_f32_16x16x32_bf16 v[130:133], v[154:157], v[162:165], v[130:133]
	v_mfma_f32_16x16x32_bf16 v[102:105], v[146:149], v[216:219], v[102:105]
	v_mfma_f32_16x16x32_bf16 v[94:97], v[154:157], v[216:219], v[94:97]
	v_mfma_f32_16x16x32_bf16 v[86:89], v[146:149], v[224:227], v[86:89]
	v_mfma_f32_16x16x32_bf16 v[78:81], v[154:157], v[224:227], v[78:81]
	v_mfma_f32_16x16x32_bf16 v[70:73], v[146:149], v[232:235], v[70:73]
	v_mfma_f32_16x16x32_bf16 v[66:69], v[154:157], v[232:235], v[66:69]
	v_mfma_f32_16x16x32_bf16 v[134:137], v[150:153], v[166:169], v[134:137]
	v_mfma_f32_16x16x32_bf16 v[130:133], v[158:161], v[166:169], v[130:133]
	v_mfma_f32_16x16x32_bf16 v[102:105], v[150:153], v[220:223], v[102:105]
	v_mfma_f32_16x16x32_bf16 v[94:97], v[158:161], v[220:223], v[94:97]
	v_mfma_f32_16x16x32_bf16 v[86:89], v[150:153], v[228:231], v[86:89]
	v_mfma_f32_16x16x32_bf16 v[78:81], v[158:161], v[228:231], v[78:81]
	v_mfma_f32_16x16x32_bf16 v[70:73], v[150:153], v[236:239], v[70:73]
	v_mfma_f32_16x16x32_bf16 v[66:69], v[158:161], v[236:239], v[66:69]
	s_setprio 0
	s_barrier
	s_add_i32 s62, s62, s17
	v_lshl_add_u64 v[202:203], v[202:203], 0, s[76:77]
	s_mov_b32 m0, s62
	ds_read_b128 v[162:165], v214 offset:49152
	ds_read_b128 v[166:169], v214 offset:50176
	ds_read_b128 v[216:219], v214 offset:51200
	ds_read_b128 v[220:223], v214 offset:52224
	ds_read_b128 v[224:227], v214 offset:53248
	ds_read_b128 v[228:231], v214 offset:54272
	ds_read_b128 v[232:235], v214 offset:55296
	ds_read_b128 v[236:239], v214 offset:56320
	global_load_lds_dwordx4 v[202:203], off
	s_add_i32 m0, s62, 0x2000
	s_add_u32 s72, s94, 0x40080
	v_lshl_add_u64 v[202:203], v[240:241], 0, s[76:77]
	s_addc_u32 s73, s95, 0
	s_add_i32 s62, s63, s17
	global_load_lds_dwordx4 v[202:203], off
	v_lshl_add_u64 v[202:203], s[72:73], 0, v[174:175]
	s_mov_b32 m0, s62
	s_nop 0
	global_load_lds_dwordx4 v[202:203], off
	v_lshl_add_u64 v[202:203], s[72:73], 0, v[178:179]
	s_add_i32 m0, s62, 0x2000
	s_nop 0
	global_load_lds_dwordx4 v[202:203], off
	v_lshl_add_u64 v[202:203], v[242:243], 0, s[76:77]
	s_mov_b32 m0, s44
	s_nop 0
	global_load_lds_dwordx4 v[202:203], off
	v_lshl_add_u64 v[202:203], v[244:245], 0, s[76:77]
	s_mov_b32 m0, s36
	s_nop 0
	global_load_lds_dwordx4 v[202:203], off
	s_waitcnt vmcnt(8) lgkmcnt(0)
	s_setprio 1
	s_barrier
	v_mfma_f32_16x16x32_bf16 v[62:65], v[114:117], v[162:165], v[62:65]
	v_mfma_f32_16x16x32_bf16 v[58:61], v[122:125], v[162:165], v[58:61]
	v_mfma_f32_16x16x32_bf16 v[50:53], v[114:117], v[216:219], v[50:53]
	v_mfma_f32_16x16x32_bf16 v[42:45], v[122:125], v[216:219], v[42:45]
	v_mfma_f32_16x16x32_bf16 v[34:37], v[114:117], v[224:227], v[34:37]
	v_mfma_f32_16x16x32_bf16 v[26:29], v[122:125], v[224:227], v[26:29]
	v_mfma_f32_16x16x32_bf16 v[18:21], v[114:117], v[232:235], v[18:21]
	v_mfma_f32_16x16x32_bf16 v[10:13], v[122:125], v[232:235], v[10:13]
	v_mfma_f32_16x16x32_bf16 v[62:65], v[118:121], v[166:169], v[62:65]
	v_mfma_f32_16x16x32_bf16 v[58:61], v[126:129], v[166:169], v[58:61]
	v_mfma_f32_16x16x32_bf16 v[50:53], v[118:121], v[220:223], v[50:53]
	v_mfma_f32_16x16x32_bf16 v[42:45], v[126:129], v[220:223], v[42:45]
	v_mfma_f32_16x16x32_bf16 v[34:37], v[118:121], v[228:231], v[34:37]
	v_mfma_f32_16x16x32_bf16 v[26:29], v[126:129], v[228:231], v[26:29]
	v_mfma_f32_16x16x32_bf16 v[18:21], v[118:121], v[236:239], v[18:21]
	v_mfma_f32_16x16x32_bf16 v[10:13], v[126:129], v[236:239], v[10:13]
	v_mfma_f32_16x16x32_bf16 v[54:57], v[146:149], v[162:165], v[54:57]
	v_mfma_f32_16x16x32_bf16 v[46:49], v[154:157], v[162:165], v[46:49]
	v_mfma_f32_16x16x32_bf16 v[38:41], v[146:149], v[216:219], v[38:41]
	v_mfma_f32_16x16x32_bf16 v[30:33], v[154:157], v[216:219], v[30:33]
	v_mfma_f32_16x16x32_bf16 v[22:25], v[146:149], v[224:227], v[22:25]
	v_mfma_f32_16x16x32_bf16 v[14:17], v[154:157], v[224:227], v[14:17]
	v_mfma_f32_16x16x32_bf16 v[6:9], v[146:149], v[232:235], v[6:9]
	v_mfma_f32_16x16x32_bf16 v[2:5], v[154:157], v[232:235], v[2:5]
	v_mfma_f32_16x16x32_bf16 v[54:57], v[150:153], v[166:169], v[54:57]
	v_mfma_f32_16x16x32_bf16 v[46:49], v[158:161], v[166:169], v[46:49]
	v_mfma_f32_16x16x32_bf16 v[38:41], v[150:153], v[220:223], v[38:41]
	v_mfma_f32_16x16x32_bf16 v[30:33], v[158:161], v[220:223], v[30:33]
	v_mfma_f32_16x16x32_bf16 v[22:25], v[150:153], v[228:231], v[22:25]
	v_mfma_f32_16x16x32_bf16 v[14:17], v[158:161], v[228:231], v[14:17]
	v_mfma_f32_16x16x32_bf16 v[6:9], v[150:153], v[236:239], v[6:9]
	v_mfma_f32_16x16x32_bf16 v[2:5], v[158:161], v[236:239], v[2:5]
	s_setprio 0
	s_barrier
	s_add_u32 s10, s10, 0x100
	s_addc_u32 s11, s11, 0
	s_add_u32 vcc_lo, vcc_lo, 0x100
	s_addc_u32 vcc_hi, vcc_hi, 0
	s_cmp_ge_i32 s66, s18
	s_mov_b32 s94, s66
	s_cbranch_scc0 .LBB0_1428
	s_and_b64 vcc, exec, s[82:83]
	s_cbranch_vccz .LBB0_1431
	s_barrier

.LBB0_1618:
	s_add_u32 s24, s96, s20
	s_addc_u32 s25, s97, s21
	s_and_b64 s[14:15], s[4:5], exec
	s_cselect_b32 s14, s25, s29
	s_cselect_b32 s15, s24, s28
	s_add_u32 s26, s2, s22
	s_addc_u32 s27, s3, s23
	s_and_b64 s[36:37], s[4:5], exec
	s_cselect_b32 s17, s27, s31
	s_cselect_b32 s49, s26, s30
	s_add_u32 s28, s28, 0x40080
	s_addc_u32 s29, s29, 0
	s_add_u32 s50, s30, 0x100
	s_addc_u32 s51, s31, 0
	s_mov_b32 s62, -2
	ds_read_b128 v[154:157], v150
	ds_read_b128 v[158:161], v150 offset:1024
	ds_read_b128 v[162:165], v150 offset:2048
	ds_read_b128 v[166:169], v150 offset:3072
	ds_read_b128 v[170:173], v151
	ds_read_b128 v[174:177], v151 offset:1024
	ds_read_b128 v[178:181], v151 offset:2048
	ds_read_b128 v[182:185], v151 offset:3072
	s_add_u32 s30, s28, 0xfffc0080
	s_addc_u32 s31, s29, -1
	s_cmp_eq_u32 s62, 12
	s_cselect_b32 s37, s14, s31
	s_cselect_b32 s36, s15, s30
	s_cselect_b32 s31, s17, s51
	s_cselect_b32 s30, s49, s50
	v_lshl_add_u64 v[146:147], s[28:29], 0, v[138:139]
	s_add_i32 m0, s19, 0xc000
	ds_read_b128 v[186:189], v152
	ds_read_b128 v[190:193], v152 offset:1024
	ds_read_b128 v[194:197], v152 offset:2048
	ds_read_b128 v[198:201], v152 offset:3072
	ds_read_b128 v[206:209], v152 offset:4096
	ds_read_b128 v[210:213], v152 offset:5120
	ds_read_b128 v[214:217], v152 offset:6144
	ds_read_b128 v[218:221], v152 offset:7168
	global_load_lds_dwordx4 v[146:147], off
	v_lshl_add_u64 v[146:147], s[28:29], 0, v[140:141]
	s_add_i32 m0, s19, 0xe000
	s_nop 0
	global_load_lds_dwordx4 v[146:147], off
	s_waitcnt vmcnt(8) lgkmcnt(0)
	s_setprio 1
	s_barrier
	v_mfma_f32_16x16x32_bf16 v[126:129], v[154:157], v[186:189], 0
	v_mfma_f32_16x16x32_bf16 v[122:125], v[162:165], v[186:189], 0
	v_mfma_f32_16x16x32_bf16 v[110:113], v[154:157], v[194:197], 0
	v_mfma_f32_16x16x32_bf16 v[106:109], v[162:165], v[194:197], 0
	v_mfma_f32_16x16x32_bf16 v[94:97], v[154:157], v[206:209], 0
	v_mfma_f32_16x16x32_bf16 v[90:93], v[162:165], v[206:209], 0
	v_mfma_f32_16x16x32_bf16 v[78:81], v[154:157], v[214:217], 0
	v_mfma_f32_16x16x32_bf16 v[74:77], v[162:165], v[214:217], 0
	v_mfma_f32_16x16x32_bf16 v[126:129], v[158:161], v[190:193], v[126:129]
	v_mfma_f32_16x16x32_bf16 v[122:125], v[166:169], v[190:193], v[122:125]
	v_mfma_f32_16x16x32_bf16 v[110:113], v[158:161], v[198:201], v[110:113]
	v_mfma_f32_16x16x32_bf16 v[106:109], v[166:169], v[198:201], v[106:109]
	v_mfma_f32_16x16x32_bf16 v[94:97], v[158:161], v[210:213], v[94:97]
	v_mfma_f32_16x16x32_bf16 v[90:93], v[166:169], v[210:213], v[90:93]
	v_mfma_f32_16x16x32_bf16 v[78:81], v[158:161], v[218:221], v[78:81]
	v_mfma_f32_16x16x32_bf16 v[74:77], v[166:169], v[218:221], v[74:77]
	v_mfma_f32_16x16x32_bf16 v[118:121], v[170:173], v[186:189], 0
	v_mfma_f32_16x16x32_bf16 v[114:117], v[178:181], v[186:189], 0
	v_mfma_f32_16x16x32_bf16 v[102:105], v[170:173], v[194:197], 0
	v_mfma_f32_16x16x32_bf16 v[98:101], v[178:181], v[194:197], 0
	v_mfma_f32_16x16x32_bf16 v[86:89], v[170:173], v[206:209], 0
	v_mfma_f32_16x16x32_bf16 v[82:85], v[178:181], v[206:209], 0
	v_mfma_f32_16x16x32_bf16 v[70:73], v[170:173], v[214:217], 0
	v_mfma_f32_16x16x32_bf16 v[66:69], v[178:181], v[214:217], 0
	v_mfma_f32_16x16x32_bf16 v[118:121], v[174:177], v[190:193], v[118:121]
	v_mfma_f32_16x16x32_bf16 v[114:117], v[182:185], v[190:193], v[114:117]
	v_mfma_f32_16x16x32_bf16 v[102:105], v[174:177], v[198:201], v[102:105]
	v_mfma_f32_16x16x32_bf16 v[98:101], v[182:185], v[198:201], v[98:101]
	v_mfma_f32_16x16x32_bf16 v[86:89], v[174:177], v[210:213], v[86:89]
	v_mfma_f32_16x16x32_bf16 v[82:85], v[182:185], v[210:213], v[82:85]
	v_mfma_f32_16x16x32_bf16 v[70:73], v[174:177], v[218:221], v[70:73]
	v_mfma_f32_16x16x32_bf16 v[66:69], v[182:185], v[218:221], v[66:69]
	s_setprio 0
	s_barrier
	s_add_i32 s63, s45, s12
	v_lshl_add_u64 v[146:147], s[30:31], 0, v[134:135]
	s_mov_b32 m0, s63
	ds_read_b128 v[186:189], v152 offset:16384
	ds_read_b128 v[190:193], v152 offset:17408
	ds_read_b128 v[194:197], v152 offset:18432
	ds_read_b128 v[198:201], v152 offset:19456
	ds_read_b128 v[206:209], v152 offset:20480
	ds_read_b128 v[210:213], v152 offset:21504
	ds_read_b128 v[214:217], v152 offset:22528
	ds_read_b128 v[218:221], v152 offset:23552
	global_load_lds_dwordx4 v[146:147], off
	s_add_i32 m0, s63, 0x2000
	s_add_u32 s64, s30, 0x40000
	v_lshl_add_u64 v[202:203], s[30:31], 0, v[130:131]
	s_addc_u32 s65, s31, 0
	s_add_i32 s63, s46, s12
	global_load_lds_dwordx4 v[202:203], off
	v_lshl_add_u64 v[222:223], s[64:65], 0, v[134:135]
	s_mov_b32 m0, s63
	v_lshl_add_u64 v[224:225], s[36:37], 0, v[132:133]
	global_load_lds_dwordx4 v[222:223], off
	v_lshl_add_u64 v[222:223], s[64:65], 0, v[130:131]
	s_add_i32 m0, s63, 0x2000
	s_nop 0
	global_load_lds_dwordx4 v[222:223], off
	v_lshl_add_u64 v[222:223], s[36:37], 0, v[136:137]
	s_mov_b32 m0, s19
	s_nop 0
	global_load_lds_dwordx4 v[222:223], off
	s_mov_b32 m0, s33
	s_nop 0
	global_load_lds_dwordx4 v[224:225], off
	s_waitcnt vmcnt(8) lgkmcnt(0)
	s_setprio 1
	s_barrier
	v_mfma_f32_16x16x32_bf16 v[62:65], v[154:157], v[186:189], 0
	v_mfma_f32_16x16x32_bf16 v[58:61], v[162:165], v[186:189], 0
	v_mfma_f32_16x16x32_bf16 v[46:49], v[154:157], v[194:197], 0
	v_mfma_f32_16x16x32_bf16 v[42:45], v[162:165], v[194:197], 0
	v_mfma_f32_16x16x32_bf16 v[30:33], v[154:157], v[206:209], 0
	v_mfma_f32_16x16x32_bf16 v[26:29], v[162:165], v[206:209], 0
	v_mfma_f32_16x16x32_bf16 v[14:17], v[154:157], v[214:217], 0
	v_mfma_f32_16x16x32_bf16 v[10:13], v[162:165], v[214:217], 0
	v_mfma_f32_16x16x32_bf16 v[62:65], v[158:161], v[190:193], v[62:65]
	v_mfma_f32_16x16x32_bf16 v[58:61], v[166:169], v[190:193], v[58:61]
	v_mfma_f32_16x16x32_bf16 v[46:49], v[158:161], v[198:201], v[46:49]
	v_mfma_f32_16x16x32_bf16 v[42:45], v[166:169], v[198:201], v[42:45]
	v_mfma_f32_16x16x32_bf16 v[30:33], v[158:161], v[210:213], v[30:33]
	v_mfma_f32_16x16x32_bf16 v[26:29], v[166:169], v[210:213], v[26:29]
	v_mfma_f32_16x16x32_bf16 v[14:17], v[158:161], v[218:221], v[14:17]
	v_mfma_f32_16x16x32_bf16 v[10:13], v[166:169], v[218:221], v[10:13]
	v_mfma_f32_16x16x32_bf16 v[54:57], v[170:173], v[186:189], 0
	v_mfma_f32_16x16x32_bf16 v[50:53], v[178:181], v[186:189], 0
	v_mfma_f32_16x16x32_bf16 v[38:41], v[170:173], v[194:197], 0
	v_mfma_f32_16x16x32_bf16 v[34:37], v[178:181], v[194:197], 0
	v_mfma_f32_16x16x32_bf16 v[22:25], v[170:173], v[206:209], 0
	v_mfma_f32_16x16x32_bf16 v[18:21], v[178:181], v[206:209], 0
	v_mfma_f32_16x16x32_bf16 v[6:9], v[170:173], v[214:217], 0
	v_mfma_f32_16x16x32_bf16 v[2:5], v[178:181], v[214:217], 0
	v_mfma_f32_16x16x32_bf16 v[54:57], v[174:177], v[190:193], v[54:57]
	v_mfma_f32_16x16x32_bf16 v[50:53], v[182:185], v[190:193], v[50:53]
	v_mfma_f32_16x16x32_bf16 v[38:41], v[174:177], v[198:201], v[38:41]
	v_mfma_f32_16x16x32_bf16 v[34:37], v[182:185], v[198:201], v[34:37]
	v_mfma_f32_16x16x32_bf16 v[22:25], v[174:177], v[210:213], v[22:25]
	v_mfma_f32_16x16x32_bf16 v[18:21], v[182:185], v[210:213], v[18:21]
	v_mfma_f32_16x16x32_bf16 v[6:9], v[174:177], v[218:221], v[6:9]
	v_mfma_f32_16x16x32_bf16 v[2:5], v[182:185], v[218:221], v[2:5]
	s_setprio 0
	s_barrier
	s_add_i32 s63, 0, 0x18000
	v_add_u32_e32 v153, s63, v149
	s_add_i32 s64, 0, 0x1c000
	ds_read_b128 v[154:157], v153
	ds_read_b128 v[158:161], v153 offset:1024
	ds_read_b128 v[162:165], v153 offset:2048
	ds_read_b128 v[166:169], v153 offset:3072
	v_add_u32_e32 v153, s64, v149
	ds_read_b128 v[170:173], v153
	ds_read_b128 v[174:177], v153 offset:1024
	ds_read_b128 v[178:181], v153 offset:2048
	ds_read_b128 v[182:185], v153 offset:3072
	s_add_u32 s36, s36, 0x40000
	s_addc_u32 s37, s37, 0
	s_mov_b32 m0, s35
	v_lshl_add_u64 v[226:227], s[36:37], 0, v[136:137]
	ds_read_b128 v[186:189], v152 offset:32768
	ds_read_b128 v[190:193], v152 offset:33792
	ds_read_b128 v[194:197], v152 offset:34816
	ds_read_b128 v[198:201], v152 offset:35840
	ds_read_b128 v[206:209], v152 offset:36864
	ds_read_b128 v[210:213], v152 offset:37888
	ds_read_b128 v[214:217], v152 offset:38912
	ds_read_b128 v[218:221], v152 offset:39936
	global_load_lds_dwordx4 v[226:227], off
	v_lshl_add_u64 v[226:227], s[36:37], 0, v[132:133]
	s_mov_b32 m0, s38
	s_nop 0
	global_load_lds_dwordx4 v[226:227], off
	s_waitcnt vmcnt(8) lgkmcnt(0)
	s_setprio 1
	s_barrier
	v_mfma_f32_16x16x32_bf16 v[126:129], v[154:157], v[186:189], v[126:129]
	v_mfma_f32_16x16x32_bf16 v[122:125], v[162:165], v[186:189], v[122:125]
	v_mfma_f32_16x16x32_bf16 v[110:113], v[154:157], v[194:197], v[110:113]
	v_mfma_f32_16x16x32_bf16 v[106:109], v[162:165], v[194:197], v[106:109]
	v_mfma_f32_16x16x32_bf16 v[94:97], v[154:157], v[206:209], v[94:97]
	v_mfma_f32_16x16x32_bf16 v[90:93], v[162:165], v[206:209], v[90:93]
	v_mfma_f32_16x16x32_bf16 v[78:81], v[154:157], v[214:217], v[78:81]
	v_mfma_f32_16x16x32_bf16 v[74:77], v[162:165], v[214:217], v[74:77]
	v_mfma_f32_16x16x32_bf16 v[126:129], v[158:161], v[190:193], v[126:129]
	v_mfma_f32_16x16x32_bf16 v[122:125], v[166:169], v[190:193], v[122:125]
	v_mfma_f32_16x16x32_bf16 v[110:113], v[158:161], v[198:201], v[110:113]
	v_mfma_f32_16x16x32_bf16 v[106:109], v[166:169], v[198:201], v[106:109]
	v_mfma_f32_16x16x32_bf16 v[94:97], v[158:161], v[210:213], v[94:97]
	v_mfma_f32_16x16x32_bf16 v[90:93], v[166:169], v[210:213], v[90:93]
	v_mfma_f32_16x16x32_bf16 v[78:81], v[158:161], v[218:221], v[78:81]
	v_mfma_f32_16x16x32_bf16 v[74:77], v[166:169], v[218:221], v[74:77]
	v_mfma_f32_16x16x32_bf16 v[118:121], v[170:173], v[186:189], v[118:121]
	v_mfma_f32_16x16x32_bf16 v[114:117], v[178:181], v[186:189], v[114:117]
	v_mfma_f32_16x16x32_bf16 v[102:105], v[170:173], v[194:197], v[102:105]
	v_mfma_f32_16x16x32_bf16 v[98:101], v[178:181], v[194:197], v[98:101]
	v_mfma_f32_16x16x32_bf16 v[86:89], v[170:173], v[206:209], v[86:89]
	v_mfma_f32_16x16x32_bf16 v[82:85], v[178:181], v[206:209], v[82:85]
	v_mfma_f32_16x16x32_bf16 v[70:73], v[170:173], v[214:217], v[70:73]
	v_mfma_f32_16x16x32_bf16 v[66:69], v[178:181], v[214:217], v[66:69]
	v_mfma_f32_16x16x32_bf16 v[118:121], v[174:177], v[190:193], v[118:121]
	v_mfma_f32_16x16x32_bf16 v[114:117], v[182:185], v[190:193], v[114:117]
	v_mfma_f32_16x16x32_bf16 v[102:105], v[174:177], v[198:201], v[102:105]
	v_mfma_f32_16x16x32_bf16 v[98:101], v[182:185], v[198:201], v[98:101]
	v_mfma_f32_16x16x32_bf16 v[86:89], v[174:177], v[210:213], v[86:89]
	v_mfma_f32_16x16x32_bf16 v[82:85], v[182:185], v[210:213], v[82:85]
	v_mfma_f32_16x16x32_bf16 v[70:73], v[174:177], v[218:221], v[70:73]
	v_mfma_f32_16x16x32_bf16 v[66:69], v[182:185], v[218:221], v[66:69]
	s_setprio 0
	s_barrier
	s_add_i32 s36, s63, s12
	v_lshl_add_u64 v[146:147], v[146:147], 0, s[8:9]
	s_mov_b32 m0, s36
	ds_read_b128 v[186:189], v152 offset:49152
	ds_read_b128 v[190:193], v152 offset:50176
	ds_read_b128 v[194:197], v152 offset:51200
	ds_read_b128 v[198:201], v152 offset:52224
	ds_read_b128 v[206:209], v152 offset:53248
	ds_read_b128 v[210:213], v152 offset:54272
	ds_read_b128 v[214:217], v152 offset:55296
	ds_read_b128 v[218:221], v152 offset:56320
	global_load_lds_dwordx4 v[146:147], off
	s_add_i32 m0, s36, 0x2000
	s_add_u32 s30, s30, 0x40080
	v_lshl_add_u64 v[146:147], v[202:203], 0, s[8:9]
	s_addc_u32 s31, s31, 0
	s_add_i32 s36, s64, s12
	global_load_lds_dwordx4 v[146:147], off
	v_lshl_add_u64 v[146:147], s[30:31], 0, v[134:135]
	s_mov_b32 m0, s36
	s_nop 0
	global_load_lds_dwordx4 v[146:147], off
	v_lshl_add_u64 v[146:147], s[30:31], 0, v[130:131]
	s_add_i32 m0, s36, 0x2000
	s_nop 0
	global_load_lds_dwordx4 v[146:147], off
	v_lshl_add_u64 v[146:147], v[222:223], 0, s[8:9]
	s_mov_b32 m0, s42
	s_nop 0
	global_load_lds_dwordx4 v[146:147], off
	v_lshl_add_u64 v[146:147], v[224:225], 0, s[8:9]
	s_mov_b32 m0, s43
	s_nop 0
	global_load_lds_dwordx4 v[146:147], off
	s_waitcnt vmcnt(8) lgkmcnt(0)
	s_setprio 1
	s_barrier
	v_mfma_f32_16x16x32_bf16 v[62:65], v[154:157], v[186:189], v[62:65]
	v_mfma_f32_16x16x32_bf16 v[58:61], v[162:165], v[186:189], v[58:61]
	v_mfma_f32_16x16x32_bf16 v[46:49], v[154:157], v[194:197], v[46:49]
	v_mfma_f32_16x16x32_bf16 v[42:45], v[162:165], v[194:197], v[42:45]
	v_mfma_f32_16x16x32_bf16 v[30:33], v[154:157], v[206:209], v[30:33]
	v_mfma_f32_16x16x32_bf16 v[26:29], v[162:165], v[206:209], v[26:29]
	v_mfma_f32_16x16x32_bf16 v[14:17], v[154:157], v[214:217], v[14:17]
	v_mfma_f32_16x16x32_bf16 v[10:13], v[162:165], v[214:217], v[10:13]
	v_mfma_f32_16x16x32_bf16 v[62:65], v[158:161], v[190:193], v[62:65]
	v_mfma_f32_16x16x32_bf16 v[58:61], v[166:169], v[190:193], v[58:61]
	v_mfma_f32_16x16x32_bf16 v[46:49], v[158:161], v[198:201], v[46:49]
	v_mfma_f32_16x16x32_bf16 v[42:45], v[166:169], v[198:201], v[42:45]
	v_mfma_f32_16x16x32_bf16 v[30:33], v[158:161], v[210:213], v[30:33]
	v_mfma_f32_16x16x32_bf16 v[26:29], v[166:169], v[210:213], v[26:29]
	v_mfma_f32_16x16x32_bf16 v[14:17], v[158:161], v[218:221], v[14:17]
	v_mfma_f32_16x16x32_bf16 v[10:13], v[166:169], v[218:221], v[10:13]
	v_mfma_f32_16x16x32_bf16 v[54:57], v[170:173], v[186:189], v[54:57]
	v_mfma_f32_16x16x32_bf16 v[50:53], v[178:181], v[186:189], v[50:53]
	v_mfma_f32_16x16x32_bf16 v[38:41], v[170:173], v[194:197], v[38:41]
	v_mfma_f32_16x16x32_bf16 v[34:37], v[178:181], v[194:197], v[34:37]
	v_mfma_f32_16x16x32_bf16 v[22:25], v[170:173], v[206:209], v[22:25]
	v_mfma_f32_16x16x32_bf16 v[18:21], v[178:181], v[206:209], v[18:21]
	v_mfma_f32_16x16x32_bf16 v[6:9], v[170:173], v[214:217], v[6:9]
	v_mfma_f32_16x16x32_bf16 v[2:5], v[178:181], v[214:217], v[2:5]
	v_mfma_f32_16x16x32_bf16 v[54:57], v[174:177], v[190:193], v[54:57]
	v_mfma_f32_16x16x32_bf16 v[50:53], v[182:185], v[190:193], v[50:53]
	v_mfma_f32_16x16x32_bf16 v[38:41], v[174:177], v[198:201], v[38:41]
	v_mfma_f32_16x16x32_bf16 v[34:37], v[182:185], v[198:201], v[34:37]
	v_mfma_f32_16x16x32_bf16 v[22:25], v[174:177], v[210:213], v[22:25]
	v_mfma_f32_16x16x32_bf16 v[18:21], v[182:185], v[210:213], v[18:21]
	v_mfma_f32_16x16x32_bf16 v[6:9], v[174:177], v[218:221], v[6:9]
	v_mfma_f32_16x16x32_bf16 v[2:5], v[182:185], v[218:221], v[2:5]
	s_setprio 0
	s_barrier
	s_add_i32 s62, s62, 2
	s_add_u32 s28, s28, 0x100
	s_addc_u32 s29, s29, 0
	s_add_u32 s50, s50, 0x100
	s_addc_u32 s51, s51, 0
	s_cmp_gt_u32 s62, 13
.LBB0_1619:
	ds_read_b128 v[154:157], v150
	ds_read_b128 v[158:161], v150 offset:1024
	ds_read_b128 v[162:165], v150 offset:2048
	ds_read_b128 v[166:169], v150 offset:3072
	ds_read_b128 v[170:173], v151
	ds_read_b128 v[174:177], v151 offset:1024
	ds_read_b128 v[178:181], v151 offset:2048
	ds_read_b128 v[182:185], v151 offset:3072
	s_add_u32 s30, s28, 0xfffc0080
	s_addc_u32 s31, s29, -1
	s_cmp_eq_u32 s62, 12
	s_cselect_b32 s37, s14, s31
	s_cselect_b32 s36, s15, s30
	s_cselect_b32 s31, s17, s51
	s_cselect_b32 s30, s49, s50
	v_lshl_add_u64 v[146:147], s[28:29], 0, v[138:139]
	s_add_i32 m0, s19, 0xc000
	ds_read_b128 v[186:189], v152
	ds_read_b128 v[190:193], v152 offset:1024
	ds_read_b128 v[194:197], v152 offset:2048
	ds_read_b128 v[198:201], v152 offset:3072
	ds_read_b128 v[206:209], v152 offset:4096
	ds_read_b128 v[210:213], v152 offset:5120
	ds_read_b128 v[214:217], v152 offset:6144
	ds_read_b128 v[218:221], v152 offset:7168
	global_load_lds_dwordx4 v[146:147], off
	v_lshl_add_u64 v[146:147], s[28:29], 0, v[140:141]
	s_add_i32 m0, s19, 0xe000
	s_nop 0
	global_load_lds_dwordx4 v[146:147], off
	s_waitcnt vmcnt(8) lgkmcnt(0)
	s_setprio 1
	s_barrier
	v_mfma_f32_16x16x32_bf16 v[126:129], v[154:157], v[186:189], v[126:129]
	v_mfma_f32_16x16x32_bf16 v[122:125], v[162:165], v[186:189], v[122:125]
	v_mfma_f32_16x16x32_bf16 v[110:113], v[154:157], v[194:197], v[110:113]
	v_mfma_f32_16x16x32_bf16 v[106:109], v[162:165], v[194:197], v[106:109]
	v_mfma_f32_16x16x32_bf16 v[94:97], v[154:157], v[206:209], v[94:97]
	v_mfma_f32_16x16x32_bf16 v[90:93], v[162:165], v[206:209], v[90:93]
	v_mfma_f32_16x16x32_bf16 v[78:81], v[154:157], v[214:217], v[78:81]
	v_mfma_f32_16x16x32_bf16 v[74:77], v[162:165], v[214:217], v[74:77]
	v_mfma_f32_16x16x32_bf16 v[126:129], v[158:161], v[190:193], v[126:129]
	v_mfma_f32_16x16x32_bf16 v[122:125], v[166:169], v[190:193], v[122:125]
	v_mfma_f32_16x16x32_bf16 v[110:113], v[158:161], v[198:201], v[110:113]
	v_mfma_f32_16x16x32_bf16 v[106:109], v[166:169], v[198:201], v[106:109]
	v_mfma_f32_16x16x32_bf16 v[94:97], v[158:161], v[210:213], v[94:97]
	v_mfma_f32_16x16x32_bf16 v[90:93], v[166:169], v[210:213], v[90:93]
	v_mfma_f32_16x16x32_bf16 v[78:81], v[158:161], v[218:221], v[78:81]
	v_mfma_f32_16x16x32_bf16 v[74:77], v[166:169], v[218:221], v[74:77]
	v_mfma_f32_16x16x32_bf16 v[118:121], v[170:173], v[186:189], v[118:121]
	v_mfma_f32_16x16x32_bf16 v[114:117], v[178:181], v[186:189], v[114:117]
	v_mfma_f32_16x16x32_bf16 v[102:105], v[170:173], v[194:197], v[102:105]
	v_mfma_f32_16x16x32_bf16 v[98:101], v[178:181], v[194:197], v[98:101]
	v_mfma_f32_16x16x32_bf16 v[86:89], v[170:173], v[206:209], v[86:89]
	v_mfma_f32_16x16x32_bf16 v[82:85], v[178:181], v[206:209], v[82:85]
	v_mfma_f32_16x16x32_bf16 v[70:73], v[170:173], v[214:217], v[70:73]
	v_mfma_f32_16x16x32_bf16 v[66:69], v[178:181], v[214:217], v[66:69]
	v_mfma_f32_16x16x32_bf16 v[118:121], v[174:177], v[190:193], v[118:121]
	v_mfma_f32_16x16x32_bf16 v[114:117], v[182:185], v[190:193], v[114:117]
	v_mfma_f32_16x16x32_bf16 v[102:105], v[174:177], v[198:201], v[102:105]
	v_mfma_f32_16x16x32_bf16 v[98:101], v[182:185], v[198:201], v[98:101]
	v_mfma_f32_16x16x32_bf16 v[86:89], v[174:177], v[210:213], v[86:89]
	v_mfma_f32_16x16x32_bf16 v[82:85], v[182:185], v[210:213], v[82:85]
	v_mfma_f32_16x16x32_bf16 v[70:73], v[174:177], v[218:221], v[70:73]
	v_mfma_f32_16x16x32_bf16 v[66:69], v[182:185], v[218:221], v[66:69]
	s_setprio 0
	s_barrier
	s_add_i32 s63, s45, s12
	v_lshl_add_u64 v[146:147], s[30:31], 0, v[134:135]
	s_mov_b32 m0, s63
	ds_read_b128 v[186:189], v152 offset:16384
	ds_read_b128 v[190:193], v152 offset:17408
	ds_read_b128 v[194:197], v152 offset:18432
	ds_read_b128 v[198:201], v152 offset:19456
	ds_read_b128 v[206:209], v152 offset:20480
	ds_read_b128 v[210:213], v152 offset:21504
	ds_read_b128 v[214:217], v152 offset:22528
	ds_read_b128 v[218:221], v152 offset:23552
	global_load_lds_dwordx4 v[146:147], off
	s_add_i32 m0, s63, 0x2000
	s_add_u32 s64, s30, 0x40000
	v_lshl_add_u64 v[202:203], s[30:31], 0, v[130:131]
	s_addc_u32 s65, s31, 0
	s_add_i32 s63, s46, s12
	global_load_lds_dwordx4 v[202:203], off
	v_lshl_add_u64 v[222:223], s[64:65], 0, v[134:135]
	s_mov_b32 m0, s63
	v_lshl_add_u64 v[224:225], s[36:37], 0, v[132:133]
	global_load_lds_dwordx4 v[222:223], off
	v_lshl_add_u64 v[222:223], s[64:65], 0, v[130:131]
	s_add_i32 m0, s63, 0x2000
	s_nop 0
	global_load_lds_dwordx4 v[222:223], off
	v_lshl_add_u64 v[222:223], s[36:37], 0, v[136:137]
	s_mov_b32 m0, s19
	s_nop 0
	global_load_lds_dwordx4 v[222:223], off
	s_mov_b32 m0, s33
	s_nop 0
	global_load_lds_dwordx4 v[224:225], off
	s_waitcnt vmcnt(8) lgkmcnt(0)
	s_setprio 1
	s_barrier
	v_mfma_f32_16x16x32_bf16 v[62:65], v[154:157], v[186:189], v[62:65]
	v_mfma_f32_16x16x32_bf16 v[58:61], v[162:165], v[186:189], v[58:61]
	v_mfma_f32_16x16x32_bf16 v[46:49], v[154:157], v[194:197], v[46:49]
	v_mfma_f32_16x16x32_bf16 v[42:45], v[162:165], v[194:197], v[42:45]
	v_mfma_f32_16x16x32_bf16 v[30:33], v[154:157], v[206:209], v[30:33]
	v_mfma_f32_16x16x32_bf16 v[26:29], v[162:165], v[206:209], v[26:29]
	v_mfma_f32_16x16x32_bf16 v[14:17], v[154:157], v[214:217], v[14:17]
	v_mfma_f32_16x16x32_bf16 v[10:13], v[162:165], v[214:217], v[10:13]
	v_mfma_f32_16x16x32_bf16 v[62:65], v[158:161], v[190:193], v[62:65]
	v_mfma_f32_16x16x32_bf16 v[58:61], v[166:169], v[190:193], v[58:61]
	v_mfma_f32_16x16x32_bf16 v[46:49], v[158:161], v[198:201], v[46:49]
	v_mfma_f32_16x16x32_bf16 v[42:45], v[166:169], v[198:201], v[42:45]
	v_mfma_f32_16x16x32_bf16 v[30:33], v[158:161], v[210:213], v[30:33]
	v_mfma_f32_16x16x32_bf16 v[26:29], v[166:169], v[210:213], v[26:29]
	v_mfma_f32_16x16x32_bf16 v[14:17], v[158:161], v[218:221], v[14:17]
	v_mfma_f32_16x16x32_bf16 v[10:13], v[166:169], v[218:221], v[10:13]
	v_mfma_f32_16x16x32_bf16 v[54:57], v[170:173], v[186:189], v[54:57]
	v_mfma_f32_16x16x32_bf16 v[50:53], v[178:181], v[186:189], v[50:53]
	v_mfma_f32_16x16x32_bf16 v[38:41], v[170:173], v[194:197], v[38:41]
	v_mfma_f32_16x16x32_bf16 v[34:37], v[178:181], v[194:197], v[34:37]
	v_mfma_f32_16x16x32_bf16 v[22:25], v[170:173], v[206:209], v[22:25]
	v_mfma_f32_16x16x32_bf16 v[18:21], v[178:181], v[206:209], v[18:21]
	v_mfma_f32_16x16x32_bf16 v[6:9], v[170:173], v[214:217], v[6:9]
	v_mfma_f32_16x16x32_bf16 v[2:5], v[178:181], v[214:217], v[2:5]
	v_mfma_f32_16x16x32_bf16 v[54:57], v[174:177], v[190:193], v[54:57]
	v_mfma_f32_16x16x32_bf16 v[50:53], v[182:185], v[190:193], v[50:53]
	v_mfma_f32_16x16x32_bf16 v[38:41], v[174:177], v[198:201], v[38:41]
	v_mfma_f32_16x16x32_bf16 v[34:37], v[182:185], v[198:201], v[34:37]
	v_mfma_f32_16x16x32_bf16 v[22:25], v[174:177], v[210:213], v[22:25]
	v_mfma_f32_16x16x32_bf16 v[18:21], v[182:185], v[210:213], v[18:21]
	v_mfma_f32_16x16x32_bf16 v[6:9], v[174:177], v[218:221], v[6:9]
	v_mfma_f32_16x16x32_bf16 v[2:5], v[182:185], v[218:221], v[2:5]
	s_setprio 0
	s_barrier
	s_add_i32 s63, 0, 0x18000
	v_add_u32_e32 v153, s63, v149
	s_add_i32 s64, 0, 0x1c000
	ds_read_b128 v[154:157], v153
	ds_read_b128 v[158:161], v153 offset:1024
	ds_read_b128 v[162:165], v153 offset:2048
	ds_read_b128 v[166:169], v153 offset:3072
	v_add_u32_e32 v153, s64, v149
	ds_read_b128 v[170:173], v153
	ds_read_b128 v[174:177], v153 offset:1024
	ds_read_b128 v[178:181], v153 offset:2048
	ds_read_b128 v[182:185], v153 offset:3072
	s_add_u32 s36, s36, 0x40000
	s_addc_u32 s37, s37, 0
	s_mov_b32 m0, s35
	v_lshl_add_u64 v[226:227], s[36:37], 0, v[136:137]
	ds_read_b128 v[186:189], v152 offset:32768
	ds_read_b128 v[190:193], v152 offset:33792
	ds_read_b128 v[194:197], v152 offset:34816
	ds_read_b128 v[198:201], v152 offset:35840
	ds_read_b128 v[206:209], v152 offset:36864
	ds_read_b128 v[210:213], v152 offset:37888
	ds_read_b128 v[214:217], v152 offset:38912
	ds_read_b128 v[218:221], v152 offset:39936
	global_load_lds_dwordx4 v[226:227], off
	v_lshl_add_u64 v[226:227], s[36:37], 0, v[132:133]
	s_mov_b32 m0, s38
	s_nop 0
	global_load_lds_dwordx4 v[226:227], off
	s_waitcnt vmcnt(8) lgkmcnt(0)
	s_setprio 1
	s_barrier
	v_mfma_f32_16x16x32_bf16 v[126:129], v[154:157], v[186:189], v[126:129]
	v_mfma_f32_16x16x32_bf16 v[122:125], v[162:165], v[186:189], v[122:125]
	v_mfma_f32_16x16x32_bf16 v[110:113], v[154:157], v[194:197], v[110:113]
	v_mfma_f32_16x16x32_bf16 v[106:109], v[162:165], v[194:197], v[106:109]
	v_mfma_f32_16x16x32_bf16 v[94:97], v[154:157], v[206:209], v[94:97]
	v_mfma_f32_16x16x32_bf16 v[90:93], v[162:165], v[206:209], v[90:93]
	v_mfma_f32_16x16x32_bf16 v[78:81], v[154:157], v[214:217], v[78:81]
	v_mfma_f32_16x16x32_bf16 v[74:77], v[162:165], v[214:217], v[74:77]
	v_mfma_f32_16x16x32_bf16 v[126:129], v[158:161], v[190:193], v[126:129]
	v_mfma_f32_16x16x32_bf16 v[122:125], v[166:169], v[190:193], v[122:125]
	v_mfma_f32_16x16x32_bf16 v[110:113], v[158:161], v[198:201], v[110:113]
	v_mfma_f32_16x16x32_bf16 v[106:109], v[166:169], v[198:201], v[106:109]
	v_mfma_f32_16x16x32_bf16 v[94:97], v[158:161], v[210:213], v[94:97]
	v_mfma_f32_16x16x32_bf16 v[90:93], v[166:169], v[210:213], v[90:93]
	v_mfma_f32_16x16x32_bf16 v[78:81], v[158:161], v[218:221], v[78:81]
	v_mfma_f32_16x16x32_bf16 v[74:77], v[166:169], v[218:221], v[74:77]
	v_mfma_f32_16x16x32_bf16 v[118:121], v[170:173], v[186:189], v[118:121]
	v_mfma_f32_16x16x32_bf16 v[114:117], v[178:181], v[186:189], v[114:117]
	v_mfma_f32_16x16x32_bf16 v[102:105], v[170:173], v[194:197], v[102:105]
	v_mfma_f32_16x16x32_bf16 v[98:101], v[178:181], v[194:197], v[98:101]
	v_mfma_f32_16x16x32_bf16 v[86:89], v[170:173], v[206:209], v[86:89]
	v_mfma_f32_16x16x32_bf16 v[82:85], v[178:181], v[206:209], v[82:85]
	v_mfma_f32_16x16x32_bf16 v[70:73], v[170:173], v[214:217], v[70:73]
	v_mfma_f32_16x16x32_bf16 v[66:69], v[178:181], v[214:217], v[66:69]
	v_mfma_f32_16x16x32_bf16 v[118:121], v[174:177], v[190:193], v[118:121]
	v_mfma_f32_16x16x32_bf16 v[114:117], v[182:185], v[190:193], v[114:117]
	v_mfma_f32_16x16x32_bf16 v[102:105], v[174:177], v[198:201], v[102:105]
	v_mfma_f32_16x16x32_bf16 v[98:101], v[182:185], v[198:201], v[98:101]
	v_mfma_f32_16x16x32_bf16 v[86:89], v[174:177], v[210:213], v[86:89]
	v_mfma_f32_16x16x32_bf16 v[82:85], v[182:185], v[210:213], v[82:85]
	v_mfma_f32_16x16x32_bf16 v[70:73], v[174:177], v[218:221], v[70:73]
	v_mfma_f32_16x16x32_bf16 v[66:69], v[182:185], v[218:221], v[66:69]
	s_setprio 0
	s_barrier
	s_add_i32 s36, s63, s12
	v_lshl_add_u64 v[146:147], v[146:147], 0, s[8:9]
	s_mov_b32 m0, s36
	ds_read_b128 v[186:189], v152 offset:49152
	ds_read_b128 v[190:193], v152 offset:50176
	ds_read_b128 v[194:197], v152 offset:51200
	ds_read_b128 v[198:201], v152 offset:52224
	ds_read_b128 v[206:209], v152 offset:53248
	ds_read_b128 v[210:213], v152 offset:54272
	ds_read_b128 v[214:217], v152 offset:55296
	ds_read_b128 v[218:221], v152 offset:56320
	global_load_lds_dwordx4 v[146:147], off
	s_add_i32 m0, s36, 0x2000
	s_add_u32 s30, s30, 0x40080
	v_lshl_add_u64 v[146:147], v[202:203], 0, s[8:9]
	s_addc_u32 s31, s31, 0
	s_add_i32 s36, s64, s12
	global_load_lds_dwordx4 v[146:147], off
	v_lshl_add_u64 v[146:147], s[30:31], 0, v[134:135]
	s_mov_b32 m0, s36
	s_nop 0
	global_load_lds_dwordx4 v[146:147], off
	v_lshl_add_u64 v[146:147], s[30:31], 0, v[130:131]
	s_add_i32 m0, s36, 0x2000
	s_nop 0
	global_load_lds_dwordx4 v[146:147], off
	v_lshl_add_u64 v[146:147], v[222:223], 0, s[8:9]
	s_mov_b32 m0, s42
	s_nop 0
	global_load_lds_dwordx4 v[146:147], off
	v_lshl_add_u64 v[146:147], v[224:225], 0, s[8:9]
	s_mov_b32 m0, s43
	s_nop 0
	global_load_lds_dwordx4 v[146:147], off
	s_waitcnt vmcnt(8) lgkmcnt(0)
	s_setprio 1
	s_barrier
	v_mfma_f32_16x16x32_bf16 v[62:65], v[154:157], v[186:189], v[62:65]
	v_mfma_f32_16x16x32_bf16 v[58:61], v[162:165], v[186:189], v[58:61]
	v_mfma_f32_16x16x32_bf16 v[46:49], v[154:157], v[194:197], v[46:49]
	v_mfma_f32_16x16x32_bf16 v[42:45], v[162:165], v[194:197], v[42:45]
	v_mfma_f32_16x16x32_bf16 v[30:33], v[154:157], v[206:209], v[30:33]
	v_mfma_f32_16x16x32_bf16 v[26:29], v[162:165], v[206:209], v[26:29]
	v_mfma_f32_16x16x32_bf16 v[14:17], v[154:157], v[214:217], v[14:17]
	v_mfma_f32_16x16x32_bf16 v[10:13], v[162:165], v[214:217], v[10:13]
	v_mfma_f32_16x16x32_bf16 v[62:65], v[158:161], v[190:193], v[62:65]
	v_mfma_f32_16x16x32_bf16 v[58:61], v[166:169], v[190:193], v[58:61]
	v_mfma_f32_16x16x32_bf16 v[46:49], v[158:161], v[198:201], v[46:49]
	v_mfma_f32_16x16x32_bf16 v[42:45], v[166:169], v[198:201], v[42:45]
	v_mfma_f32_16x16x32_bf16 v[30:33], v[158:161], v[210:213], v[30:33]
	v_mfma_f32_16x16x32_bf16 v[26:29], v[166:169], v[210:213], v[26:29]
	v_mfma_f32_16x16x32_bf16 v[14:17], v[158:161], v[218:221], v[14:17]
	v_mfma_f32_16x16x32_bf16 v[10:13], v[166:169], v[218:221], v[10:13]
	v_mfma_f32_16x16x32_bf16 v[54:57], v[170:173], v[186:189], v[54:57]
	v_mfma_f32_16x16x32_bf16 v[50:53], v[178:181], v[186:189], v[50:53]
	v_mfma_f32_16x16x32_bf16 v[38:41], v[170:173], v[194:197], v[38:41]
	v_mfma_f32_16x16x32_bf16 v[34:37], v[178:181], v[194:197], v[34:37]
	v_mfma_f32_16x16x32_bf16 v[22:25], v[170:173], v[206:209], v[22:25]
	v_mfma_f32_16x16x32_bf16 v[18:21], v[178:181], v[206:209], v[18:21]
	v_mfma_f32_16x16x32_bf16 v[6:9], v[170:173], v[214:217], v[6:9]
	v_mfma_f32_16x16x32_bf16 v[2:5], v[178:181], v[214:217], v[2:5]
	v_mfma_f32_16x16x32_bf16 v[54:57], v[174:177], v[190:193], v[54:57]
	v_mfma_f32_16x16x32_bf16 v[50:53], v[182:185], v[190:193], v[50:53]
	v_mfma_f32_16x16x32_bf16 v[38:41], v[174:177], v[198:201], v[38:41]
	v_mfma_f32_16x16x32_bf16 v[34:37], v[182:185], v[198:201], v[34:37]
	v_mfma_f32_16x16x32_bf16 v[22:25], v[174:177], v[210:213], v[22:25]
	v_mfma_f32_16x16x32_bf16 v[18:21], v[182:185], v[210:213], v[18:21]
	v_mfma_f32_16x16x32_bf16 v[6:9], v[174:177], v[218:221], v[6:9]
	v_mfma_f32_16x16x32_bf16 v[2:5], v[182:185], v[218:221], v[2:5]
	s_setprio 0
	s_barrier
	s_add_i32 s62, s62, 2
	s_add_u32 s28, s28, 0x100
	s_addc_u32 s29, s29, 0
	s_add_u32 s50, s50, 0x100
	s_addc_u32 s51, s51, 0
	s_cmp_gt_u32 s62, 13
	s_cbranch_scc0 .LBB0_1619
	s_and_b64 vcc, exec, s[10:11]
	s_cbranch_vccz .LBB0_1622
	s_barrier

.LBB0_1707:
	v_readlane_b32 s46, v249, 32
	v_readlane_b32 s47, v249, 33
	s_add_u32 s46, s46, s42
	s_addc_u32 s47, s47, s43
	s_and_b64 s[48:49], s[44:45], exec
	s_cselect_b32 s34, s47, s51
	s_cselect_b32 s66, s46, s50
	s_add_u32 s48, s35, s40
	s_addc_u32 s49, s70, s41
	s_and_b64 s[64:65], s[44:45], exec
	s_cselect_b32 s67, s49, s63
	s_cselect_b32 s68, s48, s62
	s_add_i32 s69, s7, -2
	s_add_u32 s50, s50, 0x100080
	s_addc_u32 s51, s51, 0
	s_add_u32 s91, s62, 0x100
	s_addc_u32 s92, s63, 0
	s_mov_b32 s62, 0
	s_waitcnt vmcnt(0)
	ds_read_b128 v[130:133], v168
	ds_read_b128 v[134:137], v168 offset:1024
	ds_read_b128 v[138:141], v168 offset:2048
	ds_read_b128 v[142:145], v168 offset:3072
	ds_read_b128 v[162:165], v169
	ds_read_b128 v[172:175], v169 offset:1024
	ds_read_b128 v[176:179], v169 offset:2048
	ds_read_b128 v[180:183], v169 offset:3072
	s_add_i32 s93, s62, 2
	s_add_u32 s63, s50, 0xfff00080
	s_addc_u32 s64, s51, -1
	s_cmp_eq_u32 s69, s62
	s_cselect_b32 s62, s68, s91
	s_cselect_b32 s65, s34, s64
	s_cselect_b32 s64, s66, s63
	s_cselect_b32 s63, s67, s92
	v_lshl_add_u64 v[218:219], s[50:51], 0, v[156:157]
	s_add_i32 m0, s12, 0xc000
	ds_read_b128 v[184:187], v170
	ds_read_b128 v[188:191], v170 offset:1024
	ds_read_b128 v[192:195], v170 offset:2048
	ds_read_b128 v[196:199], v170 offset:3072
	ds_read_b128 v[200:203], v170 offset:4096
	ds_read_b128 v[206:209], v170 offset:5120
	ds_read_b128 v[210:213], v170 offset:6144
	ds_read_b128 v[214:217], v170 offset:7168
	global_load_lds_dwordx4 v[218:219], off
	v_lshl_add_u64 v[218:219], s[50:51], 0, v[158:159]
	s_add_i32 m0, s12, 0xe000
	s_nop 0
	global_load_lds_dwordx4 v[218:219], off
	s_waitcnt vmcnt(8) lgkmcnt(0)
	s_setprio 1
	s_barrier
	v_mfma_f32_16x16x32_bf16 v[126:129], v[130:133], v[184:187], 0
	v_mfma_f32_16x16x32_bf16 v[122:125], v[138:141], v[184:187], 0
	v_mfma_f32_16x16x32_bf16 v[110:113], v[130:133], v[192:195], 0
	v_mfma_f32_16x16x32_bf16 v[106:109], v[138:141], v[192:195], 0
	v_mfma_f32_16x16x32_bf16 v[98:101], v[130:133], v[200:203], 0
	v_mfma_f32_16x16x32_bf16 v[90:93], v[138:141], v[200:203], 0
	v_mfma_f32_16x16x32_bf16 v[82:85], v[130:133], v[210:213], 0
	v_mfma_f32_16x16x32_bf16 v[74:77], v[138:141], v[210:213], 0
	v_mfma_f32_16x16x32_bf16 v[126:129], v[134:137], v[188:191], v[126:129]
	v_mfma_f32_16x16x32_bf16 v[122:125], v[142:145], v[188:191], v[122:125]
	v_mfma_f32_16x16x32_bf16 v[110:113], v[134:137], v[196:199], v[110:113]
	v_mfma_f32_16x16x32_bf16 v[106:109], v[142:145], v[196:199], v[106:109]
	v_mfma_f32_16x16x32_bf16 v[98:101], v[134:137], v[206:209], v[98:101]
	v_mfma_f32_16x16x32_bf16 v[90:93], v[142:145], v[206:209], v[90:93]
	v_mfma_f32_16x16x32_bf16 v[82:85], v[134:137], v[214:217], v[82:85]
	v_mfma_f32_16x16x32_bf16 v[74:77], v[142:145], v[214:217], v[74:77]
	v_mfma_f32_16x16x32_bf16 v[118:121], v[162:165], v[184:187], 0
	v_mfma_f32_16x16x32_bf16 v[114:117], v[176:179], v[184:187], 0
	v_mfma_f32_16x16x32_bf16 v[102:105], v[162:165], v[192:195], 0
	v_mfma_f32_16x16x32_bf16 v[94:97], v[176:179], v[192:195], 0
	v_mfma_f32_16x16x32_bf16 v[86:89], v[162:165], v[200:203], 0
	v_mfma_f32_16x16x32_bf16 v[78:81], v[176:179], v[200:203], 0
	v_mfma_f32_16x16x32_bf16 v[70:73], v[162:165], v[210:213], 0
	v_mfma_f32_16x16x32_bf16 v[66:69], v[176:179], v[210:213], 0
	v_mfma_f32_16x16x32_bf16 v[118:121], v[172:175], v[188:191], v[118:121]
	v_mfma_f32_16x16x32_bf16 v[114:117], v[180:183], v[188:191], v[114:117]
	v_mfma_f32_16x16x32_bf16 v[102:105], v[172:175], v[196:199], v[102:105]
	v_mfma_f32_16x16x32_bf16 v[94:97], v[180:183], v[196:199], v[94:97]
	v_mfma_f32_16x16x32_bf16 v[86:89], v[172:175], v[206:209], v[86:89]
	v_mfma_f32_16x16x32_bf16 v[78:81], v[180:183], v[206:209], v[78:81]
	v_mfma_f32_16x16x32_bf16 v[70:73], v[172:175], v[214:217], v[70:73]
	v_mfma_f32_16x16x32_bf16 v[66:69], v[180:183], v[214:217], v[66:69]
	s_setprio 0
	s_barrier
	s_add_i32 s94, s31, s2
	v_lshl_add_u64 v[218:219], s[62:63], 0, v[148:149]
	s_mov_b32 m0, s94
	ds_read_b128 v[184:187], v170 offset:16384
	ds_read_b128 v[188:191], v170 offset:17408
	ds_read_b128 v[192:195], v170 offset:18432
	ds_read_b128 v[196:199], v170 offset:19456
	ds_read_b128 v[200:203], v170 offset:20480
	ds_read_b128 v[206:209], v170 offset:21504
	ds_read_b128 v[210:213], v170 offset:22528
	ds_read_b128 v[214:217], v170 offset:23552
	global_load_lds_dwordx4 v[218:219], off
	s_add_i32 m0, s94, 0x2000
	s_add_u32 s94, s62, 0x100000
	v_lshl_add_u64 v[220:221], s[62:63], 0, v[152:153]
	s_addc_u32 s95, s63, 0
	s_add_i32 s96, s82, s2
	global_load_lds_dwordx4 v[220:221], off
	v_lshl_add_u64 v[222:223], s[94:95], 0, v[148:149]
	s_mov_b32 m0, s96
	v_lshl_add_u64 v[224:225], s[64:65], 0, v[150:151]
	global_load_lds_dwordx4 v[222:223], off
	v_lshl_add_u64 v[222:223], s[94:95], 0, v[152:153]
	s_add_i32 m0, s96, 0x2000
	s_nop 0
	global_load_lds_dwordx4 v[222:223], off
	v_lshl_add_u64 v[222:223], s[64:65], 0, v[146:147]
	s_mov_b32 m0, s12
	s_nop 0
	global_load_lds_dwordx4 v[222:223], off
	s_mov_b32 m0, s13
	s_nop 0
	global_load_lds_dwordx4 v[224:225], off
	s_waitcnt vmcnt(8) lgkmcnt(0)
	s_setprio 1
	s_barrier
	v_mfma_f32_16x16x32_bf16 v[62:65], v[130:133], v[184:187], 0
	v_mfma_f32_16x16x32_bf16 v[58:61], v[138:141], v[184:187], 0
	v_mfma_f32_16x16x32_bf16 v[50:53], v[130:133], v[192:195], 0
	v_mfma_f32_16x16x32_bf16 v[42:45], v[138:141], v[192:195], 0
	v_mfma_f32_16x16x32_bf16 v[34:37], v[130:133], v[200:203], 0
	v_mfma_f32_16x16x32_bf16 v[26:29], v[138:141], v[200:203], 0
	v_mfma_f32_16x16x32_bf16 v[18:21], v[130:133], v[210:213], 0
	v_mfma_f32_16x16x32_bf16 v[10:13], v[138:141], v[210:213], 0
	v_mfma_f32_16x16x32_bf16 v[62:65], v[134:137], v[188:191], v[62:65]
	v_mfma_f32_16x16x32_bf16 v[58:61], v[142:145], v[188:191], v[58:61]
	v_mfma_f32_16x16x32_bf16 v[50:53], v[134:137], v[196:199], v[50:53]
	v_mfma_f32_16x16x32_bf16 v[42:45], v[142:145], v[196:199], v[42:45]
	v_mfma_f32_16x16x32_bf16 v[34:37], v[134:137], v[206:209], v[34:37]
	v_mfma_f32_16x16x32_bf16 v[26:29], v[142:145], v[206:209], v[26:29]
	v_mfma_f32_16x16x32_bf16 v[18:21], v[134:137], v[214:217], v[18:21]
	v_mfma_f32_16x16x32_bf16 v[10:13], v[142:145], v[214:217], v[10:13]
	v_mfma_f32_16x16x32_bf16 v[54:57], v[162:165], v[184:187], 0
	v_mfma_f32_16x16x32_bf16 v[46:49], v[176:179], v[184:187], 0
	v_mfma_f32_16x16x32_bf16 v[38:41], v[162:165], v[192:195], 0
	v_mfma_f32_16x16x32_bf16 v[30:33], v[176:179], v[192:195], 0
	v_mfma_f32_16x16x32_bf16 v[22:25], v[162:165], v[200:203], 0
	v_mfma_f32_16x16x32_bf16 v[14:17], v[176:179], v[200:203], 0
	v_mfma_f32_16x16x32_bf16 v[6:9], v[162:165], v[210:213], 0
	v_mfma_f32_16x16x32_bf16 v[2:5], v[176:179], v[210:213], 0
	v_mfma_f32_16x16x32_bf16 v[54:57], v[172:175], v[188:191], v[54:57]
	v_mfma_f32_16x16x32_bf16 v[46:49], v[180:183], v[188:191], v[46:49]
	v_mfma_f32_16x16x32_bf16 v[38:41], v[172:175], v[196:199], v[38:41]
	v_mfma_f32_16x16x32_bf16 v[30:33], v[180:183], v[196:199], v[30:33]
	v_mfma_f32_16x16x32_bf16 v[22:25], v[172:175], v[206:209], v[22:25]
	v_mfma_f32_16x16x32_bf16 v[14:17], v[180:183], v[206:209], v[14:17]
	v_mfma_f32_16x16x32_bf16 v[6:9], v[172:175], v[214:217], v[6:9]
	v_mfma_f32_16x16x32_bf16 v[2:5], v[180:183], v[214:217], v[2:5]
	s_setprio 0
	s_barrier
	s_add_i32 s94, 0, 0x18000
	s_add_i32 s95, 0, 0x1c000
	v_add_u32_e32 v142, s94, v167
	v_add_u32_e32 v154, s95, v167
	ds_read_b128 v[130:133], v142
	ds_read_b128 v[134:137], v142 offset:1024
	ds_read_b128 v[138:141], v142 offset:2048
	ds_read_b128 v[142:145], v142 offset:3072
	ds_read_b128 v[162:165], v154
	ds_read_b128 v[172:175], v154 offset:1024
	ds_read_b128 v[176:179], v154 offset:2048
	ds_read_b128 v[180:183], v154 offset:3072
	s_add_u32 s64, s64, 0x100000
	s_addc_u32 s65, s65, 0
	s_mov_b32 m0, s18
	v_lshl_add_u64 v[226:227], s[64:65], 0, v[146:147]
	ds_read_b128 v[184:187], v170 offset:32768
	ds_read_b128 v[188:191], v170 offset:33792
	ds_read_b128 v[192:195], v170 offset:34816
	ds_read_b128 v[196:199], v170 offset:35840
	ds_read_b128 v[200:203], v170 offset:36864
	ds_read_b128 v[206:209], v170 offset:37888
	ds_read_b128 v[210:213], v170 offset:38912
	ds_read_b128 v[214:217], v170 offset:39936
	global_load_lds_dwordx4 v[226:227], off
	v_lshl_add_u64 v[226:227], s[64:65], 0, v[150:151]
	s_mov_b32 m0, s19
	s_nop 0
	global_load_lds_dwordx4 v[226:227], off
	s_waitcnt vmcnt(8) lgkmcnt(0)
	s_setprio 1
	s_barrier
	v_mfma_f32_16x16x32_bf16 v[126:129], v[130:133], v[184:187], v[126:129]
	v_mfma_f32_16x16x32_bf16 v[122:125], v[138:141], v[184:187], v[122:125]
	v_mfma_f32_16x16x32_bf16 v[110:113], v[130:133], v[192:195], v[110:113]
	v_mfma_f32_16x16x32_bf16 v[106:109], v[138:141], v[192:195], v[106:109]
	v_mfma_f32_16x16x32_bf16 v[98:101], v[130:133], v[200:203], v[98:101]
	v_mfma_f32_16x16x32_bf16 v[90:93], v[138:141], v[200:203], v[90:93]
	v_mfma_f32_16x16x32_bf16 v[82:85], v[130:133], v[210:213], v[82:85]
	v_mfma_f32_16x16x32_bf16 v[74:77], v[138:141], v[210:213], v[74:77]
	v_mfma_f32_16x16x32_bf16 v[126:129], v[134:137], v[188:191], v[126:129]
	v_mfma_f32_16x16x32_bf16 v[122:125], v[142:145], v[188:191], v[122:125]
	v_mfma_f32_16x16x32_bf16 v[110:113], v[134:137], v[196:199], v[110:113]
	v_mfma_f32_16x16x32_bf16 v[106:109], v[142:145], v[196:199], v[106:109]
	v_mfma_f32_16x16x32_bf16 v[98:101], v[134:137], v[206:209], v[98:101]
	v_mfma_f32_16x16x32_bf16 v[90:93], v[142:145], v[206:209], v[90:93]
	v_mfma_f32_16x16x32_bf16 v[82:85], v[134:137], v[214:217], v[82:85]
	v_mfma_f32_16x16x32_bf16 v[74:77], v[142:145], v[214:217], v[74:77]
	v_mfma_f32_16x16x32_bf16 v[118:121], v[162:165], v[184:187], v[118:121]
	v_mfma_f32_16x16x32_bf16 v[114:117], v[176:179], v[184:187], v[114:117]
	v_mfma_f32_16x16x32_bf16 v[102:105], v[162:165], v[192:195], v[102:105]
	v_mfma_f32_16x16x32_bf16 v[94:97], v[176:179], v[192:195], v[94:97]
	v_mfma_f32_16x16x32_bf16 v[86:89], v[162:165], v[200:203], v[86:89]
	v_mfma_f32_16x16x32_bf16 v[78:81], v[176:179], v[200:203], v[78:81]
	v_mfma_f32_16x16x32_bf16 v[70:73], v[162:165], v[210:213], v[70:73]
	v_mfma_f32_16x16x32_bf16 v[66:69], v[176:179], v[210:213], v[66:69]
	v_mfma_f32_16x16x32_bf16 v[118:121], v[172:175], v[188:191], v[118:121]
	v_mfma_f32_16x16x32_bf16 v[114:117], v[180:183], v[188:191], v[114:117]
	v_mfma_f32_16x16x32_bf16 v[102:105], v[172:175], v[196:199], v[102:105]
	v_mfma_f32_16x16x32_bf16 v[94:97], v[180:183], v[196:199], v[94:97]
	v_mfma_f32_16x16x32_bf16 v[86:89], v[172:175], v[206:209], v[86:89]
	v_mfma_f32_16x16x32_bf16 v[78:81], v[180:183], v[206:209], v[78:81]
	v_mfma_f32_16x16x32_bf16 v[70:73], v[172:175], v[214:217], v[70:73]
	v_mfma_f32_16x16x32_bf16 v[66:69], v[180:183], v[214:217], v[66:69]
	s_setprio 0
	s_barrier
	s_add_i32 s64, s94, s2
	v_lshl_add_u64 v[218:219], v[218:219], 0, s[16:17]
	s_mov_b32 m0, s64
	ds_read_b128 v[184:187], v170 offset:49152
	ds_read_b128 v[188:191], v170 offset:50176
	ds_read_b128 v[192:195], v170 offset:51200
	ds_read_b128 v[196:199], v170 offset:52224
	ds_read_b128 v[200:203], v170 offset:53248
	ds_read_b128 v[206:209], v170 offset:54272
	ds_read_b128 v[210:213], v170 offset:55296
	ds_read_b128 v[214:217], v170 offset:56320
	global_load_lds_dwordx4 v[218:219], off
	s_add_i32 m0, s64, 0x2000
	s_add_u32 s62, s62, 0x100080
	v_lshl_add_u64 v[218:219], v[220:221], 0, s[16:17]
	s_addc_u32 s63, s63, 0
	s_add_i32 s64, s95, s2
	global_load_lds_dwordx4 v[218:219], off
	v_lshl_add_u64 v[218:219], s[62:63], 0, v[148:149]
	s_mov_b32 m0, s64
	s_nop 0
	global_load_lds_dwordx4 v[218:219], off
	v_lshl_add_u64 v[218:219], s[62:63], 0, v[152:153]
	s_add_i32 m0, s64, 0x2000
	s_nop 0
	global_load_lds_dwordx4 v[218:219], off
	v_lshl_add_u64 v[218:219], v[222:223], 0, s[16:17]
	s_mov_b32 m0, s74
	s_nop 0
	global_load_lds_dwordx4 v[218:219], off
	v_lshl_add_u64 v[218:219], v[224:225], 0, s[16:17]
	s_mov_b32 m0, s75
	s_nop 0
	global_load_lds_dwordx4 v[218:219], off
	s_waitcnt vmcnt(8) lgkmcnt(0)
	s_setprio 1
	s_barrier
	v_mfma_f32_16x16x32_bf16 v[62:65], v[130:133], v[184:187], v[62:65]
	v_mfma_f32_16x16x32_bf16 v[58:61], v[138:141], v[184:187], v[58:61]
	v_mfma_f32_16x16x32_bf16 v[50:53], v[130:133], v[192:195], v[50:53]
	v_mfma_f32_16x16x32_bf16 v[42:45], v[138:141], v[192:195], v[42:45]
	v_mfma_f32_16x16x32_bf16 v[34:37], v[130:133], v[200:203], v[34:37]
	v_mfma_f32_16x16x32_bf16 v[26:29], v[138:141], v[200:203], v[26:29]
	v_mfma_f32_16x16x32_bf16 v[18:21], v[130:133], v[210:213], v[18:21]
	v_mfma_f32_16x16x32_bf16 v[10:13], v[138:141], v[210:213], v[10:13]
	v_mfma_f32_16x16x32_bf16 v[62:65], v[134:137], v[188:191], v[62:65]
	v_mfma_f32_16x16x32_bf16 v[58:61], v[142:145], v[188:191], v[58:61]
	v_mfma_f32_16x16x32_bf16 v[50:53], v[134:137], v[196:199], v[50:53]
	v_mfma_f32_16x16x32_bf16 v[42:45], v[142:145], v[196:199], v[42:45]
	v_mfma_f32_16x16x32_bf16 v[34:37], v[134:137], v[206:209], v[34:37]
	v_mfma_f32_16x16x32_bf16 v[26:29], v[142:145], v[206:209], v[26:29]
	v_mfma_f32_16x16x32_bf16 v[18:21], v[134:137], v[214:217], v[18:21]
	v_mfma_f32_16x16x32_bf16 v[10:13], v[142:145], v[214:217], v[10:13]
	v_mfma_f32_16x16x32_bf16 v[54:57], v[162:165], v[184:187], v[54:57]
	v_mfma_f32_16x16x32_bf16 v[46:49], v[176:179], v[184:187], v[46:49]
	v_mfma_f32_16x16x32_bf16 v[38:41], v[162:165], v[192:195], v[38:41]
	v_mfma_f32_16x16x32_bf16 v[30:33], v[176:179], v[192:195], v[30:33]
	v_mfma_f32_16x16x32_bf16 v[22:25], v[162:165], v[200:203], v[22:25]
	v_mfma_f32_16x16x32_bf16 v[14:17], v[176:179], v[200:203], v[14:17]
	v_mfma_f32_16x16x32_bf16 v[6:9], v[162:165], v[210:213], v[6:9]
	v_mfma_f32_16x16x32_bf16 v[2:5], v[176:179], v[210:213], v[2:5]
	v_mfma_f32_16x16x32_bf16 v[54:57], v[172:175], v[188:191], v[54:57]
	v_mfma_f32_16x16x32_bf16 v[46:49], v[180:183], v[188:191], v[46:49]
	v_mfma_f32_16x16x32_bf16 v[38:41], v[172:175], v[196:199], v[38:41]
	v_mfma_f32_16x16x32_bf16 v[30:33], v[180:183], v[196:199], v[30:33]
	v_mfma_f32_16x16x32_bf16 v[22:25], v[172:175], v[206:209], v[22:25]
	v_mfma_f32_16x16x32_bf16 v[14:17], v[180:183], v[206:209], v[14:17]
	v_mfma_f32_16x16x32_bf16 v[6:9], v[172:175], v[214:217], v[6:9]
	v_mfma_f32_16x16x32_bf16 v[2:5], v[180:183], v[214:217], v[2:5]
	s_setprio 0
	s_barrier
	s_add_u32 s50, s50, 0x100
	s_addc_u32 s51, s51, 0
	s_add_u32 s91, s91, 0x100
	s_addc_u32 s92, s92, 0
	s_cmp_ge_i32 s93, s7
	s_mov_b32 s62, s93
.LBB0_1708:
	ds_read_b128 v[130:133], v168
	ds_read_b128 v[134:137], v168 offset:1024
	ds_read_b128 v[138:141], v168 offset:2048
	ds_read_b128 v[142:145], v168 offset:3072
	ds_read_b128 v[162:165], v169
	ds_read_b128 v[172:175], v169 offset:1024
	ds_read_b128 v[176:179], v169 offset:2048
	ds_read_b128 v[180:183], v169 offset:3072
	s_add_i32 s93, s62, 2
	s_add_u32 s63, s50, 0xfff00080
	s_addc_u32 s64, s51, -1
	s_cmp_eq_u32 s69, s62
	s_cselect_b32 s62, s68, s91
	s_cselect_b32 s65, s34, s64
	s_cselect_b32 s64, s66, s63
	s_cselect_b32 s63, s67, s92
	v_lshl_add_u64 v[218:219], s[50:51], 0, v[156:157]
	s_add_i32 m0, s12, 0xc000
	ds_read_b128 v[184:187], v170
	ds_read_b128 v[188:191], v170 offset:1024
	ds_read_b128 v[192:195], v170 offset:2048
	ds_read_b128 v[196:199], v170 offset:3072
	ds_read_b128 v[200:203], v170 offset:4096
	ds_read_b128 v[206:209], v170 offset:5120
	ds_read_b128 v[210:213], v170 offset:6144
	ds_read_b128 v[214:217], v170 offset:7168
	global_load_lds_dwordx4 v[218:219], off
	v_lshl_add_u64 v[218:219], s[50:51], 0, v[158:159]
	s_add_i32 m0, s12, 0xe000
	s_nop 0
	global_load_lds_dwordx4 v[218:219], off
	s_waitcnt vmcnt(8) lgkmcnt(0)
	s_setprio 1
	s_barrier
	v_mfma_f32_16x16x32_bf16 v[126:129], v[130:133], v[184:187], v[126:129]
	v_mfma_f32_16x16x32_bf16 v[122:125], v[138:141], v[184:187], v[122:125]
	v_mfma_f32_16x16x32_bf16 v[110:113], v[130:133], v[192:195], v[110:113]
	v_mfma_f32_16x16x32_bf16 v[106:109], v[138:141], v[192:195], v[106:109]
	v_mfma_f32_16x16x32_bf16 v[98:101], v[130:133], v[200:203], v[98:101]
	v_mfma_f32_16x16x32_bf16 v[90:93], v[138:141], v[200:203], v[90:93]
	v_mfma_f32_16x16x32_bf16 v[82:85], v[130:133], v[210:213], v[82:85]
	v_mfma_f32_16x16x32_bf16 v[74:77], v[138:141], v[210:213], v[74:77]
	v_mfma_f32_16x16x32_bf16 v[126:129], v[134:137], v[188:191], v[126:129]
	v_mfma_f32_16x16x32_bf16 v[122:125], v[142:145], v[188:191], v[122:125]
	v_mfma_f32_16x16x32_bf16 v[110:113], v[134:137], v[196:199], v[110:113]
	v_mfma_f32_16x16x32_bf16 v[106:109], v[142:145], v[196:199], v[106:109]
	v_mfma_f32_16x16x32_bf16 v[98:101], v[134:137], v[206:209], v[98:101]
	v_mfma_f32_16x16x32_bf16 v[90:93], v[142:145], v[206:209], v[90:93]
	v_mfma_f32_16x16x32_bf16 v[82:85], v[134:137], v[214:217], v[82:85]
	v_mfma_f32_16x16x32_bf16 v[74:77], v[142:145], v[214:217], v[74:77]
	v_mfma_f32_16x16x32_bf16 v[118:121], v[162:165], v[184:187], v[118:121]
	v_mfma_f32_16x16x32_bf16 v[114:117], v[176:179], v[184:187], v[114:117]
	v_mfma_f32_16x16x32_bf16 v[102:105], v[162:165], v[192:195], v[102:105]
	v_mfma_f32_16x16x32_bf16 v[94:97], v[176:179], v[192:195], v[94:97]
	v_mfma_f32_16x16x32_bf16 v[86:89], v[162:165], v[200:203], v[86:89]
	v_mfma_f32_16x16x32_bf16 v[78:81], v[176:179], v[200:203], v[78:81]
	v_mfma_f32_16x16x32_bf16 v[70:73], v[162:165], v[210:213], v[70:73]
	v_mfma_f32_16x16x32_bf16 v[66:69], v[176:179], v[210:213], v[66:69]
	v_mfma_f32_16x16x32_bf16 v[118:121], v[172:175], v[188:191], v[118:121]
	v_mfma_f32_16x16x32_bf16 v[114:117], v[180:183], v[188:191], v[114:117]
	v_mfma_f32_16x16x32_bf16 v[102:105], v[172:175], v[196:199], v[102:105]
	v_mfma_f32_16x16x32_bf16 v[94:97], v[180:183], v[196:199], v[94:97]
	v_mfma_f32_16x16x32_bf16 v[86:89], v[172:175], v[206:209], v[86:89]
	v_mfma_f32_16x16x32_bf16 v[78:81], v[180:183], v[206:209], v[78:81]
	v_mfma_f32_16x16x32_bf16 v[70:73], v[172:175], v[214:217], v[70:73]
	v_mfma_f32_16x16x32_bf16 v[66:69], v[180:183], v[214:217], v[66:69]
	s_setprio 0
	s_barrier
	s_add_i32 s94, s31, s2
	v_lshl_add_u64 v[218:219], s[62:63], 0, v[148:149]
	s_mov_b32 m0, s94
	ds_read_b128 v[184:187], v170 offset:16384
	ds_read_b128 v[188:191], v170 offset:17408
	ds_read_b128 v[192:195], v170 offset:18432
	ds_read_b128 v[196:199], v170 offset:19456
	ds_read_b128 v[200:203], v170 offset:20480
	ds_read_b128 v[206:209], v170 offset:21504
	ds_read_b128 v[210:213], v170 offset:22528
	ds_read_b128 v[214:217], v170 offset:23552
	global_load_lds_dwordx4 v[218:219], off
	s_add_i32 m0, s94, 0x2000
	s_add_u32 s94, s62, 0x100000
	v_lshl_add_u64 v[220:221], s[62:63], 0, v[152:153]
	s_addc_u32 s95, s63, 0
	s_add_i32 s96, s82, s2
	global_load_lds_dwordx4 v[220:221], off
	v_lshl_add_u64 v[222:223], s[94:95], 0, v[148:149]
	s_mov_b32 m0, s96
	v_lshl_add_u64 v[224:225], s[64:65], 0, v[150:151]
	global_load_lds_dwordx4 v[222:223], off
	v_lshl_add_u64 v[222:223], s[94:95], 0, v[152:153]
	s_add_i32 m0, s96, 0x2000
	s_nop 0
	global_load_lds_dwordx4 v[222:223], off
	v_lshl_add_u64 v[222:223], s[64:65], 0, v[146:147]
	s_mov_b32 m0, s12
	s_nop 0
	global_load_lds_dwordx4 v[222:223], off
	s_mov_b32 m0, s13
	s_nop 0
	global_load_lds_dwordx4 v[224:225], off
	s_waitcnt vmcnt(8) lgkmcnt(0)
	s_setprio 1
	s_barrier
	v_mfma_f32_16x16x32_bf16 v[62:65], v[130:133], v[184:187], v[62:65]
	v_mfma_f32_16x16x32_bf16 v[58:61], v[138:141], v[184:187], v[58:61]
	v_mfma_f32_16x16x32_bf16 v[50:53], v[130:133], v[192:195], v[50:53]
	v_mfma_f32_16x16x32_bf16 v[42:45], v[138:141], v[192:195], v[42:45]
	v_mfma_f32_16x16x32_bf16 v[34:37], v[130:133], v[200:203], v[34:37]
	v_mfma_f32_16x16x32_bf16 v[26:29], v[138:141], v[200:203], v[26:29]
	v_mfma_f32_16x16x32_bf16 v[18:21], v[130:133], v[210:213], v[18:21]
	v_mfma_f32_16x16x32_bf16 v[10:13], v[138:141], v[210:213], v[10:13]
	v_mfma_f32_16x16x32_bf16 v[62:65], v[134:137], v[188:191], v[62:65]
	v_mfma_f32_16x16x32_bf16 v[58:61], v[142:145], v[188:191], v[58:61]
	v_mfma_f32_16x16x32_bf16 v[50:53], v[134:137], v[196:199], v[50:53]
	v_mfma_f32_16x16x32_bf16 v[42:45], v[142:145], v[196:199], v[42:45]
	v_mfma_f32_16x16x32_bf16 v[34:37], v[134:137], v[206:209], v[34:37]
	v_mfma_f32_16x16x32_bf16 v[26:29], v[142:145], v[206:209], v[26:29]
	v_mfma_f32_16x16x32_bf16 v[18:21], v[134:137], v[214:217], v[18:21]
	v_mfma_f32_16x16x32_bf16 v[10:13], v[142:145], v[214:217], v[10:13]
	v_mfma_f32_16x16x32_bf16 v[54:57], v[162:165], v[184:187], v[54:57]
	v_mfma_f32_16x16x32_bf16 v[46:49], v[176:179], v[184:187], v[46:49]
	v_mfma_f32_16x16x32_bf16 v[38:41], v[162:165], v[192:195], v[38:41]
	v_mfma_f32_16x16x32_bf16 v[30:33], v[176:179], v[192:195], v[30:33]
	v_mfma_f32_16x16x32_bf16 v[22:25], v[162:165], v[200:203], v[22:25]
	v_mfma_f32_16x16x32_bf16 v[14:17], v[176:179], v[200:203], v[14:17]
	v_mfma_f32_16x16x32_bf16 v[6:9], v[162:165], v[210:213], v[6:9]
	v_mfma_f32_16x16x32_bf16 v[2:5], v[176:179], v[210:213], v[2:5]
	v_mfma_f32_16x16x32_bf16 v[54:57], v[172:175], v[188:191], v[54:57]
	v_mfma_f32_16x16x32_bf16 v[46:49], v[180:183], v[188:191], v[46:49]
	v_mfma_f32_16x16x32_bf16 v[38:41], v[172:175], v[196:199], v[38:41]
	v_mfma_f32_16x16x32_bf16 v[30:33], v[180:183], v[196:199], v[30:33]
	v_mfma_f32_16x16x32_bf16 v[22:25], v[172:175], v[206:209], v[22:25]
	v_mfma_f32_16x16x32_bf16 v[14:17], v[180:183], v[206:209], v[14:17]
	v_mfma_f32_16x16x32_bf16 v[6:9], v[172:175], v[214:217], v[6:9]
	v_mfma_f32_16x16x32_bf16 v[2:5], v[180:183], v[214:217], v[2:5]
	s_setprio 0
	s_barrier
	s_add_i32 s94, 0, 0x18000
	s_add_i32 s95, 0, 0x1c000
	v_add_u32_e32 v142, s94, v167
	v_add_u32_e32 v154, s95, v167
	ds_read_b128 v[130:133], v142
	ds_read_b128 v[134:137], v142 offset:1024
	ds_read_b128 v[138:141], v142 offset:2048
	ds_read_b128 v[142:145], v142 offset:3072
	ds_read_b128 v[162:165], v154
	ds_read_b128 v[172:175], v154 offset:1024
	ds_read_b128 v[176:179], v154 offset:2048
	ds_read_b128 v[180:183], v154 offset:3072
	s_add_u32 s64, s64, 0x100000
	s_addc_u32 s65, s65, 0
	s_mov_b32 m0, s18
	v_lshl_add_u64 v[226:227], s[64:65], 0, v[146:147]
	ds_read_b128 v[184:187], v170 offset:32768
	ds_read_b128 v[188:191], v170 offset:33792
	ds_read_b128 v[192:195], v170 offset:34816
	ds_read_b128 v[196:199], v170 offset:35840
	ds_read_b128 v[200:203], v170 offset:36864
	ds_read_b128 v[206:209], v170 offset:37888
	ds_read_b128 v[210:213], v170 offset:38912
	ds_read_b128 v[214:217], v170 offset:39936
	global_load_lds_dwordx4 v[226:227], off
	v_lshl_add_u64 v[226:227], s[64:65], 0, v[150:151]
	s_mov_b32 m0, s19
	s_nop 0
	global_load_lds_dwordx4 v[226:227], off
	s_waitcnt vmcnt(8) lgkmcnt(0)
	s_setprio 1
	s_barrier
	v_mfma_f32_16x16x32_bf16 v[126:129], v[130:133], v[184:187], v[126:129]
	v_mfma_f32_16x16x32_bf16 v[122:125], v[138:141], v[184:187], v[122:125]
	v_mfma_f32_16x16x32_bf16 v[110:113], v[130:133], v[192:195], v[110:113]
	v_mfma_f32_16x16x32_bf16 v[106:109], v[138:141], v[192:195], v[106:109]
	v_mfma_f32_16x16x32_bf16 v[98:101], v[130:133], v[200:203], v[98:101]
	v_mfma_f32_16x16x32_bf16 v[90:93], v[138:141], v[200:203], v[90:93]
	v_mfma_f32_16x16x32_bf16 v[82:85], v[130:133], v[210:213], v[82:85]
	v_mfma_f32_16x16x32_bf16 v[74:77], v[138:141], v[210:213], v[74:77]
	v_mfma_f32_16x16x32_bf16 v[126:129], v[134:137], v[188:191], v[126:129]
	v_mfma_f32_16x16x32_bf16 v[122:125], v[142:145], v[188:191], v[122:125]
	v_mfma_f32_16x16x32_bf16 v[110:113], v[134:137], v[196:199], v[110:113]
	v_mfma_f32_16x16x32_bf16 v[106:109], v[142:145], v[196:199], v[106:109]
	v_mfma_f32_16x16x32_bf16 v[98:101], v[134:137], v[206:209], v[98:101]
	v_mfma_f32_16x16x32_bf16 v[90:93], v[142:145], v[206:209], v[90:93]
	v_mfma_f32_16x16x32_bf16 v[82:85], v[134:137], v[214:217], v[82:85]
	v_mfma_f32_16x16x32_bf16 v[74:77], v[142:145], v[214:217], v[74:77]
	v_mfma_f32_16x16x32_bf16 v[118:121], v[162:165], v[184:187], v[118:121]
	v_mfma_f32_16x16x32_bf16 v[114:117], v[176:179], v[184:187], v[114:117]
	v_mfma_f32_16x16x32_bf16 v[102:105], v[162:165], v[192:195], v[102:105]
	v_mfma_f32_16x16x32_bf16 v[94:97], v[176:179], v[192:195], v[94:97]
	v_mfma_f32_16x16x32_bf16 v[86:89], v[162:165], v[200:203], v[86:89]
	v_mfma_f32_16x16x32_bf16 v[78:81], v[176:179], v[200:203], v[78:81]
	v_mfma_f32_16x16x32_bf16 v[70:73], v[162:165], v[210:213], v[70:73]
	v_mfma_f32_16x16x32_bf16 v[66:69], v[176:179], v[210:213], v[66:69]
	v_mfma_f32_16x16x32_bf16 v[118:121], v[172:175], v[188:191], v[118:121]
	v_mfma_f32_16x16x32_bf16 v[114:117], v[180:183], v[188:191], v[114:117]
	v_mfma_f32_16x16x32_bf16 v[102:105], v[172:175], v[196:199], v[102:105]
	v_mfma_f32_16x16x32_bf16 v[94:97], v[180:183], v[196:199], v[94:97]
	v_mfma_f32_16x16x32_bf16 v[86:89], v[172:175], v[206:209], v[86:89]
	v_mfma_f32_16x16x32_bf16 v[78:81], v[180:183], v[206:209], v[78:81]
	v_mfma_f32_16x16x32_bf16 v[70:73], v[172:175], v[214:217], v[70:73]
	v_mfma_f32_16x16x32_bf16 v[66:69], v[180:183], v[214:217], v[66:69]
	s_setprio 0
	s_barrier
	s_add_i32 s64, s94, s2
	v_lshl_add_u64 v[218:219], v[218:219], 0, s[16:17]
	s_mov_b32 m0, s64
	ds_read_b128 v[184:187], v170 offset:49152
	ds_read_b128 v[188:191], v170 offset:50176
	ds_read_b128 v[192:195], v170 offset:51200
	ds_read_b128 v[196:199], v170 offset:52224
	ds_read_b128 v[200:203], v170 offset:53248
	ds_read_b128 v[206:209], v170 offset:54272
	ds_read_b128 v[210:213], v170 offset:55296
	ds_read_b128 v[214:217], v170 offset:56320
	global_load_lds_dwordx4 v[218:219], off
	s_add_i32 m0, s64, 0x2000
	s_add_u32 s62, s62, 0x100080
	v_lshl_add_u64 v[218:219], v[220:221], 0, s[16:17]
	s_addc_u32 s63, s63, 0
	s_add_i32 s64, s95, s2
	global_load_lds_dwordx4 v[218:219], off
	v_lshl_add_u64 v[218:219], s[62:63], 0, v[148:149]
	s_mov_b32 m0, s64
	s_nop 0
	global_load_lds_dwordx4 v[218:219], off
	v_lshl_add_u64 v[218:219], s[62:63], 0, v[152:153]
	s_add_i32 m0, s64, 0x2000
	s_nop 0
	global_load_lds_dwordx4 v[218:219], off
	v_lshl_add_u64 v[218:219], v[222:223], 0, s[16:17]
	s_mov_b32 m0, s74
	s_nop 0
	global_load_lds_dwordx4 v[218:219], off
	v_lshl_add_u64 v[218:219], v[224:225], 0, s[16:17]
	s_mov_b32 m0, s75
	s_nop 0
	global_load_lds_dwordx4 v[218:219], off
	s_waitcnt vmcnt(8) lgkmcnt(0)
	s_setprio 1
	s_barrier
	v_mfma_f32_16x16x32_bf16 v[62:65], v[130:133], v[184:187], v[62:65]
	v_mfma_f32_16x16x32_bf16 v[58:61], v[138:141], v[184:187], v[58:61]
	v_mfma_f32_16x16x32_bf16 v[50:53], v[130:133], v[192:195], v[50:53]
	v_mfma_f32_16x16x32_bf16 v[42:45], v[138:141], v[192:195], v[42:45]
	v_mfma_f32_16x16x32_bf16 v[34:37], v[130:133], v[200:203], v[34:37]
	v_mfma_f32_16x16x32_bf16 v[26:29], v[138:141], v[200:203], v[26:29]
	v_mfma_f32_16x16x32_bf16 v[18:21], v[130:133], v[210:213], v[18:21]
	v_mfma_f32_16x16x32_bf16 v[10:13], v[138:141], v[210:213], v[10:13]
	v_mfma_f32_16x16x32_bf16 v[62:65], v[134:137], v[188:191], v[62:65]
	v_mfma_f32_16x16x32_bf16 v[58:61], v[142:145], v[188:191], v[58:61]
	v_mfma_f32_16x16x32_bf16 v[50:53], v[134:137], v[196:199], v[50:53]
	v_mfma_f32_16x16x32_bf16 v[42:45], v[142:145], v[196:199], v[42:45]
	v_mfma_f32_16x16x32_bf16 v[34:37], v[134:137], v[206:209], v[34:37]
	v_mfma_f32_16x16x32_bf16 v[26:29], v[142:145], v[206:209], v[26:29]
	v_mfma_f32_16x16x32_bf16 v[18:21], v[134:137], v[214:217], v[18:21]
	v_mfma_f32_16x16x32_bf16 v[10:13], v[142:145], v[214:217], v[10:13]
	v_mfma_f32_16x16x32_bf16 v[54:57], v[162:165], v[184:187], v[54:57]
	v_mfma_f32_16x16x32_bf16 v[46:49], v[176:179], v[184:187], v[46:49]
	v_mfma_f32_16x16x32_bf16 v[38:41], v[162:165], v[192:195], v[38:41]
	v_mfma_f32_16x16x32_bf16 v[30:33], v[176:179], v[192:195], v[30:33]
	v_mfma_f32_16x16x32_bf16 v[22:25], v[162:165], v[200:203], v[22:25]
	v_mfma_f32_16x16x32_bf16 v[14:17], v[176:179], v[200:203], v[14:17]
	v_mfma_f32_16x16x32_bf16 v[6:9], v[162:165], v[210:213], v[6:9]
	v_mfma_f32_16x16x32_bf16 v[2:5], v[176:179], v[210:213], v[2:5]
	v_mfma_f32_16x16x32_bf16 v[54:57], v[172:175], v[188:191], v[54:57]
	v_mfma_f32_16x16x32_bf16 v[46:49], v[180:183], v[188:191], v[46:49]
	v_mfma_f32_16x16x32_bf16 v[38:41], v[172:175], v[196:199], v[38:41]
	v_mfma_f32_16x16x32_bf16 v[30:33], v[180:183], v[196:199], v[30:33]
	v_mfma_f32_16x16x32_bf16 v[22:25], v[172:175], v[206:209], v[22:25]
	v_mfma_f32_16x16x32_bf16 v[14:17], v[180:183], v[206:209], v[14:17]
	v_mfma_f32_16x16x32_bf16 v[6:9], v[172:175], v[214:217], v[6:9]
	v_mfma_f32_16x16x32_bf16 v[2:5], v[180:183], v[214:217], v[2:5]
	s_setprio 0
	s_barrier
	s_add_u32 s50, s50, 0x100
	s_addc_u32 s51, s51, 0
	s_add_u32 s91, s91, 0x100
	s_addc_u32 s92, s92, 0
	s_cmp_ge_i32 s93, s7
	s_mov_b32 s62, s93
	s_cbranch_scc0 .LBB0_1708
	s_and_b64 vcc, exec, s[20:21]
	s_cbranch_vccz .LBB0_1711
	s_barrier
